# FFT radix-8 passes unrolled x2 with early LDS reads for the second sub-iteration; natten validity masking via v_bfe_i32+v_bfi_b32 (2 VALU per element instead of and+cmp+cndmask)
# speedup vs baseline: 1.0365x; 1.0051x over previous
; #define LAS __attribute__((address_space(3)))
; __device__ __forceinline__ int otid() { int t = threadIdx.x; asm volatile("" : "+v"(t)); return t; }
; __device__ __forceinline__ cf twc(cf ws, int k16) { if (k16 == 0) return ws; if (k16 == 4) return cf{ws.y, -ws.x}; return cmul(ws, cf{c16(k16), -s16(k16)}); }
; template <int LR> __device__ __forceinline__ void dif_reg(cf (&x)[1 << LR], cf w) {
;     constexpr int R = 1 << LR; cf ws = w;
; #pragma unroll
;     for (int s = 0; s < LR; ++s) { const int half = R >> (s + 1);
; #pragma unroll
;         for (int m0 = 0; m0 < R; m0 += 2 * half)
; #pragma unroll
;             for (int mm = 0; mm < half; ++mm) { const int ia = m0 + mm, ib = ia + half; const cf a = x[ia], b = x[ib];
;                 x[ia] = cf{a.x + b.x, a.y + b.y}; const cf d{a.x - b.x, a.y - b.y};
;                 x[ib] = cmul(d, twc(ws, (mm << s) * (16 / R))); }
;         ws = cmul(ws, ws); }
; }
; template <int LR, bool INV> __device__ __forceinline__ void fft_pass(ldsf2 buf, int base, int stride, int twi) {
;     constexpr int R = 1 << LR; cf x[R];
;     const v2f wv = ((ldsf2)((LAS unsigned char*)buf + 139264))[twi];
; #pragma unroll
;     for (int m = 0; m < R; ++m) { const v2f v = buf[base + m * stride]; x[m] = cf{v.x, v.y}; }
;     const cf w{wv.x, wv.y};
;     if (INV) dit_reg<LR>(x, w); else dif_reg<LR>(x, w);
; #pragma unroll
;     for (int m = 0; m < R; ++m) buf[base + m * stride] = mkv2(x[m].x, x[m].y);
; }
; __device__ __forceinline__ void wave_lds_fence() { asm volatile("s_waitcnt lgkmcnt(0)" ::: "memory"); }
; __device__ __forceinline__ void fft_fwd_abc(ldsf2 buf) {
;     const int tid = otid(); const int wv = tid >> 6, l = tid & 63;
; #pragma unroll 1
;     for (int u = 0; u < 2; ++u) { const int bf = tid + NT * u; fft_pass<3, false>(buf, bf + (bf >> 4), 1088, bf); }
.LBB0_347:
	v_add_u32_e32 v72, s0, v68
	v_ashrrev_i32_e32 v69, 4, v72
	v_lshl_add_u32 v72, v72, 3, 0
	v_add_u32_e32 v73, 0x22000, v72
	v_lshl_add_u32 v69, v69, 3, v72
	ds_read_b64 v[88:89], v73
	ds_read2st64_b64 v[72:75], v69 offset1:17
	ds_read2st64_b64 v[76:79], v69 offset0:68 offset1:85
	ds_read2st64_b64 v[80:83], v69 offset0:34 offset1:51
	ds_read2st64_b64 v[84:87], v69 offset0:102 offset1:119
	s_movk_i32 s0, 0x200
	v_add_u32_e32 v112, s0, v68
	v_ashrrev_i32_e32 v114, 4, v112
	v_lshl_add_u32 v112, v112, 3, 0
	v_add_u32_e32 v116, 0x22000, v112
	v_lshl_add_u32 v114, v114, 3, v112
	ds_read_b64 v[118:119], v116
	ds_read2st64_b64 v[120:123], v114 offset1:17
	ds_read2st64_b64 v[124:127], v114 offset0:68 offset1:85
	ds_read2st64_b64 v[128:131], v114 offset0:34 offset1:51
	ds_read2st64_b64 v[132:135], v114 offset0:102 offset1:119
	s_waitcnt lgkmcnt(5)
	v_pk_add_f32 v[90:91], v[88:89], v[88:89] op_sel:[0,1] op_sel_hi:[1,0] neg_lo:[0,0] neg_hi:[0,1]
	v_pk_mul_f32 v[92:93], v[90:91], s[16:17] op_sel:[0,0] op_sel_hi:[1,0]
	v_pk_mul_f32 v[94:95], v[90:91], s[16:17] op_sel:[1,0] op_sel_hi:[0,0] neg_lo:[0,0] neg_hi:[1,0]
	v_pk_mul_f32 v[96:97], v[88:89], v[88:89] op_sel:[1,1] op_sel_hi:[1,0]
	v_pk_fma_f32 v[96:97], v[88:89], v[88:89], v[96:97] op_sel:[0,0,0] op_sel_hi:[0,1,1] neg_lo:[0,0,1] neg_hi:[0,0,0]
	v_pk_mul_f32 v[98:99], v[96:97], v[96:97] op_sel:[1,1] op_sel_hi:[1,0]
	v_pk_fma_f32 v[98:99], v[96:97], v[96:97], v[98:99] op_sel:[0,0,0] op_sel_hi:[0,1,1] neg_lo:[0,0,1] neg_hi:[0,0,0]
	v_pk_add_f32 v[100:101], v[72:73], v[76:77] neg_lo:[0,1] neg_hi:[0,1]
	v_pk_add_f32 v[102:103], v[74:75], v[78:79] neg_lo:[0,1] neg_hi:[0,1]
	v_pk_add_f32 v[104:105], v[80:81], v[84:85] neg_lo:[0,1] neg_hi:[0,1]
	v_pk_add_f32 v[106:107], v[82:83], v[86:87] neg_lo:[0,1] neg_hi:[0,1]
	v_pk_add_f32 v[72:73], v[72:73], v[76:77]
	v_pk_add_f32 v[74:75], v[74:75], v[78:79]
	v_pk_add_f32 v[80:81], v[80:81], v[84:85]
	v_pk_add_f32 v[82:83], v[82:83], v[86:87]
	v_pk_mul_f32 v[76:77], v[100:101], v[88:89] op_sel:[1,1] op_sel_hi:[1,0]
	v_pk_mul_f32 v[78:79], v[102:103], v[92:93] op_sel:[1,1] op_sel_hi:[1,0]
	v_pk_mul_f32 v[84:85], v[104:105], v[88:89] op_sel:[1,0] op_sel_hi:[1,1]
	v_pk_mul_f32 v[86:87], v[106:107], v[94:95] op_sel:[1,1] op_sel_hi:[1,0]
	v_pk_fma_f32 v[76:77], v[100:101], v[88:89], v[76:77] op_sel:[0,0,0] op_sel_hi:[0,1,1] neg_lo:[0,0,1] neg_hi:[0,0,0]
	v_pk_fma_f32 v[78:79], v[102:103], v[92:93], v[78:79] op_sel:[0,0,0] op_sel_hi:[0,1,1] neg_lo:[0,0,1] neg_hi:[0,0,0]
	v_pk_fma_f32 v[84:85], v[104:105], v[88:89], v[84:85] op_sel:[0,1,0] op_sel_hi:[0,0,1] neg_lo:[0,0,0] neg_hi:[0,1,0]
	v_pk_fma_f32 v[86:87], v[106:107], v[94:95], v[86:87] op_sel:[0,0,0] op_sel_hi:[0,1,1] neg_lo:[0,0,1] neg_hi:[0,0,0]
	v_pk_add_f32 v[100:101], v[72:73], v[80:81] neg_lo:[0,1] neg_hi:[0,1]
	v_pk_add_f32 v[102:103], v[74:75], v[82:83] neg_lo:[0,1] neg_hi:[0,1]
	v_pk_add_f32 v[104:105], v[76:77], v[84:85] neg_lo:[0,1] neg_hi:[0,1]
	v_pk_add_f32 v[106:107], v[78:79], v[86:87] neg_lo:[0,1] neg_hi:[0,1]
	v_pk_add_f32 v[72:73], v[72:73], v[80:81]
	v_pk_add_f32 v[74:75], v[74:75], v[82:83]
	v_pk_add_f32 v[76:77], v[76:77], v[84:85]
	v_pk_add_f32 v[78:79], v[78:79], v[86:87]
	v_pk_mul_f32 v[80:81], v[100:101], v[96:97] op_sel:[1,1] op_sel_hi:[1,0]
	v_pk_mul_f32 v[82:83], v[102:103], v[96:97] op_sel:[1,0] op_sel_hi:[1,1]
	v_pk_mul_f32 v[84:85], v[104:105], v[96:97] op_sel:[1,1] op_sel_hi:[1,0]
	v_pk_mul_f32 v[86:87], v[106:107], v[96:97] op_sel:[1,0] op_sel_hi:[1,1]
	v_pk_fma_f32 v[80:81], v[100:101], v[96:97], v[80:81] op_sel:[0,0,0] op_sel_hi:[0,1,1] neg_lo:[0,0,1] neg_hi:[0,0,0]
	v_pk_fma_f32 v[82:83], v[102:103], v[96:97], v[82:83] op_sel:[0,1,0] op_sel_hi:[0,0,1] neg_lo:[0,0,0] neg_hi:[0,1,0]
	v_pk_fma_f32 v[84:85], v[104:105], v[96:97], v[84:85] op_sel:[0,0,0] op_sel_hi:[0,1,1] neg_lo:[0,0,1] neg_hi:[0,0,0]
	v_pk_fma_f32 v[86:87], v[106:107], v[96:97], v[86:87] op_sel:[0,1,0] op_sel_hi:[0,0,1] neg_lo:[0,0,0] neg_hi:[0,1,0]
	v_pk_add_f32 v[100:101], v[72:73], v[74:75] neg_lo:[0,1] neg_hi:[0,1]
	v_pk_add_f32 v[102:103], v[80:81], v[82:83] neg_lo:[0,1] neg_hi:[0,1]
	v_pk_add_f32 v[104:105], v[76:77], v[78:79] neg_lo:[0,1] neg_hi:[0,1]
	v_pk_add_f32 v[106:107], v[84:85], v[86:87] neg_lo:[0,1] neg_hi:[0,1]
	v_pk_add_f32 v[72:73], v[72:73], v[74:75]
	v_pk_add_f32 v[80:81], v[80:81], v[82:83]
	v_pk_add_f32 v[76:77], v[76:77], v[78:79]
	v_pk_add_f32 v[84:85], v[84:85], v[86:87]
	v_pk_mul_f32 v[74:75], v[100:101], v[98:99] op_sel:[1,1] op_sel_hi:[1,0]
	v_pk_mul_f32 v[82:83], v[102:103], v[98:99] op_sel:[1,1] op_sel_hi:[1,0]
	v_pk_mul_f32 v[78:79], v[104:105], v[98:99] op_sel:[1,1] op_sel_hi:[1,0]
	v_pk_mul_f32 v[86:87], v[106:107], v[98:99] op_sel:[1,1] op_sel_hi:[1,0]
	v_pk_fma_f32 v[74:75], v[100:101], v[98:99], v[74:75] op_sel:[0,0,0] op_sel_hi:[0,1,1] neg_lo:[0,0,1] neg_hi:[0,0,0]
	v_pk_fma_f32 v[82:83], v[102:103], v[98:99], v[82:83] op_sel:[0,0,0] op_sel_hi:[0,1,1] neg_lo:[0,0,1] neg_hi:[0,0,0]
	v_pk_fma_f32 v[78:79], v[104:105], v[98:99], v[78:79] op_sel:[0,0,0] op_sel_hi:[0,1,1] neg_lo:[0,0,1] neg_hi:[0,0,0]
	v_pk_fma_f32 v[86:87], v[106:107], v[98:99], v[86:87] op_sel:[0,0,0] op_sel_hi:[0,1,1] neg_lo:[0,0,1] neg_hi:[0,0,0]
	ds_write2st64_b64 v69, v[72:73], v[74:75] offset1:17
	ds_write2st64_b64 v69, v[80:81], v[82:83] offset0:34 offset1:51
	ds_write2st64_b64 v69, v[76:77], v[78:79] offset0:68 offset1:85
	ds_write2st64_b64 v69, v[84:85], v[86:87] offset0:102 offset1:119
	s_waitcnt lgkmcnt(4)
; #define LAS __attribute__((address_space(3)))
; __device__ __forceinline__ int otid() { int t = threadIdx.x; asm volatile("" : "+v"(t)); return t; }
; __device__ __forceinline__ cf twc(cf ws, int k16) { if (k16 == 0) return ws; if (k16 == 4) return cf{ws.y, -ws.x}; return cmul(ws, cf{c16(k16), -s16(k16)}); }
; __device__ __forceinline__ void lds_barrier() { asm volatile("s_waitcnt lgkmcnt(0)\n\ts_barrier" ::: "memory"); }
; template <int LR> __device__ __forceinline__ void dif_reg(cf (&x)[1 << LR], cf w) {
;     constexpr int R = 1 << LR; cf ws = w;
; #pragma unroll
;     for (int s = 0; s < LR; ++s) { const int half = R >> (s + 1);
; #pragma unroll
;         for (int m0 = 0; m0 < R; m0 += 2 * half)
; #pragma unroll
;             for (int mm = 0; mm < half; ++mm) { const int ia = m0 + mm, ib = ia + half; const cf a = x[ia], b = x[ib];
;                 x[ia] = cf{a.x + b.x, a.y + b.y}; const cf d{a.x - b.x, a.y - b.y};
;                 x[ib] = cmul(d, twc(ws, (mm << s) * (16 / R))); }
;         ws = cmul(ws, ws); }
; }
; template <int LR, bool INV> __device__ __forceinline__ void fft_pass(ldsf2 buf, int base, int stride, int twi) {
;     constexpr int R = 1 << LR; cf x[R];
;     const v2f wv = ((ldsf2)((LAS unsigned char*)buf + 139264))[twi];
; #pragma unroll
;     for (int m = 0; m < R; ++m) { const v2f v = buf[base + m * stride]; x[m] = cf{v.x, v.y}; }
;     const cf w{wv.x, wv.y};
;     if (INV) dit_reg<LR>(x, w); else dif_reg<LR>(x, w);
; #pragma unroll
;     for (int m = 0; m < R; ++m) buf[base + m * stride] = mkv2(x[m].x, x[m].y);
; }
; __device__ __forceinline__ void wave_lds_fence() { asm volatile("s_waitcnt lgkmcnt(0)" ::: "memory"); }
; __device__ __forceinline__ void fft_fwd_abc(ldsf2 buf) {
;     const int tid = otid(); const int wv = tid >> 6, l = tid & 63;
; #pragma unroll 1
;     for (int u = 0; u < 2; ++u) { const int bf = tid + NT * u; fft_pass<3, false>(buf, bf + (bf >> 4), 1088, bf); }
;     lds_barrier();
; #pragma unroll 1
;     for (int u = 0; u < 2; ++u) { const int o = l + 64 * u, e0 = wv * 1024 + o; fft_pass<3, false>(buf, e0 + (e0 >> 4), 136, o * 8); }
	v_pk_add_f32 v[148:149], v[118:119], v[118:119] op_sel:[0,1] op_sel_hi:[1,0] neg_lo:[0,0] neg_hi:[0,1]
	v_pk_mul_f32 v[150:151], v[148:149], s[16:17] op_sel:[0,0] op_sel_hi:[1,0]
	v_pk_mul_f32 v[152:153], v[148:149], s[16:17] op_sel:[1,0] op_sel_hi:[0,0] neg_lo:[0,0] neg_hi:[1,0]
	v_pk_mul_f32 v[154:155], v[118:119], v[118:119] op_sel:[1,1] op_sel_hi:[1,0]
	v_pk_fma_f32 v[154:155], v[118:119], v[118:119], v[154:155] op_sel:[0,0,0] op_sel_hi:[0,1,1] neg_lo:[0,0,1] neg_hi:[0,0,0]
	v_pk_mul_f32 v[156:157], v[154:155], v[154:155] op_sel:[1,1] op_sel_hi:[1,0]
	v_pk_fma_f32 v[156:157], v[154:155], v[154:155], v[156:157] op_sel:[0,0,0] op_sel_hi:[0,1,1] neg_lo:[0,0,1] neg_hi:[0,0,0]
	v_pk_add_f32 v[158:159], v[120:121], v[124:125] neg_lo:[0,1] neg_hi:[0,1]
	v_pk_add_f32 v[160:161], v[122:123], v[126:127] neg_lo:[0,1] neg_hi:[0,1]
	v_pk_add_f32 v[162:163], v[128:129], v[132:133] neg_lo:[0,1] neg_hi:[0,1]
	v_pk_add_f32 v[164:165], v[130:131], v[134:135] neg_lo:[0,1] neg_hi:[0,1]
	v_pk_add_f32 v[120:121], v[120:121], v[124:125]
	v_pk_add_f32 v[122:123], v[122:123], v[126:127]
	v_pk_add_f32 v[128:129], v[128:129], v[132:133]
	v_pk_add_f32 v[130:131], v[130:131], v[134:135]
	v_pk_mul_f32 v[124:125], v[158:159], v[118:119] op_sel:[1,1] op_sel_hi:[1,0]
	v_pk_mul_f32 v[126:127], v[160:161], v[150:151] op_sel:[1,1] op_sel_hi:[1,0]
	v_pk_mul_f32 v[132:133], v[162:163], v[118:119] op_sel:[1,0] op_sel_hi:[1,1]
	v_pk_mul_f32 v[134:135], v[164:165], v[152:153] op_sel:[1,1] op_sel_hi:[1,0]
	v_pk_fma_f32 v[124:125], v[158:159], v[118:119], v[124:125] op_sel:[0,0,0] op_sel_hi:[0,1,1] neg_lo:[0,0,1] neg_hi:[0,0,0]
	v_pk_fma_f32 v[126:127], v[160:161], v[150:151], v[126:127] op_sel:[0,0,0] op_sel_hi:[0,1,1] neg_lo:[0,0,1] neg_hi:[0,0,0]
	v_pk_fma_f32 v[132:133], v[162:163], v[118:119], v[132:133] op_sel:[0,1,0] op_sel_hi:[0,0,1] neg_lo:[0,0,0] neg_hi:[0,1,0]
	v_pk_fma_f32 v[134:135], v[164:165], v[152:153], v[134:135] op_sel:[0,0,0] op_sel_hi:[0,1,1] neg_lo:[0,0,1] neg_hi:[0,0,0]
	v_pk_add_f32 v[158:159], v[120:121], v[128:129] neg_lo:[0,1] neg_hi:[0,1]
	v_pk_add_f32 v[160:161], v[122:123], v[130:131] neg_lo:[0,1] neg_hi:[0,1]
	v_pk_add_f32 v[162:163], v[124:125], v[132:133] neg_lo:[0,1] neg_hi:[0,1]
	v_pk_add_f32 v[164:165], v[126:127], v[134:135] neg_lo:[0,1] neg_hi:[0,1]
	v_pk_add_f32 v[120:121], v[120:121], v[128:129]
	v_pk_add_f32 v[122:123], v[122:123], v[130:131]
	v_pk_add_f32 v[124:125], v[124:125], v[132:133]
	v_pk_add_f32 v[126:127], v[126:127], v[134:135]
	v_pk_mul_f32 v[128:129], v[158:159], v[154:155] op_sel:[1,1] op_sel_hi:[1,0]
	v_pk_mul_f32 v[130:131], v[160:161], v[154:155] op_sel:[1,0] op_sel_hi:[1,1]
	v_pk_mul_f32 v[132:133], v[162:163], v[154:155] op_sel:[1,1] op_sel_hi:[1,0]
	v_pk_mul_f32 v[134:135], v[164:165], v[154:155] op_sel:[1,0] op_sel_hi:[1,1]
	v_pk_fma_f32 v[128:129], v[158:159], v[154:155], v[128:129] op_sel:[0,0,0] op_sel_hi:[0,1,1] neg_lo:[0,0,1] neg_hi:[0,0,0]
	v_pk_fma_f32 v[130:131], v[160:161], v[154:155], v[130:131] op_sel:[0,1,0] op_sel_hi:[0,0,1] neg_lo:[0,0,0] neg_hi:[0,1,0]
	v_pk_fma_f32 v[132:133], v[162:163], v[154:155], v[132:133] op_sel:[0,0,0] op_sel_hi:[0,1,1] neg_lo:[0,0,1] neg_hi:[0,0,0]
	v_pk_fma_f32 v[134:135], v[164:165], v[154:155], v[134:135] op_sel:[0,1,0] op_sel_hi:[0,0,1] neg_lo:[0,0,0] neg_hi:[0,1,0]
	v_pk_add_f32 v[158:159], v[120:121], v[122:123] neg_lo:[0,1] neg_hi:[0,1]
	v_pk_add_f32 v[160:161], v[128:129], v[130:131] neg_lo:[0,1] neg_hi:[0,1]
	v_pk_add_f32 v[162:163], v[124:125], v[126:127] neg_lo:[0,1] neg_hi:[0,1]
	v_pk_add_f32 v[164:165], v[132:133], v[134:135] neg_lo:[0,1] neg_hi:[0,1]
	v_pk_add_f32 v[120:121], v[120:121], v[122:123]
	v_pk_add_f32 v[128:129], v[128:129], v[130:131]
	v_pk_add_f32 v[124:125], v[124:125], v[126:127]
	v_pk_add_f32 v[132:133], v[132:133], v[134:135]
	v_pk_mul_f32 v[122:123], v[158:159], v[156:157] op_sel:[1,1] op_sel_hi:[1,0]
	v_pk_mul_f32 v[130:131], v[160:161], v[156:157] op_sel:[1,1] op_sel_hi:[1,0]
	v_pk_mul_f32 v[126:127], v[162:163], v[156:157] op_sel:[1,1] op_sel_hi:[1,0]
	v_pk_mul_f32 v[134:135], v[164:165], v[156:157] op_sel:[1,1] op_sel_hi:[1,0]
	v_pk_fma_f32 v[122:123], v[158:159], v[156:157], v[122:123] op_sel:[0,0,0] op_sel_hi:[0,1,1] neg_lo:[0,0,1] neg_hi:[0,0,0]
	v_pk_fma_f32 v[130:131], v[160:161], v[156:157], v[130:131] op_sel:[0,0,0] op_sel_hi:[0,1,1] neg_lo:[0,0,1] neg_hi:[0,0,0]
	v_pk_fma_f32 v[126:127], v[162:163], v[156:157], v[126:127] op_sel:[0,0,0] op_sel_hi:[0,1,1] neg_lo:[0,0,1] neg_hi:[0,0,0]
	v_pk_fma_f32 v[134:135], v[164:165], v[156:157], v[134:135] op_sel:[0,0,0] op_sel_hi:[0,1,1] neg_lo:[0,0,1] neg_hi:[0,0,0]
	ds_write2st64_b64 v114, v[120:121], v[122:123] offset1:17
	ds_write2st64_b64 v114, v[128:129], v[130:131] offset0:34 offset1:51
	ds_write2st64_b64 v114, v[124:125], v[126:127] offset0:68 offset1:85
	ds_write2st64_b64 v114, v[132:133], v[134:135] offset0:102 offset1:119
	s_mov_b64 s[6:7], 0
	s_waitcnt lgkmcnt(0)
	s_barrier
	v_lshlrev_b32_e32 v72, 4, v68
	v_and_b32_e32 v69, 63, v68
	v_and_b32_e32 v72, 0xfffffc00, v72
	s_mov_b32 s0, 0
	s_mov_b64 s[6:7], -1
; #define LAS __attribute__((address_space(3)))
; __device__ __forceinline__ int otid() { int t = threadIdx.x; asm volatile("" : "+v"(t)); return t; }
; __device__ __forceinline__ cf twc(cf ws, int k16) { if (k16 == 0) return ws; if (k16 == 4) return cf{ws.y, -ws.x}; return cmul(ws, cf{c16(k16), -s16(k16)}); }
; __device__ __forceinline__ void lds_barrier() { asm volatile("s_waitcnt lgkmcnt(0)\n\ts_barrier" ::: "memory"); }
; template <int LR> __device__ __forceinline__ void dif_reg(cf (&x)[1 << LR], cf w) {
;     constexpr int R = 1 << LR; cf ws = w;
; #pragma unroll
;     for (int s = 0; s < LR; ++s) { const int half = R >> (s + 1);
; #pragma unroll
;         for (int m0 = 0; m0 < R; m0 += 2 * half)
; #pragma unroll
;             for (int mm = 0; mm < half; ++mm) { const int ia = m0 + mm, ib = ia + half; const cf a = x[ia], b = x[ib];
;                 x[ia] = cf{a.x + b.x, a.y + b.y}; const cf d{a.x - b.x, a.y - b.y};
;                 x[ib] = cmul(d, twc(ws, (mm << s) * (16 / R))); }
;         ws = cmul(ws, ws); }
; }
; template <int LR, bool INV> __device__ __forceinline__ void fft_pass(ldsf2 buf, int base, int stride, int twi) {
;     constexpr int R = 1 << LR; cf x[R];
;     const v2f wv = ((ldsf2)((LAS unsigned char*)buf + 139264))[twi];
; #pragma unroll
;     for (int m = 0; m < R; ++m) { const v2f v = buf[base + m * stride]; x[m] = cf{v.x, v.y}; }
;     const cf w{wv.x, wv.y};
;     if (INV) dit_reg<LR>(x, w); else dif_reg<LR>(x, w);
; #pragma unroll
;     for (int m = 0; m < R; ++m) buf[base + m * stride] = mkv2(x[m].x, x[m].y);
; }
; __device__ __forceinline__ void wave_lds_fence() { asm volatile("s_waitcnt lgkmcnt(0)" ::: "memory"); }
; __device__ __forceinline__ void fft_fwd_abc(ldsf2 buf) {
;     const int tid = otid(); const int wv = tid >> 6, l = tid & 63;
; #pragma unroll 1
;     for (int u = 0; u < 2; ++u) { const int bf = tid + NT * u; fft_pass<3, false>(buf, bf + (bf >> 4), 1088, bf); }
;     lds_barrier();
; #pragma unroll 1
;     for (int u = 0; u < 2; ++u) { const int o = l + 64 * u, e0 = wv * 1024 + o; fft_pass<3, false>(buf, e0 + (e0 >> 4), 136, o * 8); }
.LBB0_349:
	v_or_b32_e32 v74, s0, v69
	v_or_b32_e32 v73, v74, v72
	v_lshl_add_u32 v74, v74, 6, 0
	v_ashrrev_i32_e32 v75, 4, v73
	v_add_u32_e32 v74, 0x22000, v74
	v_lshlrev_b32_e32 v73, 3, v73
	ds_read_b64 v[90:91], v74
	v_lshlrev_b32_e32 v74, 3, v75
	v_add3_u32 v73, 0, v73, v74
	v_add_u32_e32 v113, 0x800, v73
	ds_read2_b64 v[74:77], v73 offset1:136
	v_add_u32_e32 v118, 0x1000, v73
	v_add_u32_e32 v119, 0x1800, v73
	ds_read2_b64 v[78:81], v113 offset0:16 offset1:152
	ds_read2_b64 v[82:85], v118 offset0:32 offset1:168
	ds_read2_b64 v[86:89], v119 offset0:48 offset1:184
	s_mov_b32 s0, 64
	v_or_b32_e32 v120, s0, v69
	v_or_b32_e32 v122, v120, v72
	v_lshl_add_u32 v120, v120, 6, 0
	v_ashrrev_i32_e32 v124, 4, v122
	v_add_u32_e32 v120, 0x22000, v120
	v_lshlrev_b32_e32 v122, 3, v122
	ds_read_b64 v[126:127], v120
	v_lshlrev_b32_e32 v120, 3, v124
	v_add3_u32 v122, 0, v122, v120
	v_add_u32_e32 v128, 0x800, v122
	ds_read2_b64 v[130:133], v122 offset1:136
	v_add_u32_e32 v134, 0x1000, v122
	v_add_u32_e32 v148, 0x1800, v122
	ds_read2_b64 v[150:153], v128 offset0:16 offset1:152
	ds_read2_b64 v[154:157], v134 offset0:32 offset1:168
	ds_read2_b64 v[158:161], v148 offset0:48 offset1:184
	s_waitcnt lgkmcnt(5)
	v_pk_add_f32 v[92:93], v[90:91], v[90:91] op_sel:[0,1] op_sel_hi:[1,0] neg_lo:[0,0] neg_hi:[0,1]
	v_pk_mul_f32 v[94:95], v[92:93], s[16:17] op_sel:[0,0] op_sel_hi:[1,0]
	v_pk_mul_f32 v[96:97], v[92:93], s[16:17] op_sel:[1,0] op_sel_hi:[0,0] neg_lo:[0,0] neg_hi:[1,0]
	v_pk_mul_f32 v[98:99], v[90:91], v[90:91] op_sel:[1,1] op_sel_hi:[1,0]
	v_pk_fma_f32 v[98:99], v[90:91], v[90:91], v[98:99] op_sel:[0,0,0] op_sel_hi:[0,1,1] neg_lo:[0,0,1] neg_hi:[0,0,0]
	v_pk_mul_f32 v[100:101], v[98:99], v[98:99] op_sel:[1,1] op_sel_hi:[1,0]
	v_pk_fma_f32 v[100:101], v[98:99], v[98:99], v[100:101] op_sel:[0,0,0] op_sel_hi:[0,1,1] neg_lo:[0,0,1] neg_hi:[0,0,0]
	v_pk_add_f32 v[102:103], v[74:75], v[82:83] neg_lo:[0,1] neg_hi:[0,1]
	v_pk_add_f32 v[104:105], v[76:77], v[84:85] neg_lo:[0,1] neg_hi:[0,1]
	v_pk_add_f32 v[106:107], v[78:79], v[86:87] neg_lo:[0,1] neg_hi:[0,1]
	v_pk_add_f32 v[108:109], v[80:81], v[88:89] neg_lo:[0,1] neg_hi:[0,1]
	v_pk_add_f32 v[74:75], v[74:75], v[82:83]
	v_pk_add_f32 v[76:77], v[76:77], v[84:85]
	v_pk_add_f32 v[78:79], v[78:79], v[86:87]
	v_pk_add_f32 v[80:81], v[80:81], v[88:89]
	v_pk_mul_f32 v[82:83], v[102:103], v[90:91] op_sel:[1,1] op_sel_hi:[1,0]
	v_pk_mul_f32 v[84:85], v[104:105], v[94:95] op_sel:[1,1] op_sel_hi:[1,0]
	v_pk_mul_f32 v[86:87], v[106:107], v[90:91] op_sel:[1,0] op_sel_hi:[1,1]
	v_pk_mul_f32 v[88:89], v[108:109], v[96:97] op_sel:[1,1] op_sel_hi:[1,0]
	v_pk_fma_f32 v[82:83], v[102:103], v[90:91], v[82:83] op_sel:[0,0,0] op_sel_hi:[0,1,1] neg_lo:[0,0,1] neg_hi:[0,0,0]
	v_pk_fma_f32 v[84:85], v[104:105], v[94:95], v[84:85] op_sel:[0,0,0] op_sel_hi:[0,1,1] neg_lo:[0,0,1] neg_hi:[0,0,0]
	v_pk_fma_f32 v[86:87], v[106:107], v[90:91], v[86:87] op_sel:[0,1,0] op_sel_hi:[0,0,1] neg_lo:[0,0,0] neg_hi:[0,1,0]
	v_pk_fma_f32 v[88:89], v[108:109], v[96:97], v[88:89] op_sel:[0,0,0] op_sel_hi:[0,1,1] neg_lo:[0,0,1] neg_hi:[0,0,0]
	v_pk_add_f32 v[102:103], v[74:75], v[78:79] neg_lo:[0,1] neg_hi:[0,1]
	v_pk_add_f32 v[104:105], v[76:77], v[80:81] neg_lo:[0,1] neg_hi:[0,1]
	v_pk_add_f32 v[106:107], v[82:83], v[86:87] neg_lo:[0,1] neg_hi:[0,1]
	v_pk_add_f32 v[108:109], v[84:85], v[88:89] neg_lo:[0,1] neg_hi:[0,1]
	v_pk_add_f32 v[74:75], v[74:75], v[78:79]
	v_pk_add_f32 v[76:77], v[76:77], v[80:81]
	v_pk_add_f32 v[82:83], v[82:83], v[86:87]
	v_pk_add_f32 v[84:85], v[84:85], v[88:89]
	v_pk_mul_f32 v[78:79], v[102:103], v[98:99] op_sel:[1,1] op_sel_hi:[1,0]
	v_pk_mul_f32 v[80:81], v[104:105], v[98:99] op_sel:[1,0] op_sel_hi:[1,1]
	v_pk_mul_f32 v[86:87], v[106:107], v[98:99] op_sel:[1,1] op_sel_hi:[1,0]
	v_pk_mul_f32 v[88:89], v[108:109], v[98:99] op_sel:[1,0] op_sel_hi:[1,1]
	v_pk_fma_f32 v[78:79], v[102:103], v[98:99], v[78:79] op_sel:[0,0,0] op_sel_hi:[0,1,1] neg_lo:[0,0,1] neg_hi:[0,0,0]
	v_pk_fma_f32 v[80:81], v[104:105], v[98:99], v[80:81] op_sel:[0,1,0] op_sel_hi:[0,0,1] neg_lo:[0,0,0] neg_hi:[0,1,0]
	v_pk_fma_f32 v[86:87], v[106:107], v[98:99], v[86:87] op_sel:[0,0,0] op_sel_hi:[0,1,1] neg_lo:[0,0,1] neg_hi:[0,0,0]
	v_pk_fma_f32 v[88:89], v[108:109], v[98:99], v[88:89] op_sel:[0,1,0] op_sel_hi:[0,0,1] neg_lo:[0,0,0] neg_hi:[0,1,0]
	v_pk_add_f32 v[102:103], v[74:75], v[76:77] neg_lo:[0,1] neg_hi:[0,1]
	v_pk_add_f32 v[104:105], v[78:79], v[80:81] neg_lo:[0,1] neg_hi:[0,1]
	v_pk_add_f32 v[106:107], v[82:83], v[84:85] neg_lo:[0,1] neg_hi:[0,1]
	v_pk_add_f32 v[108:109], v[86:87], v[88:89] neg_lo:[0,1] neg_hi:[0,1]
	v_pk_add_f32 v[74:75], v[74:75], v[76:77]
	v_pk_add_f32 v[78:79], v[78:79], v[80:81]
	v_pk_add_f32 v[82:83], v[82:83], v[84:85]
	v_pk_add_f32 v[86:87], v[86:87], v[88:89]
	v_pk_mul_f32 v[76:77], v[102:103], v[100:101] op_sel:[1,1] op_sel_hi:[1,0]
	v_pk_mul_f32 v[80:81], v[104:105], v[100:101] op_sel:[1,1] op_sel_hi:[1,0]
	v_pk_mul_f32 v[84:85], v[106:107], v[100:101] op_sel:[1,1] op_sel_hi:[1,0]
	v_pk_mul_f32 v[88:89], v[108:109], v[100:101] op_sel:[1,1] op_sel_hi:[1,0]
	v_pk_fma_f32 v[76:77], v[102:103], v[100:101], v[76:77] op_sel:[0,0,0] op_sel_hi:[0,1,1] neg_lo:[0,0,1] neg_hi:[0,0,0]
	v_pk_fma_f32 v[80:81], v[104:105], v[100:101], v[80:81] op_sel:[0,0,0] op_sel_hi:[0,1,1] neg_lo:[0,0,1] neg_hi:[0,0,0]
	v_pk_fma_f32 v[84:85], v[106:107], v[100:101], v[84:85] op_sel:[0,0,0] op_sel_hi:[0,1,1] neg_lo:[0,0,1] neg_hi:[0,0,0]
	v_pk_fma_f32 v[88:89], v[108:109], v[100:101], v[88:89] op_sel:[0,0,0] op_sel_hi:[0,1,1] neg_lo:[0,0,1] neg_hi:[0,0,0]
	ds_write2_b64 v73, v[74:75], v[76:77] offset1:136
	ds_write2_b64 v113, v[78:79], v[80:81] offset0:16 offset1:152
	ds_write2_b64 v118, v[82:83], v[84:85] offset0:32 offset1:168
	ds_write2_b64 v119, v[86:87], v[88:89] offset0:48 offset1:184
	s_waitcnt lgkmcnt(4)
; #define LAS __attribute__((address_space(3)))
; __device__ __forceinline__ int otid() { int t = threadIdx.x; asm volatile("" : "+v"(t)); return t; }
; __device__ __forceinline__ cf twc(cf ws, int k16) { if (k16 == 0) return ws; if (k16 == 4) return cf{ws.y, -ws.x}; return cmul(ws, cf{c16(k16), -s16(k16)}); }
; __device__ __forceinline__ void lds_barrier() { asm volatile("s_waitcnt lgkmcnt(0)\n\ts_barrier" ::: "memory"); }
; template <int LR> __device__ __forceinline__ void dif_reg(cf (&x)[1 << LR], cf w) {
;     constexpr int R = 1 << LR; cf ws = w;
; #pragma unroll
;     for (int s = 0; s < LR; ++s) { const int half = R >> (s + 1);
; #pragma unroll
;         for (int m0 = 0; m0 < R; m0 += 2 * half)
; #pragma unroll
;             for (int mm = 0; mm < half; ++mm) { const int ia = m0 + mm, ib = ia + half; const cf a = x[ia], b = x[ib];
;                 x[ia] = cf{a.x + b.x, a.y + b.y}; const cf d{a.x - b.x, a.y - b.y};
;                 x[ib] = cmul(d, twc(ws, (mm << s) * (16 / R))); }
;         ws = cmul(ws, ws); }
; }
; template <int LR, bool INV> __device__ __forceinline__ void fft_pass(ldsf2 buf, int base, int stride, int twi) {
;     constexpr int R = 1 << LR; cf x[R];
;     const v2f wv = ((ldsf2)((LAS unsigned char*)buf + 139264))[twi];
; #pragma unroll
;     for (int m = 0; m < R; ++m) { const v2f v = buf[base + m * stride]; x[m] = cf{v.x, v.y}; }
;     const cf w{wv.x, wv.y};
;     if (INV) dit_reg<LR>(x, w); else dif_reg<LR>(x, w);
; #pragma unroll
;     for (int m = 0; m < R; ++m) buf[base + m * stride] = mkv2(x[m].x, x[m].y);
; }
; __device__ __forceinline__ void wave_lds_fence() { asm volatile("s_waitcnt lgkmcnt(0)" ::: "memory"); }
; __device__ __forceinline__ void fft_fwd_abc(ldsf2 buf) {
;     const int tid = otid(); const int wv = tid >> 6, l = tid & 63;
; #pragma unroll 1
;     for (int u = 0; u < 2; ++u) { const int bf = tid + NT * u; fft_pass<3, false>(buf, bf + (bf >> 4), 1088, bf); }
;     lds_barrier();
; #pragma unroll 1
;     for (int u = 0; u < 2; ++u) { const int o = l + 64 * u, e0 = wv * 1024 + o; fft_pass<3, false>(buf, e0 + (e0 >> 4), 136, o * 8); }
;     wave_lds_fence();
; #pragma unroll 1
;     for (int u = 0; u < 2; ++u) { const int j = l + 64 * u, o = j & 15, e0 = wv * 1024 + (j >> 4) * 128 + o; fft_pass<3, false>(buf, e0 + (e0 >> 4), 17, o * 64); }
	v_pk_add_f32 v[162:163], v[126:127], v[126:127] op_sel:[0,1] op_sel_hi:[1,0] neg_lo:[0,0] neg_hi:[0,1]
	v_pk_mul_f32 v[164:165], v[162:163], s[16:17] op_sel:[0,0] op_sel_hi:[1,0]
	v_pk_mul_f32 v[166:167], v[162:163], s[16:17] op_sel:[1,0] op_sel_hi:[0,0] neg_lo:[0,0] neg_hi:[1,0]
	v_pk_mul_f32 v[168:169], v[126:127], v[126:127] op_sel:[1,1] op_sel_hi:[1,0]
	v_pk_fma_f32 v[168:169], v[126:127], v[126:127], v[168:169] op_sel:[0,0,0] op_sel_hi:[0,1,1] neg_lo:[0,0,1] neg_hi:[0,0,0]
	v_pk_mul_f32 v[170:171], v[168:169], v[168:169] op_sel:[1,1] op_sel_hi:[1,0]
	v_pk_fma_f32 v[170:171], v[168:169], v[168:169], v[170:171] op_sel:[0,0,0] op_sel_hi:[0,1,1] neg_lo:[0,0,1] neg_hi:[0,0,0]
	v_pk_add_f32 v[172:173], v[130:131], v[154:155] neg_lo:[0,1] neg_hi:[0,1]
	v_pk_add_f32 v[174:175], v[132:133], v[156:157] neg_lo:[0,1] neg_hi:[0,1]
	v_pk_add_f32 v[188:189], v[150:151], v[158:159] neg_lo:[0,1] neg_hi:[0,1]
	v_pk_add_f32 v[190:191], v[152:153], v[160:161] neg_lo:[0,1] neg_hi:[0,1]
	v_pk_add_f32 v[130:131], v[130:131], v[154:155]
	v_pk_add_f32 v[132:133], v[132:133], v[156:157]
	v_pk_add_f32 v[150:151], v[150:151], v[158:159]
	v_pk_add_f32 v[152:153], v[152:153], v[160:161]
	v_pk_mul_f32 v[154:155], v[172:173], v[126:127] op_sel:[1,1] op_sel_hi:[1,0]
	v_pk_mul_f32 v[156:157], v[174:175], v[164:165] op_sel:[1,1] op_sel_hi:[1,0]
	v_pk_mul_f32 v[158:159], v[188:189], v[126:127] op_sel:[1,0] op_sel_hi:[1,1]
	v_pk_mul_f32 v[160:161], v[190:191], v[166:167] op_sel:[1,1] op_sel_hi:[1,0]
	v_pk_fma_f32 v[154:155], v[172:173], v[126:127], v[154:155] op_sel:[0,0,0] op_sel_hi:[0,1,1] neg_lo:[0,0,1] neg_hi:[0,0,0]
	v_pk_fma_f32 v[156:157], v[174:175], v[164:165], v[156:157] op_sel:[0,0,0] op_sel_hi:[0,1,1] neg_lo:[0,0,1] neg_hi:[0,0,0]
	v_pk_fma_f32 v[158:159], v[188:189], v[126:127], v[158:159] op_sel:[0,1,0] op_sel_hi:[0,0,1] neg_lo:[0,0,0] neg_hi:[0,1,0]
	v_pk_fma_f32 v[160:161], v[190:191], v[166:167], v[160:161] op_sel:[0,0,0] op_sel_hi:[0,1,1] neg_lo:[0,0,1] neg_hi:[0,0,0]
	v_pk_add_f32 v[172:173], v[130:131], v[150:151] neg_lo:[0,1] neg_hi:[0,1]
	v_pk_add_f32 v[174:175], v[132:133], v[152:153] neg_lo:[0,1] neg_hi:[0,1]
	v_pk_add_f32 v[188:189], v[154:155], v[158:159] neg_lo:[0,1] neg_hi:[0,1]
	v_pk_add_f32 v[190:191], v[156:157], v[160:161] neg_lo:[0,1] neg_hi:[0,1]
	v_pk_add_f32 v[130:131], v[130:131], v[150:151]
	v_pk_add_f32 v[132:133], v[132:133], v[152:153]
	v_pk_add_f32 v[154:155], v[154:155], v[158:159]
	v_pk_add_f32 v[156:157], v[156:157], v[160:161]
	v_pk_mul_f32 v[150:151], v[172:173], v[168:169] op_sel:[1,1] op_sel_hi:[1,0]
	v_pk_mul_f32 v[152:153], v[174:175], v[168:169] op_sel:[1,0] op_sel_hi:[1,1]
	v_pk_mul_f32 v[158:159], v[188:189], v[168:169] op_sel:[1,1] op_sel_hi:[1,0]
	v_pk_mul_f32 v[160:161], v[190:191], v[168:169] op_sel:[1,0] op_sel_hi:[1,1]
	v_pk_fma_f32 v[150:151], v[172:173], v[168:169], v[150:151] op_sel:[0,0,0] op_sel_hi:[0,1,1] neg_lo:[0,0,1] neg_hi:[0,0,0]
	v_pk_fma_f32 v[152:153], v[174:175], v[168:169], v[152:153] op_sel:[0,1,0] op_sel_hi:[0,0,1] neg_lo:[0,0,0] neg_hi:[0,1,0]
	v_pk_fma_f32 v[158:159], v[188:189], v[168:169], v[158:159] op_sel:[0,0,0] op_sel_hi:[0,1,1] neg_lo:[0,0,1] neg_hi:[0,0,0]
	v_pk_fma_f32 v[160:161], v[190:191], v[168:169], v[160:161] op_sel:[0,1,0] op_sel_hi:[0,0,1] neg_lo:[0,0,0] neg_hi:[0,1,0]
	v_pk_add_f32 v[172:173], v[130:131], v[132:133] neg_lo:[0,1] neg_hi:[0,1]
	v_pk_add_f32 v[174:175], v[150:151], v[152:153] neg_lo:[0,1] neg_hi:[0,1]
	v_pk_add_f32 v[188:189], v[154:155], v[156:157] neg_lo:[0,1] neg_hi:[0,1]
	v_pk_add_f32 v[190:191], v[158:159], v[160:161] neg_lo:[0,1] neg_hi:[0,1]
	v_pk_add_f32 v[130:131], v[130:131], v[132:133]
	v_pk_add_f32 v[150:151], v[150:151], v[152:153]
	v_pk_add_f32 v[154:155], v[154:155], v[156:157]
	v_pk_add_f32 v[158:159], v[158:159], v[160:161]
	v_pk_mul_f32 v[132:133], v[172:173], v[170:171] op_sel:[1,1] op_sel_hi:[1,0]
	v_pk_mul_f32 v[152:153], v[174:175], v[170:171] op_sel:[1,1] op_sel_hi:[1,0]
	v_pk_mul_f32 v[156:157], v[188:189], v[170:171] op_sel:[1,1] op_sel_hi:[1,0]
	v_pk_mul_f32 v[160:161], v[190:191], v[170:171] op_sel:[1,1] op_sel_hi:[1,0]
	v_pk_fma_f32 v[132:133], v[172:173], v[170:171], v[132:133] op_sel:[0,0,0] op_sel_hi:[0,1,1] neg_lo:[0,0,1] neg_hi:[0,0,0]
	v_pk_fma_f32 v[152:153], v[174:175], v[170:171], v[152:153] op_sel:[0,0,0] op_sel_hi:[0,1,1] neg_lo:[0,0,1] neg_hi:[0,0,0]
	v_pk_fma_f32 v[156:157], v[188:189], v[170:171], v[156:157] op_sel:[0,0,0] op_sel_hi:[0,1,1] neg_lo:[0,0,1] neg_hi:[0,0,0]
	v_pk_fma_f32 v[160:161], v[190:191], v[170:171], v[160:161] op_sel:[0,0,0] op_sel_hi:[0,1,1] neg_lo:[0,0,1] neg_hi:[0,0,0]
	ds_write2_b64 v122, v[130:131], v[132:133] offset1:136
	ds_write2_b64 v128, v[150:151], v[152:153] offset0:16 offset1:152
	ds_write2_b64 v134, v[154:155], v[156:157] offset0:32 offset1:168
	ds_write2_b64 v148, v[158:159], v[160:161] offset0:48 offset1:184
	s_mov_b64 s[6:7], 0
	v_and_b32_e32 v68, 15, v68
	s_waitcnt lgkmcnt(0)
	v_lshlrev_b32_e32 v69, 3, v69
	v_lshlrev_b32_e32 v73, 9, v68
	v_and_or_b32 v69, v69, s90, v72
	v_add_u32_e32 v72, 0, v73
	v_lshl_add_u32 v68, v68, 3, 0
	s_mov_b32 s0, 0
	s_mov_b64 s[6:7], -1
	v_add_u32_e32 v72, 0x22000, v72
; #define LAS __attribute__((address_space(3)))
; __device__ __forceinline__ int otid() { int t = threadIdx.x; asm volatile("" : "+v"(t)); return t; }
; __device__ __forceinline__ cf twc(cf ws, int k16) { if (k16 == 0) return ws; if (k16 == 4) return cf{ws.y, -ws.x}; return cmul(ws, cf{c16(k16), -s16(k16)}); }
; __device__ __forceinline__ void lds_barrier() { asm volatile("s_waitcnt lgkmcnt(0)\n\ts_barrier" ::: "memory"); }
; template <int LR> __device__ __forceinline__ void dif_reg(cf (&x)[1 << LR], cf w) {
;     constexpr int R = 1 << LR; cf ws = w;
; #pragma unroll
;     for (int s = 0; s < LR; ++s) { const int half = R >> (s + 1);
; #pragma unroll
;         for (int m0 = 0; m0 < R; m0 += 2 * half)
; #pragma unroll
;             for (int mm = 0; mm < half; ++mm) { const int ia = m0 + mm, ib = ia + half; const cf a = x[ia], b = x[ib];
;                 x[ia] = cf{a.x + b.x, a.y + b.y}; const cf d{a.x - b.x, a.y - b.y};
;                 x[ib] = cmul(d, twc(ws, (mm << s) * (16 / R))); }
;         ws = cmul(ws, ws); }
; }
; template <int LR, bool INV> __device__ __forceinline__ void fft_pass(ldsf2 buf, int base, int stride, int twi) {
;     constexpr int R = 1 << LR; cf x[R];
;     const v2f wv = ((ldsf2)((LAS unsigned char*)buf + 139264))[twi];
; #pragma unroll
;     for (int m = 0; m < R; ++m) { const v2f v = buf[base + m * stride]; x[m] = cf{v.x, v.y}; }
;     const cf w{wv.x, wv.y};
;     if (INV) dit_reg<LR>(x, w); else dif_reg<LR>(x, w);
; #pragma unroll
;     for (int m = 0; m < R; ++m) buf[base + m * stride] = mkv2(x[m].x, x[m].y);
; }
; __device__ __forceinline__ void wave_lds_fence() { asm volatile("s_waitcnt lgkmcnt(0)" ::: "memory"); }
; __device__ __forceinline__ void fft_fwd_abc(ldsf2 buf) {
;     const int tid = otid(); const int wv = tid >> 6, l = tid & 63;
; #pragma unroll 1
;     for (int u = 0; u < 2; ++u) { const int bf = tid + NT * u; fft_pass<3, false>(buf, bf + (bf >> 4), 1088, bf); }
;     lds_barrier();
; #pragma unroll 1
;     for (int u = 0; u < 2; ++u) { const int o = l + 64 * u, e0 = wv * 1024 + o; fft_pass<3, false>(buf, e0 + (e0 >> 4), 136, o * 8); }
;     wave_lds_fence();
; #pragma unroll 1
;     for (int u = 0; u < 2; ++u) { const int j = l + 64 * u, o = j & 15, e0 = wv * 1024 + (j >> 4) * 128 + o; fft_pass<3, false>(buf, e0 + (e0 >> 4), 17, o * 64); }
.LBB0_351:
	v_or_b32_e32 v73, s0, v69
	ds_read_b64 v[90:91], v72
	v_lshlrev_b32_e32 v74, 3, v73
	v_ashrrev_i32_e32 v73, 1, v73
	v_add3_u32 v73, v68, v74, v73
	ds_read2_b64 v[74:77], v73 offset1:17
	ds_read2_b64 v[78:81], v73 offset0:34 offset1:51
	ds_read2_b64 v[82:85], v73 offset0:68 offset1:85
	ds_read2_b64 v[86:89], v73 offset0:102 offset1:119
	s_movk_i32 s0, 0x200
	v_or_b32_e32 v118, s0, v69
	ds_read_b64 v[120:121], v72
	v_lshlrev_b32_e32 v122, 3, v118
	v_ashrrev_i32_e32 v118, 1, v118
	v_add3_u32 v118, v68, v122, v118
	ds_read2_b64 v[124:127], v118 offset1:17
	ds_read2_b64 v[128:131], v118 offset0:34 offset1:51
	ds_read2_b64 v[132:135], v118 offset0:68 offset1:85
	ds_read2_b64 v[148:151], v118 offset0:102 offset1:119
	s_waitcnt lgkmcnt(5)
	v_pk_add_f32 v[92:93], v[90:91], v[90:91] op_sel:[0,1] op_sel_hi:[1,0] neg_lo:[0,0] neg_hi:[0,1]
	v_pk_mul_f32 v[94:95], v[92:93], s[16:17] op_sel:[0,0] op_sel_hi:[1,0]
	v_pk_mul_f32 v[96:97], v[92:93], s[16:17] op_sel:[1,0] op_sel_hi:[0,0] neg_lo:[0,0] neg_hi:[1,0]
	v_pk_mul_f32 v[98:99], v[90:91], v[90:91] op_sel:[1,1] op_sel_hi:[1,0]
	v_pk_fma_f32 v[98:99], v[90:91], v[90:91], v[98:99] op_sel:[0,0,0] op_sel_hi:[0,1,1] neg_lo:[0,0,1] neg_hi:[0,0,0]
	v_pk_mul_f32 v[100:101], v[98:99], v[98:99] op_sel:[1,1] op_sel_hi:[1,0]
	v_pk_fma_f32 v[100:101], v[98:99], v[98:99], v[100:101] op_sel:[0,0,0] op_sel_hi:[0,1,1] neg_lo:[0,0,1] neg_hi:[0,0,0]
	v_pk_add_f32 v[102:103], v[74:75], v[82:83] neg_lo:[0,1] neg_hi:[0,1]
	v_pk_add_f32 v[104:105], v[76:77], v[84:85] neg_lo:[0,1] neg_hi:[0,1]
	v_pk_add_f32 v[106:107], v[78:79], v[86:87] neg_lo:[0,1] neg_hi:[0,1]
	v_pk_add_f32 v[108:109], v[80:81], v[88:89] neg_lo:[0,1] neg_hi:[0,1]
	v_pk_add_f32 v[74:75], v[74:75], v[82:83]
	v_pk_add_f32 v[76:77], v[76:77], v[84:85]
	v_pk_add_f32 v[78:79], v[78:79], v[86:87]
	v_pk_add_f32 v[80:81], v[80:81], v[88:89]
	v_pk_mul_f32 v[82:83], v[102:103], v[90:91] op_sel:[1,1] op_sel_hi:[1,0]
	v_pk_mul_f32 v[84:85], v[104:105], v[94:95] op_sel:[1,1] op_sel_hi:[1,0]
	v_pk_mul_f32 v[86:87], v[106:107], v[90:91] op_sel:[1,0] op_sel_hi:[1,1]
	v_pk_mul_f32 v[88:89], v[108:109], v[96:97] op_sel:[1,1] op_sel_hi:[1,0]
	v_pk_fma_f32 v[82:83], v[102:103], v[90:91], v[82:83] op_sel:[0,0,0] op_sel_hi:[0,1,1] neg_lo:[0,0,1] neg_hi:[0,0,0]
	v_pk_fma_f32 v[84:85], v[104:105], v[94:95], v[84:85] op_sel:[0,0,0] op_sel_hi:[0,1,1] neg_lo:[0,0,1] neg_hi:[0,0,0]
	v_pk_fma_f32 v[86:87], v[106:107], v[90:91], v[86:87] op_sel:[0,1,0] op_sel_hi:[0,0,1] neg_lo:[0,0,0] neg_hi:[0,1,0]
	v_pk_fma_f32 v[88:89], v[108:109], v[96:97], v[88:89] op_sel:[0,0,0] op_sel_hi:[0,1,1] neg_lo:[0,0,1] neg_hi:[0,0,0]
	v_pk_add_f32 v[102:103], v[74:75], v[78:79] neg_lo:[0,1] neg_hi:[0,1]
	v_pk_add_f32 v[104:105], v[76:77], v[80:81] neg_lo:[0,1] neg_hi:[0,1]
	v_pk_add_f32 v[106:107], v[82:83], v[86:87] neg_lo:[0,1] neg_hi:[0,1]
	v_pk_add_f32 v[108:109], v[84:85], v[88:89] neg_lo:[0,1] neg_hi:[0,1]
	v_pk_add_f32 v[74:75], v[74:75], v[78:79]
	v_pk_add_f32 v[76:77], v[76:77], v[80:81]
	v_pk_add_f32 v[82:83], v[82:83], v[86:87]
	v_pk_add_f32 v[84:85], v[84:85], v[88:89]
	v_pk_mul_f32 v[78:79], v[102:103], v[98:99] op_sel:[1,1] op_sel_hi:[1,0]
	v_pk_mul_f32 v[80:81], v[104:105], v[98:99] op_sel:[1,0] op_sel_hi:[1,1]
	v_pk_mul_f32 v[86:87], v[106:107], v[98:99] op_sel:[1,1] op_sel_hi:[1,0]
	v_pk_mul_f32 v[88:89], v[108:109], v[98:99] op_sel:[1,0] op_sel_hi:[1,1]
	v_pk_fma_f32 v[78:79], v[102:103], v[98:99], v[78:79] op_sel:[0,0,0] op_sel_hi:[0,1,1] neg_lo:[0,0,1] neg_hi:[0,0,0]
	v_pk_fma_f32 v[80:81], v[104:105], v[98:99], v[80:81] op_sel:[0,1,0] op_sel_hi:[0,0,1] neg_lo:[0,0,0] neg_hi:[0,1,0]
	v_pk_fma_f32 v[86:87], v[106:107], v[98:99], v[86:87] op_sel:[0,0,0] op_sel_hi:[0,1,1] neg_lo:[0,0,1] neg_hi:[0,0,0]
	v_pk_fma_f32 v[88:89], v[108:109], v[98:99], v[88:89] op_sel:[0,1,0] op_sel_hi:[0,0,1] neg_lo:[0,0,0] neg_hi:[0,1,0]
	v_pk_add_f32 v[102:103], v[74:75], v[76:77] neg_lo:[0,1] neg_hi:[0,1]
	v_pk_add_f32 v[104:105], v[78:79], v[80:81] neg_lo:[0,1] neg_hi:[0,1]
	v_pk_add_f32 v[106:107], v[82:83], v[84:85] neg_lo:[0,1] neg_hi:[0,1]
	v_pk_add_f32 v[108:109], v[86:87], v[88:89] neg_lo:[0,1] neg_hi:[0,1]
	v_pk_add_f32 v[74:75], v[74:75], v[76:77]
	v_pk_add_f32 v[78:79], v[78:79], v[80:81]
	v_pk_add_f32 v[82:83], v[82:83], v[84:85]
	v_pk_add_f32 v[86:87], v[86:87], v[88:89]
	v_pk_mul_f32 v[76:77], v[102:103], v[100:101] op_sel:[1,1] op_sel_hi:[1,0]
	v_pk_mul_f32 v[80:81], v[104:105], v[100:101] op_sel:[1,1] op_sel_hi:[1,0]
	v_pk_mul_f32 v[84:85], v[106:107], v[100:101] op_sel:[1,1] op_sel_hi:[1,0]
	v_pk_mul_f32 v[88:89], v[108:109], v[100:101] op_sel:[1,1] op_sel_hi:[1,0]
	v_pk_fma_f32 v[76:77], v[102:103], v[100:101], v[76:77] op_sel:[0,0,0] op_sel_hi:[0,1,1] neg_lo:[0,0,1] neg_hi:[0,0,0]
	v_pk_fma_f32 v[80:81], v[104:105], v[100:101], v[80:81] op_sel:[0,0,0] op_sel_hi:[0,1,1] neg_lo:[0,0,1] neg_hi:[0,0,0]
	v_pk_fma_f32 v[84:85], v[106:107], v[100:101], v[84:85] op_sel:[0,0,0] op_sel_hi:[0,1,1] neg_lo:[0,0,1] neg_hi:[0,0,0]
	v_pk_fma_f32 v[88:89], v[108:109], v[100:101], v[88:89] op_sel:[0,0,0] op_sel_hi:[0,1,1] neg_lo:[0,0,1] neg_hi:[0,0,0]
	ds_write2_b64 v73, v[74:75], v[76:77] offset1:17
	ds_write2_b64 v73, v[78:79], v[80:81] offset0:34 offset1:51
	ds_write2_b64 v73, v[82:83], v[84:85] offset0:68 offset1:85
	ds_write2_b64 v73, v[86:87], v[88:89] offset0:102 offset1:119
	s_waitcnt lgkmcnt(4)
; #define LAS __attribute__((address_space(3)))
; __device__ __forceinline__ int otid() { int t = threadIdx.x; asm volatile("" : "+v"(t)); return t; }
; template <int LR, bool INV> __device__ __forceinline__ void fft_pass(ldsf2 buf, int base, int stride, int twi) {
;     constexpr int R = 1 << LR; cf x[R];
;     const v2f wv = ((ldsf2)((LAS unsigned char*)buf + 139264))[twi];
; #pragma unroll
;     for (int m = 0; m < R; ++m) { const v2f v = buf[base + m * stride]; x[m] = cf{v.x, v.y}; }
;     const cf w{wv.x, wv.y};
;     if (INV) dit_reg<LR>(x, w); else dif_reg<LR>(x, w);
; #pragma unroll
;     for (int m = 0; m < R; ++m) buf[base + m * stride] = mkv2(x[m].x, x[m].y);
; }
; __device__ __forceinline__ void fft_conv(ldsf2 buf, const LAS unsigned* spec) {
;     fft_fwd_abc(buf);
;     { const int tid = otid(); cf x[16];
; #pragma unroll
;       for (int m = 0; m < 16; ++m) { const v2f v = buf[tid * 17 + m]; x[m] = cf{v.x, v.y}; }
;       dif_reg<4>(x, cf{1.0f, 0.0f});
; #pragma unroll
;       for (int m = 0; m < 16; ++m) { const h2_t hv = __builtin_bit_cast(h2_t, spec[tid * 17 + m]); x[m] = cmul(x[m], cf{(float)hv.x, (float)hv.y}); }
	v_pk_add_f32 v[152:153], v[120:121], v[120:121] op_sel:[0,1] op_sel_hi:[1,0] neg_lo:[0,0] neg_hi:[0,1]
	v_pk_mul_f32 v[154:155], v[152:153], s[16:17] op_sel:[0,0] op_sel_hi:[1,0]
	v_pk_mul_f32 v[156:157], v[152:153], s[16:17] op_sel:[1,0] op_sel_hi:[0,0] neg_lo:[0,0] neg_hi:[1,0]
	v_pk_mul_f32 v[158:159], v[120:121], v[120:121] op_sel:[1,1] op_sel_hi:[1,0]
	v_pk_fma_f32 v[158:159], v[120:121], v[120:121], v[158:159] op_sel:[0,0,0] op_sel_hi:[0,1,1] neg_lo:[0,0,1] neg_hi:[0,0,0]
	v_pk_mul_f32 v[160:161], v[158:159], v[158:159] op_sel:[1,1] op_sel_hi:[1,0]
	v_pk_fma_f32 v[160:161], v[158:159], v[158:159], v[160:161] op_sel:[0,0,0] op_sel_hi:[0,1,1] neg_lo:[0,0,1] neg_hi:[0,0,0]
	v_pk_add_f32 v[162:163], v[124:125], v[132:133] neg_lo:[0,1] neg_hi:[0,1]
	v_pk_add_f32 v[164:165], v[126:127], v[134:135] neg_lo:[0,1] neg_hi:[0,1]
	v_pk_add_f32 v[166:167], v[128:129], v[148:149] neg_lo:[0,1] neg_hi:[0,1]
	v_pk_add_f32 v[168:169], v[130:131], v[150:151] neg_lo:[0,1] neg_hi:[0,1]
	v_pk_add_f32 v[124:125], v[124:125], v[132:133]
	v_pk_add_f32 v[126:127], v[126:127], v[134:135]
	v_pk_add_f32 v[128:129], v[128:129], v[148:149]
	v_pk_add_f32 v[130:131], v[130:131], v[150:151]
	v_pk_mul_f32 v[132:133], v[162:163], v[120:121] op_sel:[1,1] op_sel_hi:[1,0]
	v_pk_mul_f32 v[134:135], v[164:165], v[154:155] op_sel:[1,1] op_sel_hi:[1,0]
	v_pk_mul_f32 v[148:149], v[166:167], v[120:121] op_sel:[1,0] op_sel_hi:[1,1]
	v_pk_mul_f32 v[150:151], v[168:169], v[156:157] op_sel:[1,1] op_sel_hi:[1,0]
	v_pk_fma_f32 v[132:133], v[162:163], v[120:121], v[132:133] op_sel:[0,0,0] op_sel_hi:[0,1,1] neg_lo:[0,0,1] neg_hi:[0,0,0]
	v_pk_fma_f32 v[134:135], v[164:165], v[154:155], v[134:135] op_sel:[0,0,0] op_sel_hi:[0,1,1] neg_lo:[0,0,1] neg_hi:[0,0,0]
	v_pk_fma_f32 v[148:149], v[166:167], v[120:121], v[148:149] op_sel:[0,1,0] op_sel_hi:[0,0,1] neg_lo:[0,0,0] neg_hi:[0,1,0]
	v_pk_fma_f32 v[150:151], v[168:169], v[156:157], v[150:151] op_sel:[0,0,0] op_sel_hi:[0,1,1] neg_lo:[0,0,1] neg_hi:[0,0,0]
	v_pk_add_f32 v[162:163], v[124:125], v[128:129] neg_lo:[0,1] neg_hi:[0,1]
	v_pk_add_f32 v[164:165], v[126:127], v[130:131] neg_lo:[0,1] neg_hi:[0,1]
	v_pk_add_f32 v[166:167], v[132:133], v[148:149] neg_lo:[0,1] neg_hi:[0,1]
	v_pk_add_f32 v[168:169], v[134:135], v[150:151] neg_lo:[0,1] neg_hi:[0,1]
	v_pk_add_f32 v[124:125], v[124:125], v[128:129]
	v_pk_add_f32 v[126:127], v[126:127], v[130:131]
	v_pk_add_f32 v[132:133], v[132:133], v[148:149]
	v_pk_add_f32 v[134:135], v[134:135], v[150:151]
	v_pk_mul_f32 v[128:129], v[162:163], v[158:159] op_sel:[1,1] op_sel_hi:[1,0]
	v_pk_mul_f32 v[130:131], v[164:165], v[158:159] op_sel:[1,0] op_sel_hi:[1,1]
	v_pk_mul_f32 v[148:149], v[166:167], v[158:159] op_sel:[1,1] op_sel_hi:[1,0]
	v_pk_mul_f32 v[150:151], v[168:169], v[158:159] op_sel:[1,0] op_sel_hi:[1,1]
	v_pk_fma_f32 v[128:129], v[162:163], v[158:159], v[128:129] op_sel:[0,0,0] op_sel_hi:[0,1,1] neg_lo:[0,0,1] neg_hi:[0,0,0]
	v_pk_fma_f32 v[130:131], v[164:165], v[158:159], v[130:131] op_sel:[0,1,0] op_sel_hi:[0,0,1] neg_lo:[0,0,0] neg_hi:[0,1,0]
	v_pk_fma_f32 v[148:149], v[166:167], v[158:159], v[148:149] op_sel:[0,0,0] op_sel_hi:[0,1,1] neg_lo:[0,0,1] neg_hi:[0,0,0]
	v_pk_fma_f32 v[150:151], v[168:169], v[158:159], v[150:151] op_sel:[0,1,0] op_sel_hi:[0,0,1] neg_lo:[0,0,0] neg_hi:[0,1,0]
	v_pk_add_f32 v[162:163], v[124:125], v[126:127] neg_lo:[0,1] neg_hi:[0,1]
	v_pk_add_f32 v[164:165], v[128:129], v[130:131] neg_lo:[0,1] neg_hi:[0,1]
	v_pk_add_f32 v[166:167], v[132:133], v[134:135] neg_lo:[0,1] neg_hi:[0,1]
	v_pk_add_f32 v[168:169], v[148:149], v[150:151] neg_lo:[0,1] neg_hi:[0,1]
	v_pk_add_f32 v[124:125], v[124:125], v[126:127]
	v_pk_add_f32 v[128:129], v[128:129], v[130:131]
	v_pk_add_f32 v[132:133], v[132:133], v[134:135]
	v_pk_add_f32 v[148:149], v[148:149], v[150:151]
	v_pk_mul_f32 v[126:127], v[162:163], v[160:161] op_sel:[1,1] op_sel_hi:[1,0]
	v_pk_mul_f32 v[130:131], v[164:165], v[160:161] op_sel:[1,1] op_sel_hi:[1,0]
	v_pk_mul_f32 v[134:135], v[166:167], v[160:161] op_sel:[1,1] op_sel_hi:[1,0]
	v_pk_mul_f32 v[150:151], v[168:169], v[160:161] op_sel:[1,1] op_sel_hi:[1,0]
	v_pk_fma_f32 v[126:127], v[162:163], v[160:161], v[126:127] op_sel:[0,0,0] op_sel_hi:[0,1,1] neg_lo:[0,0,1] neg_hi:[0,0,0]
	v_pk_fma_f32 v[130:131], v[164:165], v[160:161], v[130:131] op_sel:[0,0,0] op_sel_hi:[0,1,1] neg_lo:[0,0,1] neg_hi:[0,0,0]
	v_pk_fma_f32 v[134:135], v[166:167], v[160:161], v[134:135] op_sel:[0,0,0] op_sel_hi:[0,1,1] neg_lo:[0,0,1] neg_hi:[0,0,0]
	v_pk_fma_f32 v[150:151], v[168:169], v[160:161], v[150:151] op_sel:[0,0,0] op_sel_hi:[0,1,1] neg_lo:[0,0,1] neg_hi:[0,0,0]
	ds_write2_b64 v118, v[124:125], v[126:127] offset1:17
	ds_write2_b64 v118, v[128:129], v[130:131] offset0:34 offset1:51
	ds_write2_b64 v118, v[132:133], v[134:135] offset0:68 offset1:85
	ds_write2_b64 v118, v[148:149], v[150:151] offset0:102 offset1:119
	s_mov_b64 s[6:7], 0
	v_mov_b32_e32 v158, v195
	s_movk_i32 s0, 0x88
	s_waitcnt lgkmcnt(0)
	s_mov_b32 s86, s63
	v_mul_lo_u32 v68, v158, s0
	v_add_u32_e32 v147, 0, v68
	ds_read2_b64 v[72:75], v147 offset1:1
	ds_read2_b64 v[76:79], v147 offset0:2 offset1:3
	ds_read2_b64 v[90:93], v147 offset0:4 offset1:5
	ds_read2_b64 v[94:97], v147 offset0:6 offset1:7
	ds_read2_b64 v[98:101], v147 offset0:8 offset1:9
	ds_read2_b64 v[102:105], v147 offset0:10 offset1:11
	ds_read2_b64 v[118:121], v147 offset0:12 offset1:13
	ds_read2_b64 v[126:129], v147 offset0:14 offset1:15
	s_mov_b32 s6, s63
	s_mov_b32 s7, s16
	s_mov_b32 s17, s5
	s_mov_b32 s0, s16
	s_mov_b32 s1, s4
	s_mov_b32 s0, s63
	s_mov_b32 s1, s5
	s_mov_b32 s0, s87
	s_mov_b32 s1, s4
	s_mov_b32 s1, s5
	s_mov_b32 s35, s4
	s_mov_b32 s12, s63
	s_movk_i32 s0, 0x44
	v_mul_lo_u32 v106, v158, s0
	v_add_u32_e32 v106, 0, v106
	v_add_u32_e32 v106, 0x11000, v106
	ds_read2_b32 v[156:157], v106 offset1:1
	ds_read2_b32 v[158:159], v106 offset0:2 offset1:3
	ds_read2_b32 v[160:161], v106 offset0:4 offset1:5
	ds_read2_b32 v[162:163], v106 offset0:6 offset1:7
	ds_read2_b32 v[164:165], v106 offset0:8 offset1:9
	ds_read2_b32 v[134:135], v106 offset0:10 offset1:11
	ds_read2_b32 v[130:131], v106 offset0:12 offset1:13
	ds_read2_b32 v[168:169], v106 offset0:14 offset1:15
	s_mov_b32 s0, s5
	s_mov_b64 s[6:7], -1
	s_mov_b32 s35, s13
	s_mov_b32 s0, s13
	s_waitcnt lgkmcnt(8)
; __device__ __forceinline__ int otid() { int t = threadIdx.x; asm volatile("" : "+v"(t)); return t; }
; __device__ __forceinline__ cf twc(cf ws, int k16) { if (k16 == 0) return ws; if (k16 == 4) return cf{ws.y, -ws.x}; return cmul(ws, cf{c16(k16), -s16(k16)}); }
; template <int LR> __device__ __forceinline__ void dif_reg(cf (&x)[1 << LR], cf w) {
;     constexpr int R = 1 << LR; cf ws = w;
; #pragma unroll
;     for (int s = 0; s < LR; ++s) { const int half = R >> (s + 1);
; #pragma unroll
;         for (int m0 = 0; m0 < R; m0 += 2 * half)
; #pragma unroll
;             for (int mm = 0; mm < half; ++mm) { const int ia = m0 + mm, ib = ia + half; const cf a = x[ia], b = x[ib];
;                 x[ia] = cf{a.x + b.x, a.y + b.y}; const cf d{a.x - b.x, a.y - b.y};
;                 x[ib] = cmul(d, twc(ws, (mm << s) * (16 / R))); }
;         ws = cmul(ws, ws); }
; }
; __device__ __forceinline__ void fft_conv(ldsf2 buf, const LAS unsigned* spec) {
;     ...
;     { const int tid = otid(); cf x[16];
; #pragma unroll
;       for (int m = 0; m < 16; ++m) { const v2f v = buf[tid * 17 + m]; x[m] = cf{v.x, v.y}; }
;       dif_reg<4>(x, cf{1.0f, 0.0f});
	v_pk_add_f32 v[80:81], v[72:73], v[98:99]
	v_pk_add_f32 v[82:83], v[74:75], v[100:101]
	v_pk_add_f32 v[84:85], v[76:77], v[102:103]
	v_pk_add_f32 v[86:87], v[78:79], v[104:105]
	v_pk_add_f32 v[72:73], v[72:73], v[98:99] neg_lo:[0,1] neg_hi:[0,1]
	v_pk_add_f32 v[74:75], v[74:75], v[100:101] neg_lo:[0,1] neg_hi:[0,1]
	v_pk_add_f32 v[76:77], v[76:77], v[102:103] neg_lo:[0,1] neg_hi:[0,1]
	v_pk_add_f32 v[78:79], v[78:79], v[104:105] neg_lo:[0,1] neg_hi:[0,1]
	v_pk_mul_f32 v[100:101], v[74:75], s[4:5] op_sel:[1,1] op_sel_hi:[1,0] neg_lo:[0,1] neg_hi:[0,0]
	v_pk_mul_f32 v[102:103], v[76:77], s[16:17] op_sel:[1,0] op_sel_hi:[1,0] neg_lo:[0,1] neg_hi:[0,0]
	v_pk_mul_f32 v[104:105], v[78:79], s[4:5] op_sel:[1,0] op_sel_hi:[1,1] neg_lo:[0,1] neg_hi:[0,0]
	v_pk_fma_f32 v[100:101], v[74:75], s[4:5], v[100:101] op_sel:[0,0,0] op_sel_hi:[0,1,1] neg_lo:[0,0,1] neg_hi:[0,1,0]
	v_pk_fma_f32 v[102:103], v[76:77], s[16:17], v[102:103] op_sel:[0,0,0] op_sel_hi:[0,0,1] neg_lo:[0,0,1] neg_hi:[0,1,0]
	v_pk_fma_f32 v[104:105], v[78:79], s[4:5], v[104:105] op_sel:[0,1,0] op_sel_hi:[0,0,1] neg_lo:[0,0,1] neg_hi:[0,1,0]
	v_pk_add_f32 v[88:89], v[90:91], v[118:119]
	v_pk_add_f32 v[108:109], v[92:93], v[120:121]
	v_pk_add_f32 v[110:111], v[94:95], v[126:127]
	v_pk_add_f32 v[112:113], v[96:97], v[128:129]
	v_pk_add_f32 v[90:91], v[90:91], v[118:119] op_sel:[1,1] op_sel_hi:[0,0] neg_lo:[0,1] neg_hi:[1,0]
	v_pk_add_f32 v[92:93], v[92:93], v[120:121] neg_lo:[0,1] neg_hi:[0,1]
	v_pk_add_f32 v[94:95], v[94:95], v[126:127] neg_lo:[0,1] neg_hi:[0,1]
	v_pk_add_f32 v[96:97], v[96:97], v[128:129] neg_lo:[0,1] neg_hi:[0,1]
	v_pk_mul_f32 v[120:121], v[92:93], s[4:5] op_sel:[1,0] op_sel_hi:[1,1] neg_lo:[0,1] neg_hi:[0,1]
	v_pk_mul_f32 v[126:127], v[94:95], s[16:17] op_sel:[1,0] op_sel_hi:[1,0] neg_lo:[0,1] neg_hi:[0,1]
	v_pk_mul_f32 v[128:129], v[96:97], s[4:5] op_sel:[1,1] op_sel_hi:[1,0] neg_lo:[0,1] neg_hi:[0,1]
	v_pk_fma_f32 v[120:121], v[92:93], s[4:5], v[120:121] op_sel:[0,1,0] op_sel_hi:[0,0,1] neg_lo:[0,1,1] neg_hi:[0,1,0]
	v_pk_fma_f32 v[126:127], v[94:95], s[16:17], v[126:127] op_sel:[0,0,0] op_sel_hi:[0,0,1] neg_lo:[0,1,1] neg_hi:[0,1,0]
	v_pk_fma_f32 v[128:129], v[96:97], s[4:5], v[128:129] op_sel:[0,0,0] op_sel_hi:[0,1,1] neg_lo:[0,1,1] neg_hi:[0,1,0]
	v_pk_add_f32 v[114:115], v[80:81], v[88:89]
	v_pk_add_f32 v[116:117], v[82:83], v[108:109]
	v_pk_add_f32 v[122:123], v[84:85], v[110:111]
	v_pk_add_f32 v[124:125], v[86:87], v[112:113]
	v_pk_add_f32 v[80:81], v[80:81], v[88:89] neg_lo:[0,1] neg_hi:[0,1]
	v_pk_add_f32 v[82:83], v[82:83], v[108:109] neg_lo:[0,1] neg_hi:[0,1]
	v_pk_add_f32 v[84:85], v[84:85], v[110:111] op_sel:[1,1] op_sel_hi:[0,0] neg_lo:[0,1] neg_hi:[1,0]
	v_pk_add_f32 v[86:87], v[86:87], v[112:113] neg_lo:[0,1] neg_hi:[0,1]
	v_pk_mul_f32 v[108:109], v[82:83], s[16:17] op_sel:[1,0] op_sel_hi:[1,0] neg_lo:[0,1] neg_hi:[0,0]
	v_pk_mul_f32 v[112:113], v[86:87], s[16:17] op_sel:[1,0] op_sel_hi:[1,0] neg_lo:[0,1] neg_hi:[0,1]
	v_pk_fma_f32 v[108:109], v[82:83], s[16:17], v[108:109] op_sel:[0,0,0] op_sel_hi:[0,0,1] neg_lo:[0,0,1] neg_hi:[0,1,0]
	v_pk_fma_f32 v[112:113], v[86:87], s[16:17], v[112:113] op_sel:[0,0,0] op_sel_hi:[0,0,1] neg_lo:[0,1,1] neg_hi:[0,1,0]
	v_pk_add_f32 v[132:133], v[72:73], v[90:91]
	v_pk_add_f32 v[148:149], v[100:101], v[120:121]
	v_pk_add_f32 v[150:151], v[102:103], v[126:127]
	v_pk_add_f32 v[152:153], v[104:105], v[128:129]
	v_pk_add_f32 v[72:73], v[72:73], v[90:91] neg_lo:[0,1] neg_hi:[0,1]
	v_pk_add_f32 v[100:101], v[100:101], v[120:121] neg_lo:[0,1] neg_hi:[0,1]
	v_pk_add_f32 v[102:103], v[102:103], v[126:127] op_sel:[1,1] op_sel_hi:[0,0] neg_lo:[0,1] neg_hi:[1,0]
	v_pk_add_f32 v[104:105], v[104:105], v[128:129] neg_lo:[0,1] neg_hi:[0,1]
	v_pk_mul_f32 v[120:121], v[100:101], s[16:17] op_sel:[1,0] op_sel_hi:[1,0] neg_lo:[0,1] neg_hi:[0,0]
	v_pk_mul_f32 v[128:129], v[104:105], s[16:17] op_sel:[1,0] op_sel_hi:[1,0] neg_lo:[0,1] neg_hi:[0,1]
	v_pk_fma_f32 v[120:121], v[100:101], s[16:17], v[120:121] op_sel:[0,0,0] op_sel_hi:[0,0,1] neg_lo:[0,0,1] neg_hi:[0,1,0]
	v_pk_fma_f32 v[128:129], v[104:105], s[16:17], v[128:129] op_sel:[0,0,0] op_sel_hi:[0,0,1] neg_lo:[0,1,1] neg_hi:[0,1,0]
	v_pk_add_f32 v[154:155], v[114:115], v[122:123]
	v_pk_add_f32 v[166:167], v[116:117], v[124:125]
	v_pk_add_f32 v[98:99], v[80:81], v[84:85]
	v_pk_add_f32 v[74:75], v[108:109], v[112:113]
	v_pk_add_f32 v[114:115], v[114:115], v[122:123] neg_lo:[0,1] neg_hi:[0,1]
	v_pk_add_f32 v[116:117], v[116:117], v[124:125] op_sel:[1,1] op_sel_hi:[0,0] neg_lo:[0,1] neg_hi:[1,0]
	v_pk_add_f32 v[80:81], v[80:81], v[84:85] neg_lo:[0,1] neg_hi:[0,1]
	v_pk_add_f32 v[108:109], v[108:109], v[112:113] op_sel:[1,1] op_sel_hi:[0,0] neg_lo:[0,1] neg_hi:[1,0]
	v_pk_add_f32 v[76:77], v[132:133], v[150:151]
	v_pk_add_f32 v[78:79], v[148:149], v[152:153]
	v_pk_add_f32 v[118:119], v[72:73], v[102:103]
	v_pk_add_f32 v[92:93], v[120:121], v[128:129]
	v_pk_add_f32 v[132:133], v[132:133], v[150:151] neg_lo:[0,1] neg_hi:[0,1]
	v_pk_add_f32 v[148:149], v[148:149], v[152:153] op_sel:[1,1] op_sel_hi:[0,0] neg_lo:[0,1] neg_hi:[1,0]
	v_pk_add_f32 v[72:73], v[72:73], v[102:103] neg_lo:[0,1] neg_hi:[0,1]
	v_pk_add_f32 v[120:121], v[120:121], v[128:129] op_sel:[1,1] op_sel_hi:[0,0] neg_lo:[0,1] neg_hi:[1,0]
	v_pk_add_f32 v[94:95], v[154:155], v[166:167]
	v_pk_add_f32 v[96:97], v[114:115], v[116:117]
	v_pk_add_f32 v[88:89], v[98:99], v[74:75]
	v_pk_add_f32 v[82:83], v[80:81], v[108:109]
	v_pk_add_f32 v[154:155], v[154:155], v[166:167] neg_lo:[0,1] neg_hi:[0,1]
	v_pk_add_f32 v[114:115], v[114:115], v[116:117] neg_lo:[0,1] neg_hi:[0,1]
	v_pk_add_f32 v[98:99], v[98:99], v[74:75] neg_lo:[0,1] neg_hi:[0,1]
	v_pk_add_f32 v[80:81], v[80:81], v[108:109] neg_lo:[0,1] neg_hi:[0,1]
	v_pk_add_f32 v[110:111], v[76:77], v[78:79]
	v_pk_add_f32 v[86:87], v[132:133], v[148:149]
	v_pk_add_f32 v[90:91], v[118:119], v[92:93]
	v_pk_add_f32 v[100:101], v[72:73], v[120:121]
	v_pk_add_f32 v[76:77], v[76:77], v[78:79] neg_lo:[0,1] neg_hi:[0,1]
	v_pk_add_f32 v[132:133], v[132:133], v[148:149] neg_lo:[0,1] neg_hi:[0,1]
	v_pk_add_f32 v[118:119], v[118:119], v[92:93] neg_lo:[0,1] neg_hi:[0,1]
	v_pk_add_f32 v[72:73], v[72:73], v[120:121] neg_lo:[0,1] neg_hi:[0,1]
	s_waitcnt lgkmcnt(0)
; __device__ __forceinline__ cf twc(cf ws, int k16) { if (k16 == 0) return ws; if (k16 == 4) return cf{ws.y, -ws.x}; return cmul(ws, cf{c16(k16), -s16(k16)}); }
; template <int LR> __device__ __forceinline__ void dit_reg(cf (&x)[1 << LR], cf w) {
;     constexpr int R = 1 << LR; cf wsv[LR]; wsv[0] = w;
; #pragma unroll
;     for (int s = 1; s < LR; ++s) wsv[s] = cmul(wsv[s - 1], wsv[s - 1]);
; #pragma unroll
;     for (int s = LR - 1; s >= 0; --s) { const int half = R >> (s + 1);
; #pragma unroll
;         for (int m0 = 0; m0 < R; m0 += 2 * half)
; #pragma unroll
;             for (int mm = 0; mm < half; ++mm) { const int ia = m0 + mm, ib = ia + half; const cf a = x[ia];
;                 const cf b = cmulc(x[ib], twc(wsv[s], (mm << s) * (16 / R)));
;                 x[ia] = cf{a.x + b.x, a.y + b.y}; x[ib] = cf{a.x - b.x, a.y - b.y}; } }
; }
; __device__ __forceinline__ void fft_conv(ldsf2 buf, const LAS unsigned* spec) {
;     ...
;       dif_reg<4>(x, cf{1.0f, 0.0f});
; #pragma unroll
;       for (int m = 0; m < 16; ++m) { const h2_t hv = __builtin_bit_cast(h2_t, spec[tid * 17 + m]); x[m] = cmul(x[m], cf{(float)hv.x, (float)hv.y}); }
;       dit_reg<4>(x, cf{1.0f, 0.0f});
	v_cvt_f32_f16_e32 v126, v156
	v_cvt_f32_f16_e32 v122, v157
	v_cvt_f32_f16_e32 v84, v158
	v_cvt_f32_f16_e32 v150, v159
	v_cvt_f32_f16_sdwa v127, v156 dst_sel:DWORD dst_unused:UNUSED_PAD src0_sel:WORD_1
	v_cvt_f32_f16_sdwa v123, v157 dst_sel:DWORD dst_unused:UNUSED_PAD src0_sel:WORD_1
	v_cvt_f32_f16_sdwa v85, v158 dst_sel:DWORD dst_unused:UNUSED_PAD src0_sel:WORD_1
	v_cvt_f32_f16_sdwa v151, v159 dst_sel:DWORD dst_unused:UNUSED_PAD src0_sel:WORD_1
	v_pk_mul_f32 v[104:105], v[94:95], v[126:127] op_sel:[1,1] op_sel_hi:[1,0]
	v_pk_mul_f32 v[124:125], v[154:155], v[122:123] op_sel:[1,1] op_sel_hi:[1,0]
	v_pk_mul_f32 v[112:113], v[96:97], v[84:85] op_sel:[1,1] op_sel_hi:[1,0]
	v_pk_mul_f32 v[152:153], v[114:115], v[150:151] op_sel:[1,1] op_sel_hi:[1,0]
	v_pk_fma_f32 v[126:127], v[94:95], v[126:127], v[104:105] op_sel:[0,0,0] op_sel_hi:[0,1,1] neg_lo:[0,0,1] neg_hi:[0,0,0]
	v_pk_fma_f32 v[122:123], v[154:155], v[122:123], v[124:125] op_sel:[0,0,0] op_sel_hi:[0,1,1] neg_lo:[0,0,1] neg_hi:[0,0,0]
	v_pk_fma_f32 v[84:85], v[96:97], v[84:85], v[112:113] op_sel:[0,0,0] op_sel_hi:[0,1,1] neg_lo:[0,0,1] neg_hi:[0,0,0]
	v_pk_fma_f32 v[150:151], v[114:115], v[150:151], v[152:153] op_sel:[0,0,0] op_sel_hi:[0,1,1] neg_lo:[0,0,1] neg_hi:[0,0,0]
	v_cvt_f32_f16_e32 v102, v160
	v_cvt_f32_f16_e32 v166, v161
	v_cvt_f32_f16_e32 v74, v162
	v_cvt_f32_f16_e32 v78, v163
	v_cvt_f32_f16_sdwa v103, v160 dst_sel:DWORD dst_unused:UNUSED_PAD src0_sel:WORD_1
	v_cvt_f32_f16_sdwa v167, v161 dst_sel:DWORD dst_unused:UNUSED_PAD src0_sel:WORD_1
	v_cvt_f32_f16_sdwa v75, v162 dst_sel:DWORD dst_unused:UNUSED_PAD src0_sel:WORD_1
	v_cvt_f32_f16_sdwa v79, v163 dst_sel:DWORD dst_unused:UNUSED_PAD src0_sel:WORD_1
	v_pk_mul_f32 v[128:129], v[88:89], v[102:103] op_sel:[1,1] op_sel_hi:[1,0]
	v_pk_mul_f32 v[116:117], v[98:99], v[166:167] op_sel:[1,1] op_sel_hi:[1,0]
	v_pk_mul_f32 v[108:109], v[82:83], v[74:75] op_sel:[1,1] op_sel_hi:[1,0]
	v_pk_mul_f32 v[148:149], v[80:81], v[78:79] op_sel:[1,1] op_sel_hi:[1,0]
	v_pk_fma_f32 v[102:103], v[88:89], v[102:103], v[128:129] op_sel:[0,0,0] op_sel_hi:[0,1,1] neg_lo:[0,0,1] neg_hi:[0,0,0]
	v_pk_fma_f32 v[166:167], v[98:99], v[166:167], v[116:117] op_sel:[0,0,0] op_sel_hi:[0,1,1] neg_lo:[0,0,1] neg_hi:[0,0,0]
	v_pk_fma_f32 v[74:75], v[82:83], v[74:75], v[108:109] op_sel:[0,0,0] op_sel_hi:[0,1,1] neg_lo:[0,0,1] neg_hi:[0,0,0]
	v_pk_fma_f32 v[78:79], v[80:81], v[78:79], v[148:149] op_sel:[0,0,0] op_sel_hi:[0,1,1] neg_lo:[0,0,1] neg_hi:[0,0,0]
	v_cvt_f32_f16_e32 v92, v164
	v_cvt_f32_f16_e32 v104, v165
	v_cvt_f32_f16_e32 v124, v134
	v_cvt_f32_f16_e32 v112, v135
	v_cvt_f32_f16_sdwa v93, v164 dst_sel:DWORD dst_unused:UNUSED_PAD src0_sel:WORD_1
	v_cvt_f32_f16_sdwa v105, v165 dst_sel:DWORD dst_unused:UNUSED_PAD src0_sel:WORD_1
	v_cvt_f32_f16_sdwa v125, v134 dst_sel:DWORD dst_unused:UNUSED_PAD src0_sel:WORD_1
	v_cvt_f32_f16_sdwa v113, v135 dst_sel:DWORD dst_unused:UNUSED_PAD src0_sel:WORD_1
	v_pk_mul_f32 v[120:121], v[110:111], v[92:93] op_sel:[1,1] op_sel_hi:[1,0]
	v_pk_mul_f32 v[94:95], v[76:77], v[104:105] op_sel:[1,1] op_sel_hi:[1,0]
	v_pk_mul_f32 v[154:155], v[86:87], v[124:125] op_sel:[1,1] op_sel_hi:[1,0]
	v_pk_mul_f32 v[96:97], v[132:133], v[112:113] op_sel:[1,1] op_sel_hi:[1,0]
	v_pk_fma_f32 v[92:93], v[110:111], v[92:93], v[120:121] op_sel:[0,0,0] op_sel_hi:[0,1,1] neg_lo:[0,0,1] neg_hi:[0,0,0]
	v_pk_fma_f32 v[104:105], v[76:77], v[104:105], v[94:95] op_sel:[0,0,0] op_sel_hi:[0,1,1] neg_lo:[0,0,1] neg_hi:[0,0,0]
	v_pk_fma_f32 v[124:125], v[86:87], v[124:125], v[154:155] op_sel:[0,0,0] op_sel_hi:[0,1,1] neg_lo:[0,0,1] neg_hi:[0,0,0]
	v_pk_fma_f32 v[112:113], v[132:133], v[112:113], v[96:97] op_sel:[0,0,0] op_sel_hi:[0,1,1] neg_lo:[0,0,1] neg_hi:[0,0,0]
	v_cvt_f32_f16_e32 v152, v130
	v_cvt_f32_f16_e32 v128, v131
	v_cvt_f32_f16_e32 v116, v168
	v_cvt_f32_f16_e32 v108, v169
	v_cvt_f32_f16_sdwa v153, v130 dst_sel:DWORD dst_unused:UNUSED_PAD src0_sel:WORD_1
	v_cvt_f32_f16_sdwa v129, v131 dst_sel:DWORD dst_unused:UNUSED_PAD src0_sel:WORD_1
	v_cvt_f32_f16_sdwa v117, v168 dst_sel:DWORD dst_unused:UNUSED_PAD src0_sel:WORD_1
	v_cvt_f32_f16_sdwa v109, v169 dst_sel:DWORD dst_unused:UNUSED_PAD src0_sel:WORD_1
	v_pk_mul_f32 v[114:115], v[90:91], v[152:153] op_sel:[1,1] op_sel_hi:[1,0]
	v_pk_mul_f32 v[88:89], v[118:119], v[128:129] op_sel:[1,1] op_sel_hi:[1,0]
	v_pk_mul_f32 v[98:99], v[100:101], v[116:117] op_sel:[1,1] op_sel_hi:[1,0]
	v_pk_mul_f32 v[82:83], v[72:73], v[108:109] op_sel:[1,1] op_sel_hi:[1,0]
	v_pk_fma_f32 v[152:153], v[90:91], v[152:153], v[114:115] op_sel:[0,0,0] op_sel_hi:[0,1,1] neg_lo:[0,0,1] neg_hi:[0,0,0]
	v_pk_fma_f32 v[128:129], v[118:119], v[128:129], v[88:89] op_sel:[0,0,0] op_sel_hi:[0,1,1] neg_lo:[0,0,1] neg_hi:[0,0,0]
	v_pk_fma_f32 v[116:117], v[100:101], v[116:117], v[98:99] op_sel:[0,0,0] op_sel_hi:[0,1,1] neg_lo:[0,0,1] neg_hi:[0,0,0]
	v_pk_fma_f32 v[108:109], v[72:73], v[108:109], v[82:83] op_sel:[0,0,0] op_sel_hi:[0,1,1] neg_lo:[0,0,1] neg_hi:[0,0,0]
	v_pk_add_f32 v[148:149], v[126:127], v[122:123]
	v_pk_add_f32 v[80:81], v[84:85], v[150:151]
	v_pk_add_f32 v[120:121], v[102:103], v[166:167]
	v_pk_add_f32 v[110:111], v[74:75], v[78:79]
	v_pk_add_f32 v[126:127], v[126:127], v[122:123] neg_lo:[0,1] neg_hi:[0,1]
	v_pk_add_f32 v[84:85], v[84:85], v[150:151] neg_lo:[0,1] neg_hi:[0,1]
	v_pk_add_f32 v[102:103], v[102:103], v[166:167] neg_lo:[0,1] neg_hi:[0,1]
	v_pk_add_f32 v[74:75], v[74:75], v[78:79] neg_lo:[0,1] neg_hi:[0,1]
	v_pk_add_f32 v[94:95], v[92:93], v[104:105]
	v_pk_add_f32 v[76:77], v[124:125], v[112:113]
	v_pk_add_f32 v[154:155], v[152:153], v[128:129]
	v_pk_add_f32 v[86:87], v[116:117], v[108:109]
; __device__ __forceinline__ cf twc(cf ws, int k16) { if (k16 == 0) return ws; if (k16 == 4) return cf{ws.y, -ws.x}; return cmul(ws, cf{c16(k16), -s16(k16)}); }
; __device__ __forceinline__ void wave_lds_fence() { asm volatile("s_waitcnt lgkmcnt(0)" ::: "memory"); }
; template <int LR> __device__ __forceinline__ void dit_reg(cf (&x)[1 << LR], cf w) {
;     constexpr int R = 1 << LR; cf wsv[LR]; wsv[0] = w;
; #pragma unroll
;     for (int s = 1; s < LR; ++s) wsv[s] = cmul(wsv[s - 1], wsv[s - 1]);
; #pragma unroll
;     for (int s = LR - 1; s >= 0; --s) { const int half = R >> (s + 1);
; #pragma unroll
;         for (int m0 = 0; m0 < R; m0 += 2 * half)
; #pragma unroll
;             for (int mm = 0; mm < half; ++mm) { const int ia = m0 + mm, ib = ia + half; const cf a = x[ia];
;                 const cf b = cmulc(x[ib], twc(wsv[s], (mm << s) * (16 / R)));
;                 x[ia] = cf{a.x + b.x, a.y + b.y}; x[ib] = cf{a.x - b.x, a.y - b.y}; } }
; __device__ __forceinline__ void fft_conv(ldsf2 buf, const LAS unsigned* spec) {
;     ...
;       for (int m = 0; m < 16; ++m) { const v2f v = buf[tid * 17 + m]; x[m] = cf{v.x, v.y}; }
;       dif_reg<4>(x, cf{1.0f, 0.0f});
; #pragma unroll
;       for (int m = 0; m < 16; ++m) { const h2_t hv = __builtin_bit_cast(h2_t, spec[tid * 17 + m]); x[m] = cmul(x[m], cf{(float)hv.x, (float)hv.y}); }
;       dit_reg<4>(x, cf{1.0f, 0.0f});
; #pragma unroll
;       for (int m = 0; m < 16; ++m) buf[tid * 17 + m] = mkv2(x[m].x, x[m].y); }
;     wave_lds_fence();
	v_pk_add_f32 v[92:93], v[92:93], v[104:105] neg_lo:[0,1] neg_hi:[0,1]
	v_pk_add_f32 v[124:125], v[124:125], v[112:113] neg_lo:[0,1] neg_hi:[0,1]
	v_pk_add_f32 v[152:153], v[152:153], v[128:129] neg_lo:[0,1] neg_hi:[0,1]
	v_pk_add_f32 v[116:117], v[116:117], v[108:109] neg_lo:[0,1] neg_hi:[0,1]
	v_pk_add_f32 v[96:97], v[148:149], v[80:81]
	v_pk_add_f32 v[132:133], v[126:127], v[84:85] op_sel:[0,1] op_sel_hi:[1,0] neg_lo:[0,1] neg_hi:[0,0]
	v_pk_add_f32 v[114:115], v[120:121], v[110:111]
	v_pk_add_f32 v[90:91], v[102:103], v[74:75] op_sel:[0,1] op_sel_hi:[1,0] neg_lo:[0,1] neg_hi:[0,0]
	v_pk_add_f32 v[148:149], v[148:149], v[80:81] neg_lo:[0,1] neg_hi:[0,1]
	v_pk_add_f32 v[126:127], v[126:127], v[84:85] op_sel:[0,1] op_sel_hi:[1,0] neg_lo:[0,0] neg_hi:[0,1]
	v_pk_add_f32 v[120:121], v[120:121], v[110:111] neg_lo:[0,1] neg_hi:[0,1]
	v_pk_add_f32 v[102:103], v[102:103], v[74:75] op_sel:[0,1] op_sel_hi:[1,0] neg_lo:[0,0] neg_hi:[0,1]
	v_pk_add_f32 v[88:89], v[94:95], v[76:77]
	v_pk_add_f32 v[118:119], v[92:93], v[124:125] op_sel:[0,1] op_sel_hi:[1,0] neg_lo:[0,1] neg_hi:[0,0]
	v_pk_add_f32 v[98:99], v[154:155], v[86:87]
	v_pk_add_f32 v[100:101], v[152:153], v[116:117] op_sel:[0,1] op_sel_hi:[1,0] neg_lo:[0,1] neg_hi:[0,0]
	v_pk_add_f32 v[94:95], v[94:95], v[76:77] neg_lo:[0,1] neg_hi:[0,1]
	v_pk_add_f32 v[92:93], v[92:93], v[124:125] op_sel:[0,1] op_sel_hi:[1,0] neg_lo:[0,0] neg_hi:[0,1]
	v_pk_add_f32 v[154:155], v[154:155], v[86:87] neg_lo:[0,1] neg_hi:[0,1]
	v_pk_add_f32 v[152:153], v[152:153], v[116:117] op_sel:[0,1] op_sel_hi:[1,0] neg_lo:[0,0] neg_hi:[0,1]
	v_pk_add_f32 v[82:83], v[96:97], v[114:115]
	v_pk_mul_f32 v[72:73], v[90:91], s[16:17] op_sel:[1,0] op_sel_hi:[1,0] neg_lo:[0,1] neg_hi:[0,0]
	v_pk_add_f32 v[122:123], v[148:149], v[120:121] op_sel:[0,1] op_sel_hi:[1,0] neg_lo:[0,1] neg_hi:[0,0]
	v_pk_mul_f32 v[150:151], v[102:103], s[16:17] op_sel:[1,0] op_sel_hi:[1,0] neg_lo:[0,1] neg_hi:[0,1]
	v_pk_add_f32 v[96:97], v[96:97], v[114:115] neg_lo:[0,1] neg_hi:[0,1]
	v_pk_fma_f32 v[72:73], v[90:91], s[16:17], v[72:73] op_sel:[0,0,0] op_sel_hi:[0,0,1] neg_lo:[0,0,0] neg_hi:[0,0,0]
	v_pk_add_f32 v[148:149], v[148:149], v[120:121] op_sel:[0,1] op_sel_hi:[1,0] neg_lo:[0,0] neg_hi:[0,1]
	v_pk_fma_f32 v[150:151], v[102:103], s[16:17], v[150:151] op_sel:[0,0,0] op_sel_hi:[0,0,1] neg_lo:[0,1,0] neg_hi:[0,0,0]
	v_pk_add_f32 v[90:91], v[132:133], v[72:73] neg_lo:[0,1] neg_hi:[0,1]
	v_pk_add_f32 v[102:103], v[126:127], v[150:151] neg_lo:[0,1] neg_hi:[0,1]
	v_pk_add_f32 v[132:133], v[132:133], v[72:73]
	v_pk_add_f32 v[126:127], v[126:127], v[150:151]
	v_pk_add_f32 v[166:167], v[88:89], v[98:99]
	v_pk_mul_f32 v[78:79], v[100:101], s[16:17] op_sel:[1,0] op_sel_hi:[1,0] neg_lo:[0,1] neg_hi:[0,0]
	v_pk_add_f32 v[104:105], v[94:95], v[154:155] op_sel:[0,1] op_sel_hi:[1,0] neg_lo:[0,1] neg_hi:[0,0]
	v_pk_mul_f32 v[112:113], v[152:153], s[16:17] op_sel:[1,0] op_sel_hi:[1,0] neg_lo:[0,1] neg_hi:[0,1]
	v_pk_add_f32 v[88:89], v[88:89], v[98:99] neg_lo:[0,1] neg_hi:[0,1]
	v_pk_fma_f32 v[78:79], v[100:101], s[16:17], v[78:79] op_sel:[0,0,0] op_sel_hi:[0,0,1] neg_lo:[0,0,0] neg_hi:[0,0,0]
	v_pk_add_f32 v[94:95], v[94:95], v[154:155] op_sel:[0,1] op_sel_hi:[1,0] neg_lo:[0,0] neg_hi:[0,1]
	v_pk_fma_f32 v[112:113], v[152:153], s[16:17], v[112:113] op_sel:[0,0,0] op_sel_hi:[0,0,1] neg_lo:[0,1,0] neg_hi:[0,0,0]
	v_pk_add_f32 v[100:101], v[118:119], v[78:79] neg_lo:[0,1] neg_hi:[0,1]
	v_pk_add_f32 v[152:153], v[92:93], v[112:113] neg_lo:[0,1] neg_hi:[0,1]
	v_pk_add_f32 v[118:119], v[118:119], v[78:79]
	v_pk_add_f32 v[92:93], v[92:93], v[112:113]
	v_pk_add_f32 v[128:129], v[82:83], v[166:167]
	v_pk_mul_f32 v[108:109], v[118:119], s[4:5] op_sel:[1,1] op_sel_hi:[1,0] neg_lo:[0,1] neg_hi:[0,0]
	v_pk_mul_f32 v[80:81], v[104:105], s[16:17] op_sel:[1,0] op_sel_hi:[1,0] neg_lo:[0,1] neg_hi:[0,0]
	v_pk_mul_f32 v[84:85], v[92:93], s[4:5] op_sel:[1,0] op_sel_hi:[1,1] neg_lo:[0,1] neg_hi:[0,0]
	v_pk_add_f32 v[82:83], v[82:83], v[166:167] neg_lo:[0,1] neg_hi:[0,1]
	v_pk_fma_f32 v[108:109], v[118:119], s[4:5], v[108:109] op_sel:[0,0,0] op_sel_hi:[0,1,1] neg_lo:[0,0,0] neg_hi:[0,0,0]
	v_pk_fma_f32 v[80:81], v[104:105], s[16:17], v[80:81] op_sel:[0,0,0] op_sel_hi:[0,0,1] neg_lo:[0,0,0] neg_hi:[0,0,0]
	v_pk_fma_f32 v[84:85], v[92:93], s[4:5], v[84:85] op_sel:[0,1,0] op_sel_hi:[0,0,1] neg_lo:[0,0,0] neg_hi:[0,0,0]
	v_pk_add_f32 v[118:119], v[132:133], v[108:109] neg_lo:[0,1] neg_hi:[0,1]
	v_pk_add_f32 v[104:105], v[122:123], v[80:81] neg_lo:[0,1] neg_hi:[0,1]
	v_pk_add_f32 v[92:93], v[126:127], v[84:85] neg_lo:[0,1] neg_hi:[0,1]
	v_pk_add_f32 v[132:133], v[132:133], v[108:109]
	v_pk_add_f32 v[122:123], v[122:123], v[80:81]
	v_pk_add_f32 v[126:127], v[126:127], v[84:85]
	v_pk_add_f32 v[110:111], v[96:97], v[88:89] op_sel:[0,1] op_sel_hi:[1,0] neg_lo:[0,1] neg_hi:[0,0]
	v_pk_mul_f32 v[74:75], v[100:101], s[4:5] op_sel:[1,0] op_sel_hi:[1,1] neg_lo:[0,1] neg_hi:[0,1]
	v_pk_mul_f32 v[76:77], v[94:95], s[16:17] op_sel:[1,0] op_sel_hi:[1,0] neg_lo:[0,1] neg_hi:[0,1]
	v_pk_mul_f32 v[124:125], v[152:153], s[4:5] op_sel:[1,1] op_sel_hi:[1,0] neg_lo:[0,1] neg_hi:[0,1]
	v_pk_add_f32 v[96:97], v[96:97], v[88:89] op_sel:[0,1] op_sel_hi:[1,0] neg_lo:[0,0] neg_hi:[0,1]
	v_pk_fma_f32 v[74:75], v[100:101], s[4:5], v[74:75] op_sel:[0,1,0] op_sel_hi:[0,0,1] neg_lo:[0,1,0] neg_hi:[0,0,0]
	v_pk_fma_f32 v[76:77], v[94:95], s[16:17], v[76:77] op_sel:[0,0,0] op_sel_hi:[0,0,1] neg_lo:[0,1,0] neg_hi:[0,0,0]
	v_pk_fma_f32 v[124:125], v[152:153], s[4:5], v[124:125] op_sel:[0,0,0] op_sel_hi:[0,1,1] neg_lo:[0,1,0] neg_hi:[0,0,0]
	v_pk_add_f32 v[100:101], v[90:91], v[74:75] neg_lo:[0,1] neg_hi:[0,1]
	v_pk_add_f32 v[94:95], v[148:149], v[76:77] neg_lo:[0,1] neg_hi:[0,1]
	v_pk_add_f32 v[152:153], v[102:103], v[124:125] neg_lo:[0,1] neg_hi:[0,1]
	v_pk_add_f32 v[90:91], v[90:91], v[74:75]
	v_pk_add_f32 v[148:149], v[148:149], v[76:77]
	v_pk_add_f32 v[102:103], v[102:103], v[124:125]
	ds_write2_b64 v147, v[128:129], v[132:133] offset1:1
	ds_write2_b64 v147, v[122:123], v[126:127] offset0:2 offset1:3
	ds_write2_b64 v147, v[110:111], v[90:91] offset0:4 offset1:5
	ds_write2_b64 v147, v[148:149], v[102:103] offset0:6 offset1:7
	ds_write2_b64 v147, v[82:83], v[118:119] offset0:8 offset1:9
	ds_write2_b64 v147, v[104:105], v[92:93] offset0:10 offset1:11
	ds_write2_b64 v147, v[96:97], v[100:101] offset0:12 offset1:13
	ds_write2_b64 v147, v[94:95], v[152:153] offset0:14 offset1:15
	v_mov_b32_e32 v68, v195
	s_waitcnt lgkmcnt(0)
	s_mov_b32 s0, 0
	v_and_b32_e32 v73, 15, v68
	v_lshlrev_b32_e32 v72, 4, v68
	v_lshlrev_b32_e32 v75, 9, v73
	v_and_b32_e32 v72, 0xfffffc00, v72
	v_lshlrev_b32_e32 v74, 3, v68
	v_add_u32_e32 v75, 0, v75
	v_and_b32_e32 v69, 63, v68
	v_lshl_add_u32 v73, v73, 3, 0
	v_and_or_b32 v74, v74, s90, v72
	v_add_u32_e32 v75, 0x22000, v75
; #define LAS __attribute__((address_space(3)))
; __device__ __forceinline__ cf twc(cf ws, int k16) { if (k16 == 0) return ws; if (k16 == 4) return cf{ws.y, -ws.x}; return cmul(ws, cf{c16(k16), -s16(k16)}); }
; template <int LR> __device__ __forceinline__ void dit_reg(cf (&x)[1 << LR], cf w) {
;     constexpr int R = 1 << LR; cf wsv[LR]; wsv[0] = w;
; #pragma unroll
;     for (int s = 1; s < LR; ++s) wsv[s] = cmul(wsv[s - 1], wsv[s - 1]);
; #pragma unroll
;     for (int s = LR - 1; s >= 0; --s) { const int half = R >> (s + 1);
; #pragma unroll
;         for (int m0 = 0; m0 < R; m0 += 2 * half)
; #pragma unroll
;             for (int mm = 0; mm < half; ++mm) { const int ia = m0 + mm, ib = ia + half; const cf a = x[ia];
;                 const cf b = cmulc(x[ib], twc(wsv[s], (mm << s) * (16 / R)));
;                 x[ia] = cf{a.x + b.x, a.y + b.y}; x[ib] = cf{a.x - b.x, a.y - b.y}; } }
; }
; __device__ __forceinline__ void lds_barrier() { asm volatile("s_waitcnt lgkmcnt(0)\n\ts_barrier" ::: "memory"); }
; template <int LR, bool INV> __device__ __forceinline__ void fft_pass(ldsf2 buf, int base, int stride, int twi) {
;     constexpr int R = 1 << LR; cf x[R];
;     const v2f wv = ((ldsf2)((LAS unsigned char*)buf + 139264))[twi];
; #pragma unroll
;     for (int m = 0; m < R; ++m) { const v2f v = buf[base + m * stride]; x[m] = cf{v.x, v.y}; }
;     const cf w{wv.x, wv.y};
;     if (INV) dit_reg<LR>(x, w); else dif_reg<LR>(x, w);
; #pragma unroll
;     for (int m = 0; m < R; ++m) buf[base + m * stride] = mkv2(x[m].x, x[m].y);
; }
; __device__ __forceinline__ void fft_inv_cba(ldsf2 buf) {
;     ...
;     for (int u = 0; u < 2; ++u) { const int j = l + 64 * u, o = j & 15, e0 = wv * 1024 + (j >> 4) * 128 + o; fft_pass<3, true>(buf, e0 + (e0 >> 4), 17, o * 64); }
.LBB0_353:
	ds_read_b64 v[92:93], v75
	v_or_b32_e32 v76, s0, v74
	v_lshlrev_b32_e32 v77, 3, v76
	v_ashrrev_i32_e32 v76, 1, v76
	v_add3_u32 v122, v73, v77, v76
	ds_read2_b64 v[76:79], v122 offset1:17
	ds_read2_b64 v[80:83], v122 offset0:34 offset1:51
	ds_read2_b64 v[84:87], v122 offset0:68 offset1:85
	ds_read2_b64 v[88:91], v122 offset0:102 offset1:119
	s_movk_i32 s0, 0x200
	ds_read_b64 v[124:125], v75
	v_or_b32_e32 v126, s0, v74
	v_lshlrev_b32_e32 v128, 3, v126
	v_ashrrev_i32_e32 v126, 1, v126
	v_add3_u32 v130, v73, v128, v126
	ds_read2_b64 v[132:135], v130 offset1:17
	ds_read2_b64 v[148:151], v130 offset0:34 offset1:51
	ds_read2_b64 v[152:155], v130 offset0:68 offset1:85
	ds_read2_b64 v[156:159], v130 offset0:102 offset1:119
	s_waitcnt lgkmcnt(5)
	v_pk_add_f32 v[94:95], v[92:93], v[92:93] op_sel:[0,1] op_sel_hi:[1,0] neg_lo:[0,0] neg_hi:[0,1]
	v_pk_mul_f32 v[96:97], v[94:95], s[16:17] op_sel:[0,0] op_sel_hi:[1,0]
	v_pk_mul_f32 v[98:99], v[94:95], s[16:17] op_sel:[1,0] op_sel_hi:[0,0] neg_lo:[0,0] neg_hi:[1,0]
	v_pk_mul_f32 v[100:101], v[92:93], v[92:93] op_sel:[1,1] op_sel_hi:[1,0]
	v_pk_fma_f32 v[100:101], v[92:93], v[92:93], v[100:101] op_sel:[0,0,0] op_sel_hi:[0,1,1] neg_lo:[0,0,1] neg_hi:[0,0,0]
	v_pk_mul_f32 v[102:103], v[100:101], v[100:101] op_sel:[1,1] op_sel_hi:[1,0]
	v_pk_fma_f32 v[102:103], v[100:101], v[100:101], v[102:103] op_sel:[0,0,0] op_sel_hi:[0,1,1] neg_lo:[0,0,1] neg_hi:[0,0,0]
	v_pk_mul_f32 v[104:105], v[78:79], v[102:103] op_sel:[1,1] op_sel_hi:[1,0]
	v_pk_mul_f32 v[106:107], v[82:83], v[102:103] op_sel:[1,1] op_sel_hi:[1,0]
	v_pk_mul_f32 v[108:109], v[86:87], v[102:103] op_sel:[1,1] op_sel_hi:[1,0]
	v_pk_mul_f32 v[110:111], v[90:91], v[102:103] op_sel:[1,1] op_sel_hi:[1,0]
	v_pk_fma_f32 v[104:105], v[78:79], v[102:103], v[104:105] op_sel:[0,0,0] op_sel_hi:[0,1,1] neg_lo:[0,0,0] neg_hi:[0,1,0]
	v_pk_fma_f32 v[106:107], v[82:83], v[102:103], v[106:107] op_sel:[0,0,0] op_sel_hi:[0,1,1] neg_lo:[0,0,0] neg_hi:[0,1,0]
	v_pk_fma_f32 v[108:109], v[86:87], v[102:103], v[108:109] op_sel:[0,0,0] op_sel_hi:[0,1,1] neg_lo:[0,0,0] neg_hi:[0,1,0]
	v_pk_fma_f32 v[110:111], v[90:91], v[102:103], v[110:111] op_sel:[0,0,0] op_sel_hi:[0,1,1] neg_lo:[0,0,0] neg_hi:[0,1,0]
	v_pk_add_f32 v[78:79], v[76:77], v[104:105] neg_lo:[0,1] neg_hi:[0,1]
	v_pk_add_f32 v[82:83], v[80:81], v[106:107] neg_lo:[0,1] neg_hi:[0,1]
	v_pk_add_f32 v[86:87], v[84:85], v[108:109] neg_lo:[0,1] neg_hi:[0,1]
	v_pk_add_f32 v[90:91], v[88:89], v[110:111] neg_lo:[0,1] neg_hi:[0,1]
	v_pk_add_f32 v[76:77], v[76:77], v[104:105]
	v_pk_add_f32 v[80:81], v[80:81], v[106:107]
	v_pk_add_f32 v[84:85], v[84:85], v[108:109]
	v_pk_add_f32 v[88:89], v[88:89], v[110:111]
	v_pk_mul_f32 v[104:105], v[80:81], v[100:101] op_sel:[1,1] op_sel_hi:[1,0]
	v_pk_mul_f32 v[106:107], v[82:83], v[100:101] op_sel:[1,0] op_sel_hi:[1,1]
	v_pk_mul_f32 v[108:109], v[88:89], v[100:101] op_sel:[1,1] op_sel_hi:[1,0]
	v_pk_mul_f32 v[110:111], v[90:91], v[100:101] op_sel:[1,0] op_sel_hi:[1,1]
	v_pk_fma_f32 v[104:105], v[80:81], v[100:101], v[104:105] op_sel:[0,0,0] op_sel_hi:[0,1,1] neg_lo:[0,0,0] neg_hi:[0,1,0]
	v_pk_fma_f32 v[106:107], v[82:83], v[100:101], v[106:107] op_sel:[0,1,0] op_sel_hi:[0,0,1] neg_lo:[0,0,1] neg_hi:[0,0,0]
	v_pk_fma_f32 v[108:109], v[88:89], v[100:101], v[108:109] op_sel:[0,0,0] op_sel_hi:[0,1,1] neg_lo:[0,0,0] neg_hi:[0,1,0]
	v_pk_fma_f32 v[110:111], v[90:91], v[100:101], v[110:111] op_sel:[0,1,0] op_sel_hi:[0,0,1] neg_lo:[0,0,1] neg_hi:[0,0,0]
	v_pk_add_f32 v[80:81], v[76:77], v[104:105] neg_lo:[0,1] neg_hi:[0,1]
	v_pk_add_f32 v[82:83], v[78:79], v[106:107] neg_lo:[0,1] neg_hi:[0,1]
	v_pk_add_f32 v[88:89], v[84:85], v[108:109] neg_lo:[0,1] neg_hi:[0,1]
	v_pk_add_f32 v[90:91], v[86:87], v[110:111] neg_lo:[0,1] neg_hi:[0,1]
	v_pk_add_f32 v[76:77], v[76:77], v[104:105]
	v_pk_add_f32 v[78:79], v[78:79], v[106:107]
	v_pk_add_f32 v[84:85], v[84:85], v[108:109]
	v_pk_add_f32 v[86:87], v[86:87], v[110:111]
	v_pk_mul_f32 v[104:105], v[84:85], v[92:93] op_sel:[1,1] op_sel_hi:[1,0]
	v_pk_mul_f32 v[106:107], v[86:87], v[96:97] op_sel:[1,1] op_sel_hi:[1,0]
	v_pk_mul_f32 v[108:109], v[88:89], v[92:93] op_sel:[1,0] op_sel_hi:[1,1]
	v_pk_mul_f32 v[110:111], v[90:91], v[98:99] op_sel:[1,1] op_sel_hi:[1,0]
	v_pk_fma_f32 v[104:105], v[84:85], v[92:93], v[104:105] op_sel:[0,0,0] op_sel_hi:[0,1,1] neg_lo:[0,0,0] neg_hi:[0,1,0]
	v_pk_fma_f32 v[106:107], v[86:87], v[96:97], v[106:107] op_sel:[0,0,0] op_sel_hi:[0,1,1] neg_lo:[0,0,0] neg_hi:[0,1,0]
	v_pk_fma_f32 v[108:109], v[88:89], v[92:93], v[108:109] op_sel:[0,1,0] op_sel_hi:[0,0,1] neg_lo:[0,0,1] neg_hi:[0,0,0]
	v_pk_fma_f32 v[110:111], v[90:91], v[98:99], v[110:111] op_sel:[0,0,0] op_sel_hi:[0,1,1] neg_lo:[0,0,0] neg_hi:[0,1,0]
	v_pk_add_f32 v[84:85], v[76:77], v[104:105] neg_lo:[0,1] neg_hi:[0,1]
	v_pk_add_f32 v[86:87], v[78:79], v[106:107] neg_lo:[0,1] neg_hi:[0,1]
	v_pk_add_f32 v[88:89], v[80:81], v[108:109] neg_lo:[0,1] neg_hi:[0,1]
	v_pk_add_f32 v[90:91], v[82:83], v[110:111] neg_lo:[0,1] neg_hi:[0,1]
	v_pk_add_f32 v[76:77], v[76:77], v[104:105]
	v_pk_add_f32 v[78:79], v[78:79], v[106:107]
	v_pk_add_f32 v[80:81], v[80:81], v[108:109]
	v_pk_add_f32 v[82:83], v[82:83], v[110:111]
	ds_write2_b64 v122, v[76:77], v[78:79] offset1:17
	ds_write2_b64 v122, v[80:81], v[82:83] offset0:34 offset1:51
	ds_write2_b64 v122, v[84:85], v[86:87] offset0:68 offset1:85
	ds_write2_b64 v122, v[88:89], v[90:91] offset0:102 offset1:119
	s_waitcnt lgkmcnt(4)
; #define LAS __attribute__((address_space(3)))
; __device__ __forceinline__ cf twc(cf ws, int k16) { if (k16 == 0) return ws; if (k16 == 4) return cf{ws.y, -ws.x}; return cmul(ws, cf{c16(k16), -s16(k16)}); }
; __device__ __forceinline__ void wave_lds_fence() { asm volatile("s_waitcnt lgkmcnt(0)" ::: "memory"); }
; template <int LR> __device__ __forceinline__ void dit_reg(cf (&x)[1 << LR], cf w) {
;     constexpr int R = 1 << LR; cf wsv[LR]; wsv[0] = w;
; #pragma unroll
;     for (int s = 1; s < LR; ++s) wsv[s] = cmul(wsv[s - 1], wsv[s - 1]);
; #pragma unroll
;     for (int s = LR - 1; s >= 0; --s) { const int half = R >> (s + 1);
; #pragma unroll
;         for (int m0 = 0; m0 < R; m0 += 2 * half)
; #pragma unroll
;             for (int mm = 0; mm < half; ++mm) { const int ia = m0 + mm, ib = ia + half; const cf a = x[ia];
;                 const cf b = cmulc(x[ib], twc(wsv[s], (mm << s) * (16 / R)));
;                 x[ia] = cf{a.x + b.x, a.y + b.y}; x[ib] = cf{a.x - b.x, a.y - b.y}; } }
; }
; __device__ __forceinline__ void lds_barrier() { asm volatile("s_waitcnt lgkmcnt(0)\n\ts_barrier" ::: "memory"); }
; template <int LR, bool INV> __device__ __forceinline__ void fft_pass(ldsf2 buf, int base, int stride, int twi) {
;     constexpr int R = 1 << LR; cf x[R];
;     const v2f wv = ((ldsf2)((LAS unsigned char*)buf + 139264))[twi];
; #pragma unroll
;     for (int m = 0; m < R; ++m) { const v2f v = buf[base + m * stride]; x[m] = cf{v.x, v.y}; }
;     const cf w{wv.x, wv.y};
;     if (INV) dit_reg<LR>(x, w); else dif_reg<LR>(x, w);
; #pragma unroll
;     for (int m = 0; m < R; ++m) buf[base + m * stride] = mkv2(x[m].x, x[m].y);
; }
; __device__ __forceinline__ void fft_inv_cba(ldsf2 buf) {
;     ...
;     for (int u = 0; u < 2; ++u) { const int j = l + 64 * u, o = j & 15, e0 = wv * 1024 + (j >> 4) * 128 + o; fft_pass<3, true>(buf, e0 + (e0 >> 4), 17, o * 64); }
;     wave_lds_fence();
	v_pk_add_f32 v[160:161], v[124:125], v[124:125] op_sel:[0,1] op_sel_hi:[1,0] neg_lo:[0,0] neg_hi:[0,1]
	v_pk_mul_f32 v[162:163], v[160:161], s[16:17] op_sel:[0,0] op_sel_hi:[1,0]
	v_pk_mul_f32 v[164:165], v[160:161], s[16:17] op_sel:[1,0] op_sel_hi:[0,0] neg_lo:[0,0] neg_hi:[1,0]
	v_pk_mul_f32 v[166:167], v[124:125], v[124:125] op_sel:[1,1] op_sel_hi:[1,0]
	v_pk_fma_f32 v[166:167], v[124:125], v[124:125], v[166:167] op_sel:[0,0,0] op_sel_hi:[0,1,1] neg_lo:[0,0,1] neg_hi:[0,0,0]
	v_pk_mul_f32 v[168:169], v[166:167], v[166:167] op_sel:[1,1] op_sel_hi:[1,0]
	v_pk_fma_f32 v[168:169], v[166:167], v[166:167], v[168:169] op_sel:[0,0,0] op_sel_hi:[0,1,1] neg_lo:[0,0,1] neg_hi:[0,0,0]
	v_pk_mul_f32 v[170:171], v[134:135], v[168:169] op_sel:[1,1] op_sel_hi:[1,0]
	v_pk_mul_f32 v[172:173], v[150:151], v[168:169] op_sel:[1,1] op_sel_hi:[1,0]
	v_pk_mul_f32 v[174:175], v[154:155], v[168:169] op_sel:[1,1] op_sel_hi:[1,0]
	v_pk_mul_f32 v[188:189], v[158:159], v[168:169] op_sel:[1,1] op_sel_hi:[1,0]
	v_pk_fma_f32 v[170:171], v[134:135], v[168:169], v[170:171] op_sel:[0,0,0] op_sel_hi:[0,1,1] neg_lo:[0,0,0] neg_hi:[0,1,0]
	v_pk_fma_f32 v[172:173], v[150:151], v[168:169], v[172:173] op_sel:[0,0,0] op_sel_hi:[0,1,1] neg_lo:[0,0,0] neg_hi:[0,1,0]
	v_pk_fma_f32 v[174:175], v[154:155], v[168:169], v[174:175] op_sel:[0,0,0] op_sel_hi:[0,1,1] neg_lo:[0,0,0] neg_hi:[0,1,0]
	v_pk_fma_f32 v[188:189], v[158:159], v[168:169], v[188:189] op_sel:[0,0,0] op_sel_hi:[0,1,1] neg_lo:[0,0,0] neg_hi:[0,1,0]
	v_pk_add_f32 v[134:135], v[132:133], v[170:171] neg_lo:[0,1] neg_hi:[0,1]
	v_pk_add_f32 v[150:151], v[148:149], v[172:173] neg_lo:[0,1] neg_hi:[0,1]
	v_pk_add_f32 v[154:155], v[152:153], v[174:175] neg_lo:[0,1] neg_hi:[0,1]
	v_pk_add_f32 v[158:159], v[156:157], v[188:189] neg_lo:[0,1] neg_hi:[0,1]
	v_pk_add_f32 v[132:133], v[132:133], v[170:171]
	v_pk_add_f32 v[148:149], v[148:149], v[172:173]
	v_pk_add_f32 v[152:153], v[152:153], v[174:175]
	v_pk_add_f32 v[156:157], v[156:157], v[188:189]
	v_pk_mul_f32 v[170:171], v[148:149], v[166:167] op_sel:[1,1] op_sel_hi:[1,0]
	v_pk_mul_f32 v[172:173], v[150:151], v[166:167] op_sel:[1,0] op_sel_hi:[1,1]
	v_pk_mul_f32 v[174:175], v[156:157], v[166:167] op_sel:[1,1] op_sel_hi:[1,0]
	v_pk_mul_f32 v[188:189], v[158:159], v[166:167] op_sel:[1,0] op_sel_hi:[1,1]
	v_pk_fma_f32 v[170:171], v[148:149], v[166:167], v[170:171] op_sel:[0,0,0] op_sel_hi:[0,1,1] neg_lo:[0,0,0] neg_hi:[0,1,0]
	v_pk_fma_f32 v[172:173], v[150:151], v[166:167], v[172:173] op_sel:[0,1,0] op_sel_hi:[0,0,1] neg_lo:[0,0,1] neg_hi:[0,0,0]
	v_pk_fma_f32 v[174:175], v[156:157], v[166:167], v[174:175] op_sel:[0,0,0] op_sel_hi:[0,1,1] neg_lo:[0,0,0] neg_hi:[0,1,0]
	v_pk_fma_f32 v[188:189], v[158:159], v[166:167], v[188:189] op_sel:[0,1,0] op_sel_hi:[0,0,1] neg_lo:[0,0,1] neg_hi:[0,0,0]
	v_pk_add_f32 v[148:149], v[132:133], v[170:171] neg_lo:[0,1] neg_hi:[0,1]
	v_pk_add_f32 v[150:151], v[134:135], v[172:173] neg_lo:[0,1] neg_hi:[0,1]
	v_pk_add_f32 v[156:157], v[152:153], v[174:175] neg_lo:[0,1] neg_hi:[0,1]
	v_pk_add_f32 v[158:159], v[154:155], v[188:189] neg_lo:[0,1] neg_hi:[0,1]
	v_pk_add_f32 v[132:133], v[132:133], v[170:171]
	v_pk_add_f32 v[134:135], v[134:135], v[172:173]
	v_pk_add_f32 v[152:153], v[152:153], v[174:175]
	v_pk_add_f32 v[154:155], v[154:155], v[188:189]
	v_pk_mul_f32 v[170:171], v[152:153], v[124:125] op_sel:[1,1] op_sel_hi:[1,0]
	v_pk_mul_f32 v[172:173], v[154:155], v[162:163] op_sel:[1,1] op_sel_hi:[1,0]
	v_pk_mul_f32 v[174:175], v[156:157], v[124:125] op_sel:[1,0] op_sel_hi:[1,1]
	v_pk_mul_f32 v[188:189], v[158:159], v[164:165] op_sel:[1,1] op_sel_hi:[1,0]
	v_pk_fma_f32 v[170:171], v[152:153], v[124:125], v[170:171] op_sel:[0,0,0] op_sel_hi:[0,1,1] neg_lo:[0,0,0] neg_hi:[0,1,0]
	v_pk_fma_f32 v[172:173], v[154:155], v[162:163], v[172:173] op_sel:[0,0,0] op_sel_hi:[0,1,1] neg_lo:[0,0,0] neg_hi:[0,1,0]
	v_pk_fma_f32 v[174:175], v[156:157], v[124:125], v[174:175] op_sel:[0,1,0] op_sel_hi:[0,0,1] neg_lo:[0,0,1] neg_hi:[0,0,0]
	v_pk_fma_f32 v[188:189], v[158:159], v[164:165], v[188:189] op_sel:[0,0,0] op_sel_hi:[0,1,1] neg_lo:[0,0,0] neg_hi:[0,1,0]
	v_pk_add_f32 v[152:153], v[132:133], v[170:171] neg_lo:[0,1] neg_hi:[0,1]
	v_pk_add_f32 v[154:155], v[134:135], v[172:173] neg_lo:[0,1] neg_hi:[0,1]
	v_pk_add_f32 v[156:157], v[148:149], v[174:175] neg_lo:[0,1] neg_hi:[0,1]
	v_pk_add_f32 v[158:159], v[150:151], v[188:189] neg_lo:[0,1] neg_hi:[0,1]
	v_pk_add_f32 v[132:133], v[132:133], v[170:171]
	v_pk_add_f32 v[134:135], v[134:135], v[172:173]
	v_pk_add_f32 v[148:149], v[148:149], v[174:175]
	v_pk_add_f32 v[150:151], v[150:151], v[188:189]
	ds_write2_b64 v130, v[132:133], v[134:135] offset1:17
	ds_write2_b64 v130, v[148:149], v[150:151] offset0:34 offset1:51
	ds_write2_b64 v130, v[152:153], v[154:155] offset0:68 offset1:85
	ds_write2_b64 v130, v[156:157], v[158:159] offset0:102 offset1:119
	s_mov_b64 s[6:7], 0
	s_waitcnt lgkmcnt(0)
	s_mov_b32 s0, 0
	s_mov_b64 s[6:7], -1
; #define LAS __attribute__((address_space(3)))
; __device__ __forceinline__ cf twc(cf ws, int k16) { if (k16 == 0) return ws; if (k16 == 4) return cf{ws.y, -ws.x}; return cmul(ws, cf{c16(k16), -s16(k16)}); }
; template <int LR> __device__ __forceinline__ void dit_reg(cf (&x)[1 << LR], cf w) {
;     constexpr int R = 1 << LR; cf wsv[LR]; wsv[0] = w;
; #pragma unroll
;     for (int s = 1; s < LR; ++s) wsv[s] = cmul(wsv[s - 1], wsv[s - 1]);
; #pragma unroll
;     for (int s = LR - 1; s >= 0; --s) { const int half = R >> (s + 1);
; #pragma unroll
;         for (int m0 = 0; m0 < R; m0 += 2 * half)
; #pragma unroll
;             for (int mm = 0; mm < half; ++mm) { const int ia = m0 + mm, ib = ia + half; const cf a = x[ia];
;                 const cf b = cmulc(x[ib], twc(wsv[s], (mm << s) * (16 / R)));
;                 x[ia] = cf{a.x + b.x, a.y + b.y}; x[ib] = cf{a.x - b.x, a.y - b.y}; } }
; }
; __device__ __forceinline__ void lds_barrier() { asm volatile("s_waitcnt lgkmcnt(0)\n\ts_barrier" ::: "memory"); }
; template <int LR, bool INV> __device__ __forceinline__ void fft_pass(ldsf2 buf, int base, int stride, int twi) {
;     constexpr int R = 1 << LR; cf x[R];
;     const v2f wv = ((ldsf2)((LAS unsigned char*)buf + 139264))[twi];
; #pragma unroll
;     for (int m = 0; m < R; ++m) { const v2f v = buf[base + m * stride]; x[m] = cf{v.x, v.y}; }
;     const cf w{wv.x, wv.y};
;     if (INV) dit_reg<LR>(x, w); else dif_reg<LR>(x, w);
; #pragma unroll
;     for (int m = 0; m < R; ++m) buf[base + m * stride] = mkv2(x[m].x, x[m].y);
; }
; __device__ __forceinline__ void fft_inv_cba(ldsf2 buf) {
;     ...
;     for (int u = 0; u < 2; ++u) { const int o = l + 64 * u, e0 = wv * 1024 + o; fft_pass<3, true>(buf, e0 + (e0 >> 4), 136, o * 8); }
.LBB0_355:
	v_or_b32_e32 v73, s0, v69
	v_or_b32_e32 v74, v73, v72
	v_lshl_add_u32 v73, v73, 6, 0
	v_add_u32_e32 v73, 0x22000, v73
	ds_read_b64 v[90:91], v73
	v_ashrrev_i32_e32 v75, 4, v74
	v_lshlrev_b32_e32 v73, 3, v74
	v_lshlrev_b32_e32 v74, 3, v75
	v_add3_u32 v73, 0, v73, v74
	v_add_u32_e32 v122, 0x1800, v73
	v_add_u32_e32 v121, 0x1000, v73
	ds_read2_b64 v[86:89], v122 offset0:48 offset1:184
	ds_read2_b64 v[82:85], v121 offset0:32 offset1:168
	v_add_u32_e32 v120, 0x800, v73
	ds_read2_b64 v[74:77], v73 offset1:136
	ds_read2_b64 v[78:81], v120 offset0:16 offset1:152
	s_mov_b32 s0, 64
	v_or_b32_e32 v124, s0, v69
	v_or_b32_e32 v126, v124, v72
	v_lshl_add_u32 v124, v124, 6, 0
	v_add_u32_e32 v124, 0x22000, v124
	ds_read_b64 v[128:129], v124
	v_ashrrev_i32_e32 v130, 4, v126
	v_lshlrev_b32_e32 v124, 3, v126
	v_lshlrev_b32_e32 v126, 3, v130
	v_add3_u32 v124, 0, v124, v126
	v_add_u32_e32 v132, 0x1800, v124
	v_add_u32_e32 v134, 0x1000, v124
	ds_read2_b64 v[148:151], v132 offset0:48 offset1:184
	ds_read2_b64 v[152:155], v134 offset0:32 offset1:168
	v_add_u32_e32 v156, 0x800, v124
	ds_read2_b64 v[158:161], v124 offset1:136
	ds_read2_b64 v[162:165], v156 offset0:16 offset1:152
	s_waitcnt lgkmcnt(5)
	v_pk_add_f32 v[92:93], v[90:91], v[90:91] op_sel:[0,1] op_sel_hi:[1,0] neg_lo:[0,0] neg_hi:[0,1]
	v_pk_mul_f32 v[94:95], v[92:93], s[16:17] op_sel:[0,0] op_sel_hi:[1,0]
	v_pk_mul_f32 v[96:97], v[92:93], s[16:17] op_sel:[1,0] op_sel_hi:[0,0] neg_lo:[0,0] neg_hi:[1,0]
	v_pk_mul_f32 v[98:99], v[90:91], v[90:91] op_sel:[1,1] op_sel_hi:[1,0]
	v_pk_fma_f32 v[98:99], v[90:91], v[90:91], v[98:99] op_sel:[0,0,0] op_sel_hi:[0,1,1] neg_lo:[0,0,1] neg_hi:[0,0,0]
	v_pk_mul_f32 v[100:101], v[98:99], v[98:99] op_sel:[1,1] op_sel_hi:[1,0]
	v_pk_fma_f32 v[100:101], v[98:99], v[98:99], v[100:101] op_sel:[0,0,0] op_sel_hi:[0,1,1] neg_lo:[0,0,1] neg_hi:[0,0,0]
	v_pk_mul_f32 v[102:103], v[76:77], v[100:101] op_sel:[1,1] op_sel_hi:[1,0]
	v_pk_mul_f32 v[104:105], v[80:81], v[100:101] op_sel:[1,1] op_sel_hi:[1,0]
	v_pk_mul_f32 v[106:107], v[84:85], v[100:101] op_sel:[1,1] op_sel_hi:[1,0]
	v_pk_mul_f32 v[108:109], v[88:89], v[100:101] op_sel:[1,1] op_sel_hi:[1,0]
	v_pk_fma_f32 v[102:103], v[76:77], v[100:101], v[102:103] op_sel:[0,0,0] op_sel_hi:[0,1,1] neg_lo:[0,0,0] neg_hi:[0,1,0]
	v_pk_fma_f32 v[104:105], v[80:81], v[100:101], v[104:105] op_sel:[0,0,0] op_sel_hi:[0,1,1] neg_lo:[0,0,0] neg_hi:[0,1,0]
	v_pk_fma_f32 v[106:107], v[84:85], v[100:101], v[106:107] op_sel:[0,0,0] op_sel_hi:[0,1,1] neg_lo:[0,0,0] neg_hi:[0,1,0]
	v_pk_fma_f32 v[108:109], v[88:89], v[100:101], v[108:109] op_sel:[0,0,0] op_sel_hi:[0,1,1] neg_lo:[0,0,0] neg_hi:[0,1,0]
	v_pk_add_f32 v[76:77], v[74:75], v[102:103] neg_lo:[0,1] neg_hi:[0,1]
	v_pk_add_f32 v[80:81], v[78:79], v[104:105] neg_lo:[0,1] neg_hi:[0,1]
	v_pk_add_f32 v[84:85], v[82:83], v[106:107] neg_lo:[0,1] neg_hi:[0,1]
	v_pk_add_f32 v[88:89], v[86:87], v[108:109] neg_lo:[0,1] neg_hi:[0,1]
	v_pk_add_f32 v[74:75], v[74:75], v[102:103]
	v_pk_add_f32 v[78:79], v[78:79], v[104:105]
	v_pk_add_f32 v[82:83], v[82:83], v[106:107]
	v_pk_add_f32 v[86:87], v[86:87], v[108:109]
	v_pk_mul_f32 v[102:103], v[78:79], v[98:99] op_sel:[1,1] op_sel_hi:[1,0]
	v_pk_mul_f32 v[104:105], v[80:81], v[98:99] op_sel:[1,0] op_sel_hi:[1,1]
	v_pk_mul_f32 v[106:107], v[86:87], v[98:99] op_sel:[1,1] op_sel_hi:[1,0]
	v_pk_mul_f32 v[108:109], v[88:89], v[98:99] op_sel:[1,0] op_sel_hi:[1,1]
	v_pk_fma_f32 v[102:103], v[78:79], v[98:99], v[102:103] op_sel:[0,0,0] op_sel_hi:[0,1,1] neg_lo:[0,0,0] neg_hi:[0,1,0]
	v_pk_fma_f32 v[104:105], v[80:81], v[98:99], v[104:105] op_sel:[0,1,0] op_sel_hi:[0,0,1] neg_lo:[0,0,1] neg_hi:[0,0,0]
	v_pk_fma_f32 v[106:107], v[86:87], v[98:99], v[106:107] op_sel:[0,0,0] op_sel_hi:[0,1,1] neg_lo:[0,0,0] neg_hi:[0,1,0]
	v_pk_fma_f32 v[108:109], v[88:89], v[98:99], v[108:109] op_sel:[0,1,0] op_sel_hi:[0,0,1] neg_lo:[0,0,1] neg_hi:[0,0,0]
	v_pk_add_f32 v[78:79], v[74:75], v[102:103] neg_lo:[0,1] neg_hi:[0,1]
	v_pk_add_f32 v[80:81], v[76:77], v[104:105] neg_lo:[0,1] neg_hi:[0,1]
	v_pk_add_f32 v[86:87], v[82:83], v[106:107] neg_lo:[0,1] neg_hi:[0,1]
	v_pk_add_f32 v[88:89], v[84:85], v[108:109] neg_lo:[0,1] neg_hi:[0,1]
	v_pk_add_f32 v[74:75], v[74:75], v[102:103]
	v_pk_add_f32 v[76:77], v[76:77], v[104:105]
	v_pk_add_f32 v[82:83], v[82:83], v[106:107]
	v_pk_add_f32 v[84:85], v[84:85], v[108:109]
	v_pk_mul_f32 v[102:103], v[82:83], v[90:91] op_sel:[1,1] op_sel_hi:[1,0]
	v_pk_mul_f32 v[104:105], v[84:85], v[94:95] op_sel:[1,1] op_sel_hi:[1,0]
	v_pk_mul_f32 v[106:107], v[86:87], v[90:91] op_sel:[1,0] op_sel_hi:[1,1]
	v_pk_mul_f32 v[108:109], v[88:89], v[96:97] op_sel:[1,1] op_sel_hi:[1,0]
	v_pk_fma_f32 v[102:103], v[82:83], v[90:91], v[102:103] op_sel:[0,0,0] op_sel_hi:[0,1,1] neg_lo:[0,0,0] neg_hi:[0,1,0]
	v_pk_fma_f32 v[104:105], v[84:85], v[94:95], v[104:105] op_sel:[0,0,0] op_sel_hi:[0,1,1] neg_lo:[0,0,0] neg_hi:[0,1,0]
	v_pk_fma_f32 v[106:107], v[86:87], v[90:91], v[106:107] op_sel:[0,1,0] op_sel_hi:[0,0,1] neg_lo:[0,0,1] neg_hi:[0,0,0]
	v_pk_fma_f32 v[108:109], v[88:89], v[96:97], v[108:109] op_sel:[0,0,0] op_sel_hi:[0,1,1] neg_lo:[0,0,0] neg_hi:[0,1,0]
	v_pk_add_f32 v[82:83], v[74:75], v[102:103] neg_lo:[0,1] neg_hi:[0,1]
	v_pk_add_f32 v[84:85], v[76:77], v[104:105] neg_lo:[0,1] neg_hi:[0,1]
	v_pk_add_f32 v[86:87], v[78:79], v[106:107] neg_lo:[0,1] neg_hi:[0,1]
	v_pk_add_f32 v[88:89], v[80:81], v[108:109] neg_lo:[0,1] neg_hi:[0,1]
	v_pk_add_f32 v[74:75], v[74:75], v[102:103]
	v_pk_add_f32 v[76:77], v[76:77], v[104:105]
	v_pk_add_f32 v[78:79], v[78:79], v[106:107]
	v_pk_add_f32 v[80:81], v[80:81], v[108:109]
	ds_write2_b64 v73, v[74:75], v[76:77] offset1:136
	ds_write2_b64 v120, v[78:79], v[80:81] offset0:16 offset1:152
	ds_write2_b64 v121, v[82:83], v[84:85] offset0:32 offset1:168
	ds_write2_b64 v122, v[86:87], v[88:89] offset0:48 offset1:184
	s_waitcnt lgkmcnt(4)
; #define LAS __attribute__((address_space(3)))
; __device__ __forceinline__ cf twc(cf ws, int k16) { if (k16 == 0) return ws; if (k16 == 4) return cf{ws.y, -ws.x}; return cmul(ws, cf{c16(k16), -s16(k16)}); }
; template <int LR> __device__ __forceinline__ void dit_reg(cf (&x)[1 << LR], cf w) {
;     constexpr int R = 1 << LR; cf wsv[LR]; wsv[0] = w;
; #pragma unroll
;     for (int s = 1; s < LR; ++s) wsv[s] = cmul(wsv[s - 1], wsv[s - 1]);
; #pragma unroll
;     for (int s = LR - 1; s >= 0; --s) { const int half = R >> (s + 1);
; #pragma unroll
;         for (int m0 = 0; m0 < R; m0 += 2 * half)
; #pragma unroll
;             for (int mm = 0; mm < half; ++mm) { const int ia = m0 + mm, ib = ia + half; const cf a = x[ia];
;                 const cf b = cmulc(x[ib], twc(wsv[s], (mm << s) * (16 / R)));
;                 x[ia] = cf{a.x + b.x, a.y + b.y}; x[ib] = cf{a.x - b.x, a.y - b.y}; } }
; }
; __device__ __forceinline__ void lds_barrier() { asm volatile("s_waitcnt lgkmcnt(0)\n\ts_barrier" ::: "memory"); }
; template <int LR, bool INV> __device__ __forceinline__ void fft_pass(ldsf2 buf, int base, int stride, int twi) {
;     constexpr int R = 1 << LR; cf x[R];
;     const v2f wv = ((ldsf2)((LAS unsigned char*)buf + 139264))[twi];
; #pragma unroll
;     for (int m = 0; m < R; ++m) { const v2f v = buf[base + m * stride]; x[m] = cf{v.x, v.y}; }
;     const cf w{wv.x, wv.y};
;     if (INV) dit_reg<LR>(x, w); else dif_reg<LR>(x, w);
; #pragma unroll
;     for (int m = 0; m < R; ++m) buf[base + m * stride] = mkv2(x[m].x, x[m].y);
; }
; __device__ __forceinline__ void fft_inv_cba(ldsf2 buf) {
;     ...
;     for (int u = 0; u < 2; ++u) { const int o = l + 64 * u, e0 = wv * 1024 + o; fft_pass<3, true>(buf, e0 + (e0 >> 4), 136, o * 8); }
;     lds_barrier();
	v_pk_add_f32 v[166:167], v[128:129], v[128:129] op_sel:[0,1] op_sel_hi:[1,0] neg_lo:[0,0] neg_hi:[0,1]
	v_pk_mul_f32 v[168:169], v[166:167], s[16:17] op_sel:[0,0] op_sel_hi:[1,0]
	v_pk_mul_f32 v[170:171], v[166:167], s[16:17] op_sel:[1,0] op_sel_hi:[0,0] neg_lo:[0,0] neg_hi:[1,0]
	v_pk_mul_f32 v[172:173], v[128:129], v[128:129] op_sel:[1,1] op_sel_hi:[1,0]
	v_pk_fma_f32 v[172:173], v[128:129], v[128:129], v[172:173] op_sel:[0,0,0] op_sel_hi:[0,1,1] neg_lo:[0,0,1] neg_hi:[0,0,0]
	v_pk_mul_f32 v[174:175], v[172:173], v[172:173] op_sel:[1,1] op_sel_hi:[1,0]
	v_pk_fma_f32 v[174:175], v[172:173], v[172:173], v[174:175] op_sel:[0,0,0] op_sel_hi:[0,1,1] neg_lo:[0,0,1] neg_hi:[0,0,0]
	v_pk_mul_f32 v[188:189], v[160:161], v[174:175] op_sel:[1,1] op_sel_hi:[1,0]
	v_pk_mul_f32 v[190:191], v[164:165], v[174:175] op_sel:[1,1] op_sel_hi:[1,0]
	v_pk_mul_f32 v[196:197], v[154:155], v[174:175] op_sel:[1,1] op_sel_hi:[1,0]
	v_pk_mul_f32 v[198:199], v[150:151], v[174:175] op_sel:[1,1] op_sel_hi:[1,0]
	v_pk_fma_f32 v[188:189], v[160:161], v[174:175], v[188:189] op_sel:[0,0,0] op_sel_hi:[0,1,1] neg_lo:[0,0,0] neg_hi:[0,1,0]
	v_pk_fma_f32 v[190:191], v[164:165], v[174:175], v[190:191] op_sel:[0,0,0] op_sel_hi:[0,1,1] neg_lo:[0,0,0] neg_hi:[0,1,0]
	v_pk_fma_f32 v[196:197], v[154:155], v[174:175], v[196:197] op_sel:[0,0,0] op_sel_hi:[0,1,1] neg_lo:[0,0,0] neg_hi:[0,1,0]
	v_pk_fma_f32 v[198:199], v[150:151], v[174:175], v[198:199] op_sel:[0,0,0] op_sel_hi:[0,1,1] neg_lo:[0,0,0] neg_hi:[0,1,0]
	v_pk_add_f32 v[160:161], v[158:159], v[188:189] neg_lo:[0,1] neg_hi:[0,1]
	v_pk_add_f32 v[164:165], v[162:163], v[190:191] neg_lo:[0,1] neg_hi:[0,1]
	v_pk_add_f32 v[154:155], v[152:153], v[196:197] neg_lo:[0,1] neg_hi:[0,1]
	v_pk_add_f32 v[150:151], v[148:149], v[198:199] neg_lo:[0,1] neg_hi:[0,1]
	v_pk_add_f32 v[158:159], v[158:159], v[188:189]
	v_pk_add_f32 v[162:163], v[162:163], v[190:191]
	v_pk_add_f32 v[152:153], v[152:153], v[196:197]
	v_pk_add_f32 v[148:149], v[148:149], v[198:199]
	v_pk_mul_f32 v[188:189], v[162:163], v[172:173] op_sel:[1,1] op_sel_hi:[1,0]
	v_pk_mul_f32 v[190:191], v[164:165], v[172:173] op_sel:[1,0] op_sel_hi:[1,1]
	v_pk_mul_f32 v[196:197], v[148:149], v[172:173] op_sel:[1,1] op_sel_hi:[1,0]
	v_pk_mul_f32 v[198:199], v[150:151], v[172:173] op_sel:[1,0] op_sel_hi:[1,1]
	v_pk_fma_f32 v[188:189], v[162:163], v[172:173], v[188:189] op_sel:[0,0,0] op_sel_hi:[0,1,1] neg_lo:[0,0,0] neg_hi:[0,1,0]
	v_pk_fma_f32 v[190:191], v[164:165], v[172:173], v[190:191] op_sel:[0,1,0] op_sel_hi:[0,0,1] neg_lo:[0,0,1] neg_hi:[0,0,0]
	v_pk_fma_f32 v[196:197], v[148:149], v[172:173], v[196:197] op_sel:[0,0,0] op_sel_hi:[0,1,1] neg_lo:[0,0,0] neg_hi:[0,1,0]
	v_pk_fma_f32 v[198:199], v[150:151], v[172:173], v[198:199] op_sel:[0,1,0] op_sel_hi:[0,0,1] neg_lo:[0,0,1] neg_hi:[0,0,0]
	v_pk_add_f32 v[162:163], v[158:159], v[188:189] neg_lo:[0,1] neg_hi:[0,1]
	v_pk_add_f32 v[164:165], v[160:161], v[190:191] neg_lo:[0,1] neg_hi:[0,1]
	v_pk_add_f32 v[148:149], v[152:153], v[196:197] neg_lo:[0,1] neg_hi:[0,1]
	v_pk_add_f32 v[150:151], v[154:155], v[198:199] neg_lo:[0,1] neg_hi:[0,1]
	v_pk_add_f32 v[158:159], v[158:159], v[188:189]
	v_pk_add_f32 v[160:161], v[160:161], v[190:191]
	v_pk_add_f32 v[152:153], v[152:153], v[196:197]
	v_pk_add_f32 v[154:155], v[154:155], v[198:199]
	v_pk_mul_f32 v[188:189], v[152:153], v[128:129] op_sel:[1,1] op_sel_hi:[1,0]
	v_pk_mul_f32 v[190:191], v[154:155], v[168:169] op_sel:[1,1] op_sel_hi:[1,0]
	v_pk_mul_f32 v[196:197], v[148:149], v[128:129] op_sel:[1,0] op_sel_hi:[1,1]
	v_pk_mul_f32 v[198:199], v[150:151], v[170:171] op_sel:[1,1] op_sel_hi:[1,0]
	v_pk_fma_f32 v[188:189], v[152:153], v[128:129], v[188:189] op_sel:[0,0,0] op_sel_hi:[0,1,1] neg_lo:[0,0,0] neg_hi:[0,1,0]
	v_pk_fma_f32 v[190:191], v[154:155], v[168:169], v[190:191] op_sel:[0,0,0] op_sel_hi:[0,1,1] neg_lo:[0,0,0] neg_hi:[0,1,0]
	v_pk_fma_f32 v[196:197], v[148:149], v[128:129], v[196:197] op_sel:[0,1,0] op_sel_hi:[0,0,1] neg_lo:[0,0,1] neg_hi:[0,0,0]
	v_pk_fma_f32 v[198:199], v[150:151], v[170:171], v[198:199] op_sel:[0,0,0] op_sel_hi:[0,1,1] neg_lo:[0,0,0] neg_hi:[0,1,0]
	v_pk_add_f32 v[152:153], v[158:159], v[188:189] neg_lo:[0,1] neg_hi:[0,1]
	v_pk_add_f32 v[154:155], v[160:161], v[190:191] neg_lo:[0,1] neg_hi:[0,1]
	v_pk_add_f32 v[148:149], v[162:163], v[196:197] neg_lo:[0,1] neg_hi:[0,1]
	v_pk_add_f32 v[150:151], v[164:165], v[198:199] neg_lo:[0,1] neg_hi:[0,1]
	v_pk_add_f32 v[158:159], v[158:159], v[188:189]
	v_pk_add_f32 v[160:161], v[160:161], v[190:191]
	v_pk_add_f32 v[162:163], v[162:163], v[196:197]
	v_pk_add_f32 v[164:165], v[164:165], v[198:199]
	ds_write2_b64 v124, v[158:159], v[160:161] offset1:136
	ds_write2_b64 v156, v[162:163], v[164:165] offset0:16 offset1:152
	ds_write2_b64 v134, v[152:153], v[154:155] offset0:32 offset1:168
	ds_write2_b64 v132, v[148:149], v[150:151] offset0:48 offset1:184
	s_mov_b64 s[6:7], 0
	s_waitcnt lgkmcnt(0)
	s_barrier
	s_mov_b32 s0, 0
	s_mov_b64 s[6:7], -1
; #define LAS __attribute__((address_space(3)))
; __device__ __forceinline__ cf twc(cf ws, int k16) { if (k16 == 0) return ws; if (k16 == 4) return cf{ws.y, -ws.x}; return cmul(ws, cf{c16(k16), -s16(k16)}); }
; template <int LR> __device__ __forceinline__ void dit_reg(cf (&x)[1 << LR], cf w) {
;     constexpr int R = 1 << LR; cf wsv[LR]; wsv[0] = w;
; #pragma unroll
;     for (int s = 1; s < LR; ++s) wsv[s] = cmul(wsv[s - 1], wsv[s - 1]);
; #pragma unroll
;     for (int s = LR - 1; s >= 0; --s) { const int half = R >> (s + 1);
; #pragma unroll
;         for (int m0 = 0; m0 < R; m0 += 2 * half)
; #pragma unroll
;             for (int mm = 0; mm < half; ++mm) { const int ia = m0 + mm, ib = ia + half; const cf a = x[ia];
;                 const cf b = cmulc(x[ib], twc(wsv[s], (mm << s) * (16 / R)));
;                 x[ia] = cf{a.x + b.x, a.y + b.y}; x[ib] = cf{a.x - b.x, a.y - b.y}; } }
; }
; __device__ __forceinline__ void lds_barrier() { asm volatile("s_waitcnt lgkmcnt(0)\n\ts_barrier" ::: "memory"); }
; template <int LR, bool INV> __device__ __forceinline__ void fft_pass(ldsf2 buf, int base, int stride, int twi) {
;     constexpr int R = 1 << LR; cf x[R];
;     const v2f wv = ((ldsf2)((LAS unsigned char*)buf + 139264))[twi];
; #pragma unroll
;     for (int m = 0; m < R; ++m) { const v2f v = buf[base + m * stride]; x[m] = cf{v.x, v.y}; }
;     const cf w{wv.x, wv.y};
;     if (INV) dit_reg<LR>(x, w); else dif_reg<LR>(x, w);
; #pragma unroll
;     for (int m = 0; m < R; ++m) buf[base + m * stride] = mkv2(x[m].x, x[m].y);
; }
; __device__ __forceinline__ void fft_inv_cba(ldsf2 buf) {
;     ...
;     for (int u = 0; u < 2; ++u) { const int bf = tid + NT * u; fft_pass<3, true>(buf, bf + (bf >> 4), 1088, bf); }
.LBB0_357:
	v_add_u32_e32 v69, s0, v68
	v_ashrrev_i32_e32 v72, 4, v69
	v_lshl_add_u32 v69, v69, 3, 0
	v_add_u32_e32 v73, 0x22000, v69
	ds_read_b64 v[88:89], v73
	v_lshl_add_u32 v69, v72, 3, v69
	ds_read2st64_b64 v[72:75], v69 offset1:17
	ds_read2st64_b64 v[76:79], v69 offset0:34 offset1:51
	ds_read2st64_b64 v[80:83], v69 offset0:68 offset1:85
	ds_read2st64_b64 v[84:87], v69 offset0:102 offset1:119
	s_movk_i32 s0, 0x200
	v_add_u32_e32 v118, s0, v68
	v_ashrrev_i32_e32 v120, 4, v118
	v_lshl_add_u32 v118, v118, 3, 0
	v_add_u32_e32 v122, 0x22000, v118
	ds_read_b64 v[124:125], v122
	v_lshl_add_u32 v118, v120, 3, v118
	ds_read2st64_b64 v[126:129], v118 offset1:17
	ds_read2st64_b64 v[130:133], v118 offset0:34 offset1:51
	ds_read2st64_b64 v[148:151], v118 offset0:68 offset1:85
	ds_read2st64_b64 v[152:155], v118 offset0:102 offset1:119
	s_waitcnt lgkmcnt(5)
	v_pk_add_f32 v[90:91], v[88:89], v[88:89] op_sel:[0,1] op_sel_hi:[1,0] neg_lo:[0,0] neg_hi:[0,1]
	v_pk_mul_f32 v[92:93], v[90:91], s[16:17] op_sel:[0,0] op_sel_hi:[1,0]
	v_pk_mul_f32 v[94:95], v[90:91], s[16:17] op_sel:[1,0] op_sel_hi:[0,0] neg_lo:[0,0] neg_hi:[1,0]
	v_pk_mul_f32 v[96:97], v[88:89], v[88:89] op_sel:[1,1] op_sel_hi:[1,0]
	v_pk_fma_f32 v[96:97], v[88:89], v[88:89], v[96:97] op_sel:[0,0,0] op_sel_hi:[0,1,1] neg_lo:[0,0,1] neg_hi:[0,0,0]
	v_pk_mul_f32 v[98:99], v[96:97], v[96:97] op_sel:[1,1] op_sel_hi:[1,0]
	v_pk_fma_f32 v[98:99], v[96:97], v[96:97], v[98:99] op_sel:[0,0,0] op_sel_hi:[0,1,1] neg_lo:[0,0,1] neg_hi:[0,0,0]
	v_pk_mul_f32 v[100:101], v[74:75], v[98:99] op_sel:[1,1] op_sel_hi:[1,0]
	v_pk_mul_f32 v[102:103], v[78:79], v[98:99] op_sel:[1,1] op_sel_hi:[1,0]
	v_pk_mul_f32 v[104:105], v[82:83], v[98:99] op_sel:[1,1] op_sel_hi:[1,0]
	v_pk_mul_f32 v[106:107], v[86:87], v[98:99] op_sel:[1,1] op_sel_hi:[1,0]
	v_pk_fma_f32 v[100:101], v[74:75], v[98:99], v[100:101] op_sel:[0,0,0] op_sel_hi:[0,1,1] neg_lo:[0,0,0] neg_hi:[0,1,0]
	v_pk_fma_f32 v[102:103], v[78:79], v[98:99], v[102:103] op_sel:[0,0,0] op_sel_hi:[0,1,1] neg_lo:[0,0,0] neg_hi:[0,1,0]
	v_pk_fma_f32 v[104:105], v[82:83], v[98:99], v[104:105] op_sel:[0,0,0] op_sel_hi:[0,1,1] neg_lo:[0,0,0] neg_hi:[0,1,0]
	v_pk_fma_f32 v[106:107], v[86:87], v[98:99], v[106:107] op_sel:[0,0,0] op_sel_hi:[0,1,1] neg_lo:[0,0,0] neg_hi:[0,1,0]
	v_pk_add_f32 v[74:75], v[72:73], v[100:101] neg_lo:[0,1] neg_hi:[0,1]
	v_pk_add_f32 v[78:79], v[76:77], v[102:103] neg_lo:[0,1] neg_hi:[0,1]
	v_pk_add_f32 v[82:83], v[80:81], v[104:105] neg_lo:[0,1] neg_hi:[0,1]
	v_pk_add_f32 v[86:87], v[84:85], v[106:107] neg_lo:[0,1] neg_hi:[0,1]
	v_pk_add_f32 v[72:73], v[72:73], v[100:101]
	v_pk_add_f32 v[76:77], v[76:77], v[102:103]
	v_pk_add_f32 v[80:81], v[80:81], v[104:105]
	v_pk_add_f32 v[84:85], v[84:85], v[106:107]
	v_pk_mul_f32 v[100:101], v[76:77], v[96:97] op_sel:[1,1] op_sel_hi:[1,0]
	v_pk_mul_f32 v[102:103], v[78:79], v[96:97] op_sel:[1,0] op_sel_hi:[1,1]
	v_pk_mul_f32 v[104:105], v[84:85], v[96:97] op_sel:[1,1] op_sel_hi:[1,0]
	v_pk_mul_f32 v[106:107], v[86:87], v[96:97] op_sel:[1,0] op_sel_hi:[1,1]
	v_pk_fma_f32 v[100:101], v[76:77], v[96:97], v[100:101] op_sel:[0,0,0] op_sel_hi:[0,1,1] neg_lo:[0,0,0] neg_hi:[0,1,0]
	v_pk_fma_f32 v[102:103], v[78:79], v[96:97], v[102:103] op_sel:[0,1,0] op_sel_hi:[0,0,1] neg_lo:[0,0,1] neg_hi:[0,0,0]
	v_pk_fma_f32 v[104:105], v[84:85], v[96:97], v[104:105] op_sel:[0,0,0] op_sel_hi:[0,1,1] neg_lo:[0,0,0] neg_hi:[0,1,0]
	v_pk_fma_f32 v[106:107], v[86:87], v[96:97], v[106:107] op_sel:[0,1,0] op_sel_hi:[0,0,1] neg_lo:[0,0,1] neg_hi:[0,0,0]
	v_pk_add_f32 v[76:77], v[72:73], v[100:101] neg_lo:[0,1] neg_hi:[0,1]
	v_pk_add_f32 v[78:79], v[74:75], v[102:103] neg_lo:[0,1] neg_hi:[0,1]
	v_pk_add_f32 v[84:85], v[80:81], v[104:105] neg_lo:[0,1] neg_hi:[0,1]
	v_pk_add_f32 v[86:87], v[82:83], v[106:107] neg_lo:[0,1] neg_hi:[0,1]
	v_pk_add_f32 v[72:73], v[72:73], v[100:101]
	v_pk_add_f32 v[74:75], v[74:75], v[102:103]
	v_pk_add_f32 v[80:81], v[80:81], v[104:105]
	v_pk_add_f32 v[82:83], v[82:83], v[106:107]
	v_pk_mul_f32 v[100:101], v[80:81], v[88:89] op_sel:[1,1] op_sel_hi:[1,0]
	v_pk_mul_f32 v[102:103], v[82:83], v[92:93] op_sel:[1,1] op_sel_hi:[1,0]
	v_pk_mul_f32 v[104:105], v[84:85], v[88:89] op_sel:[1,0] op_sel_hi:[1,1]
	v_pk_mul_f32 v[106:107], v[86:87], v[94:95] op_sel:[1,1] op_sel_hi:[1,0]
	v_pk_fma_f32 v[100:101], v[80:81], v[88:89], v[100:101] op_sel:[0,0,0] op_sel_hi:[0,1,1] neg_lo:[0,0,0] neg_hi:[0,1,0]
	v_pk_fma_f32 v[102:103], v[82:83], v[92:93], v[102:103] op_sel:[0,0,0] op_sel_hi:[0,1,1] neg_lo:[0,0,0] neg_hi:[0,1,0]
	v_pk_fma_f32 v[104:105], v[84:85], v[88:89], v[104:105] op_sel:[0,1,0] op_sel_hi:[0,0,1] neg_lo:[0,0,1] neg_hi:[0,0,0]
	v_pk_fma_f32 v[106:107], v[86:87], v[94:95], v[106:107] op_sel:[0,0,0] op_sel_hi:[0,1,1] neg_lo:[0,0,0] neg_hi:[0,1,0]
	v_pk_add_f32 v[80:81], v[72:73], v[100:101] neg_lo:[0,1] neg_hi:[0,1]
	v_pk_add_f32 v[82:83], v[74:75], v[102:103] neg_lo:[0,1] neg_hi:[0,1]
	v_pk_add_f32 v[84:85], v[76:77], v[104:105] neg_lo:[0,1] neg_hi:[0,1]
	v_pk_add_f32 v[86:87], v[78:79], v[106:107] neg_lo:[0,1] neg_hi:[0,1]
	v_pk_add_f32 v[72:73], v[72:73], v[100:101]
	v_pk_add_f32 v[74:75], v[74:75], v[102:103]
	v_pk_add_f32 v[76:77], v[76:77], v[104:105]
	v_pk_add_f32 v[78:79], v[78:79], v[106:107]
	ds_write2st64_b64 v69, v[72:73], v[74:75] offset1:17
	ds_write2st64_b64 v69, v[76:77], v[78:79] offset0:34 offset1:51
	ds_write2st64_b64 v69, v[80:81], v[82:83] offset0:68 offset1:85
	ds_write2st64_b64 v69, v[84:85], v[86:87] offset0:102 offset1:119
	s_waitcnt lgkmcnt(4)
; #define LAS __attribute__((address_space(3)))
; __device__ __forceinline__ cf twc(cf ws, int k16) { if (k16 == 0) return ws; if (k16 == 4) return cf{ws.y, -ws.x}; return cmul(ws, cf{c16(k16), -s16(k16)}); }
; template <int LR> __device__ __forceinline__ void dit_reg(cf (&x)[1 << LR], cf w) {
;     constexpr int R = 1 << LR; cf wsv[LR]; wsv[0] = w;
; #pragma unroll
;     for (int s = 1; s < LR; ++s) wsv[s] = cmul(wsv[s - 1], wsv[s - 1]);
; #pragma unroll
;     for (int s = LR - 1; s >= 0; --s) { const int half = R >> (s + 1);
; #pragma unroll
;         for (int m0 = 0; m0 < R; m0 += 2 * half)
; #pragma unroll
;             for (int mm = 0; mm < half; ++mm) { const int ia = m0 + mm, ib = ia + half; const cf a = x[ia];
;                 const cf b = cmulc(x[ib], twc(wsv[s], (mm << s) * (16 / R)));
;                 x[ia] = cf{a.x + b.x, a.y + b.y}; x[ib] = cf{a.x - b.x, a.y - b.y}; } }
; }
; __device__ __forceinline__ void lds_barrier() { asm volatile("s_waitcnt lgkmcnt(0)\n\ts_barrier" ::: "memory"); }
; template <int LR, bool INV> __device__ __forceinline__ void fft_pass(ldsf2 buf, int base, int stride, int twi) {
;     constexpr int R = 1 << LR; cf x[R];
;     const v2f wv = ((ldsf2)((LAS unsigned char*)buf + 139264))[twi];
; #pragma unroll
;     for (int m = 0; m < R; ++m) { const v2f v = buf[base + m * stride]; x[m] = cf{v.x, v.y}; }
;     const cf w{wv.x, wv.y};
;     if (INV) dit_reg<LR>(x, w); else dif_reg<LR>(x, w);
; #pragma unroll
;     for (int m = 0; m < R; ++m) buf[base + m * stride] = mkv2(x[m].x, x[m].y);
; }
; __device__ __forceinline__ void fft_inv_cba(ldsf2 buf) {
;     ...
;     for (int u = 0; u < 2; ++u) { const int bf = tid + NT * u; fft_pass<3, true>(buf, bf + (bf >> 4), 1088, bf); }
	v_pk_add_f32 v[134:135], v[124:125], v[124:125] op_sel:[0,1] op_sel_hi:[1,0] neg_lo:[0,0] neg_hi:[0,1]
	v_pk_mul_f32 v[156:157], v[134:135], s[16:17] op_sel:[0,0] op_sel_hi:[1,0]
	v_pk_mul_f32 v[158:159], v[134:135], s[16:17] op_sel:[1,0] op_sel_hi:[0,0] neg_lo:[0,0] neg_hi:[1,0]
	v_pk_mul_f32 v[160:161], v[124:125], v[124:125] op_sel:[1,1] op_sel_hi:[1,0]
	v_pk_fma_f32 v[160:161], v[124:125], v[124:125], v[160:161] op_sel:[0,0,0] op_sel_hi:[0,1,1] neg_lo:[0,0,1] neg_hi:[0,0,0]
	v_pk_mul_f32 v[162:163], v[160:161], v[160:161] op_sel:[1,1] op_sel_hi:[1,0]
	v_pk_fma_f32 v[162:163], v[160:161], v[160:161], v[162:163] op_sel:[0,0,0] op_sel_hi:[0,1,1] neg_lo:[0,0,1] neg_hi:[0,0,0]
	v_pk_mul_f32 v[164:165], v[128:129], v[162:163] op_sel:[1,1] op_sel_hi:[1,0]
	v_pk_mul_f32 v[166:167], v[132:133], v[162:163] op_sel:[1,1] op_sel_hi:[1,0]
	v_pk_mul_f32 v[168:169], v[150:151], v[162:163] op_sel:[1,1] op_sel_hi:[1,0]
	v_pk_mul_f32 v[170:171], v[154:155], v[162:163] op_sel:[1,1] op_sel_hi:[1,0]
	v_pk_fma_f32 v[164:165], v[128:129], v[162:163], v[164:165] op_sel:[0,0,0] op_sel_hi:[0,1,1] neg_lo:[0,0,0] neg_hi:[0,1,0]
	v_pk_fma_f32 v[166:167], v[132:133], v[162:163], v[166:167] op_sel:[0,0,0] op_sel_hi:[0,1,1] neg_lo:[0,0,0] neg_hi:[0,1,0]
	v_pk_fma_f32 v[168:169], v[150:151], v[162:163], v[168:169] op_sel:[0,0,0] op_sel_hi:[0,1,1] neg_lo:[0,0,0] neg_hi:[0,1,0]
	v_pk_fma_f32 v[170:171], v[154:155], v[162:163], v[170:171] op_sel:[0,0,0] op_sel_hi:[0,1,1] neg_lo:[0,0,0] neg_hi:[0,1,0]
	v_pk_add_f32 v[128:129], v[126:127], v[164:165] neg_lo:[0,1] neg_hi:[0,1]
	v_pk_add_f32 v[132:133], v[130:131], v[166:167] neg_lo:[0,1] neg_hi:[0,1]
	v_pk_add_f32 v[150:151], v[148:149], v[168:169] neg_lo:[0,1] neg_hi:[0,1]
	v_pk_add_f32 v[154:155], v[152:153], v[170:171] neg_lo:[0,1] neg_hi:[0,1]
	v_pk_add_f32 v[126:127], v[126:127], v[164:165]
	v_pk_add_f32 v[130:131], v[130:131], v[166:167]
	v_pk_add_f32 v[148:149], v[148:149], v[168:169]
	v_pk_add_f32 v[152:153], v[152:153], v[170:171]
	v_pk_mul_f32 v[164:165], v[130:131], v[160:161] op_sel:[1,1] op_sel_hi:[1,0]
	v_pk_mul_f32 v[166:167], v[132:133], v[160:161] op_sel:[1,0] op_sel_hi:[1,1]
	v_pk_mul_f32 v[168:169], v[152:153], v[160:161] op_sel:[1,1] op_sel_hi:[1,0]
	v_pk_mul_f32 v[170:171], v[154:155], v[160:161] op_sel:[1,0] op_sel_hi:[1,1]
	v_pk_fma_f32 v[164:165], v[130:131], v[160:161], v[164:165] op_sel:[0,0,0] op_sel_hi:[0,1,1] neg_lo:[0,0,0] neg_hi:[0,1,0]
	v_pk_fma_f32 v[166:167], v[132:133], v[160:161], v[166:167] op_sel:[0,1,0] op_sel_hi:[0,0,1] neg_lo:[0,0,1] neg_hi:[0,0,0]
	v_pk_fma_f32 v[168:169], v[152:153], v[160:161], v[168:169] op_sel:[0,0,0] op_sel_hi:[0,1,1] neg_lo:[0,0,0] neg_hi:[0,1,0]
	v_pk_fma_f32 v[170:171], v[154:155], v[160:161], v[170:171] op_sel:[0,1,0] op_sel_hi:[0,0,1] neg_lo:[0,0,1] neg_hi:[0,0,0]
	v_pk_add_f32 v[130:131], v[126:127], v[164:165] neg_lo:[0,1] neg_hi:[0,1]
	v_pk_add_f32 v[132:133], v[128:129], v[166:167] neg_lo:[0,1] neg_hi:[0,1]
	v_pk_add_f32 v[152:153], v[148:149], v[168:169] neg_lo:[0,1] neg_hi:[0,1]
	v_pk_add_f32 v[154:155], v[150:151], v[170:171] neg_lo:[0,1] neg_hi:[0,1]
	v_pk_add_f32 v[126:127], v[126:127], v[164:165]
	v_pk_add_f32 v[128:129], v[128:129], v[166:167]
	v_pk_add_f32 v[148:149], v[148:149], v[168:169]
	v_pk_add_f32 v[150:151], v[150:151], v[170:171]
	v_pk_mul_f32 v[164:165], v[148:149], v[124:125] op_sel:[1,1] op_sel_hi:[1,0]
	v_pk_mul_f32 v[166:167], v[150:151], v[156:157] op_sel:[1,1] op_sel_hi:[1,0]
	v_pk_mul_f32 v[168:169], v[152:153], v[124:125] op_sel:[1,0] op_sel_hi:[1,1]
	v_pk_mul_f32 v[170:171], v[154:155], v[158:159] op_sel:[1,1] op_sel_hi:[1,0]
	v_pk_fma_f32 v[164:165], v[148:149], v[124:125], v[164:165] op_sel:[0,0,0] op_sel_hi:[0,1,1] neg_lo:[0,0,0] neg_hi:[0,1,0]
	v_pk_fma_f32 v[166:167], v[150:151], v[156:157], v[166:167] op_sel:[0,0,0] op_sel_hi:[0,1,1] neg_lo:[0,0,0] neg_hi:[0,1,0]
	v_pk_fma_f32 v[168:169], v[152:153], v[124:125], v[168:169] op_sel:[0,1,0] op_sel_hi:[0,0,1] neg_lo:[0,0,1] neg_hi:[0,0,0]
	v_pk_fma_f32 v[170:171], v[154:155], v[158:159], v[170:171] op_sel:[0,0,0] op_sel_hi:[0,1,1] neg_lo:[0,0,0] neg_hi:[0,1,0]
	v_pk_add_f32 v[148:149], v[126:127], v[164:165] neg_lo:[0,1] neg_hi:[0,1]
	v_pk_add_f32 v[150:151], v[128:129], v[166:167] neg_lo:[0,1] neg_hi:[0,1]
	v_pk_add_f32 v[152:153], v[130:131], v[168:169] neg_lo:[0,1] neg_hi:[0,1]
	v_pk_add_f32 v[154:155], v[132:133], v[170:171] neg_lo:[0,1] neg_hi:[0,1]
	v_pk_add_f32 v[126:127], v[126:127], v[164:165]
	v_pk_add_f32 v[128:129], v[128:129], v[166:167]
	v_pk_add_f32 v[130:131], v[130:131], v[168:169]
	v_pk_add_f32 v[132:133], v[132:133], v[170:171]
	ds_write2st64_b64 v118, v[126:127], v[128:129] offset1:17
	ds_write2st64_b64 v118, v[130:131], v[132:133] offset0:34 offset1:51
	ds_write2st64_b64 v118, v[148:149], v[150:151] offset0:68 offset1:85
	ds_write2st64_b64 v118, v[152:153], v[154:155] offset0:102 offset1:119
	s_mov_b64 s[6:7], 0
	s_waitcnt vmcnt(5)
	v_lshlrev_b32_e32 v68, 16, v143
	v_cndmask_b32_e64 v69, 0, v68, s[42:43]
	s_waitcnt vmcnt(3)
; __device__ __forceinline__ float bf2f(bf16_t b) { return __uint_as_float(((unsigned)b) << 16); }
; __device__ __forceinline__ void sconv8(const Raw8& r, int n0, float w0, float w1, float w2, float b, float (&out)[8]) {
;     float a[10]; a[0] = n0 > 0 ? bf2f(r.eL) : 0.f; a[9] = n0 + 8 < SEQ ? bf2f(r.eR) : 0.f;
;     a[1] = __uint_as_float(r.body.x << 16); a[2] = __uint_as_float(r.body.x & 0xffff0000u); a[3] = __uint_as_float(r.body.y << 16); a[4] = __uint_as_float(r.body.y & 0xffff0000u);
;     a[5] = __uint_as_float(r.body.z << 16); a[6] = __uint_as_float(r.body.z & 0xffff0000u); a[7] = __uint_as_float(r.body.w << 16); a[8] = __uint_as_float(r.body.w & 0xffff0000u);
; #pragma unroll
;     for (int k = 0; k < 8; ++k) out[k] = w0 * a[k] + w1 * a[k + 1] + w2 * a[k + 2] + b;
	v_lshlrev_b32_e32 v68, 16, v144
	v_lshlrev_b32_e32 v75, 16, v5
	v_cndmask_b32_e64 v73, 0, v68, s[44:45]
	v_lshlrev_b32_e32 v74, 16, v4
	v_and_b32_e32 v76, 0xffff0000, v4
	v_mov_b32_e32 v68, v75
	v_and_b32_e32 v77, 0xffff0000, v5
	v_mov_b32_e32 v80, v74
	v_mov_b32_e32 v81, v76
	v_pk_mul_f32 v[68:69], v[56:57], v[68:69]
	v_lshlrev_b32_e32 v79, 16, v6
	v_pk_fma_f32 v[68:69], v[56:57], v[80:81], v[68:69] op_sel:[0,0,1] op_sel_hi:[1,1,0]
	v_pk_mul_f32 v[80:81], v[32:33], v[76:77]
	v_and_b32_e32 v5, 0xffff0000, v7
	v_mov_b32_e32 v78, v75
	v_pk_fma_f32 v[74:75], v[30:31], v[74:75], v[80:81]
	v_and_b32_e32 v81, 16, v7
	v_and_b32_e32 v80, 0xffff0000, v6
	v_lshlrev_b32_e32 v7, 16, v7
	v_pk_fma_f32 v[68:69], v[34:35], v[76:77], v[68:69]
	v_mov_b32_e32 v6, v80
	v_mov_b32_e32 v4, v80
	v_pk_mov_b32 v[76:77], v[76:77], v[80:81] op_sel:[1,0]
	v_mov_b32_e32 v80, v79
	v_mov_b32_e32 v81, v7
	v_pk_mul_f32 v[80:81], v[32:33], v[80:81]
	v_pk_fma_f32 v[74:75], v[34:35], v[78:79], v[74:75]
	v_pk_fma_f32 v[76:77], v[30:31], v[76:77], v[80:81]
	v_mov_b32_e32 v78, v5
	v_pk_fma_f32 v[80:81], v[34:35], v[4:5], v[76:77]
	v_pk_mul_f32 v[4:5], v[56:57], v[78:79]
	v_mov_b32_e32 v72, v7
	v_pk_fma_f32 v[4:5], v[56:57], v[6:7], v[4:5] op_sel:[0,0,1] op_sel_hi:[1,1,0]
	s_waitcnt vmcnt(1)
	v_lshlrev_b32_e32 v77, 16, v1
	v_pk_fma_f32 v[72:73], v[34:35], v[72:73], v[4:5]
	v_lshlrev_b32_e32 v4, 16, v139
	v_cndmask_b32_e64 v5, 0, v4, s[42:43]
	s_waitcnt vmcnt(0)
	v_lshlrev_b32_e32 v4, 16, v141
	v_cndmask_b32_e64 v7, 0, v4, s[44:45]
	v_lshlrev_b32_e32 v76, 16, v0
	v_and_b32_e32 v78, 0xffff0000, v0
	v_mov_b32_e32 v4, v77
	v_mov_b32_e32 v84, v76
	v_mov_b32_e32 v85, v78
	v_pk_mul_f32 v[4:5], v[56:57], v[4:5]
	v_and_b32_e32 v79, 0xffff0000, v1
	v_pk_fma_f32 v[4:5], v[56:57], v[84:85], v[4:5] op_sel:[0,0,1] op_sel_hi:[1,1,0]
	v_lshlrev_b32_e32 v83, 16, v2
	v_pk_fma_f32 v[84:85], v[34:35], v[78:79], v[4:5]
	v_pk_mul_f32 v[4:5], v[32:33], v[78:79]
	v_mov_b32_e32 v82, v77
	v_pk_fma_f32 v[4:5], v[30:31], v[76:77], v[4:5]
	v_and_b32_e32 v1, 0xffff0000, v3
	v_pk_fma_f32 v[86:87], v[34:35], v[82:83], v[4:5]
	v_and_b32_e32 v5, 16, v3
	v_lshlrev_b32_e32 v3, 16, v3
	v_and_b32_e32 v4, 0xffff0000, v2
	v_mov_b32_e32 v76, v83
	v_mov_b32_e32 v77, v3
	v_mov_b32_e32 v2, v4
	v_mov_b32_e32 v0, v4
	v_pk_mov_b32 v[4:5], v[78:79], v[4:5] op_sel:[1,0]
	v_pk_mul_f32 v[76:77], v[32:33], v[76:77]
	v_mov_b32_e32 v82, v1
	v_pk_fma_f32 v[4:5], v[30:31], v[4:5], v[76:77]
	s_waitcnt lgkmcnt(0)
	s_barrier
; __device__ __forceinline__ uint4 ntld_u4(const void* p) { const ntu4_t v = __builtin_nontemporal_load((const ntu4_t*)p); return make_uint4(v.x, v.y, v.z, v.w); }
; __device__ __forceinline__ void lds_barrier() { asm volatile("s_waitcnt lgkmcnt(0)\n\ts_barrier" ::: "memory"); }
; __device__ void ph_hyena_fft(const Params& P, int j, const bf16_t* __restrict__ projAT, const float* __restrict__ kf, bf16_t* __restrict__ yaT, unsigned char* lds_raw) {
;     ...
;             const size_t o0 = (size_t)(2 * bp) * SEQ, o1 = o0 + SEQ;
;             float va[8], vb[8];
;             { const Raw8 r0 = load_raw8(vrow + o0, n0), r1 = load_raw8(vrow + o1, n0); sconv8(r0, n0, wv0, wv1, wv2, bv, va); sconv8(r1, n0, wv0, wv1, wv2, bv, vb); }
; #pragma unroll
;             for (int k = 0; k < 8; ++k) { buf[ph0 + k] = mkv2(va[k], vb[k]); buf[ph0 + 4352 + k] = mkv2(0.f, 0.f); }
;             const Raw8 xa0 = load_raw8(x1row + o0, n0), xa1 = load_raw8(x1row + o1, n0);
;             lds_barrier();
;             fft_conv(buf, spec1);
;             { float xa[8], xb[8]; sconv8(xa0, n0, wa0, wa1, wa2, ba, xa); sconv8(xa1, n0, wa0, wa1, wa2, ba, xb);
; #pragma unroll
;               for (int k = 0; k < 8; ++k) { const v2f y = buf[ph0 + k]; va[k] = xa[k] * (y.x * invN + sk0 * va[k]); vb[k] = xb[k] * (y.y * invN + sk0 * vb[k]);
;                   buf[ph0 + k] = mkv2(va[k], vb[k]); buf[ph0 + 4352 + k] = mkv2(0.f, 0.f); } }
;             const Raw8 xb0 = load_raw8(x2row + o0, n0), xb1 = load_raw8(x2row + o1, n0);
;             const uint4 g0 = ntld_u4(grow + o0 + n0), g1 = ntld_u4(grow + o1 + n0);
	v_mov_b32_e32 v6, v3
	v_pk_fma_f32 v[78:79], v[34:35], v[0:1], v[4:5]
	v_pk_mul_f32 v[0:1], v[56:57], v[82:83]
	v_pk_add_f32 v[74:75], v[36:37], v[74:75]
	v_pk_fma_f32 v[0:1], v[56:57], v[2:3], v[0:1] op_sel:[0,0,1] op_sel_hi:[1,1,0]
	v_pk_add_f32 v[68:69], v[36:37], v[68:69]
	v_pk_fma_f32 v[82:83], v[34:35], v[6:7], v[0:1]
	ds_read2_b64 v[0:3], v145 offset1:1
	ds_read2_b64 v[4:7], v145 offset0:2 offset1:3
	s_mov_b32 s14, 0
	s_mov_b32 s15, s14
	s_mov_b32 s0, s14
	s_waitcnt lgkmcnt(1)
	v_mov_b32_e32 v76, v0
	s_waitcnt lgkmcnt(0)
	v_mov_b32_e32 v77, v4
	v_mov_b32_e32 v4, v1
	v_pk_mul_f32 v[0:1], v[4:5], s[80:81] op_sel_hi:[1,0]
	v_mov_b32_e32 v4, v2
	v_mov_b32_e32 v5, v6
	v_pk_mul_f32 v[4:5], v[4:5], s[80:81] op_sel_hi:[1,0]
	v_pk_mul_f32 v[76:77], v[76:77], s[80:81] op_sel_hi:[1,0]
	v_pk_fma_f32 v[4:5], v[44:45], v[62:63], v[4:5]
	v_mov_b32_e32 v6, v3
	v_pk_fma_f32 v[64:65], v[44:45], v[64:65], v[76:77]
	v_pk_mul_f32 v[74:75], v[74:75], v[4:5]
	v_pk_mul_f32 v[2:3], v[6:7], s[80:81] op_sel_hi:[1,0]
	v_pk_add_f32 v[4:5], v[36:37], v[84:85]
	v_pk_fma_f32 v[0:1], v[44:45], v[66:67], v[0:1]
	v_pk_mul_f32 v[76:77], v[68:69], v[64:65]
	v_pk_add_f32 v[6:7], v[36:37], v[86:87]
	v_pk_mul_f32 v[68:69], v[4:5], v[0:1]
	v_pk_fma_f32 v[0:1], v[44:45], v[70:71], v[2:3]
	s_mov_b32 s1, s14
	v_pk_mul_f32 v[66:67], v[6:7], v[0:1]
	v_mov_b32_e32 v0, v76
	v_mov_b32_e32 v1, v68
	v_mov_b32_e32 v2, v74
	v_mov_b32_e32 v3, v66
	v_mov_b64_e32 v[88:89], s[14:15]
	v_mov_b64_e32 v[90:91], s[0:1]
	ds_write2_b64 v145, v[0:1], v[2:3] offset1:1
	v_mov_b32_e32 v0, v77
	v_mov_b32_e32 v1, v69
	v_mov_b32_e32 v2, v75
	v_mov_b32_e32 v3, v67
	ds_write2_b64 v142, v[88:89], v[90:91] offset1:1
	ds_write2_b64 v145, v[0:1], v[2:3] offset0:2 offset1:3
	ds_write2_b64 v138, v[88:89], v[90:91] offset1:1
	ds_read2_b64 v[0:3], v145 offset0:4 offset1:5
	ds_read2_b64 v[4:7], v145 offset0:6 offset1:7
	v_pk_add_f32 v[70:71], v[36:37], v[72:73]
	v_pk_add_f32 v[64:65], v[36:37], v[80:81]
	s_lshl_b32 s62, s11, 1
	s_waitcnt lgkmcnt(1)
	v_mov_b32_e32 v62, v0
	s_waitcnt lgkmcnt(0)
	v_mov_b32_e32 v63, v4
	v_mov_b32_e32 v4, v1
	v_pk_mul_f32 v[0:1], v[4:5], s[80:81] op_sel_hi:[1,0]
	v_mov_b32_e32 v4, v2
	v_mov_b32_e32 v5, v6
	v_pk_mul_f32 v[4:5], v[4:5], s[80:81] op_sel_hi:[1,0]
	v_pk_mul_f32 v[62:63], v[62:63], s[80:81] op_sel_hi:[1,0]
	v_pk_fma_f32 v[4:5], v[44:45], v[10:11], v[4:5]
	v_mov_b32_e32 v6, v3
	v_pk_fma_f32 v[8:9], v[44:45], v[8:9], v[62:63]
	v_pk_mul_f32 v[70:71], v[70:71], v[4:5]
	v_pk_mul_f32 v[2:3], v[6:7], s[80:81] op_sel_hi:[1,0]
	v_pk_add_f32 v[4:5], v[36:37], v[78:79]
	v_pk_fma_f32 v[0:1], v[44:45], v[12:13], v[0:1]
	v_pk_mul_f32 v[72:73], v[64:65], v[8:9]
	v_pk_add_f32 v[6:7], v[36:37], v[82:83]
	v_pk_mul_f32 v[64:65], v[4:5], v[0:1]
	v_pk_fma_f32 v[0:1], v[44:45], v[14:15], v[2:3]
	v_mov_b32_e32 v2, v70
	v_pk_mul_f32 v[62:63], v[6:7], v[0:1]
	v_mov_b32_e32 v0, v72
	v_mov_b32_e32 v1, v64
	v_mov_b32_e32 v3, v62
	s_add_u32 s0, s61, s62
	ds_write2_b64 v145, v[0:1], v[2:3] offset0:4 offset1:5
	v_mov_b32_e32 v0, v73
	v_mov_b32_e32 v1, v65
	v_mov_b32_e32 v2, v71
	v_mov_b32_e32 v3, v63
	s_addc_u32 s1, s52, 0
	ds_write2_b64 v140, v[88:89], v[90:91] offset1:1
	ds_write2_b64 v145, v[0:1], v[2:3] offset0:6 offset1:7
	ds_write2_b64 v137, v[88:89], v[90:91] offset1:1
	v_lshl_add_u64 v[0:1], s[0:1], 0, v[16:17]
	s_lshl_b32 s6, s10, 1
	global_load_dwordx4 v[4:7], v[0:1], off nt
	global_load_ushort v147, v146, s[0:1] offset:-2
	v_lshl_add_u64 v[0:1], s[0:1], 0, v[22:23]
	s_add_u32 s0, s61, s6
	s_addc_u32 s1, s52, 0
	global_load_ushort v148, v[0:1], off offset:16
	v_lshl_add_u64 v[0:1], s[0:1], 0, v[16:17]
	global_load_dwordx4 v[8:11], v[0:1], off nt
	global_load_ushort v149, v146, s[0:1] offset:-2
	v_lshl_add_u64 v[0:1], s[0:1], 0, v[22:23]
	s_mov_b32 s7, s63
	global_load_ushort v150, v[0:1], off offset:16
	v_lshl_add_u64 v[0:1], v[48:49], 0, s[62:63]
	global_load_dwordx4 v[12:15], v[0:1], off nt
	v_lshl_add_u64 v[0:1], v[48:49], 0, s[6:7]
	global_load_dwordx4 v[0:3], v[0:1], off nt
	s_cmp_eq_u32 s53, 3
	s_cbranch_scc1 .Lhy_nopf
	s_add_i32 s100, s53, 1
	s_lshl_b32 s100, s100, 14
	s_add_u32 s100, s47, s100
	s_addc_u32 s101, s58, 0
	v_lshl_add_u64 v[188:189], s[100:101], 0, v[16:17]
	v_lshl_add_u64 v[190:191], s[100:101], 0, v[22:23]
	global_load_ushort v184, v146, s[100:101] offset:-2
	global_load_dwordx4 v[176:179], v[188:189], off nt
	s_add_u32 s100, s100, 0x2000
	s_addc_u32 s101, s101, 0
	v_lshl_add_u64 v[188:189], s[100:101], 0, v[22:23]
	global_load_ushort v185, v146, s[100:101] offset:-2
	global_load_ushort v186, v[188:189], off offset:16
	global_load_ushort v187, v[190:191], off offset:16
	v_lshl_add_u64 v[188:189], s[100:101], 0, v[16:17]
	global_load_dwordx4 v[180:183], v[188:189], off nt

; #define LAS __attribute__((address_space(3)))
; template <int LR> __device__ __forceinline__ void dif_reg(cf (&x)[1 << LR], cf w) {
;     constexpr int R = 1 << LR; cf ws = w;
; #pragma unroll
;     for (int s = 0; s < LR; ++s) { const int half = R >> (s + 1);
; #pragma unroll
;         for (int m0 = 0; m0 < R; m0 += 2 * half)
; #pragma unroll
;             for (int mm = 0; mm < half; ++mm) { const int ia = m0 + mm, ib = ia + half; const cf a = x[ia], b = x[ib];
;                 x[ia] = cf{a.x + b.x, a.y + b.y}; const cf d{a.x - b.x, a.y - b.y};
;                 x[ib] = cmul(d, twc(ws, (mm << s) * (16 / R))); }
;         ws = cmul(ws, ws); }
; }
; template <int LR> __device__ __forceinline__ void dit_reg(cf (&x)[1 << LR], cf w) {
;     constexpr int R = 1 << LR; cf wsv[LR]; wsv[0] = w;
; #pragma unroll
;     for (int s = 1; s < LR; ++s) wsv[s] = cmul(wsv[s - 1], wsv[s - 1]);
; #pragma unroll
;     for (int s = LR - 1; s >= 0; --s) { const int half = R >> (s + 1);
; #pragma unroll
;         for (int m0 = 0; m0 < R; m0 += 2 * half)
; #pragma unroll
;             for (int mm = 0; mm < half; ++mm) { const int ia = m0 + mm, ib = ia + half; const cf a = x[ia];
;                 const cf b = cmulc(x[ib], twc(wsv[s], (mm << s) * (16 / R)));
;                 x[ia] = cf{a.x + b.x, a.y + b.y}; x[ib] = cf{a.x - b.x, a.y - b.y}; } }
; }
; __device__ __forceinline__ void lds_barrier() { asm volatile("s_waitcnt lgkmcnt(0)\n\ts_barrier" ::: "memory"); }
; template <int LR, bool INV> __device__ __forceinline__ void fft_pass(ldsf2 buf, int base, int stride, int twi) {
;     constexpr int R = 1 << LR; cf x[R];
;     const v2f wv = ((ldsf2)((LAS unsigned char*)buf + 139264))[twi];
; #pragma unroll
;     for (int m = 0; m < R; ++m) { const v2f v = buf[base + m * stride]; x[m] = cf{v.x, v.y}; }
;     const cf w{wv.x, wv.y};
;     if (INV) dit_reg<LR>(x, w); else dif_reg<LR>(x, w);
; #pragma unroll
;     for (int m = 0; m < R; ++m) buf[base + m * stride] = mkv2(x[m].x, x[m].y);
; }
; __device__ __forceinline__ void wave_lds_fence() { asm volatile("s_waitcnt lgkmcnt(0)" ::: "memory"); }
; __device__ __forceinline__ void fft_fwd_abc(ldsf2 buf) {
;     const int tid = otid(); const int wv = tid >> 6, l = tid & 63;
; #pragma unroll 1
;     for (int u = 0; u < 2; ++u) { const int bf = tid + NT * u; fft_pass<3, false>(buf, bf + (bf >> 4), 1088, bf); }
.LBB0_359:
	v_add_u32_e32 v80, s14, v78
	v_ashrrev_i32_e32 v79, 4, v80
	v_lshl_add_u32 v80, v80, 3, 0
	v_add_u32_e32 v81, 0x22000, v80
	v_lshl_add_u32 v79, v79, 3, v80
	ds_read_b64 v[96:97], v81
	ds_read2st64_b64 v[80:83], v79 offset1:17
	ds_read2st64_b64 v[84:87], v79 offset0:68 offset1:85
	ds_read2st64_b64 v[88:91], v79 offset0:34 offset1:51
	ds_read2st64_b64 v[92:95], v79 offset0:102 offset1:119
	s_movk_i32 s14, 0x200
	v_add_u32_e32 v120, s14, v78
	v_ashrrev_i32_e32 v122, 4, v120
	v_lshl_add_u32 v120, v120, 3, 0
	v_add_u32_e32 v124, 0x22000, v120
	v_lshl_add_u32 v122, v122, 3, v120
	ds_read_b64 v[126:127], v124
	ds_read2st64_b64 v[128:131], v122 offset1:17
	ds_read2st64_b64 v[132:135], v122 offset0:68 offset1:85
	ds_read2st64_b64 v[136:139], v122 offset0:34 offset1:51
	ds_read2st64_b64 v[140:143], v122 offset0:102 offset1:119
	s_waitcnt lgkmcnt(5)
	v_pk_add_f32 v[98:99], v[96:97], v[96:97] op_sel:[0,1] op_sel_hi:[1,0] neg_lo:[0,0] neg_hi:[0,1]
	v_pk_mul_f32 v[100:101], v[98:99], s[16:17] op_sel:[0,0] op_sel_hi:[1,0]
	v_pk_mul_f32 v[102:103], v[98:99], s[16:17] op_sel:[1,0] op_sel_hi:[0,0] neg_lo:[0,0] neg_hi:[1,0]
	v_pk_mul_f32 v[104:105], v[96:97], v[96:97] op_sel:[1,1] op_sel_hi:[1,0]
	v_pk_fma_f32 v[104:105], v[96:97], v[96:97], v[104:105] op_sel:[0,0,0] op_sel_hi:[0,1,1] neg_lo:[0,0,1] neg_hi:[0,0,0]
	v_pk_mul_f32 v[106:107], v[104:105], v[104:105] op_sel:[1,1] op_sel_hi:[1,0]
	v_pk_fma_f32 v[106:107], v[104:105], v[104:105], v[106:107] op_sel:[0,0,0] op_sel_hi:[0,1,1] neg_lo:[0,0,1] neg_hi:[0,0,0]
	v_pk_add_f32 v[108:109], v[80:81], v[84:85] neg_lo:[0,1] neg_hi:[0,1]
	v_pk_add_f32 v[110:111], v[82:83], v[86:87] neg_lo:[0,1] neg_hi:[0,1]
	v_pk_add_f32 v[112:113], v[88:89], v[92:93] neg_lo:[0,1] neg_hi:[0,1]
	v_pk_add_f32 v[114:115], v[90:91], v[94:95] neg_lo:[0,1] neg_hi:[0,1]
	v_pk_add_f32 v[80:81], v[80:81], v[84:85]
	v_pk_add_f32 v[82:83], v[82:83], v[86:87]
	v_pk_add_f32 v[88:89], v[88:89], v[92:93]
	v_pk_add_f32 v[90:91], v[90:91], v[94:95]
	v_pk_mul_f32 v[84:85], v[108:109], v[96:97] op_sel:[1,1] op_sel_hi:[1,0]
	v_pk_mul_f32 v[86:87], v[110:111], v[100:101] op_sel:[1,1] op_sel_hi:[1,0]
	v_pk_mul_f32 v[92:93], v[112:113], v[96:97] op_sel:[1,0] op_sel_hi:[1,1]
	v_pk_mul_f32 v[94:95], v[114:115], v[102:103] op_sel:[1,1] op_sel_hi:[1,0]
	v_pk_fma_f32 v[84:85], v[108:109], v[96:97], v[84:85] op_sel:[0,0,0] op_sel_hi:[0,1,1] neg_lo:[0,0,1] neg_hi:[0,0,0]
	v_pk_fma_f32 v[86:87], v[110:111], v[100:101], v[86:87] op_sel:[0,0,0] op_sel_hi:[0,1,1] neg_lo:[0,0,1] neg_hi:[0,0,0]
	v_pk_fma_f32 v[92:93], v[112:113], v[96:97], v[92:93] op_sel:[0,1,0] op_sel_hi:[0,0,1] neg_lo:[0,0,0] neg_hi:[0,1,0]
	v_pk_fma_f32 v[94:95], v[114:115], v[102:103], v[94:95] op_sel:[0,0,0] op_sel_hi:[0,1,1] neg_lo:[0,0,1] neg_hi:[0,0,0]
	v_pk_add_f32 v[108:109], v[80:81], v[88:89] neg_lo:[0,1] neg_hi:[0,1]
	v_pk_add_f32 v[110:111], v[82:83], v[90:91] neg_lo:[0,1] neg_hi:[0,1]
	v_pk_add_f32 v[112:113], v[84:85], v[92:93] neg_lo:[0,1] neg_hi:[0,1]
	v_pk_add_f32 v[114:115], v[86:87], v[94:95] neg_lo:[0,1] neg_hi:[0,1]
	v_pk_add_f32 v[80:81], v[80:81], v[88:89]
	v_pk_add_f32 v[82:83], v[82:83], v[90:91]
	v_pk_add_f32 v[84:85], v[84:85], v[92:93]
	v_pk_add_f32 v[86:87], v[86:87], v[94:95]
	v_pk_mul_f32 v[88:89], v[108:109], v[104:105] op_sel:[1,1] op_sel_hi:[1,0]
	v_pk_mul_f32 v[90:91], v[110:111], v[104:105] op_sel:[1,0] op_sel_hi:[1,1]
	v_pk_mul_f32 v[92:93], v[112:113], v[104:105] op_sel:[1,1] op_sel_hi:[1,0]
	v_pk_mul_f32 v[94:95], v[114:115], v[104:105] op_sel:[1,0] op_sel_hi:[1,1]
	v_pk_fma_f32 v[88:89], v[108:109], v[104:105], v[88:89] op_sel:[0,0,0] op_sel_hi:[0,1,1] neg_lo:[0,0,1] neg_hi:[0,0,0]
	v_pk_fma_f32 v[90:91], v[110:111], v[104:105], v[90:91] op_sel:[0,1,0] op_sel_hi:[0,0,1] neg_lo:[0,0,0] neg_hi:[0,1,0]
	v_pk_fma_f32 v[92:93], v[112:113], v[104:105], v[92:93] op_sel:[0,0,0] op_sel_hi:[0,1,1] neg_lo:[0,0,1] neg_hi:[0,0,0]
	v_pk_fma_f32 v[94:95], v[114:115], v[104:105], v[94:95] op_sel:[0,1,0] op_sel_hi:[0,0,1] neg_lo:[0,0,0] neg_hi:[0,1,0]
	v_pk_add_f32 v[108:109], v[80:81], v[82:83] neg_lo:[0,1] neg_hi:[0,1]
	v_pk_add_f32 v[110:111], v[88:89], v[90:91] neg_lo:[0,1] neg_hi:[0,1]
	v_pk_add_f32 v[112:113], v[84:85], v[86:87] neg_lo:[0,1] neg_hi:[0,1]
	v_pk_add_f32 v[114:115], v[92:93], v[94:95] neg_lo:[0,1] neg_hi:[0,1]
	v_pk_add_f32 v[80:81], v[80:81], v[82:83]
	v_pk_add_f32 v[88:89], v[88:89], v[90:91]
	v_pk_add_f32 v[84:85], v[84:85], v[86:87]
	v_pk_add_f32 v[92:93], v[92:93], v[94:95]
	v_pk_mul_f32 v[82:83], v[108:109], v[106:107] op_sel:[1,1] op_sel_hi:[1,0]
	v_pk_mul_f32 v[90:91], v[110:111], v[106:107] op_sel:[1,1] op_sel_hi:[1,0]
	v_pk_mul_f32 v[86:87], v[112:113], v[106:107] op_sel:[1,1] op_sel_hi:[1,0]
	v_pk_mul_f32 v[94:95], v[114:115], v[106:107] op_sel:[1,1] op_sel_hi:[1,0]
	v_pk_fma_f32 v[82:83], v[108:109], v[106:107], v[82:83] op_sel:[0,0,0] op_sel_hi:[0,1,1] neg_lo:[0,0,1] neg_hi:[0,0,0]
	v_pk_fma_f32 v[90:91], v[110:111], v[106:107], v[90:91] op_sel:[0,0,0] op_sel_hi:[0,1,1] neg_lo:[0,0,1] neg_hi:[0,0,0]
	v_pk_fma_f32 v[86:87], v[112:113], v[106:107], v[86:87] op_sel:[0,0,0] op_sel_hi:[0,1,1] neg_lo:[0,0,1] neg_hi:[0,0,0]
	v_pk_fma_f32 v[94:95], v[114:115], v[106:107], v[94:95] op_sel:[0,0,0] op_sel_hi:[0,1,1] neg_lo:[0,0,1] neg_hi:[0,0,0]
	ds_write2st64_b64 v79, v[80:81], v[82:83] offset1:17
	ds_write2st64_b64 v79, v[88:89], v[90:91] offset0:34 offset1:51
	ds_write2st64_b64 v79, v[84:85], v[86:87] offset0:68 offset1:85
	ds_write2st64_b64 v79, v[92:93], v[94:95] offset0:102 offset1:119
	s_waitcnt lgkmcnt(4)
; #define LAS __attribute__((address_space(3)))
; template <int LR> __device__ __forceinline__ void dif_reg(cf (&x)[1 << LR], cf w) {
;     constexpr int R = 1 << LR; cf ws = w;
; #pragma unroll
;     for (int s = 0; s < LR; ++s) { const int half = R >> (s + 1);
; #pragma unroll
;         for (int m0 = 0; m0 < R; m0 += 2 * half)
; #pragma unroll
;             for (int mm = 0; mm < half; ++mm) { const int ia = m0 + mm, ib = ia + half; const cf a = x[ia], b = x[ib];
;                 x[ia] = cf{a.x + b.x, a.y + b.y}; const cf d{a.x - b.x, a.y - b.y};
;                 x[ib] = cmul(d, twc(ws, (mm << s) * (16 / R))); }
;         ws = cmul(ws, ws); }
; }
; template <int LR> __device__ __forceinline__ void dit_reg(cf (&x)[1 << LR], cf w) {
;     constexpr int R = 1 << LR; cf wsv[LR]; wsv[0] = w;
; #pragma unroll
;     for (int s = 1; s < LR; ++s) wsv[s] = cmul(wsv[s - 1], wsv[s - 1]);
; #pragma unroll
;     for (int s = LR - 1; s >= 0; --s) { const int half = R >> (s + 1);
; #pragma unroll
;         for (int m0 = 0; m0 < R; m0 += 2 * half)
; #pragma unroll
;             for (int mm = 0; mm < half; ++mm) { const int ia = m0 + mm, ib = ia + half; const cf a = x[ia];
;                 const cf b = cmulc(x[ib], twc(wsv[s], (mm << s) * (16 / R)));
;                 x[ia] = cf{a.x + b.x, a.y + b.y}; x[ib] = cf{a.x - b.x, a.y - b.y}; } }
; }
; __device__ __forceinline__ void lds_barrier() { asm volatile("s_waitcnt lgkmcnt(0)\n\ts_barrier" ::: "memory"); }
; template <int LR, bool INV> __device__ __forceinline__ void fft_pass(ldsf2 buf, int base, int stride, int twi) {
;     constexpr int R = 1 << LR; cf x[R];
;     const v2f wv = ((ldsf2)((LAS unsigned char*)buf + 139264))[twi];
; #pragma unroll
;     for (int m = 0; m < R; ++m) { const v2f v = buf[base + m * stride]; x[m] = cf{v.x, v.y}; }
;     const cf w{wv.x, wv.y};
;     if (INV) dit_reg<LR>(x, w); else dif_reg<LR>(x, w);
; #pragma unroll
;     for (int m = 0; m < R; ++m) buf[base + m * stride] = mkv2(x[m].x, x[m].y);
; }
; __device__ __forceinline__ void wave_lds_fence() { asm volatile("s_waitcnt lgkmcnt(0)" ::: "memory"); }
; __device__ __forceinline__ void fft_fwd_abc(ldsf2 buf) {
;     const int tid = otid(); const int wv = tid >> 6, l = tid & 63;
; #pragma unroll 1
;     for (int u = 0; u < 2; ++u) { const int bf = tid + NT * u; fft_pass<3, false>(buf, bf + (bf >> 4), 1088, bf); }
;     lds_barrier();
	v_pk_add_f32 v[152:153], v[126:127], v[126:127] op_sel:[0,1] op_sel_hi:[1,0] neg_lo:[0,0] neg_hi:[0,1]
	v_pk_mul_f32 v[154:155], v[152:153], s[16:17] op_sel:[0,0] op_sel_hi:[1,0]
	v_pk_mul_f32 v[156:157], v[152:153], s[16:17] op_sel:[1,0] op_sel_hi:[0,0] neg_lo:[0,0] neg_hi:[1,0]
	v_pk_mul_f32 v[158:159], v[126:127], v[126:127] op_sel:[1,1] op_sel_hi:[1,0]
	v_pk_fma_f32 v[158:159], v[126:127], v[126:127], v[158:159] op_sel:[0,0,0] op_sel_hi:[0,1,1] neg_lo:[0,0,1] neg_hi:[0,0,0]
	v_pk_mul_f32 v[160:161], v[158:159], v[158:159] op_sel:[1,1] op_sel_hi:[1,0]
	v_pk_fma_f32 v[160:161], v[158:159], v[158:159], v[160:161] op_sel:[0,0,0] op_sel_hi:[0,1,1] neg_lo:[0,0,1] neg_hi:[0,0,0]
	v_pk_add_f32 v[162:163], v[128:129], v[132:133] neg_lo:[0,1] neg_hi:[0,1]
	v_pk_add_f32 v[164:165], v[130:131], v[134:135] neg_lo:[0,1] neg_hi:[0,1]
	v_pk_add_f32 v[166:167], v[136:137], v[140:141] neg_lo:[0,1] neg_hi:[0,1]
	v_pk_add_f32 v[168:169], v[138:139], v[142:143] neg_lo:[0,1] neg_hi:[0,1]
	v_pk_add_f32 v[128:129], v[128:129], v[132:133]
	v_pk_add_f32 v[130:131], v[130:131], v[134:135]
	v_pk_add_f32 v[136:137], v[136:137], v[140:141]
	v_pk_add_f32 v[138:139], v[138:139], v[142:143]
	v_pk_mul_f32 v[132:133], v[162:163], v[126:127] op_sel:[1,1] op_sel_hi:[1,0]
	v_pk_mul_f32 v[134:135], v[164:165], v[154:155] op_sel:[1,1] op_sel_hi:[1,0]
	v_pk_mul_f32 v[140:141], v[166:167], v[126:127] op_sel:[1,0] op_sel_hi:[1,1]
	v_pk_mul_f32 v[142:143], v[168:169], v[156:157] op_sel:[1,1] op_sel_hi:[1,0]
	v_pk_fma_f32 v[132:133], v[162:163], v[126:127], v[132:133] op_sel:[0,0,0] op_sel_hi:[0,1,1] neg_lo:[0,0,1] neg_hi:[0,0,0]
	v_pk_fma_f32 v[134:135], v[164:165], v[154:155], v[134:135] op_sel:[0,0,0] op_sel_hi:[0,1,1] neg_lo:[0,0,1] neg_hi:[0,0,0]
	v_pk_fma_f32 v[140:141], v[166:167], v[126:127], v[140:141] op_sel:[0,1,0] op_sel_hi:[0,0,1] neg_lo:[0,0,0] neg_hi:[0,1,0]
	v_pk_fma_f32 v[142:143], v[168:169], v[156:157], v[142:143] op_sel:[0,0,0] op_sel_hi:[0,1,1] neg_lo:[0,0,1] neg_hi:[0,0,0]
	v_pk_add_f32 v[162:163], v[128:129], v[136:137] neg_lo:[0,1] neg_hi:[0,1]
	v_pk_add_f32 v[164:165], v[130:131], v[138:139] neg_lo:[0,1] neg_hi:[0,1]
	v_pk_add_f32 v[166:167], v[132:133], v[140:141] neg_lo:[0,1] neg_hi:[0,1]
	v_pk_add_f32 v[168:169], v[134:135], v[142:143] neg_lo:[0,1] neg_hi:[0,1]
	v_pk_add_f32 v[128:129], v[128:129], v[136:137]
	v_pk_add_f32 v[130:131], v[130:131], v[138:139]
	v_pk_add_f32 v[132:133], v[132:133], v[140:141]
	v_pk_add_f32 v[134:135], v[134:135], v[142:143]
	v_pk_mul_f32 v[136:137], v[162:163], v[158:159] op_sel:[1,1] op_sel_hi:[1,0]
	v_pk_mul_f32 v[138:139], v[164:165], v[158:159] op_sel:[1,0] op_sel_hi:[1,1]
	v_pk_mul_f32 v[140:141], v[166:167], v[158:159] op_sel:[1,1] op_sel_hi:[1,0]
	v_pk_mul_f32 v[142:143], v[168:169], v[158:159] op_sel:[1,0] op_sel_hi:[1,1]
	v_pk_fma_f32 v[136:137], v[162:163], v[158:159], v[136:137] op_sel:[0,0,0] op_sel_hi:[0,1,1] neg_lo:[0,0,1] neg_hi:[0,0,0]
	v_pk_fma_f32 v[138:139], v[164:165], v[158:159], v[138:139] op_sel:[0,1,0] op_sel_hi:[0,0,1] neg_lo:[0,0,0] neg_hi:[0,1,0]
	v_pk_fma_f32 v[140:141], v[166:167], v[158:159], v[140:141] op_sel:[0,0,0] op_sel_hi:[0,1,1] neg_lo:[0,0,1] neg_hi:[0,0,0]
	v_pk_fma_f32 v[142:143], v[168:169], v[158:159], v[142:143] op_sel:[0,1,0] op_sel_hi:[0,0,1] neg_lo:[0,0,0] neg_hi:[0,1,0]
	v_pk_add_f32 v[162:163], v[128:129], v[130:131] neg_lo:[0,1] neg_hi:[0,1]
	v_pk_add_f32 v[164:165], v[136:137], v[138:139] neg_lo:[0,1] neg_hi:[0,1]
	v_pk_add_f32 v[166:167], v[132:133], v[134:135] neg_lo:[0,1] neg_hi:[0,1]
	v_pk_add_f32 v[168:169], v[140:141], v[142:143] neg_lo:[0,1] neg_hi:[0,1]
	v_pk_add_f32 v[128:129], v[128:129], v[130:131]
	v_pk_add_f32 v[136:137], v[136:137], v[138:139]
	v_pk_add_f32 v[132:133], v[132:133], v[134:135]
	v_pk_add_f32 v[140:141], v[140:141], v[142:143]
	v_pk_mul_f32 v[130:131], v[162:163], v[160:161] op_sel:[1,1] op_sel_hi:[1,0]
	v_pk_mul_f32 v[138:139], v[164:165], v[160:161] op_sel:[1,1] op_sel_hi:[1,0]
	v_pk_mul_f32 v[134:135], v[166:167], v[160:161] op_sel:[1,1] op_sel_hi:[1,0]
	v_pk_mul_f32 v[142:143], v[168:169], v[160:161] op_sel:[1,1] op_sel_hi:[1,0]
	v_pk_fma_f32 v[130:131], v[162:163], v[160:161], v[130:131] op_sel:[0,0,0] op_sel_hi:[0,1,1] neg_lo:[0,0,1] neg_hi:[0,0,0]
	v_pk_fma_f32 v[138:139], v[164:165], v[160:161], v[138:139] op_sel:[0,0,0] op_sel_hi:[0,1,1] neg_lo:[0,0,1] neg_hi:[0,0,0]
	v_pk_fma_f32 v[134:135], v[166:167], v[160:161], v[134:135] op_sel:[0,0,0] op_sel_hi:[0,1,1] neg_lo:[0,0,1] neg_hi:[0,0,0]
	v_pk_fma_f32 v[142:143], v[168:169], v[160:161], v[142:143] op_sel:[0,0,0] op_sel_hi:[0,1,1] neg_lo:[0,0,1] neg_hi:[0,0,0]
	ds_write2st64_b64 v122, v[128:129], v[130:131] offset1:17
	ds_write2st64_b64 v122, v[136:137], v[138:139] offset0:34 offset1:51
	ds_write2st64_b64 v122, v[132:133], v[134:135] offset0:68 offset1:85
	ds_write2st64_b64 v122, v[140:141], v[142:143] offset0:102 offset1:119
	s_mov_b64 s[10:11], 0
	s_waitcnt lgkmcnt(0)
	s_barrier
	v_lshlrev_b32_e32 v80, 4, v78
	v_and_b32_e32 v79, 63, v78
	v_and_b32_e32 v80, 0xfffffc00, v80
	s_mov_b32 s0, 0
	s_mov_b64 s[10:11], -1
; template <int LR> __device__ __forceinline__ void dif_reg(cf (&x)[1 << LR], cf w) {
;     constexpr int R = 1 << LR; cf ws = w;
; #pragma unroll
;     for (int s = 0; s < LR; ++s) { const int half = R >> (s + 1);
; #pragma unroll
;         for (int m0 = 0; m0 < R; m0 += 2 * half)
; #pragma unroll
;             for (int mm = 0; mm < half; ++mm) { const int ia = m0 + mm, ib = ia + half; const cf a = x[ia], b = x[ib];
;                 x[ia] = cf{a.x + b.x, a.y + b.y}; const cf d{a.x - b.x, a.y - b.y};
;                 x[ib] = cmul(d, twc(ws, (mm << s) * (16 / R))); }
;         ws = cmul(ws, ws); }
; }
; template <int LR> __device__ __forceinline__ void dit_reg(cf (&x)[1 << LR], cf w) {
;     constexpr int R = 1 << LR; cf wsv[LR]; wsv[0] = w;
; #pragma unroll
;     for (int s = 1; s < LR; ++s) wsv[s] = cmul(wsv[s - 1], wsv[s - 1]);
; #pragma unroll
;     for (int s = LR - 1; s >= 0; --s) { const int half = R >> (s + 1);
; #pragma unroll
;         for (int m0 = 0; m0 < R; m0 += 2 * half)
; #pragma unroll
;             for (int mm = 0; mm < half; ++mm) { const int ia = m0 + mm, ib = ia + half; const cf a = x[ia];
;                 const cf b = cmulc(x[ib], twc(wsv[s], (mm << s) * (16 / R)));
;                 x[ia] = cf{a.x + b.x, a.y + b.y}; x[ib] = cf{a.x - b.x, a.y - b.y}; } }
; }
; __device__ __forceinline__ void lds_barrier() { asm volatile("s_waitcnt lgkmcnt(0)\n\ts_barrier" ::: "memory"); }
; template <int LR, bool INV> __device__ __forceinline__ void fft_pass(ldsf2 buf, int base, int stride, int twi) {
;     constexpr int R = 1 << LR; cf x[R];
;     const v2f wv = ((ldsf2)((LAS unsigned char*)buf + 139264))[twi];
; #pragma unroll
;     for (int m = 0; m < R; ++m) { const v2f v = buf[base + m * stride]; x[m] = cf{v.x, v.y}; }
;     const cf w{wv.x, wv.y};
;     if (INV) dit_reg<LR>(x, w); else dif_reg<LR>(x, w);
; #pragma unroll
;     for (int m = 0; m < R; ++m) buf[base + m * stride] = mkv2(x[m].x, x[m].y);
; }
; __device__ __forceinline__ void wave_lds_fence() { asm volatile("s_waitcnt lgkmcnt(0)" ::: "memory"); }
; __device__ __forceinline__ void fft_fwd_abc(ldsf2 buf) {
;     const int tid = otid(); const int wv = tid >> 6, l = tid & 63;
; #pragma unroll 1
;     for (int u = 0; u < 2; ++u) { const int bf = tid + NT * u; fft_pass<3, false>(buf, bf + (bf >> 4), 1088, bf); }
;     lds_barrier();
; #pragma unroll 1
.LBB0_361:
	v_or_b32_e32 v82, s0, v79
	v_or_b32_e32 v81, v82, v80
	v_lshl_add_u32 v82, v82, 6, 0
	v_ashrrev_i32_e32 v83, 4, v81
	v_add_u32_e32 v82, 0x22000, v82
	v_lshlrev_b32_e32 v81, 3, v81
	ds_read_b64 v[98:99], v82
	v_lshlrev_b32_e32 v82, 3, v83
	v_add3_u32 v81, 0, v81, v82
	v_add_u32_e32 v121, 0x800, v81
	ds_read2_b64 v[82:85], v81 offset1:136
	v_add_u32_e32 v126, 0x1000, v81
	v_add_u32_e32 v127, 0x1800, v81
	ds_read2_b64 v[86:89], v121 offset0:16 offset1:152
	ds_read2_b64 v[90:93], v126 offset0:32 offset1:168
	ds_read2_b64 v[94:97], v127 offset0:48 offset1:184
	s_mov_b32 s0, 64
	v_or_b32_e32 v128, s0, v79
	v_or_b32_e32 v130, v128, v80
	v_lshl_add_u32 v128, v128, 6, 0
	v_ashrrev_i32_e32 v132, 4, v130
	v_add_u32_e32 v128, 0x22000, v128
	v_lshlrev_b32_e32 v130, 3, v130
	ds_read_b64 v[134:135], v128
	v_lshlrev_b32_e32 v128, 3, v132
	v_add3_u32 v130, 0, v130, v128
	v_add_u32_e32 v136, 0x800, v130
	ds_read2_b64 v[138:141], v130 offset1:136
	v_add_u32_e32 v142, 0x1000, v130
	v_add_u32_e32 v152, 0x1800, v130
	ds_read2_b64 v[154:157], v136 offset0:16 offset1:152
	ds_read2_b64 v[158:161], v142 offset0:32 offset1:168
	ds_read2_b64 v[162:165], v152 offset0:48 offset1:184
	s_waitcnt lgkmcnt(5)
	v_pk_add_f32 v[100:101], v[98:99], v[98:99] op_sel:[0,1] op_sel_hi:[1,0] neg_lo:[0,0] neg_hi:[0,1]
	v_pk_mul_f32 v[102:103], v[100:101], s[16:17] op_sel:[0,0] op_sel_hi:[1,0]
	v_pk_mul_f32 v[104:105], v[100:101], s[16:17] op_sel:[1,0] op_sel_hi:[0,0] neg_lo:[0,0] neg_hi:[1,0]
	v_pk_mul_f32 v[106:107], v[98:99], v[98:99] op_sel:[1,1] op_sel_hi:[1,0]
	v_pk_fma_f32 v[106:107], v[98:99], v[98:99], v[106:107] op_sel:[0,0,0] op_sel_hi:[0,1,1] neg_lo:[0,0,1] neg_hi:[0,0,0]
	v_pk_mul_f32 v[108:109], v[106:107], v[106:107] op_sel:[1,1] op_sel_hi:[1,0]
	v_pk_fma_f32 v[108:109], v[106:107], v[106:107], v[108:109] op_sel:[0,0,0] op_sel_hi:[0,1,1] neg_lo:[0,0,1] neg_hi:[0,0,0]
	v_pk_add_f32 v[110:111], v[82:83], v[90:91] neg_lo:[0,1] neg_hi:[0,1]
	v_pk_add_f32 v[112:113], v[84:85], v[92:93] neg_lo:[0,1] neg_hi:[0,1]
	v_pk_add_f32 v[114:115], v[86:87], v[94:95] neg_lo:[0,1] neg_hi:[0,1]
	v_pk_add_f32 v[116:117], v[88:89], v[96:97] neg_lo:[0,1] neg_hi:[0,1]
	v_pk_add_f32 v[82:83], v[82:83], v[90:91]
	v_pk_add_f32 v[84:85], v[84:85], v[92:93]
	v_pk_add_f32 v[86:87], v[86:87], v[94:95]
	v_pk_add_f32 v[88:89], v[88:89], v[96:97]
	v_pk_mul_f32 v[90:91], v[110:111], v[98:99] op_sel:[1,1] op_sel_hi:[1,0]
	v_pk_mul_f32 v[92:93], v[112:113], v[102:103] op_sel:[1,1] op_sel_hi:[1,0]
	v_pk_mul_f32 v[94:95], v[114:115], v[98:99] op_sel:[1,0] op_sel_hi:[1,1]
	v_pk_mul_f32 v[96:97], v[116:117], v[104:105] op_sel:[1,1] op_sel_hi:[1,0]
	v_pk_fma_f32 v[90:91], v[110:111], v[98:99], v[90:91] op_sel:[0,0,0] op_sel_hi:[0,1,1] neg_lo:[0,0,1] neg_hi:[0,0,0]
	v_pk_fma_f32 v[92:93], v[112:113], v[102:103], v[92:93] op_sel:[0,0,0] op_sel_hi:[0,1,1] neg_lo:[0,0,1] neg_hi:[0,0,0]
	v_pk_fma_f32 v[94:95], v[114:115], v[98:99], v[94:95] op_sel:[0,1,0] op_sel_hi:[0,0,1] neg_lo:[0,0,0] neg_hi:[0,1,0]
	v_pk_fma_f32 v[96:97], v[116:117], v[104:105], v[96:97] op_sel:[0,0,0] op_sel_hi:[0,1,1] neg_lo:[0,0,1] neg_hi:[0,0,0]
	v_pk_add_f32 v[110:111], v[82:83], v[86:87] neg_lo:[0,1] neg_hi:[0,1]
	v_pk_add_f32 v[112:113], v[84:85], v[88:89] neg_lo:[0,1] neg_hi:[0,1]
	v_pk_add_f32 v[114:115], v[90:91], v[94:95] neg_lo:[0,1] neg_hi:[0,1]
	v_pk_add_f32 v[116:117], v[92:93], v[96:97] neg_lo:[0,1] neg_hi:[0,1]
	v_pk_add_f32 v[82:83], v[82:83], v[86:87]
	v_pk_add_f32 v[84:85], v[84:85], v[88:89]
	v_pk_add_f32 v[90:91], v[90:91], v[94:95]
	v_pk_add_f32 v[92:93], v[92:93], v[96:97]
	v_pk_mul_f32 v[86:87], v[110:111], v[106:107] op_sel:[1,1] op_sel_hi:[1,0]
	v_pk_mul_f32 v[88:89], v[112:113], v[106:107] op_sel:[1,0] op_sel_hi:[1,1]
	v_pk_mul_f32 v[94:95], v[114:115], v[106:107] op_sel:[1,1] op_sel_hi:[1,0]
	v_pk_mul_f32 v[96:97], v[116:117], v[106:107] op_sel:[1,0] op_sel_hi:[1,1]
	v_pk_fma_f32 v[86:87], v[110:111], v[106:107], v[86:87] op_sel:[0,0,0] op_sel_hi:[0,1,1] neg_lo:[0,0,1] neg_hi:[0,0,0]
	v_pk_fma_f32 v[88:89], v[112:113], v[106:107], v[88:89] op_sel:[0,1,0] op_sel_hi:[0,0,1] neg_lo:[0,0,0] neg_hi:[0,1,0]
	v_pk_fma_f32 v[94:95], v[114:115], v[106:107], v[94:95] op_sel:[0,0,0] op_sel_hi:[0,1,1] neg_lo:[0,0,1] neg_hi:[0,0,0]
	v_pk_fma_f32 v[96:97], v[116:117], v[106:107], v[96:97] op_sel:[0,1,0] op_sel_hi:[0,0,1] neg_lo:[0,0,0] neg_hi:[0,1,0]
	v_pk_add_f32 v[110:111], v[82:83], v[84:85] neg_lo:[0,1] neg_hi:[0,1]
	v_pk_add_f32 v[112:113], v[86:87], v[88:89] neg_lo:[0,1] neg_hi:[0,1]
	v_pk_add_f32 v[114:115], v[90:91], v[92:93] neg_lo:[0,1] neg_hi:[0,1]
	v_pk_add_f32 v[116:117], v[94:95], v[96:97] neg_lo:[0,1] neg_hi:[0,1]
	v_pk_add_f32 v[82:83], v[82:83], v[84:85]
	v_pk_add_f32 v[86:87], v[86:87], v[88:89]
	v_pk_add_f32 v[90:91], v[90:91], v[92:93]
	v_pk_add_f32 v[94:95], v[94:95], v[96:97]
	v_pk_mul_f32 v[84:85], v[110:111], v[108:109] op_sel:[1,1] op_sel_hi:[1,0]
	v_pk_mul_f32 v[88:89], v[112:113], v[108:109] op_sel:[1,1] op_sel_hi:[1,0]
	v_pk_mul_f32 v[92:93], v[114:115], v[108:109] op_sel:[1,1] op_sel_hi:[1,0]
	v_pk_mul_f32 v[96:97], v[116:117], v[108:109] op_sel:[1,1] op_sel_hi:[1,0]
	v_pk_fma_f32 v[84:85], v[110:111], v[108:109], v[84:85] op_sel:[0,0,0] op_sel_hi:[0,1,1] neg_lo:[0,0,1] neg_hi:[0,0,0]
	v_pk_fma_f32 v[88:89], v[112:113], v[108:109], v[88:89] op_sel:[0,0,0] op_sel_hi:[0,1,1] neg_lo:[0,0,1] neg_hi:[0,0,0]
	v_pk_fma_f32 v[92:93], v[114:115], v[108:109], v[92:93] op_sel:[0,0,0] op_sel_hi:[0,1,1] neg_lo:[0,0,1] neg_hi:[0,0,0]
	v_pk_fma_f32 v[96:97], v[116:117], v[108:109], v[96:97] op_sel:[0,0,0] op_sel_hi:[0,1,1] neg_lo:[0,0,1] neg_hi:[0,0,0]
	ds_write2_b64 v81, v[82:83], v[84:85] offset1:136
	ds_write2_b64 v121, v[86:87], v[88:89] offset0:16 offset1:152
	ds_write2_b64 v126, v[90:91], v[92:93] offset0:32 offset1:168
	ds_write2_b64 v127, v[94:95], v[96:97] offset0:48 offset1:184
	s_waitcnt lgkmcnt(4)
; template <int LR> __device__ __forceinline__ void dif_reg(cf (&x)[1 << LR], cf w) {
;     constexpr int R = 1 << LR; cf ws = w;
; #pragma unroll
;     for (int s = 0; s < LR; ++s) { const int half = R >> (s + 1);
; #pragma unroll
;         for (int m0 = 0; m0 < R; m0 += 2 * half)
; #pragma unroll
;             for (int mm = 0; mm < half; ++mm) { const int ia = m0 + mm, ib = ia + half; const cf a = x[ia], b = x[ib];
;                 x[ia] = cf{a.x + b.x, a.y + b.y}; const cf d{a.x - b.x, a.y - b.y};
;                 x[ib] = cmul(d, twc(ws, (mm << s) * (16 / R))); }
;         ws = cmul(ws, ws); }
; }
; template <int LR> __device__ __forceinline__ void dit_reg(cf (&x)[1 << LR], cf w) {
;     constexpr int R = 1 << LR; cf wsv[LR]; wsv[0] = w;
; #pragma unroll
;     for (int s = 1; s < LR; ++s) wsv[s] = cmul(wsv[s - 1], wsv[s - 1]);
; #pragma unroll
;     for (int s = LR - 1; s >= 0; --s) { const int half = R >> (s + 1);
; #pragma unroll
;         for (int m0 = 0; m0 < R; m0 += 2 * half)
; #pragma unroll
;             for (int mm = 0; mm < half; ++mm) { const int ia = m0 + mm, ib = ia + half; const cf a = x[ia];
;                 const cf b = cmulc(x[ib], twc(wsv[s], (mm << s) * (16 / R)));
;                 x[ia] = cf{a.x + b.x, a.y + b.y}; x[ib] = cf{a.x - b.x, a.y - b.y}; } }
; }
; __device__ __forceinline__ void lds_barrier() { asm volatile("s_waitcnt lgkmcnt(0)\n\ts_barrier" ::: "memory"); }
; template <int LR, bool INV> __device__ __forceinline__ void fft_pass(ldsf2 buf, int base, int stride, int twi) {
;     constexpr int R = 1 << LR; cf x[R];
;     const v2f wv = ((ldsf2)((LAS unsigned char*)buf + 139264))[twi];
; #pragma unroll
;     for (int m = 0; m < R; ++m) { const v2f v = buf[base + m * stride]; x[m] = cf{v.x, v.y}; }
;     const cf w{wv.x, wv.y};
;     if (INV) dit_reg<LR>(x, w); else dif_reg<LR>(x, w);
; #pragma unroll
;     for (int m = 0; m < R; ++m) buf[base + m * stride] = mkv2(x[m].x, x[m].y);
; }
; __device__ __forceinline__ void wave_lds_fence() { asm volatile("s_waitcnt lgkmcnt(0)" ::: "memory"); }
; __device__ __forceinline__ void fft_fwd_abc(ldsf2 buf) {
;     const int tid = otid(); const int wv = tid >> 6, l = tid & 63;
; #pragma unroll 1
;     for (int u = 0; u < 2; ++u) { const int bf = tid + NT * u; fft_pass<3, false>(buf, bf + (bf >> 4), 1088, bf); }
;     lds_barrier();
; #pragma unroll 1
	v_pk_add_f32 v[166:167], v[134:135], v[134:135] op_sel:[0,1] op_sel_hi:[1,0] neg_lo:[0,0] neg_hi:[0,1]
	v_pk_mul_f32 v[168:169], v[166:167], s[16:17] op_sel:[0,0] op_sel_hi:[1,0]
	v_pk_mul_f32 v[170:171], v[166:167], s[16:17] op_sel:[1,0] op_sel_hi:[0,0] neg_lo:[0,0] neg_hi:[1,0]
	v_pk_mul_f32 v[172:173], v[134:135], v[134:135] op_sel:[1,1] op_sel_hi:[1,0]
	v_pk_fma_f32 v[172:173], v[134:135], v[134:135], v[172:173] op_sel:[0,0,0] op_sel_hi:[0,1,1] neg_lo:[0,0,1] neg_hi:[0,0,0]
	v_pk_mul_f32 v[174:175], v[172:173], v[172:173] op_sel:[1,1] op_sel_hi:[1,0]
	v_pk_fma_f32 v[174:175], v[172:173], v[172:173], v[174:175] op_sel:[0,0,0] op_sel_hi:[0,1,1] neg_lo:[0,0,1] neg_hi:[0,0,0]
	v_pk_add_f32 v[188:189], v[138:139], v[158:159] neg_lo:[0,1] neg_hi:[0,1]
	v_pk_add_f32 v[190:191], v[140:141], v[160:161] neg_lo:[0,1] neg_hi:[0,1]
	v_pk_add_f32 v[196:197], v[154:155], v[162:163] neg_lo:[0,1] neg_hi:[0,1]
	v_pk_add_f32 v[198:199], v[156:157], v[164:165] neg_lo:[0,1] neg_hi:[0,1]
	v_pk_add_f32 v[138:139], v[138:139], v[158:159]
	v_pk_add_f32 v[140:141], v[140:141], v[160:161]
	v_pk_add_f32 v[154:155], v[154:155], v[162:163]
	v_pk_add_f32 v[156:157], v[156:157], v[164:165]
	v_pk_mul_f32 v[158:159], v[188:189], v[134:135] op_sel:[1,1] op_sel_hi:[1,0]
	v_pk_mul_f32 v[160:161], v[190:191], v[168:169] op_sel:[1,1] op_sel_hi:[1,0]
	v_pk_mul_f32 v[162:163], v[196:197], v[134:135] op_sel:[1,0] op_sel_hi:[1,1]
	v_pk_mul_f32 v[164:165], v[198:199], v[170:171] op_sel:[1,1] op_sel_hi:[1,0]
	v_pk_fma_f32 v[158:159], v[188:189], v[134:135], v[158:159] op_sel:[0,0,0] op_sel_hi:[0,1,1] neg_lo:[0,0,1] neg_hi:[0,0,0]
	v_pk_fma_f32 v[160:161], v[190:191], v[168:169], v[160:161] op_sel:[0,0,0] op_sel_hi:[0,1,1] neg_lo:[0,0,1] neg_hi:[0,0,0]
	v_pk_fma_f32 v[162:163], v[196:197], v[134:135], v[162:163] op_sel:[0,1,0] op_sel_hi:[0,0,1] neg_lo:[0,0,0] neg_hi:[0,1,0]
	v_pk_fma_f32 v[164:165], v[198:199], v[170:171], v[164:165] op_sel:[0,0,0] op_sel_hi:[0,1,1] neg_lo:[0,0,1] neg_hi:[0,0,0]
	v_pk_add_f32 v[188:189], v[138:139], v[154:155] neg_lo:[0,1] neg_hi:[0,1]
	v_pk_add_f32 v[190:191], v[140:141], v[156:157] neg_lo:[0,1] neg_hi:[0,1]
	v_pk_add_f32 v[196:197], v[158:159], v[162:163] neg_lo:[0,1] neg_hi:[0,1]
	v_pk_add_f32 v[198:199], v[160:161], v[164:165] neg_lo:[0,1] neg_hi:[0,1]
	v_pk_add_f32 v[138:139], v[138:139], v[154:155]
	v_pk_add_f32 v[140:141], v[140:141], v[156:157]
	v_pk_add_f32 v[158:159], v[158:159], v[162:163]
	v_pk_add_f32 v[160:161], v[160:161], v[164:165]
	v_pk_mul_f32 v[154:155], v[188:189], v[172:173] op_sel:[1,1] op_sel_hi:[1,0]
	v_pk_mul_f32 v[156:157], v[190:191], v[172:173] op_sel:[1,0] op_sel_hi:[1,1]
	v_pk_mul_f32 v[162:163], v[196:197], v[172:173] op_sel:[1,1] op_sel_hi:[1,0]
	v_pk_mul_f32 v[164:165], v[198:199], v[172:173] op_sel:[1,0] op_sel_hi:[1,1]
	v_pk_fma_f32 v[154:155], v[188:189], v[172:173], v[154:155] op_sel:[0,0,0] op_sel_hi:[0,1,1] neg_lo:[0,0,1] neg_hi:[0,0,0]
	v_pk_fma_f32 v[156:157], v[190:191], v[172:173], v[156:157] op_sel:[0,1,0] op_sel_hi:[0,0,1] neg_lo:[0,0,0] neg_hi:[0,1,0]
	v_pk_fma_f32 v[162:163], v[196:197], v[172:173], v[162:163] op_sel:[0,0,0] op_sel_hi:[0,1,1] neg_lo:[0,0,1] neg_hi:[0,0,0]
	v_pk_fma_f32 v[164:165], v[198:199], v[172:173], v[164:165] op_sel:[0,1,0] op_sel_hi:[0,0,1] neg_lo:[0,0,0] neg_hi:[0,1,0]
	v_pk_add_f32 v[188:189], v[138:139], v[140:141] neg_lo:[0,1] neg_hi:[0,1]
	v_pk_add_f32 v[190:191], v[154:155], v[156:157] neg_lo:[0,1] neg_hi:[0,1]
	v_pk_add_f32 v[196:197], v[158:159], v[160:161] neg_lo:[0,1] neg_hi:[0,1]
	v_pk_add_f32 v[198:199], v[162:163], v[164:165] neg_lo:[0,1] neg_hi:[0,1]
	v_pk_add_f32 v[138:139], v[138:139], v[140:141]
	v_pk_add_f32 v[154:155], v[154:155], v[156:157]
	v_pk_add_f32 v[158:159], v[158:159], v[160:161]
	v_pk_add_f32 v[162:163], v[162:163], v[164:165]
	v_pk_mul_f32 v[140:141], v[188:189], v[174:175] op_sel:[1,1] op_sel_hi:[1,0]
	v_pk_mul_f32 v[156:157], v[190:191], v[174:175] op_sel:[1,1] op_sel_hi:[1,0]
	v_pk_mul_f32 v[160:161], v[196:197], v[174:175] op_sel:[1,1] op_sel_hi:[1,0]
	v_pk_mul_f32 v[164:165], v[198:199], v[174:175] op_sel:[1,1] op_sel_hi:[1,0]
	v_pk_fma_f32 v[140:141], v[188:189], v[174:175], v[140:141] op_sel:[0,0,0] op_sel_hi:[0,1,1] neg_lo:[0,0,1] neg_hi:[0,0,0]
	v_pk_fma_f32 v[156:157], v[190:191], v[174:175], v[156:157] op_sel:[0,0,0] op_sel_hi:[0,1,1] neg_lo:[0,0,1] neg_hi:[0,0,0]
	v_pk_fma_f32 v[160:161], v[196:197], v[174:175], v[160:161] op_sel:[0,0,0] op_sel_hi:[0,1,1] neg_lo:[0,0,1] neg_hi:[0,0,0]
	v_pk_fma_f32 v[164:165], v[198:199], v[174:175], v[164:165] op_sel:[0,0,0] op_sel_hi:[0,1,1] neg_lo:[0,0,1] neg_hi:[0,0,0]
	ds_write2_b64 v130, v[138:139], v[140:141] offset1:136
	ds_write2_b64 v136, v[154:155], v[156:157] offset0:16 offset1:152
	ds_write2_b64 v142, v[158:159], v[160:161] offset0:32 offset1:168
	ds_write2_b64 v152, v[162:163], v[164:165] offset0:48 offset1:184
	s_mov_b64 s[10:11], 0
	v_and_b32_e32 v78, 15, v78
	s_waitcnt lgkmcnt(0)
	v_lshlrev_b32_e32 v79, 3, v79
	v_lshlrev_b32_e32 v81, 9, v78
	v_and_or_b32 v79, v79, s90, v80
	v_add_u32_e32 v80, 0, v81
	v_lshl_add_u32 v78, v78, 3, 0
	s_mov_b32 s0, 0
	s_mov_b64 s[10:11], -1
	v_add_u32_e32 v80, 0x22000, v80
; template <int LR> __device__ __forceinline__ void dif_reg(cf (&x)[1 << LR], cf w) {
;     constexpr int R = 1 << LR; cf ws = w;
; #pragma unroll
;     for (int s = 0; s < LR; ++s) { const int half = R >> (s + 1);
; #pragma unroll
;         for (int m0 = 0; m0 < R; m0 += 2 * half)
; #pragma unroll
;             for (int mm = 0; mm < half; ++mm) { const int ia = m0 + mm, ib = ia + half; const cf a = x[ia], b = x[ib];
;                 x[ia] = cf{a.x + b.x, a.y + b.y}; const cf d{a.x - b.x, a.y - b.y};
;                 x[ib] = cmul(d, twc(ws, (mm << s) * (16 / R))); }
;         ws = cmul(ws, ws); }
; }
; template <int LR> __device__ __forceinline__ void dit_reg(cf (&x)[1 << LR], cf w) {
;     constexpr int R = 1 << LR; cf wsv[LR]; wsv[0] = w;
; #pragma unroll
;     for (int s = 1; s < LR; ++s) wsv[s] = cmul(wsv[s - 1], wsv[s - 1]);
; #pragma unroll
;     for (int s = LR - 1; s >= 0; --s) { const int half = R >> (s + 1);
; #pragma unroll
;         for (int m0 = 0; m0 < R; m0 += 2 * half)
; #pragma unroll
;             for (int mm = 0; mm < half; ++mm) { const int ia = m0 + mm, ib = ia + half; const cf a = x[ia];
;                 const cf b = cmulc(x[ib], twc(wsv[s], (mm << s) * (16 / R)));
;                 x[ia] = cf{a.x + b.x, a.y + b.y}; x[ib] = cf{a.x - b.x, a.y - b.y}; } }
; }
; __device__ __forceinline__ void lds_barrier() { asm volatile("s_waitcnt lgkmcnt(0)\n\ts_barrier" ::: "memory"); }
; template <int LR, bool INV> __device__ __forceinline__ void fft_pass(ldsf2 buf, int base, int stride, int twi) {
;     constexpr int R = 1 << LR; cf x[R];
;     const v2f wv = ((ldsf2)((LAS unsigned char*)buf + 139264))[twi];
; #pragma unroll
;     for (int m = 0; m < R; ++m) { const v2f v = buf[base + m * stride]; x[m] = cf{v.x, v.y}; }
;     const cf w{wv.x, wv.y};
;     if (INV) dit_reg<LR>(x, w); else dif_reg<LR>(x, w);
; #pragma unroll
;     for (int m = 0; m < R; ++m) buf[base + m * stride] = mkv2(x[m].x, x[m].y);
; }
; __device__ __forceinline__ void wave_lds_fence() { asm volatile("s_waitcnt lgkmcnt(0)" ::: "memory"); }
; __device__ __forceinline__ void fft_fwd_abc(ldsf2 buf) {
;     const int tid = otid(); const int wv = tid >> 6, l = tid & 63;
; #pragma unroll 1
;     for (int u = 0; u < 2; ++u) { const int bf = tid + NT * u; fft_pass<3, false>(buf, bf + (bf >> 4), 1088, bf); }
;     lds_barrier();
; #pragma unroll 1
.LBB0_363:
	v_or_b32_e32 v81, s0, v79
	ds_read_b64 v[98:99], v80
	v_lshlrev_b32_e32 v82, 3, v81
	v_ashrrev_i32_e32 v81, 1, v81
	v_add3_u32 v81, v78, v82, v81
	ds_read2_b64 v[82:85], v81 offset1:17
	ds_read2_b64 v[86:89], v81 offset0:34 offset1:51
	ds_read2_b64 v[90:93], v81 offset0:68 offset1:85
	ds_read2_b64 v[94:97], v81 offset0:102 offset1:119
	s_movk_i32 s0, 0x200
	v_or_b32_e32 v126, s0, v79
	ds_read_b64 v[128:129], v80
	v_lshlrev_b32_e32 v130, 3, v126
	v_ashrrev_i32_e32 v126, 1, v126
	v_add3_u32 v126, v78, v130, v126
	ds_read2_b64 v[132:135], v126 offset1:17
	ds_read2_b64 v[136:139], v126 offset0:34 offset1:51
	ds_read2_b64 v[140:143], v126 offset0:68 offset1:85
	ds_read2_b64 v[152:155], v126 offset0:102 offset1:119
	s_waitcnt lgkmcnt(5)
	v_pk_add_f32 v[100:101], v[98:99], v[98:99] op_sel:[0,1] op_sel_hi:[1,0] neg_lo:[0,0] neg_hi:[0,1]
	v_pk_mul_f32 v[102:103], v[100:101], s[16:17] op_sel:[0,0] op_sel_hi:[1,0]
	v_pk_mul_f32 v[104:105], v[100:101], s[16:17] op_sel:[1,0] op_sel_hi:[0,0] neg_lo:[0,0] neg_hi:[1,0]
	v_pk_mul_f32 v[106:107], v[98:99], v[98:99] op_sel:[1,1] op_sel_hi:[1,0]
	v_pk_fma_f32 v[106:107], v[98:99], v[98:99], v[106:107] op_sel:[0,0,0] op_sel_hi:[0,1,1] neg_lo:[0,0,1] neg_hi:[0,0,0]
	v_pk_mul_f32 v[108:109], v[106:107], v[106:107] op_sel:[1,1] op_sel_hi:[1,0]
	v_pk_fma_f32 v[108:109], v[106:107], v[106:107], v[108:109] op_sel:[0,0,0] op_sel_hi:[0,1,1] neg_lo:[0,0,1] neg_hi:[0,0,0]
	v_pk_add_f32 v[110:111], v[82:83], v[90:91] neg_lo:[0,1] neg_hi:[0,1]
	v_pk_add_f32 v[112:113], v[84:85], v[92:93] neg_lo:[0,1] neg_hi:[0,1]
	v_pk_add_f32 v[114:115], v[86:87], v[94:95] neg_lo:[0,1] neg_hi:[0,1]
	v_pk_add_f32 v[116:117], v[88:89], v[96:97] neg_lo:[0,1] neg_hi:[0,1]
	v_pk_add_f32 v[82:83], v[82:83], v[90:91]
	v_pk_add_f32 v[84:85], v[84:85], v[92:93]
	v_pk_add_f32 v[86:87], v[86:87], v[94:95]
	v_pk_add_f32 v[88:89], v[88:89], v[96:97]
	v_pk_mul_f32 v[90:91], v[110:111], v[98:99] op_sel:[1,1] op_sel_hi:[1,0]
	v_pk_mul_f32 v[92:93], v[112:113], v[102:103] op_sel:[1,1] op_sel_hi:[1,0]
	v_pk_mul_f32 v[94:95], v[114:115], v[98:99] op_sel:[1,0] op_sel_hi:[1,1]
	v_pk_mul_f32 v[96:97], v[116:117], v[104:105] op_sel:[1,1] op_sel_hi:[1,0]
	v_pk_fma_f32 v[90:91], v[110:111], v[98:99], v[90:91] op_sel:[0,0,0] op_sel_hi:[0,1,1] neg_lo:[0,0,1] neg_hi:[0,0,0]
	v_pk_fma_f32 v[92:93], v[112:113], v[102:103], v[92:93] op_sel:[0,0,0] op_sel_hi:[0,1,1] neg_lo:[0,0,1] neg_hi:[0,0,0]
	v_pk_fma_f32 v[94:95], v[114:115], v[98:99], v[94:95] op_sel:[0,1,0] op_sel_hi:[0,0,1] neg_lo:[0,0,0] neg_hi:[0,1,0]
	v_pk_fma_f32 v[96:97], v[116:117], v[104:105], v[96:97] op_sel:[0,0,0] op_sel_hi:[0,1,1] neg_lo:[0,0,1] neg_hi:[0,0,0]
	v_pk_add_f32 v[110:111], v[82:83], v[86:87] neg_lo:[0,1] neg_hi:[0,1]
	v_pk_add_f32 v[112:113], v[84:85], v[88:89] neg_lo:[0,1] neg_hi:[0,1]
	v_pk_add_f32 v[114:115], v[90:91], v[94:95] neg_lo:[0,1] neg_hi:[0,1]
	v_pk_add_f32 v[116:117], v[92:93], v[96:97] neg_lo:[0,1] neg_hi:[0,1]
	v_pk_add_f32 v[82:83], v[82:83], v[86:87]
	v_pk_add_f32 v[84:85], v[84:85], v[88:89]
	v_pk_add_f32 v[90:91], v[90:91], v[94:95]
	v_pk_add_f32 v[92:93], v[92:93], v[96:97]
	v_pk_mul_f32 v[86:87], v[110:111], v[106:107] op_sel:[1,1] op_sel_hi:[1,0]
	v_pk_mul_f32 v[88:89], v[112:113], v[106:107] op_sel:[1,0] op_sel_hi:[1,1]
	v_pk_mul_f32 v[94:95], v[114:115], v[106:107] op_sel:[1,1] op_sel_hi:[1,0]
	v_pk_mul_f32 v[96:97], v[116:117], v[106:107] op_sel:[1,0] op_sel_hi:[1,1]
	v_pk_fma_f32 v[86:87], v[110:111], v[106:107], v[86:87] op_sel:[0,0,0] op_sel_hi:[0,1,1] neg_lo:[0,0,1] neg_hi:[0,0,0]
	v_pk_fma_f32 v[88:89], v[112:113], v[106:107], v[88:89] op_sel:[0,1,0] op_sel_hi:[0,0,1] neg_lo:[0,0,0] neg_hi:[0,1,0]
	v_pk_fma_f32 v[94:95], v[114:115], v[106:107], v[94:95] op_sel:[0,0,0] op_sel_hi:[0,1,1] neg_lo:[0,0,1] neg_hi:[0,0,0]
	v_pk_fma_f32 v[96:97], v[116:117], v[106:107], v[96:97] op_sel:[0,1,0] op_sel_hi:[0,0,1] neg_lo:[0,0,0] neg_hi:[0,1,0]
	v_pk_add_f32 v[110:111], v[82:83], v[84:85] neg_lo:[0,1] neg_hi:[0,1]
	v_pk_add_f32 v[112:113], v[86:87], v[88:89] neg_lo:[0,1] neg_hi:[0,1]
	v_pk_add_f32 v[114:115], v[90:91], v[92:93] neg_lo:[0,1] neg_hi:[0,1]
	v_pk_add_f32 v[116:117], v[94:95], v[96:97] neg_lo:[0,1] neg_hi:[0,1]
	v_pk_add_f32 v[82:83], v[82:83], v[84:85]
	v_pk_add_f32 v[86:87], v[86:87], v[88:89]
	v_pk_add_f32 v[90:91], v[90:91], v[92:93]
	v_pk_add_f32 v[94:95], v[94:95], v[96:97]
	v_pk_mul_f32 v[84:85], v[110:111], v[108:109] op_sel:[1,1] op_sel_hi:[1,0]
	v_pk_mul_f32 v[88:89], v[112:113], v[108:109] op_sel:[1,1] op_sel_hi:[1,0]
	v_pk_mul_f32 v[92:93], v[114:115], v[108:109] op_sel:[1,1] op_sel_hi:[1,0]
	v_pk_mul_f32 v[96:97], v[116:117], v[108:109] op_sel:[1,1] op_sel_hi:[1,0]
	v_pk_fma_f32 v[84:85], v[110:111], v[108:109], v[84:85] op_sel:[0,0,0] op_sel_hi:[0,1,1] neg_lo:[0,0,1] neg_hi:[0,0,0]
	v_pk_fma_f32 v[88:89], v[112:113], v[108:109], v[88:89] op_sel:[0,0,0] op_sel_hi:[0,1,1] neg_lo:[0,0,1] neg_hi:[0,0,0]
	v_pk_fma_f32 v[92:93], v[114:115], v[108:109], v[92:93] op_sel:[0,0,0] op_sel_hi:[0,1,1] neg_lo:[0,0,1] neg_hi:[0,0,0]
	v_pk_fma_f32 v[96:97], v[116:117], v[108:109], v[96:97] op_sel:[0,0,0] op_sel_hi:[0,1,1] neg_lo:[0,0,1] neg_hi:[0,0,0]
	ds_write2_b64 v81, v[82:83], v[84:85] offset1:17
	ds_write2_b64 v81, v[86:87], v[88:89] offset0:34 offset1:51
	ds_write2_b64 v81, v[90:91], v[92:93] offset0:68 offset1:85
	ds_write2_b64 v81, v[94:95], v[96:97] offset0:102 offset1:119
	s_waitcnt lgkmcnt(4)
; #define LAS __attribute__((address_space(3)))
; template <int LR> __device__ __forceinline__ void dif_reg(cf (&x)[1 << LR], cf w) {
;     constexpr int R = 1 << LR; cf ws = w;
; #pragma unroll
;     for (int s = 0; s < LR; ++s) { const int half = R >> (s + 1);
; #pragma unroll
;         for (int m0 = 0; m0 < R; m0 += 2 * half)
; #pragma unroll
;             for (int mm = 0; mm < half; ++mm) { const int ia = m0 + mm, ib = ia + half; const cf a = x[ia], b = x[ib];
;                 x[ia] = cf{a.x + b.x, a.y + b.y}; const cf d{a.x - b.x, a.y - b.y};
;                 x[ib] = cmul(d, twc(ws, (mm << s) * (16 / R))); }
;         ws = cmul(ws, ws); }
; }
; template <int LR> __device__ __forceinline__ void dit_reg(cf (&x)[1 << LR], cf w) {
;     constexpr int R = 1 << LR; cf wsv[LR]; wsv[0] = w;
; #pragma unroll
;     for (int s = 1; s < LR; ++s) wsv[s] = cmul(wsv[s - 1], wsv[s - 1]);
; #pragma unroll
;     for (int s = LR - 1; s >= 0; --s) { const int half = R >> (s + 1);
; #pragma unroll
;         for (int m0 = 0; m0 < R; m0 += 2 * half)
; #pragma unroll
;             for (int mm = 0; mm < half; ++mm) { const int ia = m0 + mm, ib = ia + half; const cf a = x[ia];
;                 const cf b = cmulc(x[ib], twc(wsv[s], (mm << s) * (16 / R)));
;                 x[ia] = cf{a.x + b.x, a.y + b.y}; x[ib] = cf{a.x - b.x, a.y - b.y}; } }
; }
; __device__ __forceinline__ void lds_barrier() { asm volatile("s_waitcnt lgkmcnt(0)\n\ts_barrier" ::: "memory"); }
; template <int LR, bool INV> __device__ __forceinline__ void fft_pass(ldsf2 buf, int base, int stride, int twi) {
;     constexpr int R = 1 << LR; cf x[R];
;     const v2f wv = ((ldsf2)((LAS unsigned char*)buf + 139264))[twi];
; #pragma unroll
;     for (int m = 0; m < R; ++m) { const v2f v = buf[base + m * stride]; x[m] = cf{v.x, v.y}; }
;     const cf w{wv.x, wv.y};
;     if (INV) dit_reg<LR>(x, w); else dif_reg<LR>(x, w);
; #pragma unroll
;     for (int m = 0; m < R; ++m) buf[base + m * stride] = mkv2(x[m].x, x[m].y);
; }
; __device__ __forceinline__ void fft_conv(ldsf2 buf, const LAS unsigned* spec) {
;     fft_fwd_abc(buf);
;     { const int tid = otid(); cf x[16];
; #pragma unroll
;       for (int m = 0; m < 16; ++m) { const v2f v = buf[tid * 17 + m]; x[m] = cf{v.x, v.y}; }
;       dif_reg<4>(x, cf{1.0f, 0.0f});
; #pragma unroll
	v_pk_add_f32 v[156:157], v[128:129], v[128:129] op_sel:[0,1] op_sel_hi:[1,0] neg_lo:[0,0] neg_hi:[0,1]
	v_pk_mul_f32 v[158:159], v[156:157], s[16:17] op_sel:[0,0] op_sel_hi:[1,0]
	v_pk_mul_f32 v[160:161], v[156:157], s[16:17] op_sel:[1,0] op_sel_hi:[0,0] neg_lo:[0,0] neg_hi:[1,0]
	v_pk_mul_f32 v[162:163], v[128:129], v[128:129] op_sel:[1,1] op_sel_hi:[1,0]
	v_pk_fma_f32 v[162:163], v[128:129], v[128:129], v[162:163] op_sel:[0,0,0] op_sel_hi:[0,1,1] neg_lo:[0,0,1] neg_hi:[0,0,0]
	v_pk_mul_f32 v[164:165], v[162:163], v[162:163] op_sel:[1,1] op_sel_hi:[1,0]
	v_pk_fma_f32 v[164:165], v[162:163], v[162:163], v[164:165] op_sel:[0,0,0] op_sel_hi:[0,1,1] neg_lo:[0,0,1] neg_hi:[0,0,0]
	v_pk_add_f32 v[166:167], v[132:133], v[140:141] neg_lo:[0,1] neg_hi:[0,1]
	v_pk_add_f32 v[168:169], v[134:135], v[142:143] neg_lo:[0,1] neg_hi:[0,1]
	v_pk_add_f32 v[170:171], v[136:137], v[152:153] neg_lo:[0,1] neg_hi:[0,1]
	v_pk_add_f32 v[172:173], v[138:139], v[154:155] neg_lo:[0,1] neg_hi:[0,1]
	v_pk_add_f32 v[132:133], v[132:133], v[140:141]
	v_pk_add_f32 v[134:135], v[134:135], v[142:143]
	v_pk_add_f32 v[136:137], v[136:137], v[152:153]
	v_pk_add_f32 v[138:139], v[138:139], v[154:155]
	v_pk_mul_f32 v[140:141], v[166:167], v[128:129] op_sel:[1,1] op_sel_hi:[1,0]
	v_pk_mul_f32 v[142:143], v[168:169], v[158:159] op_sel:[1,1] op_sel_hi:[1,0]
	v_pk_mul_f32 v[152:153], v[170:171], v[128:129] op_sel:[1,0] op_sel_hi:[1,1]
	v_pk_mul_f32 v[154:155], v[172:173], v[160:161] op_sel:[1,1] op_sel_hi:[1,0]
	v_pk_fma_f32 v[140:141], v[166:167], v[128:129], v[140:141] op_sel:[0,0,0] op_sel_hi:[0,1,1] neg_lo:[0,0,1] neg_hi:[0,0,0]
	v_pk_fma_f32 v[142:143], v[168:169], v[158:159], v[142:143] op_sel:[0,0,0] op_sel_hi:[0,1,1] neg_lo:[0,0,1] neg_hi:[0,0,0]
	v_pk_fma_f32 v[152:153], v[170:171], v[128:129], v[152:153] op_sel:[0,1,0] op_sel_hi:[0,0,1] neg_lo:[0,0,0] neg_hi:[0,1,0]
	v_pk_fma_f32 v[154:155], v[172:173], v[160:161], v[154:155] op_sel:[0,0,0] op_sel_hi:[0,1,1] neg_lo:[0,0,1] neg_hi:[0,0,0]
	v_pk_add_f32 v[166:167], v[132:133], v[136:137] neg_lo:[0,1] neg_hi:[0,1]
	v_pk_add_f32 v[168:169], v[134:135], v[138:139] neg_lo:[0,1] neg_hi:[0,1]
	v_pk_add_f32 v[170:171], v[140:141], v[152:153] neg_lo:[0,1] neg_hi:[0,1]
	v_pk_add_f32 v[172:173], v[142:143], v[154:155] neg_lo:[0,1] neg_hi:[0,1]
	v_pk_add_f32 v[132:133], v[132:133], v[136:137]
	v_pk_add_f32 v[134:135], v[134:135], v[138:139]
	v_pk_add_f32 v[140:141], v[140:141], v[152:153]
	v_pk_add_f32 v[142:143], v[142:143], v[154:155]
	v_pk_mul_f32 v[136:137], v[166:167], v[162:163] op_sel:[1,1] op_sel_hi:[1,0]
	v_pk_mul_f32 v[138:139], v[168:169], v[162:163] op_sel:[1,0] op_sel_hi:[1,1]
	v_pk_mul_f32 v[152:153], v[170:171], v[162:163] op_sel:[1,1] op_sel_hi:[1,0]
	v_pk_mul_f32 v[154:155], v[172:173], v[162:163] op_sel:[1,0] op_sel_hi:[1,1]
	v_pk_fma_f32 v[136:137], v[166:167], v[162:163], v[136:137] op_sel:[0,0,0] op_sel_hi:[0,1,1] neg_lo:[0,0,1] neg_hi:[0,0,0]
	v_pk_fma_f32 v[138:139], v[168:169], v[162:163], v[138:139] op_sel:[0,1,0] op_sel_hi:[0,0,1] neg_lo:[0,0,0] neg_hi:[0,1,0]
	v_pk_fma_f32 v[152:153], v[170:171], v[162:163], v[152:153] op_sel:[0,0,0] op_sel_hi:[0,1,1] neg_lo:[0,0,1] neg_hi:[0,0,0]
	v_pk_fma_f32 v[154:155], v[172:173], v[162:163], v[154:155] op_sel:[0,1,0] op_sel_hi:[0,0,1] neg_lo:[0,0,0] neg_hi:[0,1,0]
	v_pk_add_f32 v[166:167], v[132:133], v[134:135] neg_lo:[0,1] neg_hi:[0,1]
	v_pk_add_f32 v[168:169], v[136:137], v[138:139] neg_lo:[0,1] neg_hi:[0,1]
	v_pk_add_f32 v[170:171], v[140:141], v[142:143] neg_lo:[0,1] neg_hi:[0,1]
	v_pk_add_f32 v[172:173], v[152:153], v[154:155] neg_lo:[0,1] neg_hi:[0,1]
	v_pk_add_f32 v[132:133], v[132:133], v[134:135]
	v_pk_add_f32 v[136:137], v[136:137], v[138:139]
	v_pk_add_f32 v[140:141], v[140:141], v[142:143]
	v_pk_add_f32 v[152:153], v[152:153], v[154:155]
	v_pk_mul_f32 v[134:135], v[166:167], v[164:165] op_sel:[1,1] op_sel_hi:[1,0]
	v_pk_mul_f32 v[138:139], v[168:169], v[164:165] op_sel:[1,1] op_sel_hi:[1,0]
	v_pk_mul_f32 v[142:143], v[170:171], v[164:165] op_sel:[1,1] op_sel_hi:[1,0]
	v_pk_mul_f32 v[154:155], v[172:173], v[164:165] op_sel:[1,1] op_sel_hi:[1,0]
	v_pk_fma_f32 v[134:135], v[166:167], v[164:165], v[134:135] op_sel:[0,0,0] op_sel_hi:[0,1,1] neg_lo:[0,0,1] neg_hi:[0,0,0]
	v_pk_fma_f32 v[138:139], v[168:169], v[164:165], v[138:139] op_sel:[0,0,0] op_sel_hi:[0,1,1] neg_lo:[0,0,1] neg_hi:[0,0,0]
	v_pk_fma_f32 v[142:143], v[170:171], v[164:165], v[142:143] op_sel:[0,0,0] op_sel_hi:[0,1,1] neg_lo:[0,0,1] neg_hi:[0,0,0]
	v_pk_fma_f32 v[154:155], v[172:173], v[164:165], v[154:155] op_sel:[0,0,0] op_sel_hi:[0,1,1] neg_lo:[0,0,1] neg_hi:[0,0,0]
	ds_write2_b64 v126, v[132:133], v[134:135] offset1:17
	ds_write2_b64 v126, v[136:137], v[138:139] offset0:34 offset1:51
	ds_write2_b64 v126, v[140:141], v[142:143] offset0:68 offset1:85
	ds_write2_b64 v126, v[152:153], v[154:155] offset0:102 offset1:119
	s_mov_b64 s[10:11], 0
	v_mov_b32_e32 v162, v195
	s_movk_i32 s0, 0x88
	s_waitcnt lgkmcnt(0)
	s_mov_b32 s86, s63
	v_mul_lo_u32 v78, v162, s0
	v_add_u32_e32 v151, 0, v78
	ds_read2_b64 v[80:83], v151 offset1:1
	ds_read2_b64 v[84:87], v151 offset0:2 offset1:3
	ds_read2_b64 v[98:101], v151 offset0:4 offset1:5
	ds_read2_b64 v[102:105], v151 offset0:6 offset1:7
	ds_read2_b64 v[106:109], v151 offset0:8 offset1:9
	ds_read2_b64 v[110:113], v151 offset0:10 offset1:11
	ds_read2_b64 v[126:129], v151 offset0:12 offset1:13
	ds_read2_b64 v[134:137], v151 offset0:14 offset1:15
	s_mov_b32 s10, s63
	s_mov_b32 s11, s16
	s_mov_b32 s17, s5
	s_mov_b32 s0, s16
	s_mov_b32 s1, s4
	s_mov_b32 s0, s63
	s_mov_b32 s1, s5
	s_mov_b32 s0, s87
	s_mov_b32 s1, s4
	s_mov_b32 s1, s5
	s_mov_b32 s35, s4
	s_mov_b32 s12, s63
	s_movk_i32 s0, 0x44
	v_mul_lo_u32 v114, v162, s0
	v_add_u32_e32 v114, 0, v114
	v_add_u32_e32 v114, 0x19800, v114
	ds_read2_b32 v[160:161], v114 offset1:1
	ds_read2_b32 v[162:163], v114 offset0:2 offset1:3
	ds_read2_b32 v[164:165], v114 offset0:4 offset1:5
	ds_read2_b32 v[166:167], v114 offset0:6 offset1:7
	ds_read2_b32 v[168:169], v114 offset0:8 offset1:9
	ds_read2_b32 v[142:143], v114 offset0:10 offset1:11
	ds_read2_b32 v[138:139], v114 offset0:12 offset1:13
	ds_read2_b32 v[172:173], v114 offset0:14 offset1:15
	s_mov_b32 s0, s5
	s_mov_b64 s[14:15], -1
	s_mov_b32 s35, s13
	s_mov_b32 s0, s13
	s_waitcnt lgkmcnt(8)
; __device__ __forceinline__ cf twc(cf ws, int k16) { if (k16 == 0) return ws; if (k16 == 4) return cf{ws.y, -ws.x}; return cmul(ws, cf{c16(k16), -s16(k16)}); }
; template <int LR> __device__ __forceinline__ void dif_reg(cf (&x)[1 << LR], cf w) {
;     constexpr int R = 1 << LR; cf ws = w;
; #pragma unroll
;     for (int s = 0; s < LR; ++s) { const int half = R >> (s + 1);
; #pragma unroll
;         for (int m0 = 0; m0 < R; m0 += 2 * half)
; #pragma unroll
;             for (int mm = 0; mm < half; ++mm) { const int ia = m0 + mm, ib = ia + half; const cf a = x[ia], b = x[ib];
;                 x[ia] = cf{a.x + b.x, a.y + b.y}; const cf d{a.x - b.x, a.y - b.y};
;                 x[ib] = cmul(d, twc(ws, (mm << s) * (16 / R))); }
;         ws = cmul(ws, ws); }
; }
; __device__ __forceinline__ void fft_conv(ldsf2 buf, const LAS unsigned* spec) {
;     ...
;       for (int m = 0; m < 16; ++m) { const v2f v = buf[tid * 17 + m]; x[m] = cf{v.x, v.y}; }
;       dif_reg<4>(x, cf{1.0f, 0.0f});
	v_pk_add_f32 v[88:89], v[80:81], v[106:107]
	v_pk_add_f32 v[90:91], v[82:83], v[108:109]
	v_pk_add_f32 v[92:93], v[84:85], v[110:111]
	v_pk_add_f32 v[94:95], v[86:87], v[112:113]
	v_pk_add_f32 v[80:81], v[80:81], v[106:107] neg_lo:[0,1] neg_hi:[0,1]
	v_pk_add_f32 v[82:83], v[82:83], v[108:109] neg_lo:[0,1] neg_hi:[0,1]
	v_pk_add_f32 v[84:85], v[84:85], v[110:111] neg_lo:[0,1] neg_hi:[0,1]
	v_pk_add_f32 v[86:87], v[86:87], v[112:113] neg_lo:[0,1] neg_hi:[0,1]
	v_pk_mul_f32 v[108:109], v[82:83], s[4:5] op_sel:[1,1] op_sel_hi:[1,0] neg_lo:[0,1] neg_hi:[0,0]
	v_pk_mul_f32 v[110:111], v[84:85], s[16:17] op_sel:[1,0] op_sel_hi:[1,0] neg_lo:[0,1] neg_hi:[0,0]
	v_pk_mul_f32 v[112:113], v[86:87], s[4:5] op_sel:[1,0] op_sel_hi:[1,1] neg_lo:[0,1] neg_hi:[0,0]
	v_pk_fma_f32 v[108:109], v[82:83], s[4:5], v[108:109] op_sel:[0,0,0] op_sel_hi:[0,1,1] neg_lo:[0,0,1] neg_hi:[0,1,0]
	v_pk_fma_f32 v[110:111], v[84:85], s[16:17], v[110:111] op_sel:[0,0,0] op_sel_hi:[0,0,1] neg_lo:[0,0,1] neg_hi:[0,1,0]
	v_pk_fma_f32 v[112:113], v[86:87], s[4:5], v[112:113] op_sel:[0,1,0] op_sel_hi:[0,0,1] neg_lo:[0,0,1] neg_hi:[0,1,0]
	v_pk_add_f32 v[96:97], v[98:99], v[126:127]
	v_pk_add_f32 v[116:117], v[100:101], v[128:129]
	v_pk_add_f32 v[118:119], v[102:103], v[134:135]
	v_pk_add_f32 v[120:121], v[104:105], v[136:137]
	v_pk_add_f32 v[98:99], v[98:99], v[126:127] op_sel:[1,1] op_sel_hi:[0,0] neg_lo:[0,1] neg_hi:[1,0]
	v_pk_add_f32 v[100:101], v[100:101], v[128:129] neg_lo:[0,1] neg_hi:[0,1]
	v_pk_add_f32 v[102:103], v[102:103], v[134:135] neg_lo:[0,1] neg_hi:[0,1]
	v_pk_add_f32 v[104:105], v[104:105], v[136:137] neg_lo:[0,1] neg_hi:[0,1]
	v_pk_mul_f32 v[128:129], v[100:101], s[4:5] op_sel:[1,0] op_sel_hi:[1,1] neg_lo:[0,1] neg_hi:[0,1]
	v_pk_mul_f32 v[134:135], v[102:103], s[16:17] op_sel:[1,0] op_sel_hi:[1,0] neg_lo:[0,1] neg_hi:[0,1]
	v_pk_mul_f32 v[136:137], v[104:105], s[4:5] op_sel:[1,1] op_sel_hi:[1,0] neg_lo:[0,1] neg_hi:[0,1]
	v_pk_fma_f32 v[128:129], v[100:101], s[4:5], v[128:129] op_sel:[0,1,0] op_sel_hi:[0,0,1] neg_lo:[0,1,1] neg_hi:[0,1,0]
	v_pk_fma_f32 v[134:135], v[102:103], s[16:17], v[134:135] op_sel:[0,0,0] op_sel_hi:[0,0,1] neg_lo:[0,1,1] neg_hi:[0,1,0]
	v_pk_fma_f32 v[136:137], v[104:105], s[4:5], v[136:137] op_sel:[0,0,0] op_sel_hi:[0,1,1] neg_lo:[0,1,1] neg_hi:[0,1,0]
	v_pk_add_f32 v[122:123], v[88:89], v[96:97]
	v_pk_add_f32 v[124:125], v[90:91], v[116:117]
	v_pk_add_f32 v[130:131], v[92:93], v[118:119]
	v_pk_add_f32 v[132:133], v[94:95], v[120:121]
	v_pk_add_f32 v[88:89], v[88:89], v[96:97] neg_lo:[0,1] neg_hi:[0,1]
	v_pk_add_f32 v[90:91], v[90:91], v[116:117] neg_lo:[0,1] neg_hi:[0,1]
	v_pk_add_f32 v[92:93], v[92:93], v[118:119] op_sel:[1,1] op_sel_hi:[0,0] neg_lo:[0,1] neg_hi:[1,0]
	v_pk_add_f32 v[94:95], v[94:95], v[120:121] neg_lo:[0,1] neg_hi:[0,1]
	v_pk_mul_f32 v[116:117], v[90:91], s[16:17] op_sel:[1,0] op_sel_hi:[1,0] neg_lo:[0,1] neg_hi:[0,0]
	v_pk_mul_f32 v[120:121], v[94:95], s[16:17] op_sel:[1,0] op_sel_hi:[1,0] neg_lo:[0,1] neg_hi:[0,1]
	v_pk_fma_f32 v[116:117], v[90:91], s[16:17], v[116:117] op_sel:[0,0,0] op_sel_hi:[0,0,1] neg_lo:[0,0,1] neg_hi:[0,1,0]
	v_pk_fma_f32 v[120:121], v[94:95], s[16:17], v[120:121] op_sel:[0,0,0] op_sel_hi:[0,0,1] neg_lo:[0,1,1] neg_hi:[0,1,0]
	v_pk_add_f32 v[140:141], v[80:81], v[98:99]
	v_pk_add_f32 v[152:153], v[108:109], v[128:129]
	v_pk_add_f32 v[154:155], v[110:111], v[134:135]
	v_pk_add_f32 v[156:157], v[112:113], v[136:137]
	v_pk_add_f32 v[80:81], v[80:81], v[98:99] neg_lo:[0,1] neg_hi:[0,1]
	v_pk_add_f32 v[108:109], v[108:109], v[128:129] neg_lo:[0,1] neg_hi:[0,1]
	v_pk_add_f32 v[110:111], v[110:111], v[134:135] op_sel:[1,1] op_sel_hi:[0,0] neg_lo:[0,1] neg_hi:[1,0]
	v_pk_add_f32 v[112:113], v[112:113], v[136:137] neg_lo:[0,1] neg_hi:[0,1]
	v_pk_mul_f32 v[128:129], v[108:109], s[16:17] op_sel:[1,0] op_sel_hi:[1,0] neg_lo:[0,1] neg_hi:[0,0]
	v_pk_mul_f32 v[136:137], v[112:113], s[16:17] op_sel:[1,0] op_sel_hi:[1,0] neg_lo:[0,1] neg_hi:[0,1]
	v_pk_fma_f32 v[128:129], v[108:109], s[16:17], v[128:129] op_sel:[0,0,0] op_sel_hi:[0,0,1] neg_lo:[0,0,1] neg_hi:[0,1,0]
	v_pk_fma_f32 v[136:137], v[112:113], s[16:17], v[136:137] op_sel:[0,0,0] op_sel_hi:[0,0,1] neg_lo:[0,1,1] neg_hi:[0,1,0]
	v_pk_add_f32 v[158:159], v[122:123], v[130:131]
	v_pk_add_f32 v[170:171], v[124:125], v[132:133]
	v_pk_add_f32 v[106:107], v[88:89], v[92:93]
	v_pk_add_f32 v[82:83], v[116:117], v[120:121]
	v_pk_add_f32 v[122:123], v[122:123], v[130:131] neg_lo:[0,1] neg_hi:[0,1]
	v_pk_add_f32 v[124:125], v[124:125], v[132:133] op_sel:[1,1] op_sel_hi:[0,0] neg_lo:[0,1] neg_hi:[1,0]
	v_pk_add_f32 v[88:89], v[88:89], v[92:93] neg_lo:[0,1] neg_hi:[0,1]
	v_pk_add_f32 v[116:117], v[116:117], v[120:121] op_sel:[1,1] op_sel_hi:[0,0] neg_lo:[0,1] neg_hi:[1,0]
	v_pk_add_f32 v[84:85], v[140:141], v[154:155]
	v_pk_add_f32 v[86:87], v[152:153], v[156:157]
	v_pk_add_f32 v[126:127], v[80:81], v[110:111]
	v_pk_add_f32 v[100:101], v[128:129], v[136:137]
	v_pk_add_f32 v[140:141], v[140:141], v[154:155] neg_lo:[0,1] neg_hi:[0,1]
	v_pk_add_f32 v[152:153], v[152:153], v[156:157] op_sel:[1,1] op_sel_hi:[0,0] neg_lo:[0,1] neg_hi:[1,0]
	v_pk_add_f32 v[80:81], v[80:81], v[110:111] neg_lo:[0,1] neg_hi:[0,1]
	v_pk_add_f32 v[128:129], v[128:129], v[136:137] op_sel:[1,1] op_sel_hi:[0,0] neg_lo:[0,1] neg_hi:[1,0]
	v_pk_add_f32 v[102:103], v[158:159], v[170:171]
	v_pk_add_f32 v[104:105], v[122:123], v[124:125]
	v_pk_add_f32 v[96:97], v[106:107], v[82:83]
	v_pk_add_f32 v[90:91], v[88:89], v[116:117]
	v_pk_add_f32 v[158:159], v[158:159], v[170:171] neg_lo:[0,1] neg_hi:[0,1]
	v_pk_add_f32 v[122:123], v[122:123], v[124:125] neg_lo:[0,1] neg_hi:[0,1]
	v_pk_add_f32 v[106:107], v[106:107], v[82:83] neg_lo:[0,1] neg_hi:[0,1]
	v_pk_add_f32 v[88:89], v[88:89], v[116:117] neg_lo:[0,1] neg_hi:[0,1]
	v_pk_add_f32 v[118:119], v[84:85], v[86:87]
	v_pk_add_f32 v[94:95], v[140:141], v[152:153]
	v_pk_add_f32 v[98:99], v[126:127], v[100:101]
	v_pk_add_f32 v[108:109], v[80:81], v[128:129]
	v_pk_add_f32 v[84:85], v[84:85], v[86:87] neg_lo:[0,1] neg_hi:[0,1]
	v_pk_add_f32 v[140:141], v[140:141], v[152:153] neg_lo:[0,1] neg_hi:[0,1]
	v_pk_add_f32 v[126:127], v[126:127], v[100:101] neg_lo:[0,1] neg_hi:[0,1]
	v_pk_add_f32 v[80:81], v[80:81], v[128:129] neg_lo:[0,1] neg_hi:[0,1]
	s_waitcnt lgkmcnt(0)
; __device__ __forceinline__ cf twc(cf ws, int k16) { if (k16 == 0) return ws; if (k16 == 4) return cf{ws.y, -ws.x}; return cmul(ws, cf{c16(k16), -s16(k16)}); }
; template <int LR> __device__ __forceinline__ void dit_reg(cf (&x)[1 << LR], cf w) {
;     constexpr int R = 1 << LR; cf wsv[LR]; wsv[0] = w;
; #pragma unroll
;     for (int s = 1; s < LR; ++s) wsv[s] = cmul(wsv[s - 1], wsv[s - 1]);
; #pragma unroll
;     for (int s = LR - 1; s >= 0; --s) { const int half = R >> (s + 1);
; #pragma unroll
;         for (int m0 = 0; m0 < R; m0 += 2 * half)
; #pragma unroll
;             for (int mm = 0; mm < half; ++mm) { const int ia = m0 + mm, ib = ia + half; const cf a = x[ia];
;                 const cf b = cmulc(x[ib], twc(wsv[s], (mm << s) * (16 / R)));
;                 x[ia] = cf{a.x + b.x, a.y + b.y}; x[ib] = cf{a.x - b.x, a.y - b.y}; } }
; __device__ __forceinline__ void fft_conv(ldsf2 buf, const LAS unsigned* spec) {
;     ...
; #pragma unroll
;       for (int m = 0; m < 16; ++m) { const h2_t hv = __builtin_bit_cast(h2_t, spec[tid * 17 + m]); x[m] = cmul(x[m], cf{(float)hv.x, (float)hv.y}); }
;       dit_reg<4>(x, cf{1.0f, 0.0f});
	v_cvt_f32_f16_e32 v134, v160
	v_cvt_f32_f16_e32 v130, v161
	v_cvt_f32_f16_e32 v92, v162
	v_cvt_f32_f16_e32 v154, v163
	v_cvt_f32_f16_sdwa v135, v160 dst_sel:DWORD dst_unused:UNUSED_PAD src0_sel:WORD_1
	v_cvt_f32_f16_sdwa v131, v161 dst_sel:DWORD dst_unused:UNUSED_PAD src0_sel:WORD_1
	v_cvt_f32_f16_sdwa v93, v162 dst_sel:DWORD dst_unused:UNUSED_PAD src0_sel:WORD_1
	v_cvt_f32_f16_sdwa v155, v163 dst_sel:DWORD dst_unused:UNUSED_PAD src0_sel:WORD_1
	v_pk_mul_f32 v[112:113], v[102:103], v[134:135] op_sel:[1,1] op_sel_hi:[1,0]
	v_pk_mul_f32 v[132:133], v[158:159], v[130:131] op_sel:[1,1] op_sel_hi:[1,0]
	v_pk_mul_f32 v[120:121], v[104:105], v[92:93] op_sel:[1,1] op_sel_hi:[1,0]
	v_pk_mul_f32 v[156:157], v[122:123], v[154:155] op_sel:[1,1] op_sel_hi:[1,0]
	v_pk_fma_f32 v[134:135], v[102:103], v[134:135], v[112:113] op_sel:[0,0,0] op_sel_hi:[0,1,1] neg_lo:[0,0,1] neg_hi:[0,0,0]
	v_pk_fma_f32 v[130:131], v[158:159], v[130:131], v[132:133] op_sel:[0,0,0] op_sel_hi:[0,1,1] neg_lo:[0,0,1] neg_hi:[0,0,0]
	v_pk_fma_f32 v[92:93], v[104:105], v[92:93], v[120:121] op_sel:[0,0,0] op_sel_hi:[0,1,1] neg_lo:[0,0,1] neg_hi:[0,0,0]
	v_pk_fma_f32 v[154:155], v[122:123], v[154:155], v[156:157] op_sel:[0,0,0] op_sel_hi:[0,1,1] neg_lo:[0,0,1] neg_hi:[0,0,0]
	v_cvt_f32_f16_e32 v110, v164
	v_cvt_f32_f16_e32 v170, v165
	v_cvt_f32_f16_e32 v82, v166
	v_cvt_f32_f16_e32 v86, v167
	v_cvt_f32_f16_sdwa v111, v164 dst_sel:DWORD dst_unused:UNUSED_PAD src0_sel:WORD_1
	v_cvt_f32_f16_sdwa v171, v165 dst_sel:DWORD dst_unused:UNUSED_PAD src0_sel:WORD_1
	v_cvt_f32_f16_sdwa v83, v166 dst_sel:DWORD dst_unused:UNUSED_PAD src0_sel:WORD_1
	v_cvt_f32_f16_sdwa v87, v167 dst_sel:DWORD dst_unused:UNUSED_PAD src0_sel:WORD_1
	v_pk_mul_f32 v[136:137], v[96:97], v[110:111] op_sel:[1,1] op_sel_hi:[1,0]
	v_pk_mul_f32 v[124:125], v[106:107], v[170:171] op_sel:[1,1] op_sel_hi:[1,0]
	v_pk_mul_f32 v[116:117], v[90:91], v[82:83] op_sel:[1,1] op_sel_hi:[1,0]
	v_pk_mul_f32 v[152:153], v[88:89], v[86:87] op_sel:[1,1] op_sel_hi:[1,0]
	v_pk_fma_f32 v[110:111], v[96:97], v[110:111], v[136:137] op_sel:[0,0,0] op_sel_hi:[0,1,1] neg_lo:[0,0,1] neg_hi:[0,0,0]
	v_pk_fma_f32 v[170:171], v[106:107], v[170:171], v[124:125] op_sel:[0,0,0] op_sel_hi:[0,1,1] neg_lo:[0,0,1] neg_hi:[0,0,0]
	v_pk_fma_f32 v[82:83], v[90:91], v[82:83], v[116:117] op_sel:[0,0,0] op_sel_hi:[0,1,1] neg_lo:[0,0,1] neg_hi:[0,0,0]
	v_pk_fma_f32 v[86:87], v[88:89], v[86:87], v[152:153] op_sel:[0,0,0] op_sel_hi:[0,1,1] neg_lo:[0,0,1] neg_hi:[0,0,0]
	v_cvt_f32_f16_e32 v100, v168
	v_cvt_f32_f16_e32 v112, v169
	v_cvt_f32_f16_e32 v132, v142
	v_cvt_f32_f16_e32 v120, v143
	v_cvt_f32_f16_sdwa v101, v168 dst_sel:DWORD dst_unused:UNUSED_PAD src0_sel:WORD_1
	v_cvt_f32_f16_sdwa v113, v169 dst_sel:DWORD dst_unused:UNUSED_PAD src0_sel:WORD_1
	v_cvt_f32_f16_sdwa v133, v142 dst_sel:DWORD dst_unused:UNUSED_PAD src0_sel:WORD_1
	v_cvt_f32_f16_sdwa v121, v143 dst_sel:DWORD dst_unused:UNUSED_PAD src0_sel:WORD_1
	v_pk_mul_f32 v[128:129], v[118:119], v[100:101] op_sel:[1,1] op_sel_hi:[1,0]
	v_pk_mul_f32 v[102:103], v[84:85], v[112:113] op_sel:[1,1] op_sel_hi:[1,0]
	v_pk_mul_f32 v[158:159], v[94:95], v[132:133] op_sel:[1,1] op_sel_hi:[1,0]
	v_pk_mul_f32 v[104:105], v[140:141], v[120:121] op_sel:[1,1] op_sel_hi:[1,0]
	v_pk_fma_f32 v[100:101], v[118:119], v[100:101], v[128:129] op_sel:[0,0,0] op_sel_hi:[0,1,1] neg_lo:[0,0,1] neg_hi:[0,0,0]
	v_pk_fma_f32 v[112:113], v[84:85], v[112:113], v[102:103] op_sel:[0,0,0] op_sel_hi:[0,1,1] neg_lo:[0,0,1] neg_hi:[0,0,0]
	v_pk_fma_f32 v[132:133], v[94:95], v[132:133], v[158:159] op_sel:[0,0,0] op_sel_hi:[0,1,1] neg_lo:[0,0,1] neg_hi:[0,0,0]
	v_pk_fma_f32 v[120:121], v[140:141], v[120:121], v[104:105] op_sel:[0,0,0] op_sel_hi:[0,1,1] neg_lo:[0,0,1] neg_hi:[0,0,0]
	v_cvt_f32_f16_e32 v156, v138
	v_cvt_f32_f16_e32 v136, v139
	v_cvt_f32_f16_e32 v124, v172
	v_cvt_f32_f16_e32 v116, v173
	v_cvt_f32_f16_sdwa v157, v138 dst_sel:DWORD dst_unused:UNUSED_PAD src0_sel:WORD_1
	v_cvt_f32_f16_sdwa v137, v139 dst_sel:DWORD dst_unused:UNUSED_PAD src0_sel:WORD_1
	v_cvt_f32_f16_sdwa v125, v172 dst_sel:DWORD dst_unused:UNUSED_PAD src0_sel:WORD_1
	v_cvt_f32_f16_sdwa v117, v173 dst_sel:DWORD dst_unused:UNUSED_PAD src0_sel:WORD_1
	v_pk_mul_f32 v[122:123], v[98:99], v[156:157] op_sel:[1,1] op_sel_hi:[1,0]
	v_pk_mul_f32 v[96:97], v[126:127], v[136:137] op_sel:[1,1] op_sel_hi:[1,0]
	v_pk_mul_f32 v[106:107], v[108:109], v[124:125] op_sel:[1,1] op_sel_hi:[1,0]
	v_pk_mul_f32 v[90:91], v[80:81], v[116:117] op_sel:[1,1] op_sel_hi:[1,0]
	v_pk_fma_f32 v[156:157], v[98:99], v[156:157], v[122:123] op_sel:[0,0,0] op_sel_hi:[0,1,1] neg_lo:[0,0,1] neg_hi:[0,0,0]
	v_pk_fma_f32 v[136:137], v[126:127], v[136:137], v[96:97] op_sel:[0,0,0] op_sel_hi:[0,1,1] neg_lo:[0,0,1] neg_hi:[0,0,0]
	v_pk_fma_f32 v[124:125], v[108:109], v[124:125], v[106:107] op_sel:[0,0,0] op_sel_hi:[0,1,1] neg_lo:[0,0,1] neg_hi:[0,0,0]
	v_pk_fma_f32 v[116:117], v[80:81], v[116:117], v[90:91] op_sel:[0,0,0] op_sel_hi:[0,1,1] neg_lo:[0,0,1] neg_hi:[0,0,0]
	v_pk_add_f32 v[152:153], v[134:135], v[130:131]
	v_pk_add_f32 v[88:89], v[92:93], v[154:155]
	v_pk_add_f32 v[128:129], v[110:111], v[170:171]
	v_pk_add_f32 v[118:119], v[82:83], v[86:87]
	v_pk_add_f32 v[134:135], v[134:135], v[130:131] neg_lo:[0,1] neg_hi:[0,1]
	v_pk_add_f32 v[92:93], v[92:93], v[154:155] neg_lo:[0,1] neg_hi:[0,1]
	v_pk_add_f32 v[110:111], v[110:111], v[170:171] neg_lo:[0,1] neg_hi:[0,1]
	v_pk_add_f32 v[82:83], v[82:83], v[86:87] neg_lo:[0,1] neg_hi:[0,1]
	v_pk_add_f32 v[102:103], v[100:101], v[112:113]
	v_pk_add_f32 v[84:85], v[132:133], v[120:121]
	v_pk_add_f32 v[158:159], v[156:157], v[136:137]
	v_pk_add_f32 v[94:95], v[124:125], v[116:117]
; __device__ __forceinline__ cf twc(cf ws, int k16) { if (k16 == 0) return ws; if (k16 == 4) return cf{ws.y, -ws.x}; return cmul(ws, cf{c16(k16), -s16(k16)}); }
; __device__ __forceinline__ void wave_lds_fence() { asm volatile("s_waitcnt lgkmcnt(0)" ::: "memory"); }
; template <int LR> __device__ __forceinline__ void dit_reg(cf (&x)[1 << LR], cf w) {
;     constexpr int R = 1 << LR; cf wsv[LR]; wsv[0] = w;
; #pragma unroll
;     for (int s = 1; s < LR; ++s) wsv[s] = cmul(wsv[s - 1], wsv[s - 1]);
; #pragma unroll
;     for (int s = LR - 1; s >= 0; --s) { const int half = R >> (s + 1);
; #pragma unroll
;         for (int m0 = 0; m0 < R; m0 += 2 * half)
; #pragma unroll
;             for (int mm = 0; mm < half; ++mm) { const int ia = m0 + mm, ib = ia + half; const cf a = x[ia];
;                 const cf b = cmulc(x[ib], twc(wsv[s], (mm << s) * (16 / R)));
;                 x[ia] = cf{a.x + b.x, a.y + b.y}; x[ib] = cf{a.x - b.x, a.y - b.y}; } }
; __device__ __forceinline__ void fft_conv(ldsf2 buf, const LAS unsigned* spec) {
;     ...
;       dit_reg<4>(x, cf{1.0f, 0.0f});
; #pragma unroll
;       for (int m = 0; m < 16; ++m) buf[tid * 17 + m] = mkv2(x[m].x, x[m].y); }
;     wave_lds_fence();
	v_pk_add_f32 v[100:101], v[100:101], v[112:113] neg_lo:[0,1] neg_hi:[0,1]
	v_pk_add_f32 v[132:133], v[132:133], v[120:121] neg_lo:[0,1] neg_hi:[0,1]
	v_pk_add_f32 v[156:157], v[156:157], v[136:137] neg_lo:[0,1] neg_hi:[0,1]
	v_pk_add_f32 v[124:125], v[124:125], v[116:117] neg_lo:[0,1] neg_hi:[0,1]
	v_pk_add_f32 v[104:105], v[152:153], v[88:89]
	v_pk_add_f32 v[140:141], v[134:135], v[92:93] op_sel:[0,1] op_sel_hi:[1,0] neg_lo:[0,1] neg_hi:[0,0]
	v_pk_add_f32 v[122:123], v[128:129], v[118:119]
	v_pk_add_f32 v[98:99], v[110:111], v[82:83] op_sel:[0,1] op_sel_hi:[1,0] neg_lo:[0,1] neg_hi:[0,0]
	v_pk_add_f32 v[152:153], v[152:153], v[88:89] neg_lo:[0,1] neg_hi:[0,1]
	v_pk_add_f32 v[134:135], v[134:135], v[92:93] op_sel:[0,1] op_sel_hi:[1,0] neg_lo:[0,0] neg_hi:[0,1]
	v_pk_add_f32 v[128:129], v[128:129], v[118:119] neg_lo:[0,1] neg_hi:[0,1]
	v_pk_add_f32 v[110:111], v[110:111], v[82:83] op_sel:[0,1] op_sel_hi:[1,0] neg_lo:[0,0] neg_hi:[0,1]
	v_pk_add_f32 v[96:97], v[102:103], v[84:85]
	v_pk_add_f32 v[126:127], v[100:101], v[132:133] op_sel:[0,1] op_sel_hi:[1,0] neg_lo:[0,1] neg_hi:[0,0]
	v_pk_add_f32 v[106:107], v[158:159], v[94:95]
	v_pk_add_f32 v[108:109], v[156:157], v[124:125] op_sel:[0,1] op_sel_hi:[1,0] neg_lo:[0,1] neg_hi:[0,0]
	v_pk_add_f32 v[102:103], v[102:103], v[84:85] neg_lo:[0,1] neg_hi:[0,1]
	v_pk_add_f32 v[100:101], v[100:101], v[132:133] op_sel:[0,1] op_sel_hi:[1,0] neg_lo:[0,0] neg_hi:[0,1]
	v_pk_add_f32 v[158:159], v[158:159], v[94:95] neg_lo:[0,1] neg_hi:[0,1]
	v_pk_add_f32 v[156:157], v[156:157], v[124:125] op_sel:[0,1] op_sel_hi:[1,0] neg_lo:[0,0] neg_hi:[0,1]
	v_pk_add_f32 v[90:91], v[104:105], v[122:123]
	v_pk_mul_f32 v[80:81], v[98:99], s[16:17] op_sel:[1,0] op_sel_hi:[1,0] neg_lo:[0,1] neg_hi:[0,0]
	v_pk_add_f32 v[130:131], v[152:153], v[128:129] op_sel:[0,1] op_sel_hi:[1,0] neg_lo:[0,1] neg_hi:[0,0]
	v_pk_mul_f32 v[154:155], v[110:111], s[16:17] op_sel:[1,0] op_sel_hi:[1,0] neg_lo:[0,1] neg_hi:[0,1]
	v_pk_add_f32 v[104:105], v[104:105], v[122:123] neg_lo:[0,1] neg_hi:[0,1]
	v_pk_fma_f32 v[80:81], v[98:99], s[16:17], v[80:81] op_sel:[0,0,0] op_sel_hi:[0,0,1] neg_lo:[0,0,0] neg_hi:[0,0,0]
	v_pk_add_f32 v[152:153], v[152:153], v[128:129] op_sel:[0,1] op_sel_hi:[1,0] neg_lo:[0,0] neg_hi:[0,1]
	v_pk_fma_f32 v[154:155], v[110:111], s[16:17], v[154:155] op_sel:[0,0,0] op_sel_hi:[0,0,1] neg_lo:[0,1,0] neg_hi:[0,0,0]
	v_pk_add_f32 v[98:99], v[140:141], v[80:81] neg_lo:[0,1] neg_hi:[0,1]
	v_pk_add_f32 v[110:111], v[134:135], v[154:155] neg_lo:[0,1] neg_hi:[0,1]
	v_pk_add_f32 v[140:141], v[140:141], v[80:81]
	v_pk_add_f32 v[134:135], v[134:135], v[154:155]
	v_pk_add_f32 v[170:171], v[96:97], v[106:107]
	v_pk_mul_f32 v[86:87], v[108:109], s[16:17] op_sel:[1,0] op_sel_hi:[1,0] neg_lo:[0,1] neg_hi:[0,0]
	v_pk_add_f32 v[112:113], v[102:103], v[158:159] op_sel:[0,1] op_sel_hi:[1,0] neg_lo:[0,1] neg_hi:[0,0]
	v_pk_mul_f32 v[120:121], v[156:157], s[16:17] op_sel:[1,0] op_sel_hi:[1,0] neg_lo:[0,1] neg_hi:[0,1]
	v_pk_add_f32 v[96:97], v[96:97], v[106:107] neg_lo:[0,1] neg_hi:[0,1]
	v_pk_fma_f32 v[86:87], v[108:109], s[16:17], v[86:87] op_sel:[0,0,0] op_sel_hi:[0,0,1] neg_lo:[0,0,0] neg_hi:[0,0,0]
	v_pk_add_f32 v[102:103], v[102:103], v[158:159] op_sel:[0,1] op_sel_hi:[1,0] neg_lo:[0,0] neg_hi:[0,1]
	v_pk_fma_f32 v[120:121], v[156:157], s[16:17], v[120:121] op_sel:[0,0,0] op_sel_hi:[0,0,1] neg_lo:[0,1,0] neg_hi:[0,0,0]
	v_pk_add_f32 v[108:109], v[126:127], v[86:87] neg_lo:[0,1] neg_hi:[0,1]
	v_pk_add_f32 v[156:157], v[100:101], v[120:121] neg_lo:[0,1] neg_hi:[0,1]
	v_pk_add_f32 v[126:127], v[126:127], v[86:87]
	v_pk_add_f32 v[100:101], v[100:101], v[120:121]
	v_pk_add_f32 v[136:137], v[90:91], v[170:171]
	v_pk_mul_f32 v[116:117], v[126:127], s[4:5] op_sel:[1,1] op_sel_hi:[1,0] neg_lo:[0,1] neg_hi:[0,0]
	v_pk_mul_f32 v[88:89], v[112:113], s[16:17] op_sel:[1,0] op_sel_hi:[1,0] neg_lo:[0,1] neg_hi:[0,0]
	v_pk_mul_f32 v[92:93], v[100:101], s[4:5] op_sel:[1,0] op_sel_hi:[1,1] neg_lo:[0,1] neg_hi:[0,0]
	v_pk_add_f32 v[90:91], v[90:91], v[170:171] neg_lo:[0,1] neg_hi:[0,1]
	v_pk_fma_f32 v[116:117], v[126:127], s[4:5], v[116:117] op_sel:[0,0,0] op_sel_hi:[0,1,1] neg_lo:[0,0,0] neg_hi:[0,0,0]
	v_pk_fma_f32 v[88:89], v[112:113], s[16:17], v[88:89] op_sel:[0,0,0] op_sel_hi:[0,0,1] neg_lo:[0,0,0] neg_hi:[0,0,0]
	v_pk_fma_f32 v[92:93], v[100:101], s[4:5], v[92:93] op_sel:[0,1,0] op_sel_hi:[0,0,1] neg_lo:[0,0,0] neg_hi:[0,0,0]
	v_pk_add_f32 v[126:127], v[140:141], v[116:117] neg_lo:[0,1] neg_hi:[0,1]
	v_pk_add_f32 v[112:113], v[130:131], v[88:89] neg_lo:[0,1] neg_hi:[0,1]
	v_pk_add_f32 v[100:101], v[134:135], v[92:93] neg_lo:[0,1] neg_hi:[0,1]
	v_pk_add_f32 v[140:141], v[140:141], v[116:117]
	v_pk_add_f32 v[130:131], v[130:131], v[88:89]
	v_pk_add_f32 v[134:135], v[134:135], v[92:93]
	v_pk_add_f32 v[118:119], v[104:105], v[96:97] op_sel:[0,1] op_sel_hi:[1,0] neg_lo:[0,1] neg_hi:[0,0]
	v_pk_mul_f32 v[82:83], v[108:109], s[4:5] op_sel:[1,0] op_sel_hi:[1,1] neg_lo:[0,1] neg_hi:[0,1]
	v_pk_mul_f32 v[84:85], v[102:103], s[16:17] op_sel:[1,0] op_sel_hi:[1,0] neg_lo:[0,1] neg_hi:[0,1]
	v_pk_mul_f32 v[132:133], v[156:157], s[4:5] op_sel:[1,1] op_sel_hi:[1,0] neg_lo:[0,1] neg_hi:[0,1]
	v_pk_add_f32 v[104:105], v[104:105], v[96:97] op_sel:[0,1] op_sel_hi:[1,0] neg_lo:[0,0] neg_hi:[0,1]
	v_pk_fma_f32 v[82:83], v[108:109], s[4:5], v[82:83] op_sel:[0,1,0] op_sel_hi:[0,0,1] neg_lo:[0,1,0] neg_hi:[0,0,0]
	v_pk_fma_f32 v[84:85], v[102:103], s[16:17], v[84:85] op_sel:[0,0,0] op_sel_hi:[0,0,1] neg_lo:[0,1,0] neg_hi:[0,0,0]
	v_pk_fma_f32 v[132:133], v[156:157], s[4:5], v[132:133] op_sel:[0,0,0] op_sel_hi:[0,1,1] neg_lo:[0,1,0] neg_hi:[0,0,0]
	v_pk_add_f32 v[108:109], v[98:99], v[82:83] neg_lo:[0,1] neg_hi:[0,1]
	v_pk_add_f32 v[102:103], v[152:153], v[84:85] neg_lo:[0,1] neg_hi:[0,1]
	v_pk_add_f32 v[156:157], v[110:111], v[132:133] neg_lo:[0,1] neg_hi:[0,1]
	v_pk_add_f32 v[98:99], v[98:99], v[82:83]
	v_pk_add_f32 v[152:153], v[152:153], v[84:85]
	v_pk_add_f32 v[110:111], v[110:111], v[132:133]
	ds_write2_b64 v151, v[136:137], v[140:141] offset1:1
	ds_write2_b64 v151, v[130:131], v[134:135] offset0:2 offset1:3
	ds_write2_b64 v151, v[118:119], v[98:99] offset0:4 offset1:5
	ds_write2_b64 v151, v[152:153], v[110:111] offset0:6 offset1:7
	ds_write2_b64 v151, v[90:91], v[126:127] offset0:8 offset1:9
	ds_write2_b64 v151, v[112:113], v[100:101] offset0:10 offset1:11
	ds_write2_b64 v151, v[104:105], v[108:109] offset0:12 offset1:13
	ds_write2_b64 v151, v[102:103], v[156:157] offset0:14 offset1:15
	v_mov_b32_e32 v78, v195
	s_waitcnt lgkmcnt(0)
	s_mov_b32 s0, 0
	v_and_b32_e32 v81, 15, v78
	v_lshlrev_b32_e32 v80, 4, v78
	v_lshlrev_b32_e32 v83, 9, v81
	v_and_b32_e32 v80, 0xfffffc00, v80
	v_lshlrev_b32_e32 v82, 3, v78
	v_add_u32_e32 v83, 0, v83
	v_and_b32_e32 v79, 63, v78
	v_lshl_add_u32 v81, v81, 3, 0
	v_and_or_b32 v82, v82, s90, v80
	v_add_u32_e32 v83, 0x22000, v83
; #define LAS __attribute__((address_space(3)))
; __device__ __forceinline__ cf twc(cf ws, int k16) { if (k16 == 0) return ws; if (k16 == 4) return cf{ws.y, -ws.x}; return cmul(ws, cf{c16(k16), -s16(k16)}); }
; template <int LR> __device__ __forceinline__ void dit_reg(cf (&x)[1 << LR], cf w) {
;     constexpr int R = 1 << LR; cf wsv[LR]; wsv[0] = w;
; #pragma unroll
;     for (int s = 1; s < LR; ++s) wsv[s] = cmul(wsv[s - 1], wsv[s - 1]);
; #pragma unroll
;     for (int s = LR - 1; s >= 0; --s) { const int half = R >> (s + 1);
; #pragma unroll
;         for (int m0 = 0; m0 < R; m0 += 2 * half)
; #pragma unroll
;             for (int mm = 0; mm < half; ++mm) { const int ia = m0 + mm, ib = ia + half; const cf a = x[ia];
;                 const cf b = cmulc(x[ib], twc(wsv[s], (mm << s) * (16 / R)));
;                 x[ia] = cf{a.x + b.x, a.y + b.y}; x[ib] = cf{a.x - b.x, a.y - b.y}; } }
; }
; __device__ __forceinline__ void lds_barrier() { asm volatile("s_waitcnt lgkmcnt(0)\n\ts_barrier" ::: "memory"); }
; template <int LR, bool INV> __device__ __forceinline__ void fft_pass(ldsf2 buf, int base, int stride, int twi) {
;     constexpr int R = 1 << LR; cf x[R];
;     const v2f wv = ((ldsf2)((LAS unsigned char*)buf + 139264))[twi];
; #pragma unroll
;     for (int m = 0; m < R; ++m) { const v2f v = buf[base + m * stride]; x[m] = cf{v.x, v.y}; }
;     const cf w{wv.x, wv.y};
;     if (INV) dit_reg<LR>(x, w); else dif_reg<LR>(x, w);
; #pragma unroll
;     for (int m = 0; m < R; ++m) buf[base + m * stride] = mkv2(x[m].x, x[m].y);
; }
; __device__ __forceinline__ void fft_inv_cba(ldsf2 buf) {
;     ...
;     for (int u = 0; u < 2; ++u) { const int j = l + 64 * u, o = j & 15, e0 = wv * 1024 + (j >> 4) * 128 + o; fft_pass<3, true>(buf, e0 + (e0 >> 4), 17, o * 64); }
.LBB0_365:
	ds_read_b64 v[100:101], v83
	v_or_b32_e32 v84, s0, v82
	v_lshlrev_b32_e32 v85, 3, v84
	v_ashrrev_i32_e32 v84, 1, v84
	v_add3_u32 v130, v81, v85, v84
	ds_read2_b64 v[84:87], v130 offset1:17
	ds_read2_b64 v[88:91], v130 offset0:34 offset1:51
	ds_read2_b64 v[92:95], v130 offset0:68 offset1:85
	ds_read2_b64 v[96:99], v130 offset0:102 offset1:119
	s_movk_i32 s0, 0x200
	ds_read_b64 v[132:133], v83
	v_or_b32_e32 v134, s0, v82
	v_lshlrev_b32_e32 v136, 3, v134
	v_ashrrev_i32_e32 v134, 1, v134
	v_add3_u32 v138, v81, v136, v134
	ds_read2_b64 v[140:143], v138 offset1:17
	ds_read2_b64 v[152:155], v138 offset0:34 offset1:51
	ds_read2_b64 v[156:159], v138 offset0:68 offset1:85
	ds_read2_b64 v[160:163], v138 offset0:102 offset1:119
	s_waitcnt lgkmcnt(5)
	v_pk_add_f32 v[102:103], v[100:101], v[100:101] op_sel:[0,1] op_sel_hi:[1,0] neg_lo:[0,0] neg_hi:[0,1]
	v_pk_mul_f32 v[104:105], v[102:103], s[16:17] op_sel:[0,0] op_sel_hi:[1,0]
	v_pk_mul_f32 v[106:107], v[102:103], s[16:17] op_sel:[1,0] op_sel_hi:[0,0] neg_lo:[0,0] neg_hi:[1,0]
	v_pk_mul_f32 v[108:109], v[100:101], v[100:101] op_sel:[1,1] op_sel_hi:[1,0]
	v_pk_fma_f32 v[108:109], v[100:101], v[100:101], v[108:109] op_sel:[0,0,0] op_sel_hi:[0,1,1] neg_lo:[0,0,1] neg_hi:[0,0,0]
	v_pk_mul_f32 v[110:111], v[108:109], v[108:109] op_sel:[1,1] op_sel_hi:[1,0]
	v_pk_fma_f32 v[110:111], v[108:109], v[108:109], v[110:111] op_sel:[0,0,0] op_sel_hi:[0,1,1] neg_lo:[0,0,1] neg_hi:[0,0,0]
	v_pk_mul_f32 v[112:113], v[86:87], v[110:111] op_sel:[1,1] op_sel_hi:[1,0]
	v_pk_mul_f32 v[114:115], v[90:91], v[110:111] op_sel:[1,1] op_sel_hi:[1,0]
	v_pk_mul_f32 v[116:117], v[94:95], v[110:111] op_sel:[1,1] op_sel_hi:[1,0]
	v_pk_mul_f32 v[118:119], v[98:99], v[110:111] op_sel:[1,1] op_sel_hi:[1,0]
	v_pk_fma_f32 v[112:113], v[86:87], v[110:111], v[112:113] op_sel:[0,0,0] op_sel_hi:[0,1,1] neg_lo:[0,0,0] neg_hi:[0,1,0]
	v_pk_fma_f32 v[114:115], v[90:91], v[110:111], v[114:115] op_sel:[0,0,0] op_sel_hi:[0,1,1] neg_lo:[0,0,0] neg_hi:[0,1,0]
	v_pk_fma_f32 v[116:117], v[94:95], v[110:111], v[116:117] op_sel:[0,0,0] op_sel_hi:[0,1,1] neg_lo:[0,0,0] neg_hi:[0,1,0]
	v_pk_fma_f32 v[118:119], v[98:99], v[110:111], v[118:119] op_sel:[0,0,0] op_sel_hi:[0,1,1] neg_lo:[0,0,0] neg_hi:[0,1,0]
	v_pk_add_f32 v[86:87], v[84:85], v[112:113] neg_lo:[0,1] neg_hi:[0,1]
	v_pk_add_f32 v[90:91], v[88:89], v[114:115] neg_lo:[0,1] neg_hi:[0,1]
	v_pk_add_f32 v[94:95], v[92:93], v[116:117] neg_lo:[0,1] neg_hi:[0,1]
	v_pk_add_f32 v[98:99], v[96:97], v[118:119] neg_lo:[0,1] neg_hi:[0,1]
	v_pk_add_f32 v[84:85], v[84:85], v[112:113]
	v_pk_add_f32 v[88:89], v[88:89], v[114:115]
	v_pk_add_f32 v[92:93], v[92:93], v[116:117]
	v_pk_add_f32 v[96:97], v[96:97], v[118:119]
	v_pk_mul_f32 v[112:113], v[88:89], v[108:109] op_sel:[1,1] op_sel_hi:[1,0]
	v_pk_mul_f32 v[114:115], v[90:91], v[108:109] op_sel:[1,0] op_sel_hi:[1,1]
	v_pk_mul_f32 v[116:117], v[96:97], v[108:109] op_sel:[1,1] op_sel_hi:[1,0]
	v_pk_mul_f32 v[118:119], v[98:99], v[108:109] op_sel:[1,0] op_sel_hi:[1,1]
	v_pk_fma_f32 v[112:113], v[88:89], v[108:109], v[112:113] op_sel:[0,0,0] op_sel_hi:[0,1,1] neg_lo:[0,0,0] neg_hi:[0,1,0]
	v_pk_fma_f32 v[114:115], v[90:91], v[108:109], v[114:115] op_sel:[0,1,0] op_sel_hi:[0,0,1] neg_lo:[0,0,1] neg_hi:[0,0,0]
	v_pk_fma_f32 v[116:117], v[96:97], v[108:109], v[116:117] op_sel:[0,0,0] op_sel_hi:[0,1,1] neg_lo:[0,0,0] neg_hi:[0,1,0]
	v_pk_fma_f32 v[118:119], v[98:99], v[108:109], v[118:119] op_sel:[0,1,0] op_sel_hi:[0,0,1] neg_lo:[0,0,1] neg_hi:[0,0,0]
	v_pk_add_f32 v[88:89], v[84:85], v[112:113] neg_lo:[0,1] neg_hi:[0,1]
	v_pk_add_f32 v[90:91], v[86:87], v[114:115] neg_lo:[0,1] neg_hi:[0,1]
	v_pk_add_f32 v[96:97], v[92:93], v[116:117] neg_lo:[0,1] neg_hi:[0,1]
	v_pk_add_f32 v[98:99], v[94:95], v[118:119] neg_lo:[0,1] neg_hi:[0,1]
	v_pk_add_f32 v[84:85], v[84:85], v[112:113]
	v_pk_add_f32 v[86:87], v[86:87], v[114:115]
	v_pk_add_f32 v[92:93], v[92:93], v[116:117]
	v_pk_add_f32 v[94:95], v[94:95], v[118:119]
	v_pk_mul_f32 v[112:113], v[92:93], v[100:101] op_sel:[1,1] op_sel_hi:[1,0]
	v_pk_mul_f32 v[114:115], v[94:95], v[104:105] op_sel:[1,1] op_sel_hi:[1,0]
	v_pk_mul_f32 v[116:117], v[96:97], v[100:101] op_sel:[1,0] op_sel_hi:[1,1]
	v_pk_mul_f32 v[118:119], v[98:99], v[106:107] op_sel:[1,1] op_sel_hi:[1,0]
	v_pk_fma_f32 v[112:113], v[92:93], v[100:101], v[112:113] op_sel:[0,0,0] op_sel_hi:[0,1,1] neg_lo:[0,0,0] neg_hi:[0,1,0]
	v_pk_fma_f32 v[114:115], v[94:95], v[104:105], v[114:115] op_sel:[0,0,0] op_sel_hi:[0,1,1] neg_lo:[0,0,0] neg_hi:[0,1,0]
	v_pk_fma_f32 v[116:117], v[96:97], v[100:101], v[116:117] op_sel:[0,1,0] op_sel_hi:[0,0,1] neg_lo:[0,0,1] neg_hi:[0,0,0]
	v_pk_fma_f32 v[118:119], v[98:99], v[106:107], v[118:119] op_sel:[0,0,0] op_sel_hi:[0,1,1] neg_lo:[0,0,0] neg_hi:[0,1,0]
	v_pk_add_f32 v[92:93], v[84:85], v[112:113] neg_lo:[0,1] neg_hi:[0,1]
	v_pk_add_f32 v[94:95], v[86:87], v[114:115] neg_lo:[0,1] neg_hi:[0,1]
	v_pk_add_f32 v[96:97], v[88:89], v[116:117] neg_lo:[0,1] neg_hi:[0,1]
	v_pk_add_f32 v[98:99], v[90:91], v[118:119] neg_lo:[0,1] neg_hi:[0,1]
	v_pk_add_f32 v[84:85], v[84:85], v[112:113]
	v_pk_add_f32 v[86:87], v[86:87], v[114:115]
	v_pk_add_f32 v[88:89], v[88:89], v[116:117]
	v_pk_add_f32 v[90:91], v[90:91], v[118:119]
	ds_write2_b64 v130, v[84:85], v[86:87] offset1:17
	ds_write2_b64 v130, v[88:89], v[90:91] offset0:34 offset1:51
	ds_write2_b64 v130, v[92:93], v[94:95] offset0:68 offset1:85
	ds_write2_b64 v130, v[96:97], v[98:99] offset0:102 offset1:119
	s_waitcnt lgkmcnt(4)
; #define LAS __attribute__((address_space(3)))
; __device__ __forceinline__ cf twc(cf ws, int k16) { if (k16 == 0) return ws; if (k16 == 4) return cf{ws.y, -ws.x}; return cmul(ws, cf{c16(k16), -s16(k16)}); }
; __device__ __forceinline__ void wave_lds_fence() { asm volatile("s_waitcnt lgkmcnt(0)" ::: "memory"); }
; template <int LR> __device__ __forceinline__ void dit_reg(cf (&x)[1 << LR], cf w) {
;     constexpr int R = 1 << LR; cf wsv[LR]; wsv[0] = w;
; #pragma unroll
;     for (int s = 1; s < LR; ++s) wsv[s] = cmul(wsv[s - 1], wsv[s - 1]);
; #pragma unroll
;     for (int s = LR - 1; s >= 0; --s) { const int half = R >> (s + 1);
; #pragma unroll
;         for (int m0 = 0; m0 < R; m0 += 2 * half)
; #pragma unroll
;             for (int mm = 0; mm < half; ++mm) { const int ia = m0 + mm, ib = ia + half; const cf a = x[ia];
;                 const cf b = cmulc(x[ib], twc(wsv[s], (mm << s) * (16 / R)));
;                 x[ia] = cf{a.x + b.x, a.y + b.y}; x[ib] = cf{a.x - b.x, a.y - b.y}; } }
; }
; __device__ __forceinline__ void lds_barrier() { asm volatile("s_waitcnt lgkmcnt(0)\n\ts_barrier" ::: "memory"); }
; template <int LR, bool INV> __device__ __forceinline__ void fft_pass(ldsf2 buf, int base, int stride, int twi) {
;     constexpr int R = 1 << LR; cf x[R];
;     const v2f wv = ((ldsf2)((LAS unsigned char*)buf + 139264))[twi];
; #pragma unroll
;     for (int m = 0; m < R; ++m) { const v2f v = buf[base + m * stride]; x[m] = cf{v.x, v.y}; }
;     const cf w{wv.x, wv.y};
;     if (INV) dit_reg<LR>(x, w); else dif_reg<LR>(x, w);
; #pragma unroll
;     for (int m = 0; m < R; ++m) buf[base + m * stride] = mkv2(x[m].x, x[m].y);
; }
; __device__ __forceinline__ void fft_inv_cba(ldsf2 buf) {
;     ...
;     for (int u = 0; u < 2; ++u) { const int j = l + 64 * u, o = j & 15, e0 = wv * 1024 + (j >> 4) * 128 + o; fft_pass<3, true>(buf, e0 + (e0 >> 4), 17, o * 64); }
;     wave_lds_fence();
	v_pk_add_f32 v[164:165], v[132:133], v[132:133] op_sel:[0,1] op_sel_hi:[1,0] neg_lo:[0,0] neg_hi:[0,1]
	v_pk_mul_f32 v[166:167], v[164:165], s[16:17] op_sel:[0,0] op_sel_hi:[1,0]
	v_pk_mul_f32 v[168:169], v[164:165], s[16:17] op_sel:[1,0] op_sel_hi:[0,0] neg_lo:[0,0] neg_hi:[1,0]
	v_pk_mul_f32 v[170:171], v[132:133], v[132:133] op_sel:[1,1] op_sel_hi:[1,0]
	v_pk_fma_f32 v[170:171], v[132:133], v[132:133], v[170:171] op_sel:[0,0,0] op_sel_hi:[0,1,1] neg_lo:[0,0,1] neg_hi:[0,0,0]
	v_pk_mul_f32 v[172:173], v[170:171], v[170:171] op_sel:[1,1] op_sel_hi:[1,0]
	v_pk_fma_f32 v[172:173], v[170:171], v[170:171], v[172:173] op_sel:[0,0,0] op_sel_hi:[0,1,1] neg_lo:[0,0,1] neg_hi:[0,0,0]
	v_pk_mul_f32 v[174:175], v[142:143], v[172:173] op_sel:[1,1] op_sel_hi:[1,0]
	v_pk_mul_f32 v[188:189], v[154:155], v[172:173] op_sel:[1,1] op_sel_hi:[1,0]
	v_pk_mul_f32 v[190:191], v[158:159], v[172:173] op_sel:[1,1] op_sel_hi:[1,0]
	v_pk_mul_f32 v[196:197], v[162:163], v[172:173] op_sel:[1,1] op_sel_hi:[1,0]
	v_pk_fma_f32 v[174:175], v[142:143], v[172:173], v[174:175] op_sel:[0,0,0] op_sel_hi:[0,1,1] neg_lo:[0,0,0] neg_hi:[0,1,0]
	v_pk_fma_f32 v[188:189], v[154:155], v[172:173], v[188:189] op_sel:[0,0,0] op_sel_hi:[0,1,1] neg_lo:[0,0,0] neg_hi:[0,1,0]
	v_pk_fma_f32 v[190:191], v[158:159], v[172:173], v[190:191] op_sel:[0,0,0] op_sel_hi:[0,1,1] neg_lo:[0,0,0] neg_hi:[0,1,0]
	v_pk_fma_f32 v[196:197], v[162:163], v[172:173], v[196:197] op_sel:[0,0,0] op_sel_hi:[0,1,1] neg_lo:[0,0,0] neg_hi:[0,1,0]
	v_pk_add_f32 v[142:143], v[140:141], v[174:175] neg_lo:[0,1] neg_hi:[0,1]
	v_pk_add_f32 v[154:155], v[152:153], v[188:189] neg_lo:[0,1] neg_hi:[0,1]
	v_pk_add_f32 v[158:159], v[156:157], v[190:191] neg_lo:[0,1] neg_hi:[0,1]
	v_pk_add_f32 v[162:163], v[160:161], v[196:197] neg_lo:[0,1] neg_hi:[0,1]
	v_pk_add_f32 v[140:141], v[140:141], v[174:175]
	v_pk_add_f32 v[152:153], v[152:153], v[188:189]
	v_pk_add_f32 v[156:157], v[156:157], v[190:191]
	v_pk_add_f32 v[160:161], v[160:161], v[196:197]
	v_pk_mul_f32 v[174:175], v[152:153], v[170:171] op_sel:[1,1] op_sel_hi:[1,0]
	v_pk_mul_f32 v[188:189], v[154:155], v[170:171] op_sel:[1,0] op_sel_hi:[1,1]
	v_pk_mul_f32 v[190:191], v[160:161], v[170:171] op_sel:[1,1] op_sel_hi:[1,0]
	v_pk_mul_f32 v[196:197], v[162:163], v[170:171] op_sel:[1,0] op_sel_hi:[1,1]
	v_pk_fma_f32 v[174:175], v[152:153], v[170:171], v[174:175] op_sel:[0,0,0] op_sel_hi:[0,1,1] neg_lo:[0,0,0] neg_hi:[0,1,0]
	v_pk_fma_f32 v[188:189], v[154:155], v[170:171], v[188:189] op_sel:[0,1,0] op_sel_hi:[0,0,1] neg_lo:[0,0,1] neg_hi:[0,0,0]
	v_pk_fma_f32 v[190:191], v[160:161], v[170:171], v[190:191] op_sel:[0,0,0] op_sel_hi:[0,1,1] neg_lo:[0,0,0] neg_hi:[0,1,0]
	v_pk_fma_f32 v[196:197], v[162:163], v[170:171], v[196:197] op_sel:[0,1,0] op_sel_hi:[0,0,1] neg_lo:[0,0,1] neg_hi:[0,0,0]
	v_pk_add_f32 v[152:153], v[140:141], v[174:175] neg_lo:[0,1] neg_hi:[0,1]
	v_pk_add_f32 v[154:155], v[142:143], v[188:189] neg_lo:[0,1] neg_hi:[0,1]
	v_pk_add_f32 v[160:161], v[156:157], v[190:191] neg_lo:[0,1] neg_hi:[0,1]
	v_pk_add_f32 v[162:163], v[158:159], v[196:197] neg_lo:[0,1] neg_hi:[0,1]
	v_pk_add_f32 v[140:141], v[140:141], v[174:175]
	v_pk_add_f32 v[142:143], v[142:143], v[188:189]
	v_pk_add_f32 v[156:157], v[156:157], v[190:191]
	v_pk_add_f32 v[158:159], v[158:159], v[196:197]
	v_pk_mul_f32 v[174:175], v[156:157], v[132:133] op_sel:[1,1] op_sel_hi:[1,0]
	v_pk_mul_f32 v[188:189], v[158:159], v[166:167] op_sel:[1,1] op_sel_hi:[1,0]
	v_pk_mul_f32 v[190:191], v[160:161], v[132:133] op_sel:[1,0] op_sel_hi:[1,1]
	v_pk_mul_f32 v[196:197], v[162:163], v[168:169] op_sel:[1,1] op_sel_hi:[1,0]
	v_pk_fma_f32 v[174:175], v[156:157], v[132:133], v[174:175] op_sel:[0,0,0] op_sel_hi:[0,1,1] neg_lo:[0,0,0] neg_hi:[0,1,0]
	v_pk_fma_f32 v[188:189], v[158:159], v[166:167], v[188:189] op_sel:[0,0,0] op_sel_hi:[0,1,1] neg_lo:[0,0,0] neg_hi:[0,1,0]
	v_pk_fma_f32 v[190:191], v[160:161], v[132:133], v[190:191] op_sel:[0,1,0] op_sel_hi:[0,0,1] neg_lo:[0,0,1] neg_hi:[0,0,0]
	v_pk_fma_f32 v[196:197], v[162:163], v[168:169], v[196:197] op_sel:[0,0,0] op_sel_hi:[0,1,1] neg_lo:[0,0,0] neg_hi:[0,1,0]
	v_pk_add_f32 v[156:157], v[140:141], v[174:175] neg_lo:[0,1] neg_hi:[0,1]
	v_pk_add_f32 v[158:159], v[142:143], v[188:189] neg_lo:[0,1] neg_hi:[0,1]
	v_pk_add_f32 v[160:161], v[152:153], v[190:191] neg_lo:[0,1] neg_hi:[0,1]
	v_pk_add_f32 v[162:163], v[154:155], v[196:197] neg_lo:[0,1] neg_hi:[0,1]
	v_pk_add_f32 v[140:141], v[140:141], v[174:175]
	v_pk_add_f32 v[142:143], v[142:143], v[188:189]
	v_pk_add_f32 v[152:153], v[152:153], v[190:191]
	v_pk_add_f32 v[154:155], v[154:155], v[196:197]
	ds_write2_b64 v138, v[140:141], v[142:143] offset1:17
	ds_write2_b64 v138, v[152:153], v[154:155] offset0:34 offset1:51
	ds_write2_b64 v138, v[156:157], v[158:159] offset0:68 offset1:85
	ds_write2_b64 v138, v[160:161], v[162:163] offset0:102 offset1:119
	s_mov_b64 s[14:15], 0
	s_waitcnt lgkmcnt(0)
	s_mov_b32 s0, 0
	s_mov_b64 s[14:15], -1
; #define LAS __attribute__((address_space(3)))
; __device__ __forceinline__ cf twc(cf ws, int k16) { if (k16 == 0) return ws; if (k16 == 4) return cf{ws.y, -ws.x}; return cmul(ws, cf{c16(k16), -s16(k16)}); }
; template <int LR> __device__ __forceinline__ void dit_reg(cf (&x)[1 << LR], cf w) {
;     constexpr int R = 1 << LR; cf wsv[LR]; wsv[0] = w;
; #pragma unroll
;     for (int s = 1; s < LR; ++s) wsv[s] = cmul(wsv[s - 1], wsv[s - 1]);
; #pragma unroll
;     for (int s = LR - 1; s >= 0; --s) { const int half = R >> (s + 1);
; #pragma unroll
;         for (int m0 = 0; m0 < R; m0 += 2 * half)
; #pragma unroll
;             for (int mm = 0; mm < half; ++mm) { const int ia = m0 + mm, ib = ia + half; const cf a = x[ia];
;                 const cf b = cmulc(x[ib], twc(wsv[s], (mm << s) * (16 / R)));
;                 x[ia] = cf{a.x + b.x, a.y + b.y}; x[ib] = cf{a.x - b.x, a.y - b.y}; } }
; }
; __device__ __forceinline__ void lds_barrier() { asm volatile("s_waitcnt lgkmcnt(0)\n\ts_barrier" ::: "memory"); }
; template <int LR, bool INV> __device__ __forceinline__ void fft_pass(ldsf2 buf, int base, int stride, int twi) {
;     constexpr int R = 1 << LR; cf x[R];
;     const v2f wv = ((ldsf2)((LAS unsigned char*)buf + 139264))[twi];
; #pragma unroll
;     for (int m = 0; m < R; ++m) { const v2f v = buf[base + m * stride]; x[m] = cf{v.x, v.y}; }
;     const cf w{wv.x, wv.y};
;     if (INV) dit_reg<LR>(x, w); else dif_reg<LR>(x, w);
; #pragma unroll
;     for (int m = 0; m < R; ++m) buf[base + m * stride] = mkv2(x[m].x, x[m].y);
; }
; __device__ __forceinline__ void fft_inv_cba(ldsf2 buf) {
;     ...
;     for (int u = 0; u < 2; ++u) { const int o = l + 64 * u, e0 = wv * 1024 + o; fft_pass<3, true>(buf, e0 + (e0 >> 4), 136, o * 8); }
.LBB0_367:
	v_or_b32_e32 v81, s0, v79
	v_or_b32_e32 v82, v81, v80
	v_lshl_add_u32 v81, v81, 6, 0
	v_add_u32_e32 v81, 0x22000, v81
	ds_read_b64 v[98:99], v81
	v_ashrrev_i32_e32 v83, 4, v82
	v_lshlrev_b32_e32 v81, 3, v82
	v_lshlrev_b32_e32 v82, 3, v83
	v_add3_u32 v81, 0, v81, v82
	v_add_u32_e32 v130, 0x1800, v81
	v_add_u32_e32 v129, 0x1000, v81
	ds_read2_b64 v[94:97], v130 offset0:48 offset1:184
	ds_read2_b64 v[90:93], v129 offset0:32 offset1:168
	v_add_u32_e32 v128, 0x800, v81
	ds_read2_b64 v[82:85], v81 offset1:136
	ds_read2_b64 v[86:89], v128 offset0:16 offset1:152
	s_mov_b32 s0, 64
	v_or_b32_e32 v132, s0, v79
	v_or_b32_e32 v134, v132, v80
	v_lshl_add_u32 v132, v132, 6, 0
	v_add_u32_e32 v132, 0x22000, v132
	ds_read_b64 v[136:137], v132
	v_ashrrev_i32_e32 v138, 4, v134
	v_lshlrev_b32_e32 v132, 3, v134
	v_lshlrev_b32_e32 v134, 3, v138
	v_add3_u32 v132, 0, v132, v134
	v_add_u32_e32 v140, 0x1800, v132
	v_add_u32_e32 v142, 0x1000, v132
	ds_read2_b64 v[152:155], v140 offset0:48 offset1:184
	ds_read2_b64 v[156:159], v142 offset0:32 offset1:168
	v_add_u32_e32 v160, 0x800, v132
	ds_read2_b64 v[162:165], v132 offset1:136
	ds_read2_b64 v[166:169], v160 offset0:16 offset1:152
	s_waitcnt lgkmcnt(5)
	v_pk_add_f32 v[100:101], v[98:99], v[98:99] op_sel:[0,1] op_sel_hi:[1,0] neg_lo:[0,0] neg_hi:[0,1]
	v_pk_mul_f32 v[102:103], v[100:101], s[16:17] op_sel:[0,0] op_sel_hi:[1,0]
	v_pk_mul_f32 v[104:105], v[100:101], s[16:17] op_sel:[1,0] op_sel_hi:[0,0] neg_lo:[0,0] neg_hi:[1,0]
	v_pk_mul_f32 v[106:107], v[98:99], v[98:99] op_sel:[1,1] op_sel_hi:[1,0]
	v_pk_fma_f32 v[106:107], v[98:99], v[98:99], v[106:107] op_sel:[0,0,0] op_sel_hi:[0,1,1] neg_lo:[0,0,1] neg_hi:[0,0,0]
	v_pk_mul_f32 v[108:109], v[106:107], v[106:107] op_sel:[1,1] op_sel_hi:[1,0]
	v_pk_fma_f32 v[108:109], v[106:107], v[106:107], v[108:109] op_sel:[0,0,0] op_sel_hi:[0,1,1] neg_lo:[0,0,1] neg_hi:[0,0,0]
	v_pk_mul_f32 v[110:111], v[84:85], v[108:109] op_sel:[1,1] op_sel_hi:[1,0]
	v_pk_mul_f32 v[112:113], v[88:89], v[108:109] op_sel:[1,1] op_sel_hi:[1,0]
	v_pk_mul_f32 v[114:115], v[92:93], v[108:109] op_sel:[1,1] op_sel_hi:[1,0]
	v_pk_mul_f32 v[116:117], v[96:97], v[108:109] op_sel:[1,1] op_sel_hi:[1,0]
	v_pk_fma_f32 v[110:111], v[84:85], v[108:109], v[110:111] op_sel:[0,0,0] op_sel_hi:[0,1,1] neg_lo:[0,0,0] neg_hi:[0,1,0]
	v_pk_fma_f32 v[112:113], v[88:89], v[108:109], v[112:113] op_sel:[0,0,0] op_sel_hi:[0,1,1] neg_lo:[0,0,0] neg_hi:[0,1,0]
	v_pk_fma_f32 v[114:115], v[92:93], v[108:109], v[114:115] op_sel:[0,0,0] op_sel_hi:[0,1,1] neg_lo:[0,0,0] neg_hi:[0,1,0]
	v_pk_fma_f32 v[116:117], v[96:97], v[108:109], v[116:117] op_sel:[0,0,0] op_sel_hi:[0,1,1] neg_lo:[0,0,0] neg_hi:[0,1,0]
	v_pk_add_f32 v[84:85], v[82:83], v[110:111] neg_lo:[0,1] neg_hi:[0,1]
	v_pk_add_f32 v[88:89], v[86:87], v[112:113] neg_lo:[0,1] neg_hi:[0,1]
	v_pk_add_f32 v[92:93], v[90:91], v[114:115] neg_lo:[0,1] neg_hi:[0,1]
	v_pk_add_f32 v[96:97], v[94:95], v[116:117] neg_lo:[0,1] neg_hi:[0,1]
	v_pk_add_f32 v[82:83], v[82:83], v[110:111]
	v_pk_add_f32 v[86:87], v[86:87], v[112:113]
	v_pk_add_f32 v[90:91], v[90:91], v[114:115]
	v_pk_add_f32 v[94:95], v[94:95], v[116:117]
	v_pk_mul_f32 v[110:111], v[86:87], v[106:107] op_sel:[1,1] op_sel_hi:[1,0]
	v_pk_mul_f32 v[112:113], v[88:89], v[106:107] op_sel:[1,0] op_sel_hi:[1,1]
	v_pk_mul_f32 v[114:115], v[94:95], v[106:107] op_sel:[1,1] op_sel_hi:[1,0]
	v_pk_mul_f32 v[116:117], v[96:97], v[106:107] op_sel:[1,0] op_sel_hi:[1,1]
	v_pk_fma_f32 v[110:111], v[86:87], v[106:107], v[110:111] op_sel:[0,0,0] op_sel_hi:[0,1,1] neg_lo:[0,0,0] neg_hi:[0,1,0]
	v_pk_fma_f32 v[112:113], v[88:89], v[106:107], v[112:113] op_sel:[0,1,0] op_sel_hi:[0,0,1] neg_lo:[0,0,1] neg_hi:[0,0,0]
	v_pk_fma_f32 v[114:115], v[94:95], v[106:107], v[114:115] op_sel:[0,0,0] op_sel_hi:[0,1,1] neg_lo:[0,0,0] neg_hi:[0,1,0]
	v_pk_fma_f32 v[116:117], v[96:97], v[106:107], v[116:117] op_sel:[0,1,0] op_sel_hi:[0,0,1] neg_lo:[0,0,1] neg_hi:[0,0,0]
	v_pk_add_f32 v[86:87], v[82:83], v[110:111] neg_lo:[0,1] neg_hi:[0,1]
	v_pk_add_f32 v[88:89], v[84:85], v[112:113] neg_lo:[0,1] neg_hi:[0,1]
	v_pk_add_f32 v[94:95], v[90:91], v[114:115] neg_lo:[0,1] neg_hi:[0,1]
	v_pk_add_f32 v[96:97], v[92:93], v[116:117] neg_lo:[0,1] neg_hi:[0,1]
	v_pk_add_f32 v[82:83], v[82:83], v[110:111]
	v_pk_add_f32 v[84:85], v[84:85], v[112:113]
	v_pk_add_f32 v[90:91], v[90:91], v[114:115]
	v_pk_add_f32 v[92:93], v[92:93], v[116:117]
	v_pk_mul_f32 v[110:111], v[90:91], v[98:99] op_sel:[1,1] op_sel_hi:[1,0]
	v_pk_mul_f32 v[112:113], v[92:93], v[102:103] op_sel:[1,1] op_sel_hi:[1,0]
	v_pk_mul_f32 v[114:115], v[94:95], v[98:99] op_sel:[1,0] op_sel_hi:[1,1]
	v_pk_mul_f32 v[116:117], v[96:97], v[104:105] op_sel:[1,1] op_sel_hi:[1,0]
	v_pk_fma_f32 v[110:111], v[90:91], v[98:99], v[110:111] op_sel:[0,0,0] op_sel_hi:[0,1,1] neg_lo:[0,0,0] neg_hi:[0,1,0]
	v_pk_fma_f32 v[112:113], v[92:93], v[102:103], v[112:113] op_sel:[0,0,0] op_sel_hi:[0,1,1] neg_lo:[0,0,0] neg_hi:[0,1,0]
	v_pk_fma_f32 v[114:115], v[94:95], v[98:99], v[114:115] op_sel:[0,1,0] op_sel_hi:[0,0,1] neg_lo:[0,0,1] neg_hi:[0,0,0]
	v_pk_fma_f32 v[116:117], v[96:97], v[104:105], v[116:117] op_sel:[0,0,0] op_sel_hi:[0,1,1] neg_lo:[0,0,0] neg_hi:[0,1,0]
	v_pk_add_f32 v[90:91], v[82:83], v[110:111] neg_lo:[0,1] neg_hi:[0,1]
	v_pk_add_f32 v[92:93], v[84:85], v[112:113] neg_lo:[0,1] neg_hi:[0,1]
	v_pk_add_f32 v[94:95], v[86:87], v[114:115] neg_lo:[0,1] neg_hi:[0,1]
	v_pk_add_f32 v[96:97], v[88:89], v[116:117] neg_lo:[0,1] neg_hi:[0,1]
	v_pk_add_f32 v[82:83], v[82:83], v[110:111]
	v_pk_add_f32 v[84:85], v[84:85], v[112:113]
	v_pk_add_f32 v[86:87], v[86:87], v[114:115]
	v_pk_add_f32 v[88:89], v[88:89], v[116:117]
	ds_write2_b64 v81, v[82:83], v[84:85] offset1:136
	ds_write2_b64 v128, v[86:87], v[88:89] offset0:16 offset1:152
	ds_write2_b64 v129, v[90:91], v[92:93] offset0:32 offset1:168
	ds_write2_b64 v130, v[94:95], v[96:97] offset0:48 offset1:184
	s_waitcnt lgkmcnt(4)
; #define LAS __attribute__((address_space(3)))
; __device__ __forceinline__ cf twc(cf ws, int k16) { if (k16 == 0) return ws; if (k16 == 4) return cf{ws.y, -ws.x}; return cmul(ws, cf{c16(k16), -s16(k16)}); }
; template <int LR> __device__ __forceinline__ void dit_reg(cf (&x)[1 << LR], cf w) {
;     constexpr int R = 1 << LR; cf wsv[LR]; wsv[0] = w;
; #pragma unroll
;     for (int s = 1; s < LR; ++s) wsv[s] = cmul(wsv[s - 1], wsv[s - 1]);
; #pragma unroll
;     for (int s = LR - 1; s >= 0; --s) { const int half = R >> (s + 1);
; #pragma unroll
;         for (int m0 = 0; m0 < R; m0 += 2 * half)
; #pragma unroll
;             for (int mm = 0; mm < half; ++mm) { const int ia = m0 + mm, ib = ia + half; const cf a = x[ia];
;                 const cf b = cmulc(x[ib], twc(wsv[s], (mm << s) * (16 / R)));
;                 x[ia] = cf{a.x + b.x, a.y + b.y}; x[ib] = cf{a.x - b.x, a.y - b.y}; } }
; }
; __device__ __forceinline__ void lds_barrier() { asm volatile("s_waitcnt lgkmcnt(0)\n\ts_barrier" ::: "memory"); }
; template <int LR, bool INV> __device__ __forceinline__ void fft_pass(ldsf2 buf, int base, int stride, int twi) {
;     constexpr int R = 1 << LR; cf x[R];
;     const v2f wv = ((ldsf2)((LAS unsigned char*)buf + 139264))[twi];
; #pragma unroll
;     for (int m = 0; m < R; ++m) { const v2f v = buf[base + m * stride]; x[m] = cf{v.x, v.y}; }
;     const cf w{wv.x, wv.y};
;     if (INV) dit_reg<LR>(x, w); else dif_reg<LR>(x, w);
; #pragma unroll
;     for (int m = 0; m < R; ++m) buf[base + m * stride] = mkv2(x[m].x, x[m].y);
; }
; __device__ __forceinline__ void fft_inv_cba(ldsf2 buf) {
;     ...
;     for (int u = 0; u < 2; ++u) { const int o = l + 64 * u, e0 = wv * 1024 + o; fft_pass<3, true>(buf, e0 + (e0 >> 4), 136, o * 8); }
;     lds_barrier();
	v_pk_add_f32 v[170:171], v[136:137], v[136:137] op_sel:[0,1] op_sel_hi:[1,0] neg_lo:[0,0] neg_hi:[0,1]
	v_pk_mul_f32 v[172:173], v[170:171], s[16:17] op_sel:[0,0] op_sel_hi:[1,0]
	v_pk_mul_f32 v[174:175], v[170:171], s[16:17] op_sel:[1,0] op_sel_hi:[0,0] neg_lo:[0,0] neg_hi:[1,0]
	v_pk_mul_f32 v[188:189], v[136:137], v[136:137] op_sel:[1,1] op_sel_hi:[1,0]
	v_pk_fma_f32 v[188:189], v[136:137], v[136:137], v[188:189] op_sel:[0,0,0] op_sel_hi:[0,1,1] neg_lo:[0,0,1] neg_hi:[0,0,0]
	v_pk_mul_f32 v[190:191], v[188:189], v[188:189] op_sel:[1,1] op_sel_hi:[1,0]
	v_pk_fma_f32 v[190:191], v[188:189], v[188:189], v[190:191] op_sel:[0,0,0] op_sel_hi:[0,1,1] neg_lo:[0,0,1] neg_hi:[0,0,0]
	v_pk_mul_f32 v[196:197], v[164:165], v[190:191] op_sel:[1,1] op_sel_hi:[1,0]
	v_pk_mul_f32 v[198:199], v[168:169], v[190:191] op_sel:[1,1] op_sel_hi:[1,0]
	v_pk_mul_f32 v[200:201], v[158:159], v[190:191] op_sel:[1,1] op_sel_hi:[1,0]
	v_pk_mul_f32 v[202:203], v[154:155], v[190:191] op_sel:[1,1] op_sel_hi:[1,0]
	v_pk_fma_f32 v[196:197], v[164:165], v[190:191], v[196:197] op_sel:[0,0,0] op_sel_hi:[0,1,1] neg_lo:[0,0,0] neg_hi:[0,1,0]
	v_pk_fma_f32 v[198:199], v[168:169], v[190:191], v[198:199] op_sel:[0,0,0] op_sel_hi:[0,1,1] neg_lo:[0,0,0] neg_hi:[0,1,0]
	v_pk_fma_f32 v[200:201], v[158:159], v[190:191], v[200:201] op_sel:[0,0,0] op_sel_hi:[0,1,1] neg_lo:[0,0,0] neg_hi:[0,1,0]
	v_pk_fma_f32 v[202:203], v[154:155], v[190:191], v[202:203] op_sel:[0,0,0] op_sel_hi:[0,1,1] neg_lo:[0,0,0] neg_hi:[0,1,0]
	v_pk_add_f32 v[164:165], v[162:163], v[196:197] neg_lo:[0,1] neg_hi:[0,1]
	v_pk_add_f32 v[168:169], v[166:167], v[198:199] neg_lo:[0,1] neg_hi:[0,1]
	v_pk_add_f32 v[158:159], v[156:157], v[200:201] neg_lo:[0,1] neg_hi:[0,1]
	v_pk_add_f32 v[154:155], v[152:153], v[202:203] neg_lo:[0,1] neg_hi:[0,1]
	v_pk_add_f32 v[162:163], v[162:163], v[196:197]
	v_pk_add_f32 v[166:167], v[166:167], v[198:199]
	v_pk_add_f32 v[156:157], v[156:157], v[200:201]
	v_pk_add_f32 v[152:153], v[152:153], v[202:203]
	v_pk_mul_f32 v[196:197], v[166:167], v[188:189] op_sel:[1,1] op_sel_hi:[1,0]
	v_pk_mul_f32 v[198:199], v[168:169], v[188:189] op_sel:[1,0] op_sel_hi:[1,1]
	v_pk_mul_f32 v[200:201], v[152:153], v[188:189] op_sel:[1,1] op_sel_hi:[1,0]
	v_pk_mul_f32 v[202:203], v[154:155], v[188:189] op_sel:[1,0] op_sel_hi:[1,1]
	v_pk_fma_f32 v[196:197], v[166:167], v[188:189], v[196:197] op_sel:[0,0,0] op_sel_hi:[0,1,1] neg_lo:[0,0,0] neg_hi:[0,1,0]
	v_pk_fma_f32 v[198:199], v[168:169], v[188:189], v[198:199] op_sel:[0,1,0] op_sel_hi:[0,0,1] neg_lo:[0,0,1] neg_hi:[0,0,0]
	v_pk_fma_f32 v[200:201], v[152:153], v[188:189], v[200:201] op_sel:[0,0,0] op_sel_hi:[0,1,1] neg_lo:[0,0,0] neg_hi:[0,1,0]
	v_pk_fma_f32 v[202:203], v[154:155], v[188:189], v[202:203] op_sel:[0,1,0] op_sel_hi:[0,0,1] neg_lo:[0,0,1] neg_hi:[0,0,0]
	v_pk_add_f32 v[166:167], v[162:163], v[196:197] neg_lo:[0,1] neg_hi:[0,1]
	v_pk_add_f32 v[168:169], v[164:165], v[198:199] neg_lo:[0,1] neg_hi:[0,1]
	v_pk_add_f32 v[152:153], v[156:157], v[200:201] neg_lo:[0,1] neg_hi:[0,1]
	v_pk_add_f32 v[154:155], v[158:159], v[202:203] neg_lo:[0,1] neg_hi:[0,1]
	v_pk_add_f32 v[162:163], v[162:163], v[196:197]
	v_pk_add_f32 v[164:165], v[164:165], v[198:199]
	v_pk_add_f32 v[156:157], v[156:157], v[200:201]
	v_pk_add_f32 v[158:159], v[158:159], v[202:203]
	v_pk_mul_f32 v[196:197], v[156:157], v[136:137] op_sel:[1,1] op_sel_hi:[1,0]
	v_pk_mul_f32 v[198:199], v[158:159], v[172:173] op_sel:[1,1] op_sel_hi:[1,0]
	v_pk_mul_f32 v[200:201], v[152:153], v[136:137] op_sel:[1,0] op_sel_hi:[1,1]
	v_pk_mul_f32 v[202:203], v[154:155], v[174:175] op_sel:[1,1] op_sel_hi:[1,0]
	v_pk_fma_f32 v[196:197], v[156:157], v[136:137], v[196:197] op_sel:[0,0,0] op_sel_hi:[0,1,1] neg_lo:[0,0,0] neg_hi:[0,1,0]
	v_pk_fma_f32 v[198:199], v[158:159], v[172:173], v[198:199] op_sel:[0,0,0] op_sel_hi:[0,1,1] neg_lo:[0,0,0] neg_hi:[0,1,0]
	v_pk_fma_f32 v[200:201], v[152:153], v[136:137], v[200:201] op_sel:[0,1,0] op_sel_hi:[0,0,1] neg_lo:[0,0,1] neg_hi:[0,0,0]
	v_pk_fma_f32 v[202:203], v[154:155], v[174:175], v[202:203] op_sel:[0,0,0] op_sel_hi:[0,1,1] neg_lo:[0,0,0] neg_hi:[0,1,0]
	v_pk_add_f32 v[156:157], v[162:163], v[196:197] neg_lo:[0,1] neg_hi:[0,1]
	v_pk_add_f32 v[158:159], v[164:165], v[198:199] neg_lo:[0,1] neg_hi:[0,1]
	v_pk_add_f32 v[152:153], v[166:167], v[200:201] neg_lo:[0,1] neg_hi:[0,1]
	v_pk_add_f32 v[154:155], v[168:169], v[202:203] neg_lo:[0,1] neg_hi:[0,1]
	v_pk_add_f32 v[162:163], v[162:163], v[196:197]
	v_pk_add_f32 v[164:165], v[164:165], v[198:199]
	v_pk_add_f32 v[166:167], v[166:167], v[200:201]
	v_pk_add_f32 v[168:169], v[168:169], v[202:203]
	ds_write2_b64 v132, v[162:163], v[164:165] offset1:136
	ds_write2_b64 v160, v[166:167], v[168:169] offset0:16 offset1:152
	ds_write2_b64 v142, v[156:157], v[158:159] offset0:32 offset1:168
	ds_write2_b64 v140, v[152:153], v[154:155] offset0:48 offset1:184
	s_mov_b64 s[14:15], 0
	s_waitcnt lgkmcnt(0)
	s_barrier
	s_mov_b32 s0, 0
	s_mov_b64 s[30:31], -1
; #define LAS __attribute__((address_space(3)))
; __device__ __forceinline__ cf twc(cf ws, int k16) { if (k16 == 0) return ws; if (k16 == 4) return cf{ws.y, -ws.x}; return cmul(ws, cf{c16(k16), -s16(k16)}); }
; template <int LR> __device__ __forceinline__ void dit_reg(cf (&x)[1 << LR], cf w) {
;     constexpr int R = 1 << LR; cf wsv[LR]; wsv[0] = w;
; #pragma unroll
;     for (int s = 1; s < LR; ++s) wsv[s] = cmul(wsv[s - 1], wsv[s - 1]);
; #pragma unroll
;     for (int s = LR - 1; s >= 0; --s) { const int half = R >> (s + 1);
; #pragma unroll
;         for (int m0 = 0; m0 < R; m0 += 2 * half)
; #pragma unroll
;             for (int mm = 0; mm < half; ++mm) { const int ia = m0 + mm, ib = ia + half; const cf a = x[ia];
;                 const cf b = cmulc(x[ib], twc(wsv[s], (mm << s) * (16 / R)));
;                 x[ia] = cf{a.x + b.x, a.y + b.y}; x[ib] = cf{a.x - b.x, a.y - b.y}; } }
; }
; __device__ __forceinline__ void lds_barrier() { asm volatile("s_waitcnt lgkmcnt(0)\n\ts_barrier" ::: "memory"); }
; template <int LR, bool INV> __device__ __forceinline__ void fft_pass(ldsf2 buf, int base, int stride, int twi) {
;     constexpr int R = 1 << LR; cf x[R];
;     const v2f wv = ((ldsf2)((LAS unsigned char*)buf + 139264))[twi];
; #pragma unroll
;     for (int m = 0; m < R; ++m) { const v2f v = buf[base + m * stride]; x[m] = cf{v.x, v.y}; }
;     const cf w{wv.x, wv.y};
;     if (INV) dit_reg<LR>(x, w); else dif_reg<LR>(x, w);
; #pragma unroll
;     for (int m = 0; m < R; ++m) buf[base + m * stride] = mkv2(x[m].x, x[m].y);
; }
.LBB0_369:
	v_add_u32_e32 v79, s0, v78
	v_ashrrev_i32_e32 v80, 4, v79
	v_lshl_add_u32 v79, v79, 3, 0
	v_add_u32_e32 v81, 0x22000, v79
	ds_read_b64 v[96:97], v81
	v_lshl_add_u32 v79, v80, 3, v79
	ds_read2st64_b64 v[80:83], v79 offset1:17
	ds_read2st64_b64 v[84:87], v79 offset0:34 offset1:51
	ds_read2st64_b64 v[88:91], v79 offset0:68 offset1:85
	ds_read2st64_b64 v[92:95], v79 offset0:102 offset1:119
	s_movk_i32 s0, 0x200
	v_add_u32_e32 v126, s0, v78
	v_ashrrev_i32_e32 v128, 4, v126
	v_lshl_add_u32 v126, v126, 3, 0
	v_add_u32_e32 v130, 0x22000, v126
	ds_read_b64 v[132:133], v130
	v_lshl_add_u32 v126, v128, 3, v126
	ds_read2st64_b64 v[134:137], v126 offset1:17
	ds_read2st64_b64 v[138:141], v126 offset0:34 offset1:51
	ds_read2st64_b64 v[152:155], v126 offset0:68 offset1:85
	ds_read2st64_b64 v[156:159], v126 offset0:102 offset1:119
	s_waitcnt lgkmcnt(5)
	v_pk_add_f32 v[98:99], v[96:97], v[96:97] op_sel:[0,1] op_sel_hi:[1,0] neg_lo:[0,0] neg_hi:[0,1]
	v_pk_mul_f32 v[100:101], v[98:99], s[16:17] op_sel:[0,0] op_sel_hi:[1,0]
	v_pk_mul_f32 v[102:103], v[98:99], s[16:17] op_sel:[1,0] op_sel_hi:[0,0] neg_lo:[0,0] neg_hi:[1,0]
	v_pk_mul_f32 v[104:105], v[96:97], v[96:97] op_sel:[1,1] op_sel_hi:[1,0]
	v_pk_fma_f32 v[104:105], v[96:97], v[96:97], v[104:105] op_sel:[0,0,0] op_sel_hi:[0,1,1] neg_lo:[0,0,1] neg_hi:[0,0,0]
	v_pk_mul_f32 v[106:107], v[104:105], v[104:105] op_sel:[1,1] op_sel_hi:[1,0]
	v_pk_fma_f32 v[106:107], v[104:105], v[104:105], v[106:107] op_sel:[0,0,0] op_sel_hi:[0,1,1] neg_lo:[0,0,1] neg_hi:[0,0,0]
	v_pk_mul_f32 v[108:109], v[82:83], v[106:107] op_sel:[1,1] op_sel_hi:[1,0]
	v_pk_mul_f32 v[110:111], v[86:87], v[106:107] op_sel:[1,1] op_sel_hi:[1,0]
	v_pk_mul_f32 v[112:113], v[90:91], v[106:107] op_sel:[1,1] op_sel_hi:[1,0]
	v_pk_mul_f32 v[114:115], v[94:95], v[106:107] op_sel:[1,1] op_sel_hi:[1,0]
	v_pk_fma_f32 v[108:109], v[82:83], v[106:107], v[108:109] op_sel:[0,0,0] op_sel_hi:[0,1,1] neg_lo:[0,0,0] neg_hi:[0,1,0]
	v_pk_fma_f32 v[110:111], v[86:87], v[106:107], v[110:111] op_sel:[0,0,0] op_sel_hi:[0,1,1] neg_lo:[0,0,0] neg_hi:[0,1,0]
	v_pk_fma_f32 v[112:113], v[90:91], v[106:107], v[112:113] op_sel:[0,0,0] op_sel_hi:[0,1,1] neg_lo:[0,0,0] neg_hi:[0,1,0]
	v_pk_fma_f32 v[114:115], v[94:95], v[106:107], v[114:115] op_sel:[0,0,0] op_sel_hi:[0,1,1] neg_lo:[0,0,0] neg_hi:[0,1,0]
	v_pk_add_f32 v[82:83], v[80:81], v[108:109] neg_lo:[0,1] neg_hi:[0,1]
	v_pk_add_f32 v[86:87], v[84:85], v[110:111] neg_lo:[0,1] neg_hi:[0,1]
	v_pk_add_f32 v[90:91], v[88:89], v[112:113] neg_lo:[0,1] neg_hi:[0,1]
	v_pk_add_f32 v[94:95], v[92:93], v[114:115] neg_lo:[0,1] neg_hi:[0,1]
	v_pk_add_f32 v[80:81], v[80:81], v[108:109]
	v_pk_add_f32 v[84:85], v[84:85], v[110:111]
	v_pk_add_f32 v[88:89], v[88:89], v[112:113]
	v_pk_add_f32 v[92:93], v[92:93], v[114:115]
	v_pk_mul_f32 v[108:109], v[84:85], v[104:105] op_sel:[1,1] op_sel_hi:[1,0]
	v_pk_mul_f32 v[110:111], v[86:87], v[104:105] op_sel:[1,0] op_sel_hi:[1,1]
	v_pk_mul_f32 v[112:113], v[92:93], v[104:105] op_sel:[1,1] op_sel_hi:[1,0]
	v_pk_mul_f32 v[114:115], v[94:95], v[104:105] op_sel:[1,0] op_sel_hi:[1,1]
	v_pk_fma_f32 v[108:109], v[84:85], v[104:105], v[108:109] op_sel:[0,0,0] op_sel_hi:[0,1,1] neg_lo:[0,0,0] neg_hi:[0,1,0]
	v_pk_fma_f32 v[110:111], v[86:87], v[104:105], v[110:111] op_sel:[0,1,0] op_sel_hi:[0,0,1] neg_lo:[0,0,1] neg_hi:[0,0,0]
	v_pk_fma_f32 v[112:113], v[92:93], v[104:105], v[112:113] op_sel:[0,0,0] op_sel_hi:[0,1,1] neg_lo:[0,0,0] neg_hi:[0,1,0]
	v_pk_fma_f32 v[114:115], v[94:95], v[104:105], v[114:115] op_sel:[0,1,0] op_sel_hi:[0,0,1] neg_lo:[0,0,1] neg_hi:[0,0,0]
	v_pk_add_f32 v[84:85], v[80:81], v[108:109] neg_lo:[0,1] neg_hi:[0,1]
	v_pk_add_f32 v[86:87], v[82:83], v[110:111] neg_lo:[0,1] neg_hi:[0,1]
	v_pk_add_f32 v[92:93], v[88:89], v[112:113] neg_lo:[0,1] neg_hi:[0,1]
	v_pk_add_f32 v[94:95], v[90:91], v[114:115] neg_lo:[0,1] neg_hi:[0,1]
	v_pk_add_f32 v[80:81], v[80:81], v[108:109]
	v_pk_add_f32 v[82:83], v[82:83], v[110:111]
	v_pk_add_f32 v[88:89], v[88:89], v[112:113]
	v_pk_add_f32 v[90:91], v[90:91], v[114:115]
	v_pk_mul_f32 v[108:109], v[88:89], v[96:97] op_sel:[1,1] op_sel_hi:[1,0]
	v_pk_mul_f32 v[110:111], v[90:91], v[100:101] op_sel:[1,1] op_sel_hi:[1,0]
	v_pk_mul_f32 v[112:113], v[92:93], v[96:97] op_sel:[1,0] op_sel_hi:[1,1]
	v_pk_mul_f32 v[114:115], v[94:95], v[102:103] op_sel:[1,1] op_sel_hi:[1,0]
	v_pk_fma_f32 v[108:109], v[88:89], v[96:97], v[108:109] op_sel:[0,0,0] op_sel_hi:[0,1,1] neg_lo:[0,0,0] neg_hi:[0,1,0]
	v_pk_fma_f32 v[110:111], v[90:91], v[100:101], v[110:111] op_sel:[0,0,0] op_sel_hi:[0,1,1] neg_lo:[0,0,0] neg_hi:[0,1,0]
	v_pk_fma_f32 v[112:113], v[92:93], v[96:97], v[112:113] op_sel:[0,1,0] op_sel_hi:[0,0,1] neg_lo:[0,0,1] neg_hi:[0,0,0]
	v_pk_fma_f32 v[114:115], v[94:95], v[102:103], v[114:115] op_sel:[0,0,0] op_sel_hi:[0,1,1] neg_lo:[0,0,0] neg_hi:[0,1,0]
	v_pk_add_f32 v[88:89], v[80:81], v[108:109] neg_lo:[0,1] neg_hi:[0,1]
	v_pk_add_f32 v[90:91], v[82:83], v[110:111] neg_lo:[0,1] neg_hi:[0,1]
	v_pk_add_f32 v[92:93], v[84:85], v[112:113] neg_lo:[0,1] neg_hi:[0,1]
	v_pk_add_f32 v[94:95], v[86:87], v[114:115] neg_lo:[0,1] neg_hi:[0,1]
	v_pk_add_f32 v[80:81], v[80:81], v[108:109]
	v_pk_add_f32 v[82:83], v[82:83], v[110:111]
	v_pk_add_f32 v[84:85], v[84:85], v[112:113]
	v_pk_add_f32 v[86:87], v[86:87], v[114:115]
	ds_write2st64_b64 v79, v[80:81], v[82:83] offset1:17
	ds_write2st64_b64 v79, v[84:85], v[86:87] offset0:34 offset1:51
	ds_write2st64_b64 v79, v[88:89], v[90:91] offset0:68 offset1:85
	ds_write2st64_b64 v79, v[92:93], v[94:95] offset0:102 offset1:119
	s_waitcnt lgkmcnt(4)
; #define LAS __attribute__((address_space(3)))
; template <int LR> __device__ __forceinline__ void dit_reg(cf (&x)[1 << LR], cf w) {
;     constexpr int R = 1 << LR; cf wsv[LR]; wsv[0] = w;
; #pragma unroll
;     for (int s = 1; s < LR; ++s) wsv[s] = cmul(wsv[s - 1], wsv[s - 1]);
; #pragma unroll
;     for (int s = LR - 1; s >= 0; --s) { const int half = R >> (s + 1);
; #pragma unroll
;         for (int m0 = 0; m0 < R; m0 += 2 * half)
; #pragma unroll
;             for (int mm = 0; mm < half; ++mm) { const int ia = m0 + mm, ib = ia + half; const cf a = x[ia];
;                 const cf b = cmulc(x[ib], twc(wsv[s], (mm << s) * (16 / R)));
;                 x[ia] = cf{a.x + b.x, a.y + b.y}; x[ib] = cf{a.x - b.x, a.y - b.y}; } }
; }
; __device__ __forceinline__ void lds_barrier() { asm volatile("s_waitcnt lgkmcnt(0)\n\ts_barrier" ::: "memory"); }
; template <int LR, bool INV> __device__ __forceinline__ void fft_pass(ldsf2 buf, int base, int stride, int twi) {
;     constexpr int R = 1 << LR; cf x[R];
;     const v2f wv = ((ldsf2)((LAS unsigned char*)buf + 139264))[twi];
; #pragma unroll
;     for (int m = 0; m < R; ++m) { const v2f v = buf[base + m * stride]; x[m] = cf{v.x, v.y}; }
;     const cf w{wv.x, wv.y};
;     if (INV) dit_reg<LR>(x, w); else dif_reg<LR>(x, w);
; #pragma unroll
;     for (int m = 0; m < R; ++m) buf[base + m * stride] = mkv2(x[m].x, x[m].y);
; }
; __device__ void ph_hyena_fft(const Params& P, int j, const bf16_t* __restrict__ projAT, const float* __restrict__ kf, bf16_t* __restrict__ yaT, unsigned char* lds_raw) {
;     ...
;             { float xa[8], xb[8]; sconv8(xb0, n0, wb0, wb1, wb2, bb, xa); sconv8(xb1, n0, wb0, wb1, wb2, bb, xb);
;               const unsigned gw0[4] = {g0.x, g0.y, g0.z, g0.w}, gw1[4] = {g1.x, g1.y, g1.z, g1.w}; unsigned w0[4], w1[4];
; #pragma unroll
;               for (int k2 = 0; k2 < 4; ++k2) { const v2f ya = buf[ph0 + 2 * k2], yb = buf[ph0 + 2 * k2 + 1];
;                   const float ra = xa[2 * k2] * (ya.x * invN + sk1 * va[2 * k2]) * silu(__uint_as_float(gw0[k2] << 16));
;                   const float rb = xa[2 * k2 + 1] * (yb.x * invN + sk1 * va[2 * k2 + 1]) * silu(__uint_as_float(gw0[k2] & 0xffff0000u));
;                   const float rc = xb[2 * k2] * (ya.y * invN + sk1 * vb[2 * k2]) * silu(__uint_as_float(gw1[k2] << 16));
	v_pk_add_f32 v[142:143], v[132:133], v[132:133] op_sel:[0,1] op_sel_hi:[1,0] neg_lo:[0,0] neg_hi:[0,1]
	v_pk_mul_f32 v[160:161], v[142:143], s[16:17] op_sel:[0,0] op_sel_hi:[1,0]
	v_pk_mul_f32 v[162:163], v[142:143], s[16:17] op_sel:[1,0] op_sel_hi:[0,0] neg_lo:[0,0] neg_hi:[1,0]
	v_pk_mul_f32 v[164:165], v[132:133], v[132:133] op_sel:[1,1] op_sel_hi:[1,0]
	v_pk_fma_f32 v[164:165], v[132:133], v[132:133], v[164:165] op_sel:[0,0,0] op_sel_hi:[0,1,1] neg_lo:[0,0,1] neg_hi:[0,0,0]
	v_pk_mul_f32 v[166:167], v[164:165], v[164:165] op_sel:[1,1] op_sel_hi:[1,0]
	v_pk_fma_f32 v[166:167], v[164:165], v[164:165], v[166:167] op_sel:[0,0,0] op_sel_hi:[0,1,1] neg_lo:[0,0,1] neg_hi:[0,0,0]
	v_pk_mul_f32 v[168:169], v[136:137], v[166:167] op_sel:[1,1] op_sel_hi:[1,0]
	v_pk_mul_f32 v[170:171], v[140:141], v[166:167] op_sel:[1,1] op_sel_hi:[1,0]
	v_pk_mul_f32 v[172:173], v[154:155], v[166:167] op_sel:[1,1] op_sel_hi:[1,0]
	v_pk_mul_f32 v[174:175], v[158:159], v[166:167] op_sel:[1,1] op_sel_hi:[1,0]
	v_pk_fma_f32 v[168:169], v[136:137], v[166:167], v[168:169] op_sel:[0,0,0] op_sel_hi:[0,1,1] neg_lo:[0,0,0] neg_hi:[0,1,0]
	v_pk_fma_f32 v[170:171], v[140:141], v[166:167], v[170:171] op_sel:[0,0,0] op_sel_hi:[0,1,1] neg_lo:[0,0,0] neg_hi:[0,1,0]
	v_pk_fma_f32 v[172:173], v[154:155], v[166:167], v[172:173] op_sel:[0,0,0] op_sel_hi:[0,1,1] neg_lo:[0,0,0] neg_hi:[0,1,0]
	v_pk_fma_f32 v[174:175], v[158:159], v[166:167], v[174:175] op_sel:[0,0,0] op_sel_hi:[0,1,1] neg_lo:[0,0,0] neg_hi:[0,1,0]
	v_pk_add_f32 v[136:137], v[134:135], v[168:169] neg_lo:[0,1] neg_hi:[0,1]
	v_pk_add_f32 v[140:141], v[138:139], v[170:171] neg_lo:[0,1] neg_hi:[0,1]
	v_pk_add_f32 v[154:155], v[152:153], v[172:173] neg_lo:[0,1] neg_hi:[0,1]
	v_pk_add_f32 v[158:159], v[156:157], v[174:175] neg_lo:[0,1] neg_hi:[0,1]
	v_pk_add_f32 v[134:135], v[134:135], v[168:169]
	v_pk_add_f32 v[138:139], v[138:139], v[170:171]
	v_pk_add_f32 v[152:153], v[152:153], v[172:173]
	v_pk_add_f32 v[156:157], v[156:157], v[174:175]
	v_pk_mul_f32 v[168:169], v[138:139], v[164:165] op_sel:[1,1] op_sel_hi:[1,0]
	v_pk_mul_f32 v[170:171], v[140:141], v[164:165] op_sel:[1,0] op_sel_hi:[1,1]
	v_pk_mul_f32 v[172:173], v[156:157], v[164:165] op_sel:[1,1] op_sel_hi:[1,0]
	v_pk_mul_f32 v[174:175], v[158:159], v[164:165] op_sel:[1,0] op_sel_hi:[1,1]
	v_pk_fma_f32 v[168:169], v[138:139], v[164:165], v[168:169] op_sel:[0,0,0] op_sel_hi:[0,1,1] neg_lo:[0,0,0] neg_hi:[0,1,0]
	v_pk_fma_f32 v[170:171], v[140:141], v[164:165], v[170:171] op_sel:[0,1,0] op_sel_hi:[0,0,1] neg_lo:[0,0,1] neg_hi:[0,0,0]
	v_pk_fma_f32 v[172:173], v[156:157], v[164:165], v[172:173] op_sel:[0,0,0] op_sel_hi:[0,1,1] neg_lo:[0,0,0] neg_hi:[0,1,0]
	v_pk_fma_f32 v[174:175], v[158:159], v[164:165], v[174:175] op_sel:[0,1,0] op_sel_hi:[0,0,1] neg_lo:[0,0,1] neg_hi:[0,0,0]
	v_pk_add_f32 v[138:139], v[134:135], v[168:169] neg_lo:[0,1] neg_hi:[0,1]
	v_pk_add_f32 v[140:141], v[136:137], v[170:171] neg_lo:[0,1] neg_hi:[0,1]
	v_pk_add_f32 v[156:157], v[152:153], v[172:173] neg_lo:[0,1] neg_hi:[0,1]
	v_pk_add_f32 v[158:159], v[154:155], v[174:175] neg_lo:[0,1] neg_hi:[0,1]
	v_pk_add_f32 v[134:135], v[134:135], v[168:169]
	v_pk_add_f32 v[136:137], v[136:137], v[170:171]
	v_pk_add_f32 v[152:153], v[152:153], v[172:173]
	v_pk_add_f32 v[154:155], v[154:155], v[174:175]
	v_pk_mul_f32 v[168:169], v[152:153], v[132:133] op_sel:[1,1] op_sel_hi:[1,0]
	v_pk_mul_f32 v[170:171], v[154:155], v[160:161] op_sel:[1,1] op_sel_hi:[1,0]
	v_pk_mul_f32 v[172:173], v[156:157], v[132:133] op_sel:[1,0] op_sel_hi:[1,1]
	v_pk_mul_f32 v[174:175], v[158:159], v[162:163] op_sel:[1,1] op_sel_hi:[1,0]
	v_pk_fma_f32 v[168:169], v[152:153], v[132:133], v[168:169] op_sel:[0,0,0] op_sel_hi:[0,1,1] neg_lo:[0,0,0] neg_hi:[0,1,0]
	v_pk_fma_f32 v[170:171], v[154:155], v[160:161], v[170:171] op_sel:[0,0,0] op_sel_hi:[0,1,1] neg_lo:[0,0,0] neg_hi:[0,1,0]
	v_pk_fma_f32 v[172:173], v[156:157], v[132:133], v[172:173] op_sel:[0,1,0] op_sel_hi:[0,0,1] neg_lo:[0,0,1] neg_hi:[0,0,0]
	v_pk_fma_f32 v[174:175], v[158:159], v[162:163], v[174:175] op_sel:[0,0,0] op_sel_hi:[0,1,1] neg_lo:[0,0,0] neg_hi:[0,1,0]
	v_pk_add_f32 v[152:153], v[134:135], v[168:169] neg_lo:[0,1] neg_hi:[0,1]
	v_pk_add_f32 v[154:155], v[136:137], v[170:171] neg_lo:[0,1] neg_hi:[0,1]
	v_pk_add_f32 v[156:157], v[138:139], v[172:173] neg_lo:[0,1] neg_hi:[0,1]
	v_pk_add_f32 v[158:159], v[140:141], v[174:175] neg_lo:[0,1] neg_hi:[0,1]
	v_pk_add_f32 v[134:135], v[134:135], v[168:169]
	v_pk_add_f32 v[136:137], v[136:137], v[170:171]
	v_pk_add_f32 v[138:139], v[138:139], v[172:173]
	v_pk_add_f32 v[140:141], v[140:141], v[174:175]
	ds_write2st64_b64 v126, v[134:135], v[136:137] offset1:17
	ds_write2st64_b64 v126, v[138:139], v[140:141] offset0:34 offset1:51
	ds_write2st64_b64 v126, v[152:153], v[154:155] offset0:68 offset1:85
	ds_write2st64_b64 v126, v[156:157], v[158:159] offset0:102 offset1:119
	s_mov_b64 s[30:31], 0
	s_waitcnt vmcnt(6)
	v_lshlrev_b32_e32 v78, 16, v147
	v_cndmask_b32_e64 v97, 0, v78, s[42:43]
	s_waitcnt vmcnt(5)
	v_lshlrev_b32_e32 v78, 16, v148
	s_waitcnt vmcnt(1)
	v_lshlrev_b32_e32 v114, 16, v12
	v_cndmask_b32_e64 v99, 0, v78, s[44:45]
	v_and_b32_e32 v12, 0xffff0000, v12
	v_mul_f32_e32 v78, 0xbfb8aa3b, v114
	v_exp_f32_e32 v78, v78
	v_mul_f32_e32 v82, 0xbfb8aa3b, v12
	v_lshlrev_b32_e32 v104, 16, v5
	v_exp_f32_e32 v82, v82
	v_and_b32_e32 v102, 0xffff0000, v4
	v_mov_b32_e32 v96, v104
	v_lshlrev_b32_e32 v100, 16, v4
	v_and_b32_e32 v103, 0xffff0000, v5
	v_mov_b32_e32 v101, v102
	v_pk_mul_f32 v[96:97], v[38:39], v[96:97]
	v_lshlrev_b32_e32 v115, 16, v13
	v_pk_fma_f32 v[96:97], v[38:39], v[100:101], v[96:97] op_sel:[0,0,1] op_sel_hi:[1,1,0]
	v_mov_b32_e32 v101, v104
	v_pk_mul_f32 v[122:123], v[54:55], v[102:103]
	v_add_f32_e32 v78, 1.0, v78
	v_pk_fma_f32 v[100:101], v[52:53], v[100:101], v[122:123]
	v_rcp_f32_e32 v122, v78
	v_add_f32_e32 v78, 1.0, v82
	v_mul_f32_e32 v82, 0xbfb8aa3b, v115
	v_exp_f32_e32 v82, v82
	s_waitcnt lgkmcnt(0)
	s_barrier
; __device__ __forceinline__ bf16_t f2bf(float f) { unsigned u = __float_as_uint(f); u += 0x7FFFu + ((u >> 16) & 1u); return (bf16_t)(u >> 16); }
; __device__ __forceinline__ float silu(float x) { return x * __builtin_amdgcn_rcpf(1.0f + __expf(-x)); }
; __device__ void ph_hyena_fft(const Params& P, int j, const bf16_t* __restrict__ projAT, const float* __restrict__ kf, bf16_t* __restrict__ yaT, unsigned char* lds_raw) {
;     ...
;             { float xa[8], xb[8]; sconv8(xb0, n0, wb0, wb1, wb2, bb, xa); sconv8(xb1, n0, wb0, wb1, wb2, bb, xb);
;               const unsigned gw0[4] = {g0.x, g0.y, g0.z, g0.w}, gw1[4] = {g1.x, g1.y, g1.z, g1.w}; unsigned w0[4], w1[4];
; #pragma unroll
;               for (int k2 = 0; k2 < 4; ++k2) { const v2f ya = buf[ph0 + 2 * k2], yb = buf[ph0 + 2 * k2 + 1];
;                   const float ra = xa[2 * k2] * (ya.x * invN + sk1 * va[2 * k2]) * silu(__uint_as_float(gw0[k2] << 16));
;                   const float rb = xa[2 * k2 + 1] * (yb.x * invN + sk1 * va[2 * k2 + 1]) * silu(__uint_as_float(gw0[k2] & 0xffff0000u));
;                   const float rc = xb[2 * k2] * (ya.y * invN + sk1 * vb[2 * k2]) * silu(__uint_as_float(gw1[k2] << 16));
;                   const float rd = xb[2 * k2 + 1] * (yb.y * invN + sk1 * vb[2 * k2 + 1]) * silu(__uint_as_float(gw1[k2] & 0xffff0000u));
;                   w0[k2] = (unsigned)f2bf(ra) | ((unsigned)f2bf(rb) << 16); w1[k2] = (unsigned)f2bf(rc) | ((unsigned)f2bf(rd) << 16); }
	ds_read2_b64 v[88:91], v145 offset1:1
	ds_read2_b64 v[92:95], v145 offset0:2 offset1:3
	v_and_b32_e32 v13, 0xffff0000, v13
	v_rcp_f32_e32 v124, v78
	v_add_f32_e32 v78, 1.0, v82
	v_rcp_f32_e32 v123, v78
	v_mul_f32_e32 v78, 0xbfb8aa3b, v13
	v_exp_f32_e32 v78, v78
	s_waitcnt lgkmcnt(1)
	v_mov_b32_e32 v126, v88
	s_waitcnt lgkmcnt(0)
	v_mov_b32_e32 v127, v92
	v_pk_fma_f32 v[96:97], v[40:41], v[102:103], v[96:97]
	v_pk_mul_f32 v[126:127], v[126:127], s[80:81] op_sel_hi:[1,0]
	v_pk_add_f32 v[96:97], v[42:43], v[96:97]
	v_pk_fma_f32 v[76:77], v[46:47], v[76:77], v[126:127]
	v_add_f32_e32 v78, 1.0, v78
	v_pk_mul_f32 v[76:77], v[96:97], v[76:77]
	v_pk_mul_f32 v[96:97], v[122:123], v[114:115]
	v_rcp_f32_e32 v125, v78
	v_lshlrev_b32_e32 v105, 16, v6
	v_pk_mul_f32 v[76:77], v[96:97], v[76:77]
	v_mov_b32_e32 v96, v90
	v_mov_b32_e32 v97, v94
	v_pk_fma_f32 v[100:101], v[40:41], v[104:105], v[100:101]
	v_pk_mul_f32 v[96:97], v[96:97], s[80:81] op_sel_hi:[1,0]
	v_pk_add_f32 v[100:101], v[42:43], v[100:101]
	v_pk_fma_f32 v[74:75], v[46:47], v[74:75], v[96:97]
	v_pk_mul_f32 v[12:13], v[124:125], v[12:13]
	v_pk_mul_f32 v[74:75], v[100:101], v[74:75]
	v_lshlrev_b32_e32 v118, 16, v14
	v_pk_mul_f32 v[12:13], v[12:13], v[74:75]
	v_and_b32_sdwa v74, v77, v229 dst_sel:DWORD dst_unused:UNUSED_PAD src0_sel:WORD_1 src1_sel:DWORD
	v_add3_u32 v74, v77, v74, s33
	v_and_b32_sdwa v77, v12, v229 dst_sel:DWORD dst_unused:UNUSED_PAD src0_sel:WORD_1 src1_sel:DWORD
	v_and_b32_sdwa v75, v76, v229 dst_sel:DWORD dst_unused:UNUSED_PAD src0_sel:WORD_1 src1_sel:DWORD
	v_add3_u32 v12, v12, v77, s33
	v_and_b32_e32 v14, 0xffff0000, v14
	v_add3_u32 v75, v76, v75, s33
	v_and_b32_e32 v12, 0xffff0000, v12
	v_or_b32_sdwa v12, v12, v75 dst_sel:DWORD dst_unused:UNUSED_PAD src0_sel:DWORD src1_sel:WORD_1
	v_mul_f32_e32 v75, 0xbfb8aa3b, v14
	v_exp_f32_e32 v75, v75
	v_lshlrev_b32_e32 v4, 16, v149
	v_lshlrev_b32_e32 v119, 16, v15
	v_and_b32_sdwa v76, v13, v229 dst_sel:DWORD dst_unused:UNUSED_PAD src0_sel:WORD_1 src1_sel:DWORD
	v_add_f32_e32 v75, 1.0, v75
	v_cndmask_b32_e64 v111, 0, v4, s[42:43]
	v_lshlrev_b32_e32 v4, 16, v150
	v_add3_u32 v13, v13, v76, s33
	v_rcp_f32_e32 v76, v75
	v_mul_f32_e32 v75, 0xbfb8aa3b, v119
	v_and_b32_e32 v106, 0xffff0000, v6
	v_lshlrev_b32_e32 v109, 16, v7
	v_and_b32_e32 v107, 0xffff0000, v7
	v_cndmask_b32_e64 v79, 0, v4, s[44:45]
	v_lshlrev_b32_e32 v112, 16, v8
	v_and_b32_e32 v86, 0xffff0000, v8
	v_lshlrev_b32_e32 v80, 16, v9
	v_and_b32_e32 v87, 0xffff0000, v9
	v_lshlrev_b32_e32 v81, 16, v10
	v_and_b32_e32 v84, 0xffff0000, v10
	v_lshlrev_b32_e32 v83, 16, v11
	v_and_b32_e32 v85, 0xffff0000, v11
	ds_read2_b64 v[4:7], v145 offset0:4 offset1:5
	ds_read2_b64 v[8:11], v145 offset0:6 offset1:7
	v_exp_f32_e32 v75, v75
	v_and_b32_e32 v15, 0xffff0000, v15
	v_and_b32_e32 v13, 0xffff0000, v13
	s_waitcnt lgkmcnt(1)
	v_mov_b32_e32 v96, v4
	v_add_f32_e32 v4, 1.0, v75
	v_rcp_f32_e32 v75, v4
	v_mul_f32_e32 v4, 0xbfb8aa3b, v15
	v_exp_f32_e32 v4, v4
	s_waitcnt lgkmcnt(0)
	v_mov_b32_e32 v97, v8
	v_or_b32_sdwa v13, v13, v74 dst_sel:DWORD dst_unused:UNUSED_PAD src0_sel:DWORD src1_sel:WORD_1
	v_mul_f32_e32 v74, 0xbfb8aa3b, v118
	v_add_f32_e32 v4, 1.0, v4
	v_pk_mul_f32 v[96:97], v[96:97], s[80:81] op_sel_hi:[1,0]
	v_rcp_f32_e32 v77, v4
	v_exp_f32_e32 v74, v74
	v_pk_fma_f32 v[72:73], v[46:47], v[72:73], v[96:97]
	v_mov_b32_e32 v96, v6
	v_mov_b32_e32 v97, v10
	v_pk_mul_f32 v[96:97], v[96:97], s[80:81] op_sel_hi:[1,0]
	v_pk_mul_f32 v[14:15], v[76:77], v[14:15]
	v_pk_fma_f32 v[70:71], v[46:47], v[70:71], v[96:97]
	v_mov_b32_e32 v96, v105
	v_mov_b32_e32 v97, v109
	v_pk_mov_b32 v[76:77], v[102:103], v[106:107] op_sel:[1,0]
	v_pk_mul_f32 v[96:97], v[54:55], v[96:97]
	v_mov_b32_e32 v104, v107
	v_mov_b32_e32 v108, v106
	v_add_f32_e32 v74, 1.0, v74
	v_pk_fma_f32 v[76:77], v[52:53], v[76:77], v[96:97]
	v_pk_mul_f32 v[96:97], v[38:39], v[104:105]
	v_mov_b32_e32 v98, v109
	v_rcp_f32_e32 v74, v74
	v_pk_fma_f32 v[96:97], v[38:39], v[108:109], v[96:97] op_sel:[0,0,1] op_sel_hi:[1,1,0]
	v_pk_fma_f32 v[76:77], v[40:41], v[106:107], v[76:77]
	v_pk_fma_f32 v[96:97], v[40:41], v[98:99], v[96:97]
	v_pk_add_f32 v[76:77], v[42:43], v[76:77]
	v_pk_add_f32 v[96:97], v[42:43], v[96:97]
	v_pk_mul_f32 v[74:75], v[74:75], v[118:119]
	v_pk_mul_f32 v[70:71], v[96:97], v[70:71]
	v_pk_mul_f32 v[72:73], v[76:77], v[72:73]
	v_pk_mul_f32 v[14:15], v[14:15], v[70:71]
	v_pk_mul_f32 v[72:73], v[74:75], v[72:73]
	v_and_b32_sdwa v8, v15, v229 dst_sel:DWORD dst_unused:UNUSED_PAD src0_sel:WORD_1 src1_sel:DWORD
	v_and_b32_sdwa v4, v73, v229 dst_sel:DWORD dst_unused:UNUSED_PAD src0_sel:WORD_1 src1_sel:DWORD
	v_and_b32_sdwa v10, v14, v229 dst_sel:DWORD dst_unused:UNUSED_PAD src0_sel:WORD_1 src1_sel:DWORD
	v_add3_u32 v8, v15, v8, s33
	s_waitcnt vmcnt(0)
; __device__ __forceinline__ bf16_t f2bf(float f) { unsigned u = __float_as_uint(f); u += 0x7FFFu + ((u >> 16) & 1u); return (bf16_t)(u >> 16); }
; __device__ __forceinline__ float silu(float x) { return x * __builtin_amdgcn_rcpf(1.0f + __expf(-x)); }
; __device__ __forceinline__ void lds_barrier() { asm volatile("s_waitcnt lgkmcnt(0)\n\ts_barrier" ::: "memory"); }
; __device__ void ph_hyena_fft(const Params& P, int j, const bf16_t* __restrict__ projAT, const float* __restrict__ kf, bf16_t* __restrict__ yaT, unsigned char* lds_raw) {
;     ...
;             { float xa[8], xb[8]; sconv8(xb0, n0, wb0, wb1, wb2, bb, xa); sconv8(xb1, n0, wb0, wb1, wb2, bb, xb);
;               const unsigned gw0[4] = {g0.x, g0.y, g0.z, g0.w}, gw1[4] = {g1.x, g1.y, g1.z, g1.w}; unsigned w0[4], w1[4];
; #pragma unroll
;               for (int k2 = 0; k2 < 4; ++k2) { const v2f ya = buf[ph0 + 2 * k2], yb = buf[ph0 + 2 * k2 + 1];
;                   const float ra = xa[2 * k2] * (ya.x * invN + sk1 * va[2 * k2]) * silu(__uint_as_float(gw0[k2] << 16));
;                   const float rb = xa[2 * k2 + 1] * (yb.x * invN + sk1 * va[2 * k2 + 1]) * silu(__uint_as_float(gw0[k2] & 0xffff0000u));
;                   const float rc = xb[2 * k2] * (ya.y * invN + sk1 * vb[2 * k2]) * silu(__uint_as_float(gw1[k2] << 16));
;                   const float rd = xb[2 * k2 + 1] * (yb.y * invN + sk1 * vb[2 * k2 + 1]) * silu(__uint_as_float(gw1[k2] & 0xffff0000u));
;                   w0[k2] = (unsigned)f2bf(ra) | ((unsigned)f2bf(rb) << 16); w1[k2] = (unsigned)f2bf(rc) | ((unsigned)f2bf(rd) << 16); }
;               *(uint4*)(yaT + (size_t)c * T_TOK + o0 + n0) = make_uint4(w0[0], w0[1], w0[2], w0[3]);
;               *(uint4*)(yaT + (size_t)c * T_TOK + o1 + n0) = make_uint4(w1[0], w1[1], w1[2], w1[3]); }
;             lds_barrier();
;         }
;     }
	v_lshlrev_b32_e32 v116, 16, v0
	v_and_b32_sdwa v6, v72, v229 dst_sel:DWORD dst_unused:UNUSED_PAD src0_sel:WORD_1 src1_sel:DWORD
	v_add3_u32 v4, v73, v4, s33
	v_add3_u32 v10, v14, v10, s33
	v_and_b32_e32 v8, 0xffff0000, v8
	v_and_b32_e32 v0, 0xffff0000, v0
	v_add3_u32 v6, v72, v6, s33
	v_and_b32_e32 v10, 0xffff0000, v10
	v_or_b32_sdwa v15, v8, v4 dst_sel:DWORD dst_unused:UNUSED_PAD src0_sel:DWORD src1_sel:WORD_1
	v_mul_f32_e32 v4, 0xbfb8aa3b, v116
	v_or_b32_sdwa v14, v10, v6 dst_sel:DWORD dst_unused:UNUSED_PAD src0_sel:DWORD src1_sel:WORD_1
	v_exp_f32_e32 v4, v4
	v_mul_f32_e32 v6, 0xbfb8aa3b, v0
	v_exp_f32_e32 v6, v6
	v_lshlrev_b32_e32 v117, 16, v1
	v_add_f32_e32 v4, 1.0, v4
	v_rcp_f32_e32 v72, v4
	v_add_f32_e32 v4, 1.0, v6
	v_rcp_f32_e32 v74, v4
	v_mul_f32_e32 v4, 0xbfb8aa3b, v117
	v_exp_f32_e32 v4, v4
	v_and_b32_e32 v1, 0xffff0000, v1
	v_lshl_add_u64 v[120:121], v[50:51], 0, s[62:63]
	v_mov_b32_e32 v110, v80
	v_add_f32_e32 v4, 1.0, v4
	v_rcp_f32_e32 v73, v4
	v_mul_f32_e32 v4, 0xbfb8aa3b, v1
	v_exp_f32_e32 v4, v4
	global_store_dwordx4 v[120:121], v[12:15], off
	v_mov_b32_e32 v113, v86
	v_mov_b32_e32 v92, v89
	v_pk_mul_f32 v[14:15], v[38:39], v[110:111]
	v_pk_mul_f32 v[76:77], v[92:93], s[80:81] op_sel_hi:[1,0]
	v_pk_fma_f32 v[14:15], v[38:39], v[112:113], v[14:15] op_sel:[0,0,1] op_sel_hi:[1,1,0]
	v_add_f32_e32 v4, 1.0, v4
	v_pk_fma_f32 v[14:15], v[40:41], v[86:87], v[14:15]
	v_mov_b32_e32 v113, v80
	v_pk_add_f32 v[14:15], v[42:43], v[14:15]
	v_pk_mul_f32 v[70:71], v[54:55], v[86:87]
	v_pk_fma_f32 v[68:69], v[46:47], v[68:69], v[76:77]
	v_rcp_f32_e32 v75, v4
	v_pk_fma_f32 v[70:71], v[52:53], v[112:113], v[70:71]
	v_pk_mul_f32 v[14:15], v[14:15], v[68:69]
	v_pk_mul_f32 v[68:69], v[72:73], v[116:117]
	v_mov_b32_e32 v94, v91
	v_pk_fma_f32 v[70:71], v[40:41], v[80:81], v[70:71]
	v_pk_mul_f32 v[14:15], v[68:69], v[14:15]
	v_pk_mul_f32 v[68:69], v[94:95], s[80:81] op_sel_hi:[1,0]
	v_pk_add_f32 v[70:71], v[42:43], v[70:71]
	v_pk_fma_f32 v[66:67], v[46:47], v[66:67], v[68:69]
	v_pk_mul_f32 v[0:1], v[74:75], v[0:1]
	v_pk_mul_f32 v[66:67], v[70:71], v[66:67]
	v_and_b32_sdwa v6, v14, v229 dst_sel:DWORD dst_unused:UNUSED_PAD src0_sel:WORD_1 src1_sel:DWORD
	v_pk_mul_f32 v[0:1], v[0:1], v[66:67]
	v_and_b32_sdwa v4, v15, v229 dst_sel:DWORD dst_unused:UNUSED_PAD src0_sel:WORD_1 src1_sel:DWORD
	v_and_b32_sdwa v10, v0, v229 dst_sel:DWORD dst_unused:UNUSED_PAD src0_sel:WORD_1 src1_sel:DWORD
	v_and_b32_sdwa v8, v1, v229 dst_sel:DWORD dst_unused:UNUSED_PAD src0_sel:WORD_1 src1_sel:DWORD
	v_add3_u32 v0, v0, v10, s33
	v_add3_u32 v6, v14, v6, s33
	v_add3_u32 v1, v1, v8, s33
	v_and_b32_e32 v0, 0xffff0000, v0
	v_lshlrev_b32_e32 v14, 16, v2
	v_and_b32_e32 v2, 0xffff0000, v2
	v_add3_u32 v4, v15, v4, s33
	v_and_b32_e32 v1, 0xffff0000, v1
	v_or_b32_sdwa v0, v0, v6 dst_sel:DWORD dst_unused:UNUSED_PAD src0_sel:DWORD src1_sel:WORD_1
	v_lshlrev_b32_e32 v15, 16, v3
	v_mul_f32_e32 v6, 0xbfb8aa3b, v2
	v_or_b32_sdwa v1, v1, v4 dst_sel:DWORD dst_unused:UNUSED_PAD src0_sel:DWORD src1_sel:WORD_1
	v_mul_f32_e32 v4, 0xbfb8aa3b, v14
	v_exp_f32_e32 v6, v6
	v_mul_f32_e32 v8, 0xbfb8aa3b, v15
	v_exp_f32_e32 v4, v4
	v_exp_f32_e32 v10, v8
	v_and_b32_e32 v3, 0xffff0000, v3
	v_add_f32_e32 v6, 1.0, v6
	v_add_f32_e32 v4, 1.0, v4
	v_rcp_f32_e32 v66, v6
	v_mov_b32_e32 v8, v5
	v_add_f32_e32 v5, 1.0, v10
	v_mul_f32_e32 v6, 0xbfb8aa3b, v3
	v_rcp_f32_e32 v4, v4
	v_rcp_f32_e32 v5, v5
	v_exp_f32_e32 v6, v6
	v_mov_b32_e32 v10, v7
	v_mov_b32_e32 v80, v85
	v_pk_mul_f32 v[4:5], v[4:5], v[14:15]
	v_add_f32_e32 v6, 1.0, v6
	v_mov_b32_e32 v14, v81
	v_mov_b32_e32 v15, v83
	v_rcp_f32_e32 v67, v6
	v_pk_mul_f32 v[6:7], v[10:11], s[80:81] op_sel_hi:[1,0]
	v_pk_mov_b32 v[10:11], v[86:87], v[84:85] op_sel:[1,0]
	v_pk_mul_f32 v[14:15], v[54:55], v[14:15]
	v_mov_b32_e32 v82, v84
	v_pk_fma_f32 v[10:11], v[52:53], v[10:11], v[14:15]
	v_pk_mul_f32 v[14:15], v[38:39], v[80:81]
	v_mov_b32_e32 v78, v83
	v_pk_mul_f32 v[8:9], v[8:9], s[80:81] op_sel_hi:[1,0]
	v_pk_fma_f32 v[10:11], v[40:41], v[84:85], v[10:11]
	v_pk_fma_f32 v[14:15], v[38:39], v[82:83], v[14:15] op_sel:[0,0,1] op_sel_hi:[1,1,0]
	v_pk_fma_f32 v[8:9], v[46:47], v[64:65], v[8:9]
	v_pk_add_f32 v[10:11], v[42:43], v[10:11]
	v_pk_fma_f32 v[14:15], v[40:41], v[78:79], v[14:15]
	v_pk_fma_f32 v[6:7], v[46:47], v[62:63], v[6:7]
	v_pk_add_f32 v[14:15], v[42:43], v[14:15]
	v_pk_mul_f32 v[8:9], v[10:11], v[8:9]
	v_pk_mul_f32 v[2:3], v[66:67], v[2:3]
	v_pk_mul_f32 v[4:5], v[4:5], v[8:9]
	v_pk_mul_f32 v[6:7], v[14:15], v[6:7]
	s_mov_b32 s7, s63
	v_pk_mul_f32 v[2:3], v[2:3], v[6:7]
	v_and_b32_sdwa v6, v5, v229 dst_sel:DWORD dst_unused:UNUSED_PAD src0_sel:WORD_1 src1_sel:DWORD
	v_and_b32_sdwa v7, v4, v229 dst_sel:DWORD dst_unused:UNUSED_PAD src0_sel:WORD_1 src1_sel:DWORD
	v_add3_u32 v4, v4, v7, s33
	v_add3_u32 v5, v5, v6, s33
	v_and_b32_sdwa v6, v3, v229 dst_sel:DWORD dst_unused:UNUSED_PAD src0_sel:WORD_1 src1_sel:DWORD
	v_and_b32_sdwa v7, v2, v229 dst_sel:DWORD dst_unused:UNUSED_PAD src0_sel:WORD_1 src1_sel:DWORD
	v_add3_u32 v3, v3, v6, s33
	v_add3_u32 v2, v2, v7, s33
	v_and_b32_e32 v3, 0xffff0000, v3
	v_and_b32_e32 v2, 0xffff0000, v2
	v_lshl_add_u64 v[12:13], v[50:51], 0, s[6:7]
	v_or_b32_sdwa v3, v3, v5 dst_sel:DWORD dst_unused:UNUSED_PAD src0_sel:DWORD src1_sel:WORD_1
	v_or_b32_sdwa v2, v2, v4 dst_sel:DWORD dst_unused:UNUSED_PAD src0_sel:DWORD src1_sel:WORD_1
	global_store_dwordx4 v[12:13], v[0:3], off
	s_waitcnt lgkmcnt(0)
	s_barrier
	s_add_i32 s53, s53, 1
	s_cmp_eq_u32 s53, 4
	s_cbranch_scc0 .LBB0_346
	s_add_i32 s46, s46, s22
	v_readlane_b32 s60, v255, 27
	s_cmpk_gt_i32 s46, 0x3ff
	v_readlane_b32 s61, v255, 28
	s_movk_i32 s59, 0xffd0
	s_cbranch_scc0 .LBB0_333

; #define LAS __attribute__((address_space(3)))
; __device__ __forceinline__ float bperm_f(int addr, float v) { return __uint_as_float((unsigned)__builtin_amdgcn_ds_bpermute(addr, (int)__float_as_uint(v))); }
; __device__ __forceinline__ void natten_wave_task2(const bf16_t* __restrict__ proj, int b, int h, NatPol pA, NatPol pB, bf16_t* __restrict__ yout, int lane, LAS unsigned char* wl) {
;     ...
; #pragma unroll
;         for (int s = 0; s < 4; ++s) { scA = __builtin_amdgcn_mfma_f32_32x32x16_bf16(kf[s], qA[s], scA, 0, 0, 0); scB = __builtin_amdgcn_mfma_f32_32x32x16_bf16(kf[s], qB[s], scB, 0, 0, 0); }
;         attn_loadk<NatPol>(kbase, pA, fbn, r, hh, kf);
;         pA.scores(fb, r, hh, scA); pB.scores(fb, r, hh, scB);
;         if (fb == 0) { float ba = scA[0], bb = scB[0];
; #pragma unroll
;             for (int i = 1; i < 16; ++i) { ba = fmaxf(ba, scA[i]); bb = fmaxf(bb, scB[i]); }
;             ba = fmaxf(ba, bperm_f(xaddr, ba)); bb = fmaxf(bb, bperm_f(xaddr, bb)); mA = fmaxf(ba, -40.0f); mB = fmaxf(bb, -40.0f); }
;         float psA = 0.f, psB = 0.f;
; #pragma unroll
;         for (int i = 0; i < 16; ++i) { const float pa = __builtin_amdgcn_exp2f(scA[i] - mA); scA[i] = pa; psA += pa; const float pb = __builtin_amdgcn_exp2f(scB[i] - mB); scB[i] = pb; psB += pb; }
;         lA += psA; lB += psB;
;         { asm volatile("" ::: "memory");
; #pragma unroll
;           for (int j = 0; j < 4; ++j) *(LAS u32x4a*)(wl + (8 * j + (lane >> 3)) * 144 + (lane & 7) * 16) = vg[j];
;           asm volatile("" ::: "memory"); }
;         attn_loadv<NatPol>(vbase, pA, fbn, r, hh, vg);
.LBB0_388:
	s_waitcnt vmcnt(7)
	ds_write_b128 v243, v[140:143] offset:32768
	s_waitcnt vmcnt(6)
	ds_write_b128 v243, v[136:139] offset:33920
	s_waitcnt vmcnt(5)
	ds_write_b128 v243, v[132:135] offset:35072
	s_waitcnt vmcnt(4)
	ds_write_b128 v243, v[128:131] offset:36224
	ds_read_b128 v[140:143], v242 offset:32768
	ds_read_b128 v[136:139], v242 offset:32800
	ds_read_b128 v[132:135], v242 offset:32832
	ds_read_b128 v[128:131], v242 offset:32864
	s_waitcnt lgkmcnt(3)
	v_mfma_f32_32x32x16_bf16 v[80:95], v[140:143], v[96:99], 0
	s_mov_b32 s14, s11
	s_add_i32 s11, s11, 1
	s_cmp_lg_u32 s10, 6
	s_cselect_b32 s15, s11, 10
	v_add_u32_e32 v226, s10, v206
	v_mfma_f32_32x32x16_bf16 v[64:79], v[140:143], v[104:107], 0
	v_cmp_lt_i32_e64 s[48:49], v165, v163
	v_cmp_ge_i32_e64 s[50:51], v165, v208
	v_cmp_gt_u32_e32 vcc, 64, v165
	s_and_b64 s[26:27], s[50:51], s[48:49]
	s_and_b64 s[48:49], vcc, s[26:27]
	v_cndmask_b32_e64 v249, 0, v179, s[48:49]
	v_cmp_ge_i32_e64 s[50:51], v165, v209
	s_waitcnt lgkmcnt(2)
	v_mfma_f32_32x32x16_bf16 v[80:95], v[136:139], v[100:103], v[80:95]
	v_mfma_f32_32x32x16_bf16 v[64:79], v[136:139], v[108:111], v[64:79]
	s_waitcnt lgkmcnt(1)
	v_mfma_f32_32x32x16_bf16 v[80:95], v[132:135], v[112:115], v[80:95]
	v_mfma_f32_32x32x16_bf16 v[64:79], v[132:135], v[120:123], v[64:79]
	v_add_u32_e32 v132, s15, v207
	v_min_i32_e32 v132, 63, v132
	v_lshlrev_b32_e32 v211, 12, v132
	s_waitcnt lgkmcnt(0)
	v_mfma_f32_32x32x16_bf16 v[80:95], v[128:131], v[116:119], v[80:95]
	s_movk_i32 s15, 0x7c
	v_mfma_f32_32x32x16_bf16 v[64:79], v[128:131], v[124:127], v[64:79]
	v_add_u32_e32 v200, v211, v182
	v_or_b32_e32 v202, v211, v183
	v_ashrrev_i32_e32 v201, 31, v200
	v_ashrrev_i32_e32 v203, 31, v202
	v_lshl_add_u64 v[200:201], v[200:201], 1, v[240:241]
	v_lshl_add_u64 v[202:203], v[202:203], 1, v[240:241]
	global_load_dwordx4 v[140:143], v[200:201], off
	global_load_dwordx4 v[136:139], v[202:203], off
	v_add_u32_e32 v200, v211, v184
	v_add_u32_e32 v202, v211, v185
	v_ashrrev_i32_e32 v201, 31, v200
	v_ashrrev_i32_e32 v203, 31, v202
	v_lshl_add_u64 v[200:201], v[200:201], 1, v[240:241]
	v_lshl_add_u64 v[202:203], v[202:203], 1, v[240:241]
	global_load_dwordx4 v[132:135], v[200:201], off
	global_load_dwordx4 v[128:131], v[202:203], off
	v_med3_i32 v214, v226, -7, 7
	v_mad_i32_i24 v216, v214, s15, v188
	v_add_u32_e32 v214, 0x480, v216
	v_add_u32_e32 v217, 0x488, v216
	v_add_u32_e32 v218, 0x4a0, v216
	v_add_u32_e32 v219, 0x4a8, v216
	ds_read2_b32 v[214:215], v214 offset1:1
	ds_read2_b32 v[220:221], v217 offset1:1
	ds_read2_b32 v[222:223], v218 offset1:1
	ds_read2_b32 v[224:225], v219 offset1:1
	v_add_u32_e32 v217, 0x4c0, v216
	s_waitcnt lgkmcnt(3)
	v_fmamk_f32 v80, v80, 0x3e38aa3b, v214
	v_and_b32_e32 v214, 1, v249
	v_add_u32_e32 v218, 0x4c8, v216
	v_cmp_eq_u32_e64 s[48:49], 1, v214
	v_add_u32_e32 v219, 0x4e0, v216
	v_add_u32_e32 v216, 0x4e8, v216
	ds_read2_b32 v[234:235], v217 offset1:1
	ds_read2_b32 v[250:251], v218 offset1:1
	ds_read2_b32 v[236:237], v219 offset1:1
	ds_read2_b32 v[232:233], v216 offset1:1
	v_cndmask_b32_e64 v218, v246, v80, s[48:49]
	v_fmac_f32_e32 v215, 0x3e38aa3b, v81
	s_waitcnt lgkmcnt(6)
	v_fmamk_f32 v80, v82, 0x3e38aa3b, v220
	v_bfe_i32 v219, v249, 1, 1
	v_bfi_b32 v219, v219, v215, v246
	v_fmac_f32_e32 v221, 0x3e38aa3b, v83
	v_bfe_i32 v217, v249, 2, 1
	v_bfi_b32 v217, v217, v80, v246
	s_waitcnt lgkmcnt(5)
	v_fmamk_f32 v80, v84, 0x3e38aa3b, v222
	v_fmac_f32_e32 v223, 0x3e38aa3b, v85
	v_bfe_i32 v216, v249, 3, 1
	v_bfi_b32 v216, v216, v221, v246
	s_waitcnt lgkmcnt(4)
	v_fmac_f32_e32 v225, 0x3e38aa3b, v87
	v_bfe_i32 v215, v249, 4, 1
	v_bfi_b32 v215, v215, v80, v246
	v_fmamk_f32 v80, v86, 0x3e38aa3b, v224
	s_waitcnt lgkmcnt(3)
	v_fmac_f32_e32 v235, 0x3e38aa3b, v89
	v_bfe_i32 v214, v249, 5, 1
	v_bfi_b32 v214, v214, v223, v246
	s_waitcnt lgkmcnt(2)
	v_fmac_f32_e32 v251, 0x3e38aa3b, v91
	v_bfe_i32 v82, v249, 6, 1
	v_bfi_b32 v82, v82, v80, v246
	v_fmamk_f32 v80, v88, 0x3e38aa3b, v234
	s_waitcnt lgkmcnt(1)
	v_fmac_f32_e32 v237, 0x3e38aa3b, v93
	v_bfe_i32 v83, v249, 7, 1
	v_bfi_b32 v83, v83, v225, v246
	s_waitcnt lgkmcnt(0)
; __device__ __forceinline__ float bperm_f(int addr, float v) { return __uint_as_float((unsigned)__builtin_amdgcn_ds_bpermute(addr, (int)__float_as_uint(v))); }
; __device__ __forceinline__ void natten_wave_task2(const bf16_t* __restrict__ proj, int b, int h, NatPol pA, NatPol pB, bf16_t* __restrict__ yout, int lane, LAS unsigned char* wl) {
;     ...
;         pA.scores(fb, r, hh, scA); pB.scores(fb, r, hh, scB);
;         if (fb == 0) { float ba = scA[0], bb = scB[0];
; #pragma unroll
;             for (int i = 1; i < 16; ++i) { ba = fmaxf(ba, scA[i]); bb = fmaxf(bb, scB[i]); }
;             ba = fmaxf(ba, bperm_f(xaddr, ba)); bb = fmaxf(bb, bperm_f(xaddr, bb)); mA = fmaxf(ba, -40.0f); mB = fmaxf(bb, -40.0f); }
	v_fmac_f32_e32 v233, 0x3e38aa3b, v95
	v_bfe_i32 v84, v249, 8, 1
	v_bfi_b32 v84, v84, v80, v246
	v_fmamk_f32 v80, v90, 0x3e38aa3b, v250
	v_add_u32_e32 v90, -2, v226
	v_bfe_i32 v85, v249, 9, 1
	v_bfi_b32 v85, v85, v235, v246
	v_med3_i32 v90, v90, -7, 7
	v_bfe_i32 v86, v249, 10, 1
	v_bfi_b32 v86, v86, v80, v246
	v_fmamk_f32 v80, v92, 0x3e38aa3b, v236
	v_mad_i32_i24 v92, v90, s15, v188
	v_bfe_i32 v87, v249, 11, 1
	v_bfi_b32 v87, v87, v251, v246
	v_add_u32_e32 v90, 0x480, v92
	v_bfe_i32 v88, v249, 12, 1
	v_bfi_b32 v88, v88, v80, v246
	v_fmamk_f32 v80, v94, 0x3e38aa3b, v232
	v_add_u32_e32 v93, 0x488, v92
	v_bfe_i32 v89, v249, 13, 1
	v_bfi_b32 v89, v89, v237, v246
	v_add_u32_e32 v220, 0x4a0, v92
	v_add_u32_e32 v222, 0x4a8, v92
	v_bfe_i32 v81, v249, 14, 1
	v_bfi_b32 v81, v81, v80, v246
	ds_read2_b32 v[90:91], v90 offset1:1
	ds_read2_b32 v[94:95], v93 offset1:1
	ds_read2_b32 v[220:221], v220 offset1:1
	ds_read2_b32 v[222:223], v222 offset1:1
	v_bfe_i32 v80, v249, 15, 1
	v_bfi_b32 v80, v80, v233, v246
	v_cmp_lt_i32_e64 s[48:49], v165, v210
	s_and_b64 s[26:27], s[50:51], s[48:49]
	v_add_u32_e32 v93, 0x4c0, v92
	v_add_u32_e32 v226, 0x4c8, v92
	v_add_u32_e32 v234, 0x4e0, v92
	s_and_b64 vcc, vcc, s[26:27]
	v_add_u32_e32 v92, 0x4e8, v92
	ds_read2_b32 v[224:225], v93 offset1:1
	ds_read2_b32 v[232:233], v226 offset1:1
	ds_read2_b32 v[234:235], v234 offset1:1
	ds_read2_b32 v[236:237], v92 offset1:1
	v_cndmask_b32_e32 v226, 0, v179, vcc
	s_waitcnt lgkmcnt(7)
	v_fmamk_f32 v64, v64, 0x3e38aa3b, v90
	v_and_b32_e32 v90, 1, v226
	v_cmp_eq_u32_e32 vcc, 1, v90
	v_fmac_f32_e32 v91, 0x3e38aa3b, v65
	v_cndmask_b32_e32 v92, v246, v64, vcc
	s_waitcnt lgkmcnt(6)
	v_fmamk_f32 v64, v66, 0x3e38aa3b, v94
	v_fmac_f32_e32 v95, 0x3e38aa3b, v67
	v_bfe_i32 v93, v226, 1, 1
	v_bfi_b32 v93, v93, v91, v246
	s_waitcnt lgkmcnt(5)
	v_fmac_f32_e32 v221, 0x3e38aa3b, v69
	v_bfe_i32 v90, v226, 2, 1
	v_bfi_b32 v90, v90, v64, v246
	v_fmamk_f32 v64, v68, 0x3e38aa3b, v220
	s_waitcnt lgkmcnt(4)
	v_fmac_f32_e32 v223, 0x3e38aa3b, v71
	v_bfe_i32 v91, v226, 3, 1
	v_bfi_b32 v91, v91, v95, v246
	s_waitcnt lgkmcnt(3)
	v_fmac_f32_e32 v225, 0x3e38aa3b, v73
	v_bfe_i32 v66, v226, 4, 1
	v_bfi_b32 v66, v66, v64, v246
	v_fmamk_f32 v64, v70, 0x3e38aa3b, v222
	s_waitcnt lgkmcnt(2)
	v_fmac_f32_e32 v233, 0x3e38aa3b, v75
	v_bfe_i32 v67, v226, 5, 1
	v_bfi_b32 v67, v67, v221, v246
	s_waitcnt lgkmcnt(1)
	v_fmac_f32_e32 v235, 0x3e38aa3b, v77
	v_bfe_i32 v68, v226, 6, 1
	v_bfi_b32 v68, v68, v64, v246
	v_fmamk_f32 v64, v72, 0x3e38aa3b, v224
	s_waitcnt lgkmcnt(0)
	v_fmac_f32_e32 v237, 0x3e38aa3b, v79
	v_bfe_i32 v69, v226, 7, 1
	v_bfi_b32 v69, v69, v223, v246
	s_cmp_lg_u32 s14, 0
	v_bfe_i32 v70, v226, 8, 1
	v_bfi_b32 v70, v70, v64, v246
	v_fmamk_f32 v64, v74, 0x3e38aa3b, v232
	s_nop 0
	v_bfe_i32 v71, v226, 9, 1
	v_bfi_b32 v71, v71, v225, v246
	s_nop 0
	v_bfe_i32 v72, v226, 10, 1
	v_bfi_b32 v72, v72, v64, v246
	v_fmamk_f32 v64, v76, 0x3e38aa3b, v234
	s_nop 0
	v_bfe_i32 v73, v226, 11, 1
	v_bfi_b32 v73, v73, v233, v246
	v_and_b32_e32 v65, 0x4000, v226
	s_nop 0
	v_bfe_i32 v74, v226, 12, 1
	v_bfi_b32 v74, v74, v64, v246
	v_fmamk_f32 v64, v78, 0x3e38aa3b, v236
	s_nop 0
	v_bfe_i32 v75, v226, 13, 1
	v_bfi_b32 v75, v75, v235, v246
	v_cmp_ne_u32_e32 vcc, 0, v65
	s_nop 0
	v_cndmask_b32_e32 v64, v246, v64, vcc
	s_nop 1
	v_bfe_i32 v65, v226, 15, 1
	v_bfi_b32 v65, v65, v237, v246
	s_cbranch_scc1 .LBB0_387
	v_max_f32_e32 v76, v219, v219
	v_max_f32_e32 v77, v218, v218
	v_max_f32_e32 v76, v77, v76
	v_max_f32_e32 v77, v93, v93
	v_max_f32_e32 v78, v92, v92
	v_max_f32_e32 v77, v78, v77
	v_max3_f32 v76, v76, v217, v216
	v_max3_f32 v77, v77, v90, v91
	v_max3_f32 v76, v76, v215, v214
	v_max3_f32 v77, v77, v66, v67
	v_max3_f32 v76, v76, v82, v83
	v_max3_f32 v77, v77, v68, v69
	v_max3_f32 v76, v76, v84, v85
	v_max3_f32 v77, v77, v70, v71
	v_max3_f32 v76, v76, v86, v87
	v_max3_f32 v77, v77, v72, v73
	v_max3_f32 v76, v76, v88, v89
	v_max3_f32 v77, v77, v74, v75
	v_max3_f32 v76, v76, v81, v80
	v_max3_f32 v77, v77, v64, v65
	ds_bpermute_b32 v78, v180, v76
	ds_bpermute_b32 v79, v180, v77
	s_waitcnt lgkmcnt(1)
	v_max3_f32 v212, v76, v78, s84
	s_waitcnt lgkmcnt(0)
	v_max3_f32 v213, v77, v79, s84
	s_branch .LBB0_387

; #define LAS __attribute__((address_space(3)))
; __device__ __forceinline__ float bperm_f(int addr, float v) { return __uint_as_float((unsigned)__builtin_amdgcn_ds_bpermute(addr, (int)__float_as_uint(v))); }
; __device__ __forceinline__ void natten_wave_task2(const bf16_t* __restrict__ proj, int b, int h, NatPol pA, NatPol pB, bf16_t* __restrict__ yout, int lane, LAS unsigned char* wl) {
;     ...
; #pragma unroll
;         for (int s = 0; s < 4; ++s) { scA = __builtin_amdgcn_mfma_f32_32x32x16_bf16(kf[s], qA[s], scA, 0, 0, 0); scB = __builtin_amdgcn_mfma_f32_32x32x16_bf16(kf[s], qB[s], scB, 0, 0, 0); }
;         attn_loadk<NatPol>(kbase, pA, fbn, r, hh, kf);
;         pA.scores(fb, r, hh, scA); pB.scores(fb, r, hh, scB);
;         if (fb == 0) { float ba = scA[0], bb = scB[0];
; #pragma unroll
;             for (int i = 1; i < 16; ++i) { ba = fmaxf(ba, scA[i]); bb = fmaxf(bb, scB[i]); }
;             ba = fmaxf(ba, bperm_f(xaddr, ba)); bb = fmaxf(bb, bperm_f(xaddr, bb)); mA = fmaxf(ba, -40.0f); mB = fmaxf(bb, -40.0f); }
;         float psA = 0.f, psB = 0.f;
; #pragma unroll
;         for (int i = 0; i < 16; ++i) { const float pa = __builtin_amdgcn_exp2f(scA[i] - mA); scA[i] = pa; psA += pa; const float pb = __builtin_amdgcn_exp2f(scB[i] - mB); scB[i] = pb; psB += pb; }
;         lA += psA; lB += psB;
;         { asm volatile("" ::: "memory");
; #pragma unroll
;           for (int j = 0; j < 4; ++j) *(LAS u32x4a*)(wl + (8 * j + (lane >> 3)) * 144 + (lane & 7) * 16) = vg[j];
;           asm volatile("" ::: "memory"); }
;         attn_loadv<NatPol>(vbase, pA, fbn, r, hh, vg);
.LBB0_574:
	s_waitcnt vmcnt(7)
	ds_write_b128 v243, v[140:143] offset:32768
	s_waitcnt vmcnt(6)
	ds_write_b128 v243, v[136:139] offset:33920
	s_waitcnt vmcnt(5)
	ds_write_b128 v243, v[132:135] offset:35072
	s_waitcnt vmcnt(4)
	ds_write_b128 v243, v[128:131] offset:36224
	ds_read_b128 v[140:143], v242 offset:32768
	ds_read_b128 v[136:139], v242 offset:32800
	ds_read_b128 v[132:135], v242 offset:32832
	ds_read_b128 v[128:131], v242 offset:32864
	s_waitcnt lgkmcnt(3)
	v_mfma_f32_32x32x16_bf16 v[80:95], v[140:143], v[96:99], 0
	s_mov_b32 s14, s11
	s_add_i32 s11, s11, 1
	s_cmp_lg_u32 s10, 6
	s_cselect_b32 s15, s11, 10
	v_add_u32_e32 v226, s10, v206
	v_mfma_f32_32x32x16_bf16 v[64:79], v[140:143], v[104:107], 0
	v_cmp_lt_i32_e64 s[46:47], v165, v163
	v_cmp_ge_i32_e64 s[48:49], v165, v208
	v_cmp_gt_u32_e32 vcc, 64, v165
	s_and_b64 s[26:27], s[48:49], s[46:47]
	s_and_b64 s[46:47], vcc, s[26:27]
	v_cndmask_b32_e64 v249, 0, v179, s[46:47]
	v_cmp_ge_i32_e64 s[48:49], v165, v209
	s_waitcnt lgkmcnt(2)
	v_mfma_f32_32x32x16_bf16 v[80:95], v[136:139], v[100:103], v[80:95]
	v_mfma_f32_32x32x16_bf16 v[64:79], v[136:139], v[108:111], v[64:79]
	s_waitcnt lgkmcnt(1)
	v_mfma_f32_32x32x16_bf16 v[80:95], v[132:135], v[112:115], v[80:95]
	v_mfma_f32_32x32x16_bf16 v[64:79], v[132:135], v[120:123], v[64:79]
	v_add_u32_e32 v132, s15, v207
	v_min_i32_e32 v132, 63, v132
	v_lshlrev_b32_e32 v211, 12, v132
	s_waitcnt lgkmcnt(0)
	v_mfma_f32_32x32x16_bf16 v[80:95], v[128:131], v[116:119], v[80:95]
	s_movk_i32 s15, 0x7c
	v_mfma_f32_32x32x16_bf16 v[64:79], v[128:131], v[124:127], v[64:79]
	v_add_u32_e32 v200, v211, v182
	v_or_b32_e32 v202, v211, v183
	v_ashrrev_i32_e32 v201, 31, v200
	v_ashrrev_i32_e32 v203, 31, v202
	v_lshl_add_u64 v[200:201], v[200:201], 1, v[240:241]
	v_lshl_add_u64 v[202:203], v[202:203], 1, v[240:241]
	global_load_dwordx4 v[140:143], v[200:201], off
	global_load_dwordx4 v[136:139], v[202:203], off
	v_add_u32_e32 v200, v211, v184
	v_add_u32_e32 v202, v211, v185
	v_ashrrev_i32_e32 v201, 31, v200
	v_ashrrev_i32_e32 v203, 31, v202
	v_lshl_add_u64 v[200:201], v[200:201], 1, v[240:241]
	v_lshl_add_u64 v[202:203], v[202:203], 1, v[240:241]
	global_load_dwordx4 v[132:135], v[200:201], off
	global_load_dwordx4 v[128:131], v[202:203], off
	v_med3_i32 v214, v226, -7, 7
	v_mad_i32_i24 v216, v214, s15, v188
	v_add_u32_e32 v214, 0x480, v216
	v_add_u32_e32 v217, 0x488, v216
	v_add_u32_e32 v218, 0x4a0, v216
	v_add_u32_e32 v219, 0x4a8, v216
	ds_read2_b32 v[214:215], v214 offset1:1
	ds_read2_b32 v[220:221], v217 offset1:1
	ds_read2_b32 v[222:223], v218 offset1:1
	ds_read2_b32 v[224:225], v219 offset1:1
	v_add_u32_e32 v217, 0x4c0, v216
	s_waitcnt lgkmcnt(3)
	v_fmamk_f32 v80, v80, 0x3e38aa3b, v214
	v_and_b32_e32 v214, 1, v249
	v_add_u32_e32 v218, 0x4c8, v216
	v_cmp_eq_u32_e64 s[46:47], 1, v214
	v_add_u32_e32 v219, 0x4e0, v216
	v_add_u32_e32 v216, 0x4e8, v216
	ds_read2_b32 v[232:233], v217 offset1:1
	ds_read2_b32 v[234:235], v218 offset1:1
	ds_read2_b32 v[236:237], v219 offset1:1
	ds_read2_b32 v[250:251], v216 offset1:1
	v_cndmask_b32_e64 v218, v246, v80, s[46:47]
	v_fmac_f32_e32 v215, 0x3e38aa3b, v81
	s_waitcnt lgkmcnt(6)
	v_fmamk_f32 v80, v82, 0x3e38aa3b, v220
	v_bfe_i32 v219, v249, 1, 1
	v_bfi_b32 v219, v219, v215, v246
	v_fmac_f32_e32 v221, 0x3e38aa3b, v83
	v_bfe_i32 v217, v249, 2, 1
	v_bfi_b32 v217, v217, v80, v246
	s_waitcnt lgkmcnt(5)
	v_fmamk_f32 v80, v84, 0x3e38aa3b, v222
	v_fmac_f32_e32 v223, 0x3e38aa3b, v85
	v_bfe_i32 v216, v249, 3, 1
	v_bfi_b32 v216, v216, v221, v246
	s_waitcnt lgkmcnt(4)
	v_fmac_f32_e32 v225, 0x3e38aa3b, v87
	v_bfe_i32 v215, v249, 4, 1
	v_bfi_b32 v215, v215, v80, v246
	v_fmamk_f32 v80, v86, 0x3e38aa3b, v224
	s_waitcnt lgkmcnt(3)
	v_fmac_f32_e32 v233, 0x3e38aa3b, v89
	v_bfe_i32 v214, v249, 5, 1
	v_bfi_b32 v214, v214, v223, v246
	s_waitcnt lgkmcnt(2)
	v_fmac_f32_e32 v235, 0x3e38aa3b, v91
	v_bfe_i32 v82, v249, 6, 1
	v_bfi_b32 v82, v82, v80, v246
	v_fmamk_f32 v80, v88, 0x3e38aa3b, v232
	s_waitcnt lgkmcnt(1)
	v_fmac_f32_e32 v237, 0x3e38aa3b, v93
	v_bfe_i32 v83, v249, 7, 1
	v_bfi_b32 v83, v83, v225, v246
	s_waitcnt lgkmcnt(0)
; __device__ __forceinline__ float bperm_f(int addr, float v) { return __uint_as_float((unsigned)__builtin_amdgcn_ds_bpermute(addr, (int)__float_as_uint(v))); }
; __device__ __forceinline__ void natten_wave_task2(const bf16_t* __restrict__ proj, int b, int h, NatPol pA, NatPol pB, bf16_t* __restrict__ yout, int lane, LAS unsigned char* wl) {
;     ...
;         pA.scores(fb, r, hh, scA); pB.scores(fb, r, hh, scB);
;         if (fb == 0) { float ba = scA[0], bb = scB[0];
; #pragma unroll
;             for (int i = 1; i < 16; ++i) { ba = fmaxf(ba, scA[i]); bb = fmaxf(bb, scB[i]); }
;             ba = fmaxf(ba, bperm_f(xaddr, ba)); bb = fmaxf(bb, bperm_f(xaddr, bb)); mA = fmaxf(ba, -40.0f); mB = fmaxf(bb, -40.0f); }
	v_fmac_f32_e32 v251, 0x3e38aa3b, v95
	v_bfe_i32 v84, v249, 8, 1
	v_bfi_b32 v84, v84, v80, v246
	v_fmamk_f32 v80, v90, 0x3e38aa3b, v234
	v_add_u32_e32 v90, -2, v226
	v_bfe_i32 v85, v249, 9, 1
	v_bfi_b32 v85, v85, v233, v246
	v_med3_i32 v90, v90, -7, 7
	v_bfe_i32 v86, v249, 10, 1
	v_bfi_b32 v86, v86, v80, v246
	v_fmamk_f32 v80, v92, 0x3e38aa3b, v236
	v_mad_i32_i24 v92, v90, s15, v188
	v_bfe_i32 v87, v249, 11, 1
	v_bfi_b32 v87, v87, v235, v246
	v_add_u32_e32 v90, 0x480, v92
	v_bfe_i32 v88, v249, 12, 1
	v_bfi_b32 v88, v88, v80, v246
	v_fmamk_f32 v80, v94, 0x3e38aa3b, v250
	v_add_u32_e32 v93, 0x488, v92
	v_bfe_i32 v89, v249, 13, 1
	v_bfi_b32 v89, v89, v237, v246
	v_add_u32_e32 v220, 0x4a0, v92
	v_add_u32_e32 v222, 0x4a8, v92
	v_bfe_i32 v81, v249, 14, 1
	v_bfi_b32 v81, v81, v80, v246
	ds_read2_b32 v[90:91], v90 offset1:1
	ds_read2_b32 v[94:95], v93 offset1:1
	ds_read2_b32 v[220:221], v220 offset1:1
	ds_read2_b32 v[222:223], v222 offset1:1
	v_bfe_i32 v80, v249, 15, 1
	v_bfi_b32 v80, v80, v251, v246
	v_cmp_lt_i32_e64 s[46:47], v165, v210
	s_and_b64 s[26:27], s[48:49], s[46:47]
	v_add_u32_e32 v93, 0x4c0, v92
	v_add_u32_e32 v226, 0x4c8, v92
	v_add_u32_e32 v234, 0x4e0, v92
	s_and_b64 vcc, vcc, s[26:27]
	v_add_u32_e32 v92, 0x4e8, v92
	ds_read2_b32 v[224:225], v93 offset1:1
	ds_read2_b32 v[232:233], v226 offset1:1
	ds_read2_b32 v[234:235], v234 offset1:1
	ds_read2_b32 v[236:237], v92 offset1:1
	v_cndmask_b32_e32 v226, 0, v179, vcc
	s_waitcnt lgkmcnt(7)
	v_fmamk_f32 v64, v64, 0x3e38aa3b, v90
	v_and_b32_e32 v90, 1, v226
	v_cmp_eq_u32_e32 vcc, 1, v90
	v_fmac_f32_e32 v91, 0x3e38aa3b, v65
	v_cndmask_b32_e32 v92, v246, v64, vcc
	s_waitcnt lgkmcnt(6)
	v_fmamk_f32 v64, v66, 0x3e38aa3b, v94
	v_fmac_f32_e32 v95, 0x3e38aa3b, v67
	v_bfe_i32 v93, v226, 1, 1
	v_bfi_b32 v93, v93, v91, v246
	s_waitcnt lgkmcnt(5)
	v_fmac_f32_e32 v221, 0x3e38aa3b, v69
	v_bfe_i32 v90, v226, 2, 1
	v_bfi_b32 v90, v90, v64, v246
	v_fmamk_f32 v64, v68, 0x3e38aa3b, v220
	s_waitcnt lgkmcnt(4)
	v_fmac_f32_e32 v223, 0x3e38aa3b, v71
	v_bfe_i32 v91, v226, 3, 1
	v_bfi_b32 v91, v91, v95, v246
	s_waitcnt lgkmcnt(3)
	v_fmac_f32_e32 v225, 0x3e38aa3b, v73
	v_bfe_i32 v66, v226, 4, 1
	v_bfi_b32 v66, v66, v64, v246
	v_fmamk_f32 v64, v70, 0x3e38aa3b, v222
	s_waitcnt lgkmcnt(2)
	v_fmac_f32_e32 v233, 0x3e38aa3b, v75
	v_bfe_i32 v67, v226, 5, 1
	v_bfi_b32 v67, v67, v221, v246
	s_waitcnt lgkmcnt(1)
	v_fmac_f32_e32 v235, 0x3e38aa3b, v77
	v_bfe_i32 v68, v226, 6, 1
	v_bfi_b32 v68, v68, v64, v246
	v_fmamk_f32 v64, v72, 0x3e38aa3b, v224
	s_waitcnt lgkmcnt(0)
	v_fmac_f32_e32 v237, 0x3e38aa3b, v79
	v_bfe_i32 v69, v226, 7, 1
	v_bfi_b32 v69, v69, v223, v246
	s_cmp_lg_u32 s14, 0
	v_bfe_i32 v70, v226, 8, 1
	v_bfi_b32 v70, v70, v64, v246
	v_fmamk_f32 v64, v74, 0x3e38aa3b, v232
	s_nop 0
	v_bfe_i32 v71, v226, 9, 1
	v_bfi_b32 v71, v71, v225, v246
	s_nop 0
	v_bfe_i32 v72, v226, 10, 1
	v_bfi_b32 v72, v72, v64, v246
	v_fmamk_f32 v64, v76, 0x3e38aa3b, v234
	s_nop 0
	v_bfe_i32 v73, v226, 11, 1
	v_bfi_b32 v73, v73, v233, v246
	v_and_b32_e32 v65, 0x4000, v226
	s_nop 0
	v_bfe_i32 v74, v226, 12, 1
	v_bfi_b32 v74, v74, v64, v246
	v_fmamk_f32 v64, v78, 0x3e38aa3b, v236
	s_nop 0
	v_bfe_i32 v75, v226, 13, 1
	v_bfi_b32 v75, v75, v235, v246
	v_cmp_ne_u32_e32 vcc, 0, v65
	s_nop 0
	v_cndmask_b32_e32 v64, v246, v64, vcc
	s_nop 1
	v_bfe_i32 v65, v226, 15, 1
	v_bfi_b32 v65, v65, v237, v246
	s_cbranch_scc1 .LBB0_573
	v_max_f32_e32 v76, v219, v219
	v_max_f32_e32 v77, v218, v218
	v_max_f32_e32 v76, v77, v76
	v_max_f32_e32 v77, v93, v93
	v_max_f32_e32 v78, v92, v92
	v_max_f32_e32 v77, v78, v77
	v_max3_f32 v76, v76, v217, v216
	v_max3_f32 v77, v77, v90, v91
	v_max3_f32 v76, v76, v215, v214
	v_max3_f32 v77, v77, v66, v67
	v_max3_f32 v76, v76, v82, v83
	v_max3_f32 v77, v77, v68, v69
	v_max3_f32 v76, v76, v84, v85
	v_max3_f32 v77, v77, v70, v71
	v_max3_f32 v76, v76, v86, v87
	v_max3_f32 v77, v77, v72, v73
	v_max3_f32 v76, v76, v88, v89
	v_max3_f32 v77, v77, v74, v75
	v_max3_f32 v76, v76, v81, v80
	v_max3_f32 v77, v77, v64, v65
	ds_bpermute_b32 v78, v180, v76
	ds_bpermute_b32 v79, v180, v77
	s_waitcnt lgkmcnt(1)
	v_max3_f32 v212, v76, v78, s84
	s_waitcnt lgkmcnt(0)
	v_max3_f32 v213, v77, v79, s84
	s_branch .LBB0_573
